# rms double-buffered + batch-interleaved rows; NSA cmp-branch loads hoisted with counted waits; NSA step waits moved to consumers + permlane max; prep mod loop 32 loads in flight
# speedup vs baseline: 1.0233x; 1.0068x over previous
.LBB0_8:
	s_mov_b32 s15, s2
	s_mov_b64 s[6:7], -1
	s_mov_b64 s[0:1], 0
	s_cmp_lt_i32 s2, 19
	s_mov_b64 s[4:5], 0
	s_cbranch_scc1 .LBB0_17
	s_cmp_eq_u32 s15, 19
	s_mov_b64 s[4:5], -1
	s_cbranch_scc0 .LBB0_16
	v_mov_b32_e32 v0, 0xe0
	v_mov_b32_e32 v2, 0xd8
	v_add_u32_e32 v0, s91, v0
	ds_read_b64 v[0:1], v0
	v_mov_b32_e32 v4, 0xe0
	v_add_u32_e32 v2, s91, v2
	ds_read_b64 v[2:3], v2
	s_waitcnt lgkmcnt(0)
	v_readfirstlane_b32 s9, v1
	v_add_u32_e32 v4, s91, v4
	ds_read_b64 v[4:5], v4
	v_readfirstlane_b32 s8, v0
	v_mbcnt_lo_u32_b32 v0, -1, 0
	v_mbcnt_hi_u32_b32 v0, -1, v0
	v_readlane_b32 s2, v253, 11
	v_add_u32_e32 v1, s57, v0
	v_ashrrev_i32_e32 v1, 6, v1
	v_add_u32_e32 v52, s2, v1
	s_waitcnt lgkmcnt(1)
	v_readfirstlane_b32 s11, v3
	v_readfirstlane_b32 s10, v2
	s_waitcnt lgkmcnt(0)
	v_readfirstlane_b32 s7, v5
	v_readfirstlane_b32 s6, v4
	v_cmp_gt_i32_e32 vcc, s3, v52
	s_and_saveexec_b64 s[4:5], vcc
	s_cbranch_execz .LBB0_15
	v_readfirstlane_b32 s100, v52
	s_nop 3
	v_lshlrev_b32_e32 v120, 4, v0
	v_lshlrev_b32_e32 v121, 3, v0
	v_lshlrev_b32_e32 v122, 2, v214
	v_lshlrev_b32_e32 v123, 2, v215
	v_lshlrev_b32_e32 v124, 2, v216
	v_lshlrev_b32_e32 v125, 2, v217
	v_lshlrev_b32_e32 v126, 2, v218
	v_lshlrev_b32_e32 v127, 2, v219
	s_lshr_b32 s2, s100, 6
	s_lshl_b32 s2, s2, 11
	s_and_b32 s101, s100, 63
	s_add_u32 s2, s2, s101
	s_lshl_b32 s101, s2, 12
	s_add_u32 s8, s8, s101
	s_addc_u32 s9, s9, 0
	s_add_u32 s6, s6, s101
	s_addc_u32 s7, s7, 0
	global_load_dwordx4 v[0:3], v120, s[10:11] offset:0
	global_load_dwordx4 v[4:7], v120, s[10:11] offset:1024
	global_load_dwordx4 v[8:11], v120, s[10:11] offset:2048
	global_load_dwordx4 v[12:15], v120, s[10:11] offset:3072
	s_movk_i32 s2, 3
	global_load_dwordx4 v[48:51], v120, s[8:9] offset:0
	global_load_dwordx4 v[52:55], v120, s[8:9] offset:1024
	global_load_dwordx4 v[56:59], v120, s[8:9] offset:2048
	global_load_dwordx4 v[60:63], v120, s[8:9] offset:3072
	s_add_u32 s8, s8, 0x40000
	s_addc_u32 s9, s9, 0
	global_load_dwordx4 v[64:67], v120, s[8:9] offset:0
	global_load_dwordx4 v[68:71], v120, s[8:9] offset:1024
	global_load_dwordx4 v[72:75], v120, s[8:9] offset:2048
	global_load_dwordx4 v[76:79], v120, s[8:9] offset:3072
	s_add_u32 s8, s8, 0x40000
	s_addc_u32 s9, s9, 0
	global_load_dwordx4 v[80:83], v120, s[8:9] offset:0
	global_load_dwordx4 v[84:87], v120, s[8:9] offset:1024
	global_load_dwordx4 v[88:91], v120, s[8:9] offset:2048
	global_load_dwordx4 v[92:95], v120, s[8:9] offset:3072
	s_add_u32 s8, s8, 0x40000
	s_addc_u32 s9, s9, 0
	global_load_dwordx4 v[96:99], v120, s[8:9] offset:0
	global_load_dwordx4 v[100:103], v120, s[8:9] offset:1024
	global_load_dwordx4 v[104:107], v120, s[8:9] offset:2048
	global_load_dwordx4 v[108:111], v120, s[8:9] offset:3072
	s_add_u32 s8, s8, 0x40000
	s_addc_u32 s9, s9, 0
	global_load_dwordx4 v[132:135], v120, s[8:9] offset:0
	global_load_dwordx4 v[136:139], v120, s[8:9] offset:1024
	global_load_dwordx4 v[140:143], v120, s[8:9] offset:2048
	global_load_dwordx4 v[144:147], v120, s[8:9] offset:3072
	s_add_u32 s8, s8, 0x40000
	s_addc_u32 s9, s9, 0
	global_load_dwordx4 v[166:169], v120, s[8:9] offset:0
	global_load_dwordx4 v[170:173], v120, s[8:9] offset:1024
	global_load_dwordx4 v[174:177], v120, s[8:9] offset:2048
	global_load_dwordx4 v[178:181], v120, s[8:9] offset:3072
	s_add_u32 s8, s8, 0x40000
	s_addc_u32 s9, s9, 0
	global_load_dwordx4 v[182:185], v120, s[8:9] offset:0
	global_load_dwordx4 v[186:189], v120, s[8:9] offset:1024
	global_load_dwordx4 v[190:193], v120, s[8:9] offset:2048
	global_load_dwordx4 v[194:197], v120, s[8:9] offset:3072
	s_add_u32 s8, s8, 0x40000
	s_addc_u32 s9, s9, 0
	global_load_dwordx4 v[228:231], v120, s[8:9] offset:0
	global_load_dwordx4 v[232:235], v120, s[8:9] offset:1024
	global_load_dwordx4 v[236:239], v120, s[8:9] offset:2048
	global_load_dwordx4 v[240:243], v120, s[8:9] offset:3072
	s_add_u32 s8, s8, 0x40000
	s_addc_u32 s9, s9, 0
	s_waitcnt vmcnt(28)
	v_mul_f32_e32 v112, v48, v48
	v_fmac_f32_e32 v112, v49, v49
	v_fmac_f32_e32 v112, v50, v50
	v_fmac_f32_e32 v112, v51, v51
	v_fmac_f32_e32 v112, v52, v52
	v_fmac_f32_e32 v112, v53, v53
	v_fmac_f32_e32 v112, v54, v54
	v_fmac_f32_e32 v112, v55, v55
	v_fmac_f32_e32 v112, v56, v56
	v_fmac_f32_e32 v112, v57, v57
	v_fmac_f32_e32 v112, v58, v58
	v_fmac_f32_e32 v112, v59, v59
	v_fmac_f32_e32 v112, v60, v60
	v_fmac_f32_e32 v112, v61, v61
	v_fmac_f32_e32 v112, v62, v62
	v_fmac_f32_e32 v112, v63, v63
	s_waitcnt vmcnt(24)
	v_mul_f32_e32 v113, v64, v64
	v_fmac_f32_e32 v113, v65, v65
	v_fmac_f32_e32 v113, v66, v66
	v_fmac_f32_e32 v113, v67, v67
	v_fmac_f32_e32 v113, v68, v68
	v_fmac_f32_e32 v113, v69, v69
	v_fmac_f32_e32 v113, v70, v70
	v_fmac_f32_e32 v113, v71, v71
	v_fmac_f32_e32 v113, v72, v72
	v_fmac_f32_e32 v113, v73, v73
	v_fmac_f32_e32 v113, v74, v74
	v_fmac_f32_e32 v113, v75, v75
	v_fmac_f32_e32 v113, v76, v76
	v_fmac_f32_e32 v113, v77, v77
	v_fmac_f32_e32 v113, v78, v78
	v_fmac_f32_e32 v113, v79, v79
	s_waitcnt vmcnt(20)
	v_mul_f32_e32 v114, v80, v80
	v_fmac_f32_e32 v114, v81, v81
	v_fmac_f32_e32 v114, v82, v82
	v_fmac_f32_e32 v114, v83, v83
	v_fmac_f32_e32 v114, v84, v84
	v_fmac_f32_e32 v114, v85, v85
	v_fmac_f32_e32 v114, v86, v86
	v_fmac_f32_e32 v114, v87, v87
	v_fmac_f32_e32 v114, v88, v88
	v_fmac_f32_e32 v114, v89, v89
	v_fmac_f32_e32 v114, v90, v90
	v_fmac_f32_e32 v114, v91, v91
	v_fmac_f32_e32 v114, v92, v92
	v_fmac_f32_e32 v114, v93, v93
	v_fmac_f32_e32 v114, v94, v94
	v_fmac_f32_e32 v114, v95, v95
	s_waitcnt vmcnt(16)
	v_mul_f32_e32 v115, v96, v96
	v_fmac_f32_e32 v115, v97, v97
	v_fmac_f32_e32 v115, v98, v98
	v_fmac_f32_e32 v115, v99, v99
	v_fmac_f32_e32 v115, v100, v100
	v_fmac_f32_e32 v115, v101, v101
	v_fmac_f32_e32 v115, v102, v102
	v_fmac_f32_e32 v115, v103, v103
	v_fmac_f32_e32 v115, v104, v104
	v_fmac_f32_e32 v115, v105, v105
	v_fmac_f32_e32 v115, v106, v106
	v_fmac_f32_e32 v115, v107, v107
	v_fmac_f32_e32 v115, v108, v108
	v_fmac_f32_e32 v115, v109, v109
	v_fmac_f32_e32 v115, v110, v110
	v_fmac_f32_e32 v115, v111, v111
	ds_bpermute_b32 v116, v122, v112
	ds_bpermute_b32 v117, v122, v113
	ds_bpermute_b32 v118, v122, v114
	ds_bpermute_b32 v119, v122, v115
	s_waitcnt lgkmcnt(0)
	v_add_f32_e32 v112, v112, v116
	v_add_f32_e32 v113, v113, v117
	v_add_f32_e32 v114, v114, v118
	v_add_f32_e32 v115, v115, v119
	ds_bpermute_b32 v116, v123, v112
	ds_bpermute_b32 v117, v123, v113
	ds_bpermute_b32 v118, v123, v114
	ds_bpermute_b32 v119, v123, v115
	s_waitcnt lgkmcnt(0)
	v_add_f32_e32 v112, v112, v116
	v_add_f32_e32 v113, v113, v117
	v_add_f32_e32 v114, v114, v118
	v_add_f32_e32 v115, v115, v119
	ds_bpermute_b32 v116, v124, v112
	ds_bpermute_b32 v117, v124, v113
	ds_bpermute_b32 v118, v124, v114
	ds_bpermute_b32 v119, v124, v115
	s_waitcnt lgkmcnt(0)
	v_add_f32_e32 v112, v112, v116
	v_add_f32_e32 v113, v113, v117
	v_add_f32_e32 v114, v114, v118
	v_add_f32_e32 v115, v115, v119
	ds_bpermute_b32 v116, v125, v112
	ds_bpermute_b32 v117, v125, v113
	ds_bpermute_b32 v118, v125, v114
	ds_bpermute_b32 v119, v125, v115
	s_waitcnt lgkmcnt(0)
	v_add_f32_e32 v112, v112, v116
	v_add_f32_e32 v113, v113, v117
	v_add_f32_e32 v114, v114, v118
	v_add_f32_e32 v115, v115, v119
	ds_bpermute_b32 v116, v126, v112
	ds_bpermute_b32 v117, v126, v113
	ds_bpermute_b32 v118, v126, v114
	ds_bpermute_b32 v119, v126, v115
	s_waitcnt lgkmcnt(0)
	v_add_f32_e32 v112, v112, v116
	v_add_f32_e32 v113, v113, v117
	v_add_f32_e32 v114, v114, v118
	v_add_f32_e32 v115, v115, v119
	ds_bpermute_b32 v116, v127, v112
	ds_bpermute_b32 v117, v127, v113
	ds_bpermute_b32 v118, v127, v114
	ds_bpermute_b32 v119, v127, v115
	s_waitcnt lgkmcnt(0)
	v_add_f32_e32 v112, v112, v116
	v_add_f32_e32 v113, v113, v117
	v_add_f32_e32 v114, v114, v118
	v_add_f32_e32 v115, v115, v119
	v_fmamk_f32 v112, v112, 0x3a800000, v208
	v_fmamk_f32 v113, v113, 0x3a800000, v208
	v_fmamk_f32 v114, v114, 0x3a800000, v208
	v_fmamk_f32 v115, v115, 0x3a800000, v208
	v_rsq_f32_e32 v112, v112
	v_rsq_f32_e32 v113, v113
	v_rsq_f32_e32 v114, v114
	v_rsq_f32_e32 v115, v115
	s_nop 1
	v_mul_f32_e32 v48, v48, v112
	v_mul_f32_e32 v49, v49, v112
	v_mul_f32_e32 v50, v50, v112
	v_mul_f32_e32 v51, v51, v112
	v_mul_f32_e32 v48, v0, v48
	v_mul_f32_e32 v49, v1, v49
	v_mul_f32_e32 v50, v2, v50
	v_mul_f32_e32 v51, v3, v51
	global_store_dwordx4 v120, v[48:51], s[6:7] offset:0
	v_mul_f32_e32 v52, v52, v112
	v_mul_f32_e32 v53, v53, v112
	v_mul_f32_e32 v54, v54, v112
	v_mul_f32_e32 v55, v55, v112
	v_mul_f32_e32 v52, v4, v52
	v_mul_f32_e32 v53, v5, v53
	v_mul_f32_e32 v54, v6, v54
	v_mul_f32_e32 v55, v7, v55
	global_store_dwordx4 v120, v[52:55], s[6:7] offset:1024
	v_mul_f32_e32 v56, v56, v112
	v_mul_f32_e32 v57, v57, v112
	v_mul_f32_e32 v58, v58, v112
	v_mul_f32_e32 v59, v59, v112
	v_mul_f32_e32 v56, v8, v56
	v_mul_f32_e32 v57, v9, v57
	v_mul_f32_e32 v58, v10, v58
	v_mul_f32_e32 v59, v11, v59
	global_store_dwordx4 v120, v[56:59], s[6:7] offset:2048
	v_mul_f32_e32 v60, v60, v112
	v_mul_f32_e32 v61, v61, v112
	v_mul_f32_e32 v62, v62, v112
	v_mul_f32_e32 v63, v63, v112
	v_mul_f32_e32 v60, v12, v60
	v_mul_f32_e32 v61, v13, v61
	v_mul_f32_e32 v62, v14, v62
	v_mul_f32_e32 v63, v15, v63
	global_store_dwordx4 v120, v[60:63], s[6:7] offset:3072
	s_add_u32 s6, s6, 0x40000
	s_addc_u32 s7, s7, 0
	v_mul_f32_e32 v64, v64, v113
	v_mul_f32_e32 v65, v65, v113
	v_mul_f32_e32 v66, v66, v113
	v_mul_f32_e32 v67, v67, v113
	v_mul_f32_e32 v64, v0, v64
	v_mul_f32_e32 v65, v1, v65
	v_mul_f32_e32 v66, v2, v66
	v_mul_f32_e32 v67, v3, v67
	global_store_dwordx4 v120, v[64:67], s[6:7] offset:0
	v_mul_f32_e32 v68, v68, v113
	v_mul_f32_e32 v69, v69, v113
	v_mul_f32_e32 v70, v70, v113
	v_mul_f32_e32 v71, v71, v113
	v_mul_f32_e32 v68, v4, v68
	v_mul_f32_e32 v69, v5, v69
	v_mul_f32_e32 v70, v6, v70
	v_mul_f32_e32 v71, v7, v71
	global_store_dwordx4 v120, v[68:71], s[6:7] offset:1024
	v_mul_f32_e32 v72, v72, v113
	v_mul_f32_e32 v73, v73, v113
	v_mul_f32_e32 v74, v74, v113
	v_mul_f32_e32 v75, v75, v113
	v_mul_f32_e32 v72, v8, v72
	v_mul_f32_e32 v73, v9, v73
	v_mul_f32_e32 v74, v10, v74
	v_mul_f32_e32 v75, v11, v75
	global_store_dwordx4 v120, v[72:75], s[6:7] offset:2048
	v_mul_f32_e32 v76, v76, v113
	v_mul_f32_e32 v77, v77, v113
	v_mul_f32_e32 v78, v78, v113
	v_mul_f32_e32 v79, v79, v113
	v_mul_f32_e32 v76, v12, v76
	v_mul_f32_e32 v77, v13, v77
	v_mul_f32_e32 v78, v14, v78
	v_mul_f32_e32 v79, v15, v79
	global_store_dwordx4 v120, v[76:79], s[6:7] offset:3072
	s_add_u32 s6, s6, 0x40000
	s_addc_u32 s7, s7, 0
	v_mul_f32_e32 v80, v80, v114
	v_mul_f32_e32 v81, v81, v114
	v_mul_f32_e32 v82, v82, v114
	v_mul_f32_e32 v83, v83, v114
	v_mul_f32_e32 v80, v0, v80
	v_mul_f32_e32 v81, v1, v81
	v_mul_f32_e32 v82, v2, v82
	v_mul_f32_e32 v83, v3, v83
	global_store_dwordx4 v120, v[80:83], s[6:7] offset:0
	v_mul_f32_e32 v84, v84, v114
	v_mul_f32_e32 v85, v85, v114
	v_mul_f32_e32 v86, v86, v114
	v_mul_f32_e32 v87, v87, v114
	v_mul_f32_e32 v84, v4, v84
	v_mul_f32_e32 v85, v5, v85
	v_mul_f32_e32 v86, v6, v86
	v_mul_f32_e32 v87, v7, v87
	global_store_dwordx4 v120, v[84:87], s[6:7] offset:1024
	v_mul_f32_e32 v88, v88, v114
	v_mul_f32_e32 v89, v89, v114
	v_mul_f32_e32 v90, v90, v114
	v_mul_f32_e32 v91, v91, v114
	v_mul_f32_e32 v88, v8, v88
	v_mul_f32_e32 v89, v9, v89
	v_mul_f32_e32 v90, v10, v90
	v_mul_f32_e32 v91, v11, v91
	global_store_dwordx4 v120, v[88:91], s[6:7] offset:2048
	v_mul_f32_e32 v92, v92, v114
	v_mul_f32_e32 v93, v93, v114
	v_mul_f32_e32 v94, v94, v114
	v_mul_f32_e32 v95, v95, v114
	v_mul_f32_e32 v92, v12, v92
	v_mul_f32_e32 v93, v13, v93
	v_mul_f32_e32 v94, v14, v94
	v_mul_f32_e32 v95, v15, v95
	global_store_dwordx4 v120, v[92:95], s[6:7] offset:3072
	s_add_u32 s6, s6, 0x40000
	s_addc_u32 s7, s7, 0
	v_mul_f32_e32 v96, v96, v115
	v_mul_f32_e32 v97, v97, v115
	v_mul_f32_e32 v98, v98, v115
	v_mul_f32_e32 v99, v99, v115
	v_mul_f32_e32 v96, v0, v96
	v_mul_f32_e32 v97, v1, v97
	v_mul_f32_e32 v98, v2, v98
	v_mul_f32_e32 v99, v3, v99
	global_store_dwordx4 v120, v[96:99], s[6:7] offset:0
	v_mul_f32_e32 v100, v100, v115
	v_mul_f32_e32 v101, v101, v115
	v_mul_f32_e32 v102, v102, v115
	v_mul_f32_e32 v103, v103, v115
	v_mul_f32_e32 v100, v4, v100
	v_mul_f32_e32 v101, v5, v101
	v_mul_f32_e32 v102, v6, v102
	v_mul_f32_e32 v103, v7, v103
	global_store_dwordx4 v120, v[100:103], s[6:7] offset:1024
	v_mul_f32_e32 v104, v104, v115
	v_mul_f32_e32 v105, v105, v115
	v_mul_f32_e32 v106, v106, v115
	v_mul_f32_e32 v107, v107, v115
	v_mul_f32_e32 v104, v8, v104
	v_mul_f32_e32 v105, v9, v105
	v_mul_f32_e32 v106, v10, v106
	v_mul_f32_e32 v107, v11, v107
	global_store_dwordx4 v120, v[104:107], s[6:7] offset:2048
	v_mul_f32_e32 v108, v108, v115
	v_mul_f32_e32 v109, v109, v115
	v_mul_f32_e32 v110, v110, v115
	v_mul_f32_e32 v111, v111, v115
	v_mul_f32_e32 v108, v12, v108
	v_mul_f32_e32 v109, v13, v109
	v_mul_f32_e32 v110, v14, v110
	v_mul_f32_e32 v111, v15, v111
	global_store_dwordx4 v120, v[108:111], s[6:7] offset:3072
	s_add_u32 s6, s6, 0x40000
	s_addc_u32 s7, s7, 0
.Lrms_final_loop:
	global_load_dwordx4 v[48:51], v120, s[8:9] offset:0
	global_load_dwordx4 v[52:55], v120, s[8:9] offset:1024
	global_load_dwordx4 v[56:59], v120, s[8:9] offset:2048
	global_load_dwordx4 v[60:63], v120, s[8:9] offset:3072
	s_add_u32 s8, s8, 0x40000
	s_addc_u32 s9, s9, 0
	global_load_dwordx4 v[64:67], v120, s[8:9] offset:0
	global_load_dwordx4 v[68:71], v120, s[8:9] offset:1024
	global_load_dwordx4 v[72:75], v120, s[8:9] offset:2048
	global_load_dwordx4 v[76:79], v120, s[8:9] offset:3072
	s_add_u32 s8, s8, 0x40000
	s_addc_u32 s9, s9, 0
	global_load_dwordx4 v[80:83], v120, s[8:9] offset:0
	global_load_dwordx4 v[84:87], v120, s[8:9] offset:1024
	global_load_dwordx4 v[88:91], v120, s[8:9] offset:2048
	global_load_dwordx4 v[92:95], v120, s[8:9] offset:3072
	s_add_u32 s8, s8, 0x40000
	s_addc_u32 s9, s9, 0
	global_load_dwordx4 v[96:99], v120, s[8:9] offset:0
	global_load_dwordx4 v[100:103], v120, s[8:9] offset:1024
	global_load_dwordx4 v[104:107], v120, s[8:9] offset:2048
	global_load_dwordx4 v[108:111], v120, s[8:9] offset:3072
	s_add_u32 s8, s8, 0x40000
	s_addc_u32 s9, s9, 0
	s_waitcnt vmcnt(44)
	v_mul_f32_e32 v112, v132, v132
	v_fmac_f32_e32 v112, v133, v133
	v_fmac_f32_e32 v112, v134, v134
	v_fmac_f32_e32 v112, v135, v135
	v_fmac_f32_e32 v112, v136, v136
	v_fmac_f32_e32 v112, v137, v137
	v_fmac_f32_e32 v112, v138, v138
	v_fmac_f32_e32 v112, v139, v139
	v_fmac_f32_e32 v112, v140, v140
	v_fmac_f32_e32 v112, v141, v141
	v_fmac_f32_e32 v112, v142, v142
	v_fmac_f32_e32 v112, v143, v143
	v_fmac_f32_e32 v112, v144, v144
	v_fmac_f32_e32 v112, v145, v145
	v_fmac_f32_e32 v112, v146, v146
	v_fmac_f32_e32 v112, v147, v147
	s_waitcnt vmcnt(40)
	v_mul_f32_e32 v113, v166, v166
	v_fmac_f32_e32 v113, v167, v167
	v_fmac_f32_e32 v113, v168, v168
	v_fmac_f32_e32 v113, v169, v169
	v_fmac_f32_e32 v113, v170, v170
	v_fmac_f32_e32 v113, v171, v171
	v_fmac_f32_e32 v113, v172, v172
	v_fmac_f32_e32 v113, v173, v173
	v_fmac_f32_e32 v113, v174, v174
	v_fmac_f32_e32 v113, v175, v175
	v_fmac_f32_e32 v113, v176, v176
	v_fmac_f32_e32 v113, v177, v177
	v_fmac_f32_e32 v113, v178, v178
	v_fmac_f32_e32 v113, v179, v179
	v_fmac_f32_e32 v113, v180, v180
	v_fmac_f32_e32 v113, v181, v181
	s_waitcnt vmcnt(36)
	v_mul_f32_e32 v114, v182, v182
	v_fmac_f32_e32 v114, v183, v183
	v_fmac_f32_e32 v114, v184, v184
	v_fmac_f32_e32 v114, v185, v185
	v_fmac_f32_e32 v114, v186, v186
	v_fmac_f32_e32 v114, v187, v187
	v_fmac_f32_e32 v114, v188, v188
	v_fmac_f32_e32 v114, v189, v189
	v_fmac_f32_e32 v114, v190, v190
	v_fmac_f32_e32 v114, v191, v191
	v_fmac_f32_e32 v114, v192, v192
	v_fmac_f32_e32 v114, v193, v193
	v_fmac_f32_e32 v114, v194, v194
	v_fmac_f32_e32 v114, v195, v195
	v_fmac_f32_e32 v114, v196, v196
	v_fmac_f32_e32 v114, v197, v197
	s_waitcnt vmcnt(32)
	v_mul_f32_e32 v115, v228, v228
	v_fmac_f32_e32 v115, v229, v229
	v_fmac_f32_e32 v115, v230, v230
	v_fmac_f32_e32 v115, v231, v231
	v_fmac_f32_e32 v115, v232, v232
	v_fmac_f32_e32 v115, v233, v233
	v_fmac_f32_e32 v115, v234, v234
	v_fmac_f32_e32 v115, v235, v235
	v_fmac_f32_e32 v115, v236, v236
	v_fmac_f32_e32 v115, v237, v237
	v_fmac_f32_e32 v115, v238, v238
	v_fmac_f32_e32 v115, v239, v239
	v_fmac_f32_e32 v115, v240, v240
	v_fmac_f32_e32 v115, v241, v241
	v_fmac_f32_e32 v115, v242, v242
	v_fmac_f32_e32 v115, v243, v243
	ds_bpermute_b32 v116, v122, v112
	ds_bpermute_b32 v117, v122, v113
	ds_bpermute_b32 v118, v122, v114
	ds_bpermute_b32 v119, v122, v115
	s_waitcnt lgkmcnt(0)
	v_add_f32_e32 v112, v112, v116
	v_add_f32_e32 v113, v113, v117
	v_add_f32_e32 v114, v114, v118
	v_add_f32_e32 v115, v115, v119
	ds_bpermute_b32 v116, v123, v112
	ds_bpermute_b32 v117, v123, v113
	ds_bpermute_b32 v118, v123, v114
	ds_bpermute_b32 v119, v123, v115
	s_waitcnt lgkmcnt(0)
	v_add_f32_e32 v112, v112, v116
	v_add_f32_e32 v113, v113, v117
	v_add_f32_e32 v114, v114, v118
	v_add_f32_e32 v115, v115, v119
	ds_bpermute_b32 v116, v124, v112
	ds_bpermute_b32 v117, v124, v113
	ds_bpermute_b32 v118, v124, v114
	ds_bpermute_b32 v119, v124, v115
	s_waitcnt lgkmcnt(0)
	v_add_f32_e32 v112, v112, v116
	v_add_f32_e32 v113, v113, v117
	v_add_f32_e32 v114, v114, v118
	v_add_f32_e32 v115, v115, v119
	ds_bpermute_b32 v116, v125, v112
	ds_bpermute_b32 v117, v125, v113
	ds_bpermute_b32 v118, v125, v114
	ds_bpermute_b32 v119, v125, v115
	s_waitcnt lgkmcnt(0)
	v_add_f32_e32 v112, v112, v116
	v_add_f32_e32 v113, v113, v117
	v_add_f32_e32 v114, v114, v118
	v_add_f32_e32 v115, v115, v119
	ds_bpermute_b32 v116, v126, v112
	ds_bpermute_b32 v117, v126, v113
	ds_bpermute_b32 v118, v126, v114
	ds_bpermute_b32 v119, v126, v115
	s_waitcnt lgkmcnt(0)
	v_add_f32_e32 v112, v112, v116
	v_add_f32_e32 v113, v113, v117
	v_add_f32_e32 v114, v114, v118
	v_add_f32_e32 v115, v115, v119
	ds_bpermute_b32 v116, v127, v112
	ds_bpermute_b32 v117, v127, v113
	ds_bpermute_b32 v118, v127, v114
	ds_bpermute_b32 v119, v127, v115
	s_waitcnt lgkmcnt(0)
	v_add_f32_e32 v112, v112, v116
	v_add_f32_e32 v113, v113, v117
	v_add_f32_e32 v114, v114, v118
	v_add_f32_e32 v115, v115, v119
	v_fmamk_f32 v112, v112, 0x3a800000, v208
	v_fmamk_f32 v113, v113, 0x3a800000, v208
	v_fmamk_f32 v114, v114, 0x3a800000, v208
	v_fmamk_f32 v115, v115, 0x3a800000, v208
	v_rsq_f32_e32 v112, v112
	v_rsq_f32_e32 v113, v113
	v_rsq_f32_e32 v114, v114
	v_rsq_f32_e32 v115, v115
	s_nop 1
	v_mul_f32_e32 v132, v132, v112
	v_mul_f32_e32 v133, v133, v112
	v_mul_f32_e32 v134, v134, v112
	v_mul_f32_e32 v135, v135, v112
	v_mul_f32_e32 v132, v0, v132
	v_mul_f32_e32 v133, v1, v133
	v_mul_f32_e32 v134, v2, v134
	v_mul_f32_e32 v135, v3, v135
	global_store_dwordx4 v120, v[132:135], s[6:7] offset:0
	v_mul_f32_e32 v136, v136, v112
	v_mul_f32_e32 v137, v137, v112
	v_mul_f32_e32 v138, v138, v112
	v_mul_f32_e32 v139, v139, v112
	v_mul_f32_e32 v136, v4, v136
	v_mul_f32_e32 v137, v5, v137
	v_mul_f32_e32 v138, v6, v138
	v_mul_f32_e32 v139, v7, v139
	global_store_dwordx4 v120, v[136:139], s[6:7] offset:1024
	v_mul_f32_e32 v140, v140, v112
	v_mul_f32_e32 v141, v141, v112
	v_mul_f32_e32 v142, v142, v112
	v_mul_f32_e32 v143, v143, v112
	v_mul_f32_e32 v140, v8, v140
	v_mul_f32_e32 v141, v9, v141
	v_mul_f32_e32 v142, v10, v142
	v_mul_f32_e32 v143, v11, v143
	global_store_dwordx4 v120, v[140:143], s[6:7] offset:2048
	v_mul_f32_e32 v144, v144, v112
	v_mul_f32_e32 v145, v145, v112
	v_mul_f32_e32 v146, v146, v112
	v_mul_f32_e32 v147, v147, v112
	v_mul_f32_e32 v144, v12, v144
	v_mul_f32_e32 v145, v13, v145
	v_mul_f32_e32 v146, v14, v146
	v_mul_f32_e32 v147, v15, v147
	global_store_dwordx4 v120, v[144:147], s[6:7] offset:3072
	s_add_u32 s6, s6, 0x40000
	s_addc_u32 s7, s7, 0
	v_mul_f32_e32 v166, v166, v113
	v_mul_f32_e32 v167, v167, v113
	v_mul_f32_e32 v168, v168, v113
	v_mul_f32_e32 v169, v169, v113
	v_mul_f32_e32 v166, v0, v166
	v_mul_f32_e32 v167, v1, v167
	v_mul_f32_e32 v168, v2, v168
	v_mul_f32_e32 v169, v3, v169
	global_store_dwordx4 v120, v[166:169], s[6:7] offset:0
	v_mul_f32_e32 v170, v170, v113
	v_mul_f32_e32 v171, v171, v113
	v_mul_f32_e32 v172, v172, v113
	v_mul_f32_e32 v173, v173, v113
	v_mul_f32_e32 v170, v4, v170
	v_mul_f32_e32 v171, v5, v171
	v_mul_f32_e32 v172, v6, v172
	v_mul_f32_e32 v173, v7, v173
	global_store_dwordx4 v120, v[170:173], s[6:7] offset:1024
	v_mul_f32_e32 v174, v174, v113
	v_mul_f32_e32 v175, v175, v113
	v_mul_f32_e32 v176, v176, v113
	v_mul_f32_e32 v177, v177, v113
	v_mul_f32_e32 v174, v8, v174
	v_mul_f32_e32 v175, v9, v175
	v_mul_f32_e32 v176, v10, v176
	v_mul_f32_e32 v177, v11, v177
	global_store_dwordx4 v120, v[174:177], s[6:7] offset:2048
	v_mul_f32_e32 v178, v178, v113
	v_mul_f32_e32 v179, v179, v113
	v_mul_f32_e32 v180, v180, v113
	v_mul_f32_e32 v181, v181, v113
	v_mul_f32_e32 v178, v12, v178
	v_mul_f32_e32 v179, v13, v179
	v_mul_f32_e32 v180, v14, v180
	v_mul_f32_e32 v181, v15, v181
	global_store_dwordx4 v120, v[178:181], s[6:7] offset:3072
	s_add_u32 s6, s6, 0x40000
	s_addc_u32 s7, s7, 0
	v_mul_f32_e32 v182, v182, v114
	v_mul_f32_e32 v183, v183, v114
	v_mul_f32_e32 v184, v184, v114
	v_mul_f32_e32 v185, v185, v114
	v_mul_f32_e32 v182, v0, v182
	v_mul_f32_e32 v183, v1, v183
	v_mul_f32_e32 v184, v2, v184
	v_mul_f32_e32 v185, v3, v185
	global_store_dwordx4 v120, v[182:185], s[6:7] offset:0
	v_mul_f32_e32 v186, v186, v114
	v_mul_f32_e32 v187, v187, v114
	v_mul_f32_e32 v188, v188, v114
	v_mul_f32_e32 v189, v189, v114
	v_mul_f32_e32 v186, v4, v186
	v_mul_f32_e32 v187, v5, v187
	v_mul_f32_e32 v188, v6, v188
	v_mul_f32_e32 v189, v7, v189
	global_store_dwordx4 v120, v[186:189], s[6:7] offset:1024
	v_mul_f32_e32 v190, v190, v114
	v_mul_f32_e32 v191, v191, v114
	v_mul_f32_e32 v192, v192, v114
	v_mul_f32_e32 v193, v193, v114
	v_mul_f32_e32 v190, v8, v190
	v_mul_f32_e32 v191, v9, v191
	v_mul_f32_e32 v192, v10, v192
	v_mul_f32_e32 v193, v11, v193
	global_store_dwordx4 v120, v[190:193], s[6:7] offset:2048
	v_mul_f32_e32 v194, v194, v114
	v_mul_f32_e32 v195, v195, v114
	v_mul_f32_e32 v196, v196, v114
	v_mul_f32_e32 v197, v197, v114
	v_mul_f32_e32 v194, v12, v194
	v_mul_f32_e32 v195, v13, v195
	v_mul_f32_e32 v196, v14, v196
	v_mul_f32_e32 v197, v15, v197
	global_store_dwordx4 v120, v[194:197], s[6:7] offset:3072
	s_add_u32 s6, s6, 0x40000
	s_addc_u32 s7, s7, 0
	v_mul_f32_e32 v228, v228, v115
	v_mul_f32_e32 v229, v229, v115
	v_mul_f32_e32 v230, v230, v115
	v_mul_f32_e32 v231, v231, v115
	v_mul_f32_e32 v228, v0, v228
	v_mul_f32_e32 v229, v1, v229
	v_mul_f32_e32 v230, v2, v230
	v_mul_f32_e32 v231, v3, v231
	global_store_dwordx4 v120, v[228:231], s[6:7] offset:0
	v_mul_f32_e32 v232, v232, v115
	v_mul_f32_e32 v233, v233, v115
	v_mul_f32_e32 v234, v234, v115
	v_mul_f32_e32 v235, v235, v115
	v_mul_f32_e32 v232, v4, v232
	v_mul_f32_e32 v233, v5, v233
	v_mul_f32_e32 v234, v6, v234
	v_mul_f32_e32 v235, v7, v235
	global_store_dwordx4 v120, v[232:235], s[6:7] offset:1024
	v_mul_f32_e32 v236, v236, v115
	v_mul_f32_e32 v237, v237, v115
	v_mul_f32_e32 v238, v238, v115
	v_mul_f32_e32 v239, v239, v115
	v_mul_f32_e32 v236, v8, v236
	v_mul_f32_e32 v237, v9, v237
	v_mul_f32_e32 v238, v10, v238
	v_mul_f32_e32 v239, v11, v239
	global_store_dwordx4 v120, v[236:239], s[6:7] offset:2048
	v_mul_f32_e32 v240, v240, v115
	v_mul_f32_e32 v241, v241, v115
	v_mul_f32_e32 v242, v242, v115
	v_mul_f32_e32 v243, v243, v115
	v_mul_f32_e32 v240, v12, v240
	v_mul_f32_e32 v241, v13, v241
	v_mul_f32_e32 v242, v14, v242
	v_mul_f32_e32 v243, v15, v243
	global_store_dwordx4 v120, v[240:243], s[6:7] offset:3072
	s_add_u32 s6, s6, 0x40000
	s_addc_u32 s7, s7, 0
	global_load_dwordx4 v[132:135], v120, s[8:9] offset:0
	global_load_dwordx4 v[136:139], v120, s[8:9] offset:1024
	global_load_dwordx4 v[140:143], v120, s[8:9] offset:2048
	global_load_dwordx4 v[144:147], v120, s[8:9] offset:3072
	s_add_u32 s8, s8, 0x40000
	s_addc_u32 s9, s9, 0
	global_load_dwordx4 v[166:169], v120, s[8:9] offset:0
	global_load_dwordx4 v[170:173], v120, s[8:9] offset:1024
	global_load_dwordx4 v[174:177], v120, s[8:9] offset:2048
	global_load_dwordx4 v[178:181], v120, s[8:9] offset:3072
	s_add_u32 s8, s8, 0x40000
	s_addc_u32 s9, s9, 0
	global_load_dwordx4 v[182:185], v120, s[8:9] offset:0
	global_load_dwordx4 v[186:189], v120, s[8:9] offset:1024
	global_load_dwordx4 v[190:193], v120, s[8:9] offset:2048
	global_load_dwordx4 v[194:197], v120, s[8:9] offset:3072
	s_add_u32 s8, s8, 0x40000
	s_addc_u32 s9, s9, 0
	global_load_dwordx4 v[228:231], v120, s[8:9] offset:0
	global_load_dwordx4 v[232:235], v120, s[8:9] offset:1024
	global_load_dwordx4 v[236:239], v120, s[8:9] offset:2048
	global_load_dwordx4 v[240:243], v120, s[8:9] offset:3072
	s_add_u32 s8, s8, 0x40000
	s_addc_u32 s9, s9, 0
	s_waitcnt vmcnt(44)
	v_mul_f32_e32 v112, v48, v48
	v_fmac_f32_e32 v112, v49, v49
	v_fmac_f32_e32 v112, v50, v50
	v_fmac_f32_e32 v112, v51, v51
	v_fmac_f32_e32 v112, v52, v52
	v_fmac_f32_e32 v112, v53, v53
	v_fmac_f32_e32 v112, v54, v54
	v_fmac_f32_e32 v112, v55, v55
	v_fmac_f32_e32 v112, v56, v56
	v_fmac_f32_e32 v112, v57, v57
	v_fmac_f32_e32 v112, v58, v58
	v_fmac_f32_e32 v112, v59, v59
	v_fmac_f32_e32 v112, v60, v60
	v_fmac_f32_e32 v112, v61, v61
	v_fmac_f32_e32 v112, v62, v62
	v_fmac_f32_e32 v112, v63, v63
	s_waitcnt vmcnt(40)
	v_mul_f32_e32 v113, v64, v64
	v_fmac_f32_e32 v113, v65, v65
	v_fmac_f32_e32 v113, v66, v66
	v_fmac_f32_e32 v113, v67, v67
	v_fmac_f32_e32 v113, v68, v68
	v_fmac_f32_e32 v113, v69, v69
	v_fmac_f32_e32 v113, v70, v70
	v_fmac_f32_e32 v113, v71, v71
	v_fmac_f32_e32 v113, v72, v72
	v_fmac_f32_e32 v113, v73, v73
	v_fmac_f32_e32 v113, v74, v74
	v_fmac_f32_e32 v113, v75, v75
	v_fmac_f32_e32 v113, v76, v76
	v_fmac_f32_e32 v113, v77, v77
	v_fmac_f32_e32 v113, v78, v78
	v_fmac_f32_e32 v113, v79, v79
	s_waitcnt vmcnt(36)
	v_mul_f32_e32 v114, v80, v80
	v_fmac_f32_e32 v114, v81, v81
	v_fmac_f32_e32 v114, v82, v82
	v_fmac_f32_e32 v114, v83, v83
	v_fmac_f32_e32 v114, v84, v84
	v_fmac_f32_e32 v114, v85, v85
	v_fmac_f32_e32 v114, v86, v86
	v_fmac_f32_e32 v114, v87, v87
	v_fmac_f32_e32 v114, v88, v88
	v_fmac_f32_e32 v114, v89, v89
	v_fmac_f32_e32 v114, v90, v90
	v_fmac_f32_e32 v114, v91, v91
	v_fmac_f32_e32 v114, v92, v92
	v_fmac_f32_e32 v114, v93, v93
	v_fmac_f32_e32 v114, v94, v94
	v_fmac_f32_e32 v114, v95, v95
	s_waitcnt vmcnt(32)
	v_mul_f32_e32 v115, v96, v96
	v_fmac_f32_e32 v115, v97, v97
	v_fmac_f32_e32 v115, v98, v98
	v_fmac_f32_e32 v115, v99, v99
	v_fmac_f32_e32 v115, v100, v100
	v_fmac_f32_e32 v115, v101, v101
	v_fmac_f32_e32 v115, v102, v102
	v_fmac_f32_e32 v115, v103, v103
	v_fmac_f32_e32 v115, v104, v104
	v_fmac_f32_e32 v115, v105, v105
	v_fmac_f32_e32 v115, v106, v106
	v_fmac_f32_e32 v115, v107, v107
	v_fmac_f32_e32 v115, v108, v108
	v_fmac_f32_e32 v115, v109, v109
	v_fmac_f32_e32 v115, v110, v110
	v_fmac_f32_e32 v115, v111, v111
	ds_bpermute_b32 v116, v122, v112
	ds_bpermute_b32 v117, v122, v113
	ds_bpermute_b32 v118, v122, v114
	ds_bpermute_b32 v119, v122, v115
	s_waitcnt lgkmcnt(0)
	v_add_f32_e32 v112, v112, v116
	v_add_f32_e32 v113, v113, v117
	v_add_f32_e32 v114, v114, v118
	v_add_f32_e32 v115, v115, v119
	ds_bpermute_b32 v116, v123, v112
	ds_bpermute_b32 v117, v123, v113
	ds_bpermute_b32 v118, v123, v114
	ds_bpermute_b32 v119, v123, v115
	s_waitcnt lgkmcnt(0)
	v_add_f32_e32 v112, v112, v116
	v_add_f32_e32 v113, v113, v117
	v_add_f32_e32 v114, v114, v118
	v_add_f32_e32 v115, v115, v119
	ds_bpermute_b32 v116, v124, v112
	ds_bpermute_b32 v117, v124, v113
	ds_bpermute_b32 v118, v124, v114
	ds_bpermute_b32 v119, v124, v115
	s_waitcnt lgkmcnt(0)
	v_add_f32_e32 v112, v112, v116
	v_add_f32_e32 v113, v113, v117
	v_add_f32_e32 v114, v114, v118
	v_add_f32_e32 v115, v115, v119
	ds_bpermute_b32 v116, v125, v112
	ds_bpermute_b32 v117, v125, v113
	ds_bpermute_b32 v118, v125, v114
	ds_bpermute_b32 v119, v125, v115
	s_waitcnt lgkmcnt(0)
	v_add_f32_e32 v112, v112, v116
	v_add_f32_e32 v113, v113, v117
	v_add_f32_e32 v114, v114, v118
	v_add_f32_e32 v115, v115, v119
	ds_bpermute_b32 v116, v126, v112
	ds_bpermute_b32 v117, v126, v113
	ds_bpermute_b32 v118, v126, v114
	ds_bpermute_b32 v119, v126, v115
	s_waitcnt lgkmcnt(0)
	v_add_f32_e32 v112, v112, v116
	v_add_f32_e32 v113, v113, v117
	v_add_f32_e32 v114, v114, v118
	v_add_f32_e32 v115, v115, v119
	ds_bpermute_b32 v116, v127, v112
	ds_bpermute_b32 v117, v127, v113
	ds_bpermute_b32 v118, v127, v114
	ds_bpermute_b32 v119, v127, v115
	s_waitcnt lgkmcnt(0)
	v_add_f32_e32 v112, v112, v116
	v_add_f32_e32 v113, v113, v117
	v_add_f32_e32 v114, v114, v118
	v_add_f32_e32 v115, v115, v119
	v_fmamk_f32 v112, v112, 0x3a800000, v208
	v_fmamk_f32 v113, v113, 0x3a800000, v208
	v_fmamk_f32 v114, v114, 0x3a800000, v208
	v_fmamk_f32 v115, v115, 0x3a800000, v208
	v_rsq_f32_e32 v112, v112
	v_rsq_f32_e32 v113, v113
	v_rsq_f32_e32 v114, v114
	v_rsq_f32_e32 v115, v115
	s_nop 1
	v_mul_f32_e32 v48, v48, v112
	v_mul_f32_e32 v49, v49, v112
	v_mul_f32_e32 v50, v50, v112
	v_mul_f32_e32 v51, v51, v112
	v_mul_f32_e32 v48, v0, v48
	v_mul_f32_e32 v49, v1, v49
	v_mul_f32_e32 v50, v2, v50
	v_mul_f32_e32 v51, v3, v51
	global_store_dwordx4 v120, v[48:51], s[6:7] offset:0
	v_mul_f32_e32 v52, v52, v112
	v_mul_f32_e32 v53, v53, v112
	v_mul_f32_e32 v54, v54, v112
	v_mul_f32_e32 v55, v55, v112
	v_mul_f32_e32 v52, v4, v52
	v_mul_f32_e32 v53, v5, v53
	v_mul_f32_e32 v54, v6, v54
	v_mul_f32_e32 v55, v7, v55
	global_store_dwordx4 v120, v[52:55], s[6:7] offset:1024
	v_mul_f32_e32 v56, v56, v112
	v_mul_f32_e32 v57, v57, v112
	v_mul_f32_e32 v58, v58, v112
	v_mul_f32_e32 v59, v59, v112
	v_mul_f32_e32 v56, v8, v56
	v_mul_f32_e32 v57, v9, v57
	v_mul_f32_e32 v58, v10, v58
	v_mul_f32_e32 v59, v11, v59
	global_store_dwordx4 v120, v[56:59], s[6:7] offset:2048
	v_mul_f32_e32 v60, v60, v112
	v_mul_f32_e32 v61, v61, v112
	v_mul_f32_e32 v62, v62, v112
	v_mul_f32_e32 v63, v63, v112
	v_mul_f32_e32 v60, v12, v60
	v_mul_f32_e32 v61, v13, v61
	v_mul_f32_e32 v62, v14, v62
	v_mul_f32_e32 v63, v15, v63
	global_store_dwordx4 v120, v[60:63], s[6:7] offset:3072
	s_add_u32 s6, s6, 0x40000
	s_addc_u32 s7, s7, 0
	v_mul_f32_e32 v64, v64, v113
	v_mul_f32_e32 v65, v65, v113
	v_mul_f32_e32 v66, v66, v113
	v_mul_f32_e32 v67, v67, v113
	v_mul_f32_e32 v64, v0, v64
	v_mul_f32_e32 v65, v1, v65
	v_mul_f32_e32 v66, v2, v66
	v_mul_f32_e32 v67, v3, v67
	global_store_dwordx4 v120, v[64:67], s[6:7] offset:0
	v_mul_f32_e32 v68, v68, v113
	v_mul_f32_e32 v69, v69, v113
	v_mul_f32_e32 v70, v70, v113
	v_mul_f32_e32 v71, v71, v113
	v_mul_f32_e32 v68, v4, v68
	v_mul_f32_e32 v69, v5, v69
	v_mul_f32_e32 v70, v6, v70
	v_mul_f32_e32 v71, v7, v71
	global_store_dwordx4 v120, v[68:71], s[6:7] offset:1024
	v_mul_f32_e32 v72, v72, v113
	v_mul_f32_e32 v73, v73, v113
	v_mul_f32_e32 v74, v74, v113
	v_mul_f32_e32 v75, v75, v113
	v_mul_f32_e32 v72, v8, v72
	v_mul_f32_e32 v73, v9, v73
	v_mul_f32_e32 v74, v10, v74
	v_mul_f32_e32 v75, v11, v75
	global_store_dwordx4 v120, v[72:75], s[6:7] offset:2048
	v_mul_f32_e32 v76, v76, v113
	v_mul_f32_e32 v77, v77, v113
	v_mul_f32_e32 v78, v78, v113
	v_mul_f32_e32 v79, v79, v113
	v_mul_f32_e32 v76, v12, v76
	v_mul_f32_e32 v77, v13, v77
	v_mul_f32_e32 v78, v14, v78
	v_mul_f32_e32 v79, v15, v79
	global_store_dwordx4 v120, v[76:79], s[6:7] offset:3072
	s_add_u32 s6, s6, 0x40000
	s_addc_u32 s7, s7, 0
	v_mul_f32_e32 v80, v80, v114
	v_mul_f32_e32 v81, v81, v114
	v_mul_f32_e32 v82, v82, v114
	v_mul_f32_e32 v83, v83, v114
	v_mul_f32_e32 v80, v0, v80
	v_mul_f32_e32 v81, v1, v81
	v_mul_f32_e32 v82, v2, v82
	v_mul_f32_e32 v83, v3, v83
	global_store_dwordx4 v120, v[80:83], s[6:7] offset:0
	v_mul_f32_e32 v84, v84, v114
	v_mul_f32_e32 v85, v85, v114
	v_mul_f32_e32 v86, v86, v114
	v_mul_f32_e32 v87, v87, v114
	v_mul_f32_e32 v84, v4, v84
	v_mul_f32_e32 v85, v5, v85
	v_mul_f32_e32 v86, v6, v86
	v_mul_f32_e32 v87, v7, v87
	global_store_dwordx4 v120, v[84:87], s[6:7] offset:1024
	v_mul_f32_e32 v88, v88, v114
	v_mul_f32_e32 v89, v89, v114
	v_mul_f32_e32 v90, v90, v114
	v_mul_f32_e32 v91, v91, v114
	v_mul_f32_e32 v88, v8, v88
	v_mul_f32_e32 v89, v9, v89
	v_mul_f32_e32 v90, v10, v90
	v_mul_f32_e32 v91, v11, v91
	global_store_dwordx4 v120, v[88:91], s[6:7] offset:2048
	v_mul_f32_e32 v92, v92, v114
	v_mul_f32_e32 v93, v93, v114
	v_mul_f32_e32 v94, v94, v114
	v_mul_f32_e32 v95, v95, v114
	v_mul_f32_e32 v92, v12, v92
	v_mul_f32_e32 v93, v13, v93
	v_mul_f32_e32 v94, v14, v94
	v_mul_f32_e32 v95, v15, v95
	global_store_dwordx4 v120, v[92:95], s[6:7] offset:3072
	s_add_u32 s6, s6, 0x40000
	s_addc_u32 s7, s7, 0
	v_mul_f32_e32 v96, v96, v115
	v_mul_f32_e32 v97, v97, v115
	v_mul_f32_e32 v98, v98, v115
	v_mul_f32_e32 v99, v99, v115
	v_mul_f32_e32 v96, v0, v96
	v_mul_f32_e32 v97, v1, v97
	v_mul_f32_e32 v98, v2, v98
	v_mul_f32_e32 v99, v3, v99
	global_store_dwordx4 v120, v[96:99], s[6:7] offset:0
	v_mul_f32_e32 v100, v100, v115
	v_mul_f32_e32 v101, v101, v115
	v_mul_f32_e32 v102, v102, v115
	v_mul_f32_e32 v103, v103, v115
	v_mul_f32_e32 v100, v4, v100
	v_mul_f32_e32 v101, v5, v101
	v_mul_f32_e32 v102, v6, v102
	v_mul_f32_e32 v103, v7, v103
	global_store_dwordx4 v120, v[100:103], s[6:7] offset:1024
	v_mul_f32_e32 v104, v104, v115
	v_mul_f32_e32 v105, v105, v115
	v_mul_f32_e32 v106, v106, v115
	v_mul_f32_e32 v107, v107, v115
	v_mul_f32_e32 v104, v8, v104
	v_mul_f32_e32 v105, v9, v105
	v_mul_f32_e32 v106, v10, v106
	v_mul_f32_e32 v107, v11, v107
	global_store_dwordx4 v120, v[104:107], s[6:7] offset:2048
	v_mul_f32_e32 v108, v108, v115
	v_mul_f32_e32 v109, v109, v115
	v_mul_f32_e32 v110, v110, v115
	v_mul_f32_e32 v111, v111, v115
	v_mul_f32_e32 v108, v12, v108
	v_mul_f32_e32 v109, v13, v109
	v_mul_f32_e32 v110, v14, v110
	v_mul_f32_e32 v111, v15, v111
	global_store_dwordx4 v120, v[108:111], s[6:7] offset:3072
	s_add_u32 s6, s6, 0x40000
	s_addc_u32 s7, s7, 0
	s_sub_u32 s2, s2, 1
	s_cmp_lg_u32 s2, 0
	s_cbranch_scc1 .Lrms_final_loop
	s_waitcnt vmcnt(28)
	v_mul_f32_e32 v112, v132, v132
	v_fmac_f32_e32 v112, v133, v133
	v_fmac_f32_e32 v112, v134, v134
	v_fmac_f32_e32 v112, v135, v135
	v_fmac_f32_e32 v112, v136, v136
	v_fmac_f32_e32 v112, v137, v137
	v_fmac_f32_e32 v112, v138, v138
	v_fmac_f32_e32 v112, v139, v139
	v_fmac_f32_e32 v112, v140, v140
	v_fmac_f32_e32 v112, v141, v141
	v_fmac_f32_e32 v112, v142, v142
	v_fmac_f32_e32 v112, v143, v143
	v_fmac_f32_e32 v112, v144, v144
	v_fmac_f32_e32 v112, v145, v145
	v_fmac_f32_e32 v112, v146, v146
	v_fmac_f32_e32 v112, v147, v147
	s_waitcnt vmcnt(24)
	v_mul_f32_e32 v113, v166, v166
	v_fmac_f32_e32 v113, v167, v167
	v_fmac_f32_e32 v113, v168, v168
	v_fmac_f32_e32 v113, v169, v169
	v_fmac_f32_e32 v113, v170, v170
	v_fmac_f32_e32 v113, v171, v171
	v_fmac_f32_e32 v113, v172, v172
	v_fmac_f32_e32 v113, v173, v173
	v_fmac_f32_e32 v113, v174, v174
	v_fmac_f32_e32 v113, v175, v175
	v_fmac_f32_e32 v113, v176, v176
	v_fmac_f32_e32 v113, v177, v177
	v_fmac_f32_e32 v113, v178, v178
	v_fmac_f32_e32 v113, v179, v179
	v_fmac_f32_e32 v113, v180, v180
	v_fmac_f32_e32 v113, v181, v181
	s_waitcnt vmcnt(20)
	v_mul_f32_e32 v114, v182, v182
	v_fmac_f32_e32 v114, v183, v183
	v_fmac_f32_e32 v114, v184, v184
	v_fmac_f32_e32 v114, v185, v185
	v_fmac_f32_e32 v114, v186, v186
	v_fmac_f32_e32 v114, v187, v187
	v_fmac_f32_e32 v114, v188, v188
	v_fmac_f32_e32 v114, v189, v189
	v_fmac_f32_e32 v114, v190, v190
	v_fmac_f32_e32 v114, v191, v191
	v_fmac_f32_e32 v114, v192, v192
	v_fmac_f32_e32 v114, v193, v193
	v_fmac_f32_e32 v114, v194, v194
	v_fmac_f32_e32 v114, v195, v195
	v_fmac_f32_e32 v114, v196, v196
	v_fmac_f32_e32 v114, v197, v197
	s_waitcnt vmcnt(16)
	v_mul_f32_e32 v115, v228, v228
	v_fmac_f32_e32 v115, v229, v229
	v_fmac_f32_e32 v115, v230, v230
	v_fmac_f32_e32 v115, v231, v231
	v_fmac_f32_e32 v115, v232, v232
	v_fmac_f32_e32 v115, v233, v233
	v_fmac_f32_e32 v115, v234, v234
	v_fmac_f32_e32 v115, v235, v235
	v_fmac_f32_e32 v115, v236, v236
	v_fmac_f32_e32 v115, v237, v237
	v_fmac_f32_e32 v115, v238, v238
	v_fmac_f32_e32 v115, v239, v239
	v_fmac_f32_e32 v115, v240, v240
	v_fmac_f32_e32 v115, v241, v241
	v_fmac_f32_e32 v115, v242, v242
	v_fmac_f32_e32 v115, v243, v243
	ds_bpermute_b32 v116, v122, v112
	ds_bpermute_b32 v117, v122, v113
	ds_bpermute_b32 v118, v122, v114
	ds_bpermute_b32 v119, v122, v115
	s_waitcnt lgkmcnt(0)
	v_add_f32_e32 v112, v112, v116
	v_add_f32_e32 v113, v113, v117
	v_add_f32_e32 v114, v114, v118
	v_add_f32_e32 v115, v115, v119
	ds_bpermute_b32 v116, v123, v112
	ds_bpermute_b32 v117, v123, v113
	ds_bpermute_b32 v118, v123, v114
	ds_bpermute_b32 v119, v123, v115
	s_waitcnt lgkmcnt(0)
	v_add_f32_e32 v112, v112, v116
	v_add_f32_e32 v113, v113, v117
	v_add_f32_e32 v114, v114, v118
	v_add_f32_e32 v115, v115, v119
	ds_bpermute_b32 v116, v124, v112
	ds_bpermute_b32 v117, v124, v113
	ds_bpermute_b32 v118, v124, v114
	ds_bpermute_b32 v119, v124, v115
	s_waitcnt lgkmcnt(0)
	v_add_f32_e32 v112, v112, v116
	v_add_f32_e32 v113, v113, v117
	v_add_f32_e32 v114, v114, v118
	v_add_f32_e32 v115, v115, v119
	ds_bpermute_b32 v116, v125, v112
	ds_bpermute_b32 v117, v125, v113
	ds_bpermute_b32 v118, v125, v114
	ds_bpermute_b32 v119, v125, v115
	s_waitcnt lgkmcnt(0)
	v_add_f32_e32 v112, v112, v116
	v_add_f32_e32 v113, v113, v117
	v_add_f32_e32 v114, v114, v118
	v_add_f32_e32 v115, v115, v119
	ds_bpermute_b32 v116, v126, v112
	ds_bpermute_b32 v117, v126, v113
	ds_bpermute_b32 v118, v126, v114
	ds_bpermute_b32 v119, v126, v115
	s_waitcnt lgkmcnt(0)
	v_add_f32_e32 v112, v112, v116
	v_add_f32_e32 v113, v113, v117
	v_add_f32_e32 v114, v114, v118
	v_add_f32_e32 v115, v115, v119
	ds_bpermute_b32 v116, v127, v112
	ds_bpermute_b32 v117, v127, v113
	ds_bpermute_b32 v118, v127, v114
	ds_bpermute_b32 v119, v127, v115
	s_waitcnt lgkmcnt(0)
	v_add_f32_e32 v112, v112, v116
	v_add_f32_e32 v113, v113, v117
	v_add_f32_e32 v114, v114, v118
	v_add_f32_e32 v115, v115, v119
	v_fmamk_f32 v112, v112, 0x3a800000, v208
	v_fmamk_f32 v113, v113, 0x3a800000, v208
	v_fmamk_f32 v114, v114, 0x3a800000, v208
	v_fmamk_f32 v115, v115, 0x3a800000, v208
	v_rsq_f32_e32 v112, v112
	v_rsq_f32_e32 v113, v113
	v_rsq_f32_e32 v114, v114
	v_rsq_f32_e32 v115, v115
	s_nop 1
	v_mul_f32_e32 v132, v132, v112
	v_mul_f32_e32 v133, v133, v112
	v_mul_f32_e32 v134, v134, v112
	v_mul_f32_e32 v135, v135, v112
	v_mul_f32_e32 v132, v0, v132
	v_mul_f32_e32 v133, v1, v133
	v_mul_f32_e32 v134, v2, v134
	v_mul_f32_e32 v135, v3, v135
	global_store_dwordx4 v120, v[132:135], s[6:7] offset:0
	v_mul_f32_e32 v136, v136, v112
	v_mul_f32_e32 v137, v137, v112
	v_mul_f32_e32 v138, v138, v112
	v_mul_f32_e32 v139, v139, v112
	v_mul_f32_e32 v136, v4, v136
	v_mul_f32_e32 v137, v5, v137
	v_mul_f32_e32 v138, v6, v138
	v_mul_f32_e32 v139, v7, v139
	global_store_dwordx4 v120, v[136:139], s[6:7] offset:1024
	v_mul_f32_e32 v140, v140, v112
	v_mul_f32_e32 v141, v141, v112
	v_mul_f32_e32 v142, v142, v112
	v_mul_f32_e32 v143, v143, v112
	v_mul_f32_e32 v140, v8, v140
	v_mul_f32_e32 v141, v9, v141
	v_mul_f32_e32 v142, v10, v142
	v_mul_f32_e32 v143, v11, v143
	global_store_dwordx4 v120, v[140:143], s[6:7] offset:2048
	v_mul_f32_e32 v144, v144, v112
	v_mul_f32_e32 v145, v145, v112
	v_mul_f32_e32 v146, v146, v112
	v_mul_f32_e32 v147, v147, v112
	v_mul_f32_e32 v144, v12, v144
	v_mul_f32_e32 v145, v13, v145
	v_mul_f32_e32 v146, v14, v146
	v_mul_f32_e32 v147, v15, v147
	global_store_dwordx4 v120, v[144:147], s[6:7] offset:3072
	s_add_u32 s6, s6, 0x40000
	s_addc_u32 s7, s7, 0
	v_mul_f32_e32 v166, v166, v113
	v_mul_f32_e32 v167, v167, v113
	v_mul_f32_e32 v168, v168, v113
	v_mul_f32_e32 v169, v169, v113
	v_mul_f32_e32 v166, v0, v166
	v_mul_f32_e32 v167, v1, v167
	v_mul_f32_e32 v168, v2, v168
	v_mul_f32_e32 v169, v3, v169
	global_store_dwordx4 v120, v[166:169], s[6:7] offset:0
	v_mul_f32_e32 v170, v170, v113
	v_mul_f32_e32 v171, v171, v113
	v_mul_f32_e32 v172, v172, v113
	v_mul_f32_e32 v173, v173, v113
	v_mul_f32_e32 v170, v4, v170
	v_mul_f32_e32 v171, v5, v171
	v_mul_f32_e32 v172, v6, v172
	v_mul_f32_e32 v173, v7, v173
	global_store_dwordx4 v120, v[170:173], s[6:7] offset:1024
	v_mul_f32_e32 v174, v174, v113
	v_mul_f32_e32 v175, v175, v113
	v_mul_f32_e32 v176, v176, v113
	v_mul_f32_e32 v177, v177, v113
	v_mul_f32_e32 v174, v8, v174
	v_mul_f32_e32 v175, v9, v175
	v_mul_f32_e32 v176, v10, v176
	v_mul_f32_e32 v177, v11, v177
	global_store_dwordx4 v120, v[174:177], s[6:7] offset:2048
	v_mul_f32_e32 v178, v178, v113
	v_mul_f32_e32 v179, v179, v113
	v_mul_f32_e32 v180, v180, v113
	v_mul_f32_e32 v181, v181, v113
	v_mul_f32_e32 v178, v12, v178
	v_mul_f32_e32 v179, v13, v179
	v_mul_f32_e32 v180, v14, v180
	v_mul_f32_e32 v181, v15, v181
	global_store_dwordx4 v120, v[178:181], s[6:7] offset:3072
	s_add_u32 s6, s6, 0x40000
	s_addc_u32 s7, s7, 0
	v_mul_f32_e32 v182, v182, v114
	v_mul_f32_e32 v183, v183, v114
	v_mul_f32_e32 v184, v184, v114
	v_mul_f32_e32 v185, v185, v114
	v_mul_f32_e32 v182, v0, v182
	v_mul_f32_e32 v183, v1, v183
	v_mul_f32_e32 v184, v2, v184
	v_mul_f32_e32 v185, v3, v185
	global_store_dwordx4 v120, v[182:185], s[6:7] offset:0
	v_mul_f32_e32 v186, v186, v114
	v_mul_f32_e32 v187, v187, v114
	v_mul_f32_e32 v188, v188, v114
	v_mul_f32_e32 v189, v189, v114
	v_mul_f32_e32 v186, v4, v186
	v_mul_f32_e32 v187, v5, v187
	v_mul_f32_e32 v188, v6, v188
	v_mul_f32_e32 v189, v7, v189
	global_store_dwordx4 v120, v[186:189], s[6:7] offset:1024
	v_mul_f32_e32 v190, v190, v114
	v_mul_f32_e32 v191, v191, v114
	v_mul_f32_e32 v192, v192, v114
	v_mul_f32_e32 v193, v193, v114
	v_mul_f32_e32 v190, v8, v190
	v_mul_f32_e32 v191, v9, v191
	v_mul_f32_e32 v192, v10, v192
	v_mul_f32_e32 v193, v11, v193
	global_store_dwordx4 v120, v[190:193], s[6:7] offset:2048
	v_mul_f32_e32 v194, v194, v114
	v_mul_f32_e32 v195, v195, v114
	v_mul_f32_e32 v196, v196, v114
	v_mul_f32_e32 v197, v197, v114
	v_mul_f32_e32 v194, v12, v194
	v_mul_f32_e32 v195, v13, v195
	v_mul_f32_e32 v196, v14, v196
	v_mul_f32_e32 v197, v15, v197
	global_store_dwordx4 v120, v[194:197], s[6:7] offset:3072
	s_add_u32 s6, s6, 0x40000
	s_addc_u32 s7, s7, 0
	v_mul_f32_e32 v228, v228, v115
	v_mul_f32_e32 v229, v229, v115
	v_mul_f32_e32 v230, v230, v115
	v_mul_f32_e32 v231, v231, v115
	v_mul_f32_e32 v228, v0, v228
	v_mul_f32_e32 v229, v1, v229
	v_mul_f32_e32 v230, v2, v230
	v_mul_f32_e32 v231, v3, v231
	global_store_dwordx4 v120, v[228:231], s[6:7] offset:0
	v_mul_f32_e32 v232, v232, v115
	v_mul_f32_e32 v233, v233, v115
	v_mul_f32_e32 v234, v234, v115
	v_mul_f32_e32 v235, v235, v115
	v_mul_f32_e32 v232, v4, v232
	v_mul_f32_e32 v233, v5, v233
	v_mul_f32_e32 v234, v6, v234
	v_mul_f32_e32 v235, v7, v235
	global_store_dwordx4 v120, v[232:235], s[6:7] offset:1024
	v_mul_f32_e32 v236, v236, v115
	v_mul_f32_e32 v237, v237, v115
	v_mul_f32_e32 v238, v238, v115
	v_mul_f32_e32 v239, v239, v115
	v_mul_f32_e32 v236, v8, v236
	v_mul_f32_e32 v237, v9, v237
	v_mul_f32_e32 v238, v10, v238
	v_mul_f32_e32 v239, v11, v239
	global_store_dwordx4 v120, v[236:239], s[6:7] offset:2048
	v_mul_f32_e32 v240, v240, v115
	v_mul_f32_e32 v241, v241, v115
	v_mul_f32_e32 v242, v242, v115
	v_mul_f32_e32 v243, v243, v115
	v_mul_f32_e32 v240, v12, v240
	v_mul_f32_e32 v241, v13, v241
	v_mul_f32_e32 v242, v14, v242
	v_mul_f32_e32 v243, v15, v243
	global_store_dwordx4 v120, v[240:243], s[6:7] offset:3072
	s_add_u32 s6, s6, 0x40000
	s_addc_u32 s7, s7, 0

.LBB0_83:
	v_writelane_b32 v252, s4, 35
	s_and_b64 vcc, exec, s[8:9]
	s_nop 0
	v_writelane_b32 v252, s5, 36
	s_cbranch_vccz .LBB0_90
	v_mov_b32_e32 v0, 0xe0
	v_readlane_b32 s4, v253, 11
	v_add_u32_e32 v0, s91, v0
	ds_read_b64 v[0:1], v0
	s_waitcnt lgkmcnt(0)
	v_readfirstlane_b32 s6, v0
	v_mov_b32_e32 v0, 24
	v_readfirstlane_b32 s7, v1
	v_add_u32_e32 v0, s91, v0
	ds_read_b64 v[0:1], v0
	s_waitcnt lgkmcnt(0)
	v_readfirstlane_b32 s10, v0
	v_mov_b32_e32 v0, 0xe8
	v_readfirstlane_b32 s2, v1
	v_add_u32_e32 v0, s91, v0
	ds_read_b64 v[0:1], v0
	s_waitcnt lgkmcnt(0)
	v_readfirstlane_b32 s9, v1
	v_readfirstlane_b32 s8, v0
	v_mbcnt_lo_u32_b32 v0, -1, 0
	v_mbcnt_hi_u32_b32 v0, -1, v0
	s_nop 0
	v_add_u32_e32 v1, s57, v0
	v_ashrrev_i32_e32 v1, 6, v1
	v_add_u32_e32 v56, s4, v1
	v_cmp_gt_i32_e32 vcc, s3, v56
	s_and_saveexec_b64 s[4:5], vcc
	v_readlane_b32 s14, v252, 23
	s_cbranch_execz .LBB0_89
	v_readfirstlane_b32 s100, v56
	v_readlane_b32 s11, v252, 31
	s_nop 3
	s_lshl_b32 s12, s11, 12
	s_mov_b32 s11, s2
	s_add_u32 s10, s10, s12
	s_addc_u32 s11, s11, 0
	s_add_u32 s8, s8, 0x5200000
	s_addc_u32 s9, s9, 0
	s_nop 3
	v_lshlrev_b32_e32 v120, 4, v0
	v_lshlrev_b32_e32 v121, 3, v0
	v_lshlrev_b32_e32 v122, 2, v214
	v_lshlrev_b32_e32 v123, 2, v215
	v_lshlrev_b32_e32 v124, 2, v216
	v_lshlrev_b32_e32 v125, 2, v217
	v_lshlrev_b32_e32 v126, 2, v218
	v_lshlrev_b32_e32 v127, 2, v219
	s_lshr_b32 s2, s100, 6
	s_lshl_b32 s2, s2, 11
	s_and_b32 s101, s100, 63
	s_add_u32 s2, s2, s101
	s_lshl_b32 s101, s2, 12
	s_add_u32 s6, s6, s101
	s_addc_u32 s7, s7, 0
	s_lshl_b32 s101, s2, 11
	s_add_u32 s8, s8, s101
	s_addc_u32 s9, s9, 0
	global_load_dwordx4 v[0:3], v120, s[10:11] offset:0
	global_load_dwordx4 v[4:7], v120, s[10:11] offset:1024
	global_load_dwordx4 v[8:11], v120, s[10:11] offset:2048
	global_load_dwordx4 v[12:15], v120, s[10:11] offset:3072
	v_readlane_b32 s10, v252, 32
	v_readlane_b32 s11, v252, 33
	s_lshr_b32 s2, s100, 6
	s_mul_i32 s2, s2, 0x6000
	s_nop 3
	s_add_u32 s10, s10, s2
	s_addc_u32 s11, s11, 0
	s_add_u32 s10, s10, 0x4000
	s_addc_u32 s11, s11, 0
	global_load_dwordx4 v[16:19], v120, s[10:11] offset:0
	global_load_dwordx4 v[20:23], v120, s[10:11] offset:1024
	global_load_dwordx4 v[24:27], v120, s[10:11] offset:2048
	global_load_dwordx4 v[28:31], v120, s[10:11] offset:3072
	s_sub_u32 s10, s10, 0x1000
	s_subb_u32 s11, s11, 0
	global_load_dwordx4 v[32:35], v120, s[10:11] offset:0
	global_load_dwordx4 v[36:39], v120, s[10:11] offset:1024
	global_load_dwordx4 v[40:43], v120, s[10:11] offset:2048
	global_load_dwordx4 v[44:47], v120, s[10:11] offset:3072
	s_waitcnt vmcnt(0)
	v_add_f32_e32 v16, 1.0, v16
	v_add_f32_e32 v17, 1.0, v17
	v_add_f32_e32 v18, 1.0, v18
	v_add_f32_e32 v19, 1.0, v19
	v_add_f32_e32 v20, 1.0, v20
	v_add_f32_e32 v21, 1.0, v21
	v_add_f32_e32 v22, 1.0, v22
	v_add_f32_e32 v23, 1.0, v23
	v_add_f32_e32 v24, 1.0, v24
	v_add_f32_e32 v25, 1.0, v25
	v_add_f32_e32 v26, 1.0, v26
	v_add_f32_e32 v27, 1.0, v27
	v_add_f32_e32 v28, 1.0, v28
	v_add_f32_e32 v29, 1.0, v29
	v_add_f32_e32 v30, 1.0, v30
	v_add_f32_e32 v31, 1.0, v31
	s_movk_i32 s2, 3
	global_load_dwordx4 v[48:51], v120, s[6:7] offset:0
	global_load_dwordx4 v[52:55], v120, s[6:7] offset:1024
	global_load_dwordx4 v[56:59], v120, s[6:7] offset:2048
	global_load_dwordx4 v[60:63], v120, s[6:7] offset:3072
	s_add_u32 s6, s6, 0x40000
	s_addc_u32 s7, s7, 0
	global_load_dwordx4 v[64:67], v120, s[6:7] offset:0
	global_load_dwordx4 v[68:71], v120, s[6:7] offset:1024
	global_load_dwordx4 v[72:75], v120, s[6:7] offset:2048
	global_load_dwordx4 v[76:79], v120, s[6:7] offset:3072
	s_add_u32 s6, s6, 0x40000
	s_addc_u32 s7, s7, 0
	global_load_dwordx4 v[80:83], v120, s[6:7] offset:0
	global_load_dwordx4 v[84:87], v120, s[6:7] offset:1024
	global_load_dwordx4 v[88:91], v120, s[6:7] offset:2048
	global_load_dwordx4 v[92:95], v120, s[6:7] offset:3072
	s_add_u32 s6, s6, 0x40000
	s_addc_u32 s7, s7, 0
	global_load_dwordx4 v[96:99], v120, s[6:7] offset:0
	global_load_dwordx4 v[100:103], v120, s[6:7] offset:1024
	global_load_dwordx4 v[104:107], v120, s[6:7] offset:2048
	global_load_dwordx4 v[108:111], v120, s[6:7] offset:3072
	s_add_u32 s6, s6, 0x40000
	s_addc_u32 s7, s7, 0
	global_load_dwordx4 v[132:135], v120, s[6:7] offset:0
	global_load_dwordx4 v[136:139], v120, s[6:7] offset:1024
	global_load_dwordx4 v[140:143], v120, s[6:7] offset:2048
	global_load_dwordx4 v[144:147], v120, s[6:7] offset:3072
	s_add_u32 s6, s6, 0x40000
	s_addc_u32 s7, s7, 0
	global_load_dwordx4 v[166:169], v120, s[6:7] offset:0
	global_load_dwordx4 v[170:173], v120, s[6:7] offset:1024
	global_load_dwordx4 v[174:177], v120, s[6:7] offset:2048
	global_load_dwordx4 v[178:181], v120, s[6:7] offset:3072
	s_add_u32 s6, s6, 0x40000
	s_addc_u32 s7, s7, 0
	global_load_dwordx4 v[182:185], v120, s[6:7] offset:0
	global_load_dwordx4 v[186:189], v120, s[6:7] offset:1024
	global_load_dwordx4 v[190:193], v120, s[6:7] offset:2048
	global_load_dwordx4 v[194:197], v120, s[6:7] offset:3072
	s_add_u32 s6, s6, 0x40000
	s_addc_u32 s7, s7, 0
	global_load_dwordx4 v[228:231], v120, s[6:7] offset:0
	global_load_dwordx4 v[232:235], v120, s[6:7] offset:1024
	global_load_dwordx4 v[236:239], v120, s[6:7] offset:2048
	global_load_dwordx4 v[240:243], v120, s[6:7] offset:3072
	s_add_u32 s6, s6, 0x40000
	s_addc_u32 s7, s7, 0
	s_waitcnt vmcnt(28)
	v_mul_f32_e32 v112, v48, v48
	v_fmac_f32_e32 v112, v49, v49
	v_fmac_f32_e32 v112, v50, v50
	v_fmac_f32_e32 v112, v51, v51
	v_fmac_f32_e32 v112, v52, v52
	v_fmac_f32_e32 v112, v53, v53
	v_fmac_f32_e32 v112, v54, v54
	v_fmac_f32_e32 v112, v55, v55
	v_fmac_f32_e32 v112, v56, v56
	v_fmac_f32_e32 v112, v57, v57
	v_fmac_f32_e32 v112, v58, v58
	v_fmac_f32_e32 v112, v59, v59
	v_fmac_f32_e32 v112, v60, v60
	v_fmac_f32_e32 v112, v61, v61
	v_fmac_f32_e32 v112, v62, v62
	v_fmac_f32_e32 v112, v63, v63
	s_waitcnt vmcnt(24)
	v_mul_f32_e32 v113, v64, v64
	v_fmac_f32_e32 v113, v65, v65
	v_fmac_f32_e32 v113, v66, v66
	v_fmac_f32_e32 v113, v67, v67
	v_fmac_f32_e32 v113, v68, v68
	v_fmac_f32_e32 v113, v69, v69
	v_fmac_f32_e32 v113, v70, v70
	v_fmac_f32_e32 v113, v71, v71
	v_fmac_f32_e32 v113, v72, v72
	v_fmac_f32_e32 v113, v73, v73
	v_fmac_f32_e32 v113, v74, v74
	v_fmac_f32_e32 v113, v75, v75
	v_fmac_f32_e32 v113, v76, v76
	v_fmac_f32_e32 v113, v77, v77
	v_fmac_f32_e32 v113, v78, v78
	v_fmac_f32_e32 v113, v79, v79
	s_waitcnt vmcnt(20)
	v_mul_f32_e32 v114, v80, v80
	v_fmac_f32_e32 v114, v81, v81
	v_fmac_f32_e32 v114, v82, v82
	v_fmac_f32_e32 v114, v83, v83
	v_fmac_f32_e32 v114, v84, v84
	v_fmac_f32_e32 v114, v85, v85
	v_fmac_f32_e32 v114, v86, v86
	v_fmac_f32_e32 v114, v87, v87
	v_fmac_f32_e32 v114, v88, v88
	v_fmac_f32_e32 v114, v89, v89
	v_fmac_f32_e32 v114, v90, v90
	v_fmac_f32_e32 v114, v91, v91
	v_fmac_f32_e32 v114, v92, v92
	v_fmac_f32_e32 v114, v93, v93
	v_fmac_f32_e32 v114, v94, v94
	v_fmac_f32_e32 v114, v95, v95
	s_waitcnt vmcnt(16)
	v_mul_f32_e32 v115, v96, v96
	v_fmac_f32_e32 v115, v97, v97
	v_fmac_f32_e32 v115, v98, v98
	v_fmac_f32_e32 v115, v99, v99
	v_fmac_f32_e32 v115, v100, v100
	v_fmac_f32_e32 v115, v101, v101
	v_fmac_f32_e32 v115, v102, v102
	v_fmac_f32_e32 v115, v103, v103
	v_fmac_f32_e32 v115, v104, v104
	v_fmac_f32_e32 v115, v105, v105
	v_fmac_f32_e32 v115, v106, v106
	v_fmac_f32_e32 v115, v107, v107
	v_fmac_f32_e32 v115, v108, v108
	v_fmac_f32_e32 v115, v109, v109
	v_fmac_f32_e32 v115, v110, v110
	v_fmac_f32_e32 v115, v111, v111
	ds_bpermute_b32 v116, v122, v112
	ds_bpermute_b32 v117, v122, v113
	ds_bpermute_b32 v118, v122, v114
	ds_bpermute_b32 v119, v122, v115
	s_waitcnt lgkmcnt(0)
	v_add_f32_e32 v112, v112, v116
	v_add_f32_e32 v113, v113, v117
	v_add_f32_e32 v114, v114, v118
	v_add_f32_e32 v115, v115, v119
	ds_bpermute_b32 v116, v123, v112
	ds_bpermute_b32 v117, v123, v113
	ds_bpermute_b32 v118, v123, v114
	ds_bpermute_b32 v119, v123, v115
	s_waitcnt lgkmcnt(0)
	v_add_f32_e32 v112, v112, v116
	v_add_f32_e32 v113, v113, v117
	v_add_f32_e32 v114, v114, v118
	v_add_f32_e32 v115, v115, v119
	ds_bpermute_b32 v116, v124, v112
	ds_bpermute_b32 v117, v124, v113
	ds_bpermute_b32 v118, v124, v114
	ds_bpermute_b32 v119, v124, v115
	s_waitcnt lgkmcnt(0)
	v_add_f32_e32 v112, v112, v116
	v_add_f32_e32 v113, v113, v117
	v_add_f32_e32 v114, v114, v118
	v_add_f32_e32 v115, v115, v119
	ds_bpermute_b32 v116, v125, v112
	ds_bpermute_b32 v117, v125, v113
	ds_bpermute_b32 v118, v125, v114
	ds_bpermute_b32 v119, v125, v115
	s_waitcnt lgkmcnt(0)
	v_add_f32_e32 v112, v112, v116
	v_add_f32_e32 v113, v113, v117
	v_add_f32_e32 v114, v114, v118
	v_add_f32_e32 v115, v115, v119
	ds_bpermute_b32 v116, v126, v112
	ds_bpermute_b32 v117, v126, v113
	ds_bpermute_b32 v118, v126, v114
	ds_bpermute_b32 v119, v126, v115
	s_waitcnt lgkmcnt(0)
	v_add_f32_e32 v112, v112, v116
	v_add_f32_e32 v113, v113, v117
	v_add_f32_e32 v114, v114, v118
	v_add_f32_e32 v115, v115, v119
	ds_bpermute_b32 v116, v127, v112
	ds_bpermute_b32 v117, v127, v113
	ds_bpermute_b32 v118, v127, v114
	ds_bpermute_b32 v119, v127, v115
	s_waitcnt lgkmcnt(0)
	v_add_f32_e32 v112, v112, v116
	v_add_f32_e32 v113, v113, v117
	v_add_f32_e32 v114, v114, v118
	v_add_f32_e32 v115, v115, v119
	v_fmamk_f32 v112, v112, 0x3a800000, v208
	v_fmamk_f32 v113, v113, 0x3a800000, v208
	v_fmamk_f32 v114, v114, 0x3a800000, v208
	v_fmamk_f32 v115, v115, 0x3a800000, v208
	v_rsq_f32_e32 v112, v112
	v_rsq_f32_e32 v113, v113
	v_rsq_f32_e32 v114, v114
	v_rsq_f32_e32 v115, v115
	s_nop 1
	v_mul_f32_e32 v48, v48, v112
	v_mul_f32_e32 v49, v49, v112
	v_mul_f32_e32 v50, v50, v112
	v_mul_f32_e32 v51, v51, v112
	v_mul_f32_e32 v48, v0, v48
	v_mul_f32_e32 v49, v1, v49
	v_mul_f32_e32 v50, v2, v50
	v_mul_f32_e32 v51, v3, v51
	v_fma_f32 v48, v48, v16, v32
	v_fma_f32 v49, v49, v17, v33
	v_fma_f32 v50, v50, v18, v34
	v_fma_f32 v51, v51, v19, v35
	v_cvt_pk_bf16_f32 v128, v48, v49
	v_cvt_pk_bf16_f32 v129, v50, v51
	global_store_dwordx2 v121, v[128:129], s[8:9] offset:0
	v_mul_f32_e32 v52, v52, v112
	v_mul_f32_e32 v53, v53, v112
	v_mul_f32_e32 v54, v54, v112
	v_mul_f32_e32 v55, v55, v112
	v_mul_f32_e32 v52, v4, v52
	v_mul_f32_e32 v53, v5, v53
	v_mul_f32_e32 v54, v6, v54
	v_mul_f32_e32 v55, v7, v55
	v_fma_f32 v52, v52, v20, v36
	v_fma_f32 v53, v53, v21, v37
	v_fma_f32 v54, v54, v22, v38
	v_fma_f32 v55, v55, v23, v39
	v_cvt_pk_bf16_f32 v130, v52, v53
	v_cvt_pk_bf16_f32 v131, v54, v55
	global_store_dwordx2 v121, v[130:131], s[8:9] offset:512
	v_mul_f32_e32 v56, v56, v112
	v_mul_f32_e32 v57, v57, v112
	v_mul_f32_e32 v58, v58, v112
	v_mul_f32_e32 v59, v59, v112
	v_mul_f32_e32 v56, v8, v56
	v_mul_f32_e32 v57, v9, v57
	v_mul_f32_e32 v58, v10, v58
	v_mul_f32_e32 v59, v11, v59
	v_fma_f32 v56, v56, v24, v40
	v_fma_f32 v57, v57, v25, v41
	v_fma_f32 v58, v58, v26, v42
	v_fma_f32 v59, v59, v27, v43
	v_cvt_pk_bf16_f32 v128, v56, v57
	v_cvt_pk_bf16_f32 v129, v58, v59
	global_store_dwordx2 v121, v[128:129], s[8:9] offset:1024
	v_mul_f32_e32 v60, v60, v112
	v_mul_f32_e32 v61, v61, v112
	v_mul_f32_e32 v62, v62, v112
	v_mul_f32_e32 v63, v63, v112
	v_mul_f32_e32 v60, v12, v60
	v_mul_f32_e32 v61, v13, v61
	v_mul_f32_e32 v62, v14, v62
	v_mul_f32_e32 v63, v15, v63
	v_fma_f32 v60, v60, v28, v44
	v_fma_f32 v61, v61, v29, v45
	v_fma_f32 v62, v62, v30, v46
	v_fma_f32 v63, v63, v31, v47
	v_cvt_pk_bf16_f32 v130, v60, v61
	v_cvt_pk_bf16_f32 v131, v62, v63
	global_store_dwordx2 v121, v[130:131], s[8:9] offset:1536
	s_add_u32 s8, s8, 0x20000
	s_addc_u32 s9, s9, 0
	v_mul_f32_e32 v64, v64, v113
	v_mul_f32_e32 v65, v65, v113
	v_mul_f32_e32 v66, v66, v113
	v_mul_f32_e32 v67, v67, v113
	v_mul_f32_e32 v64, v0, v64
	v_mul_f32_e32 v65, v1, v65
	v_mul_f32_e32 v66, v2, v66
	v_mul_f32_e32 v67, v3, v67
	v_fma_f32 v64, v64, v16, v32
	v_fma_f32 v65, v65, v17, v33
	v_fma_f32 v66, v66, v18, v34
	v_fma_f32 v67, v67, v19, v35
	v_cvt_pk_bf16_f32 v128, v64, v65
	v_cvt_pk_bf16_f32 v129, v66, v67
	global_store_dwordx2 v121, v[128:129], s[8:9] offset:0
	v_mul_f32_e32 v68, v68, v113
	v_mul_f32_e32 v69, v69, v113
	v_mul_f32_e32 v70, v70, v113
	v_mul_f32_e32 v71, v71, v113
	v_mul_f32_e32 v68, v4, v68
	v_mul_f32_e32 v69, v5, v69
	v_mul_f32_e32 v70, v6, v70
	v_mul_f32_e32 v71, v7, v71
	v_fma_f32 v68, v68, v20, v36
	v_fma_f32 v69, v69, v21, v37
	v_fma_f32 v70, v70, v22, v38
	v_fma_f32 v71, v71, v23, v39
	v_cvt_pk_bf16_f32 v130, v68, v69
	v_cvt_pk_bf16_f32 v131, v70, v71
	global_store_dwordx2 v121, v[130:131], s[8:9] offset:512
	v_mul_f32_e32 v72, v72, v113
	v_mul_f32_e32 v73, v73, v113
	v_mul_f32_e32 v74, v74, v113
	v_mul_f32_e32 v75, v75, v113
	v_mul_f32_e32 v72, v8, v72
	v_mul_f32_e32 v73, v9, v73
	v_mul_f32_e32 v74, v10, v74
	v_mul_f32_e32 v75, v11, v75
	v_fma_f32 v72, v72, v24, v40
	v_fma_f32 v73, v73, v25, v41
	v_fma_f32 v74, v74, v26, v42
	v_fma_f32 v75, v75, v27, v43
	v_cvt_pk_bf16_f32 v128, v72, v73
	v_cvt_pk_bf16_f32 v129, v74, v75
	global_store_dwordx2 v121, v[128:129], s[8:9] offset:1024
	v_mul_f32_e32 v76, v76, v113
	v_mul_f32_e32 v77, v77, v113
	v_mul_f32_e32 v78, v78, v113
	v_mul_f32_e32 v79, v79, v113
	v_mul_f32_e32 v76, v12, v76
	v_mul_f32_e32 v77, v13, v77
	v_mul_f32_e32 v78, v14, v78
	v_mul_f32_e32 v79, v15, v79
	v_fma_f32 v76, v76, v28, v44
	v_fma_f32 v77, v77, v29, v45
	v_fma_f32 v78, v78, v30, v46
	v_fma_f32 v79, v79, v31, v47
	v_cvt_pk_bf16_f32 v130, v76, v77
	v_cvt_pk_bf16_f32 v131, v78, v79
	global_store_dwordx2 v121, v[130:131], s[8:9] offset:1536
	s_add_u32 s8, s8, 0x20000
	s_addc_u32 s9, s9, 0
	v_mul_f32_e32 v80, v80, v114
	v_mul_f32_e32 v81, v81, v114
	v_mul_f32_e32 v82, v82, v114
	v_mul_f32_e32 v83, v83, v114
	v_mul_f32_e32 v80, v0, v80
	v_mul_f32_e32 v81, v1, v81
	v_mul_f32_e32 v82, v2, v82
	v_mul_f32_e32 v83, v3, v83
	v_fma_f32 v80, v80, v16, v32
	v_fma_f32 v81, v81, v17, v33
	v_fma_f32 v82, v82, v18, v34
	v_fma_f32 v83, v83, v19, v35
	v_cvt_pk_bf16_f32 v128, v80, v81
	v_cvt_pk_bf16_f32 v129, v82, v83
	global_store_dwordx2 v121, v[128:129], s[8:9] offset:0
	v_mul_f32_e32 v84, v84, v114
	v_mul_f32_e32 v85, v85, v114
	v_mul_f32_e32 v86, v86, v114
	v_mul_f32_e32 v87, v87, v114
	v_mul_f32_e32 v84, v4, v84
	v_mul_f32_e32 v85, v5, v85
	v_mul_f32_e32 v86, v6, v86
	v_mul_f32_e32 v87, v7, v87
	v_fma_f32 v84, v84, v20, v36
	v_fma_f32 v85, v85, v21, v37
	v_fma_f32 v86, v86, v22, v38
	v_fma_f32 v87, v87, v23, v39
	v_cvt_pk_bf16_f32 v130, v84, v85
	v_cvt_pk_bf16_f32 v131, v86, v87
	global_store_dwordx2 v121, v[130:131], s[8:9] offset:512
	v_mul_f32_e32 v88, v88, v114
	v_mul_f32_e32 v89, v89, v114
	v_mul_f32_e32 v90, v90, v114
	v_mul_f32_e32 v91, v91, v114
	v_mul_f32_e32 v88, v8, v88
	v_mul_f32_e32 v89, v9, v89
	v_mul_f32_e32 v90, v10, v90
	v_mul_f32_e32 v91, v11, v91
	v_fma_f32 v88, v88, v24, v40
	v_fma_f32 v89, v89, v25, v41
	v_fma_f32 v90, v90, v26, v42
	v_fma_f32 v91, v91, v27, v43
	v_cvt_pk_bf16_f32 v128, v88, v89
	v_cvt_pk_bf16_f32 v129, v90, v91
	global_store_dwordx2 v121, v[128:129], s[8:9] offset:1024
	v_mul_f32_e32 v92, v92, v114
	v_mul_f32_e32 v93, v93, v114
	v_mul_f32_e32 v94, v94, v114
	v_mul_f32_e32 v95, v95, v114
	v_mul_f32_e32 v92, v12, v92
	v_mul_f32_e32 v93, v13, v93
	v_mul_f32_e32 v94, v14, v94
	v_mul_f32_e32 v95, v15, v95
	v_fma_f32 v92, v92, v28, v44
	v_fma_f32 v93, v93, v29, v45
	v_fma_f32 v94, v94, v30, v46
	v_fma_f32 v95, v95, v31, v47
	v_cvt_pk_bf16_f32 v130, v92, v93
	v_cvt_pk_bf16_f32 v131, v94, v95
	global_store_dwordx2 v121, v[130:131], s[8:9] offset:1536
	s_add_u32 s8, s8, 0x20000
	s_addc_u32 s9, s9, 0
	v_mul_f32_e32 v96, v96, v115
	v_mul_f32_e32 v97, v97, v115
	v_mul_f32_e32 v98, v98, v115
	v_mul_f32_e32 v99, v99, v115
	v_mul_f32_e32 v96, v0, v96
	v_mul_f32_e32 v97, v1, v97
	v_mul_f32_e32 v98, v2, v98
	v_mul_f32_e32 v99, v3, v99
	v_fma_f32 v96, v96, v16, v32
	v_fma_f32 v97, v97, v17, v33
	v_fma_f32 v98, v98, v18, v34
	v_fma_f32 v99, v99, v19, v35
	v_cvt_pk_bf16_f32 v128, v96, v97
	v_cvt_pk_bf16_f32 v129, v98, v99
	global_store_dwordx2 v121, v[128:129], s[8:9] offset:0
	v_mul_f32_e32 v100, v100, v115
	v_mul_f32_e32 v101, v101, v115
	v_mul_f32_e32 v102, v102, v115
	v_mul_f32_e32 v103, v103, v115
	v_mul_f32_e32 v100, v4, v100
	v_mul_f32_e32 v101, v5, v101
	v_mul_f32_e32 v102, v6, v102
	v_mul_f32_e32 v103, v7, v103
	v_fma_f32 v100, v100, v20, v36
	v_fma_f32 v101, v101, v21, v37
	v_fma_f32 v102, v102, v22, v38
	v_fma_f32 v103, v103, v23, v39
	v_cvt_pk_bf16_f32 v130, v100, v101
	v_cvt_pk_bf16_f32 v131, v102, v103
	global_store_dwordx2 v121, v[130:131], s[8:9] offset:512
	v_mul_f32_e32 v104, v104, v115
	v_mul_f32_e32 v105, v105, v115
	v_mul_f32_e32 v106, v106, v115
	v_mul_f32_e32 v107, v107, v115
	v_mul_f32_e32 v104, v8, v104
	v_mul_f32_e32 v105, v9, v105
	v_mul_f32_e32 v106, v10, v106
	v_mul_f32_e32 v107, v11, v107
	v_fma_f32 v104, v104, v24, v40
	v_fma_f32 v105, v105, v25, v41
	v_fma_f32 v106, v106, v26, v42
	v_fma_f32 v107, v107, v27, v43
	v_cvt_pk_bf16_f32 v128, v104, v105
	v_cvt_pk_bf16_f32 v129, v106, v107
	global_store_dwordx2 v121, v[128:129], s[8:9] offset:1024
	v_mul_f32_e32 v108, v108, v115
	v_mul_f32_e32 v109, v109, v115
	v_mul_f32_e32 v110, v110, v115
	v_mul_f32_e32 v111, v111, v115
	v_mul_f32_e32 v108, v12, v108
	v_mul_f32_e32 v109, v13, v109
	v_mul_f32_e32 v110, v14, v110
	v_mul_f32_e32 v111, v15, v111
	v_fma_f32 v108, v108, v28, v44
	v_fma_f32 v109, v109, v29, v45
	v_fma_f32 v110, v110, v30, v46
	v_fma_f32 v111, v111, v31, v47
	v_cvt_pk_bf16_f32 v130, v108, v109
	v_cvt_pk_bf16_f32 v131, v110, v111
	global_store_dwordx2 v121, v[130:131], s[8:9] offset:1536
	s_add_u32 s8, s8, 0x20000
	s_addc_u32 s9, s9, 0
.Lrms_sub6_loop:
	global_load_dwordx4 v[48:51], v120, s[6:7] offset:0
	global_load_dwordx4 v[52:55], v120, s[6:7] offset:1024
	global_load_dwordx4 v[56:59], v120, s[6:7] offset:2048
	global_load_dwordx4 v[60:63], v120, s[6:7] offset:3072
	s_add_u32 s6, s6, 0x40000
	s_addc_u32 s7, s7, 0
	global_load_dwordx4 v[64:67], v120, s[6:7] offset:0
	global_load_dwordx4 v[68:71], v120, s[6:7] offset:1024
	global_load_dwordx4 v[72:75], v120, s[6:7] offset:2048
	global_load_dwordx4 v[76:79], v120, s[6:7] offset:3072
	s_add_u32 s6, s6, 0x40000
	s_addc_u32 s7, s7, 0
	global_load_dwordx4 v[80:83], v120, s[6:7] offset:0
	global_load_dwordx4 v[84:87], v120, s[6:7] offset:1024
	global_load_dwordx4 v[88:91], v120, s[6:7] offset:2048
	global_load_dwordx4 v[92:95], v120, s[6:7] offset:3072
	s_add_u32 s6, s6, 0x40000
	s_addc_u32 s7, s7, 0
	global_load_dwordx4 v[96:99], v120, s[6:7] offset:0
	global_load_dwordx4 v[100:103], v120, s[6:7] offset:1024
	global_load_dwordx4 v[104:107], v120, s[6:7] offset:2048
	global_load_dwordx4 v[108:111], v120, s[6:7] offset:3072
	s_add_u32 s6, s6, 0x40000
	s_addc_u32 s7, s7, 0
	s_waitcnt vmcnt(44)
	v_mul_f32_e32 v112, v132, v132
	v_fmac_f32_e32 v112, v133, v133
	v_fmac_f32_e32 v112, v134, v134
	v_fmac_f32_e32 v112, v135, v135
	v_fmac_f32_e32 v112, v136, v136
	v_fmac_f32_e32 v112, v137, v137
	v_fmac_f32_e32 v112, v138, v138
	v_fmac_f32_e32 v112, v139, v139
	v_fmac_f32_e32 v112, v140, v140
	v_fmac_f32_e32 v112, v141, v141
	v_fmac_f32_e32 v112, v142, v142
	v_fmac_f32_e32 v112, v143, v143
	v_fmac_f32_e32 v112, v144, v144
	v_fmac_f32_e32 v112, v145, v145
	v_fmac_f32_e32 v112, v146, v146
	v_fmac_f32_e32 v112, v147, v147
	s_waitcnt vmcnt(40)
	v_mul_f32_e32 v113, v166, v166
	v_fmac_f32_e32 v113, v167, v167
	v_fmac_f32_e32 v113, v168, v168
	v_fmac_f32_e32 v113, v169, v169
	v_fmac_f32_e32 v113, v170, v170
	v_fmac_f32_e32 v113, v171, v171
	v_fmac_f32_e32 v113, v172, v172
	v_fmac_f32_e32 v113, v173, v173
	v_fmac_f32_e32 v113, v174, v174
	v_fmac_f32_e32 v113, v175, v175
	v_fmac_f32_e32 v113, v176, v176
	v_fmac_f32_e32 v113, v177, v177
	v_fmac_f32_e32 v113, v178, v178
	v_fmac_f32_e32 v113, v179, v179
	v_fmac_f32_e32 v113, v180, v180
	v_fmac_f32_e32 v113, v181, v181
	s_waitcnt vmcnt(36)
	v_mul_f32_e32 v114, v182, v182
	v_fmac_f32_e32 v114, v183, v183
	v_fmac_f32_e32 v114, v184, v184
	v_fmac_f32_e32 v114, v185, v185
	v_fmac_f32_e32 v114, v186, v186
	v_fmac_f32_e32 v114, v187, v187
	v_fmac_f32_e32 v114, v188, v188
	v_fmac_f32_e32 v114, v189, v189
	v_fmac_f32_e32 v114, v190, v190
	v_fmac_f32_e32 v114, v191, v191
	v_fmac_f32_e32 v114, v192, v192
	v_fmac_f32_e32 v114, v193, v193
	v_fmac_f32_e32 v114, v194, v194
	v_fmac_f32_e32 v114, v195, v195
	v_fmac_f32_e32 v114, v196, v196
	v_fmac_f32_e32 v114, v197, v197
	s_waitcnt vmcnt(32)
	v_mul_f32_e32 v115, v228, v228
	v_fmac_f32_e32 v115, v229, v229
	v_fmac_f32_e32 v115, v230, v230
	v_fmac_f32_e32 v115, v231, v231
	v_fmac_f32_e32 v115, v232, v232
	v_fmac_f32_e32 v115, v233, v233
	v_fmac_f32_e32 v115, v234, v234
	v_fmac_f32_e32 v115, v235, v235
	v_fmac_f32_e32 v115, v236, v236
	v_fmac_f32_e32 v115, v237, v237
	v_fmac_f32_e32 v115, v238, v238
	v_fmac_f32_e32 v115, v239, v239
	v_fmac_f32_e32 v115, v240, v240
	v_fmac_f32_e32 v115, v241, v241
	v_fmac_f32_e32 v115, v242, v242
	v_fmac_f32_e32 v115, v243, v243
	ds_bpermute_b32 v116, v122, v112
	ds_bpermute_b32 v117, v122, v113
	ds_bpermute_b32 v118, v122, v114
	ds_bpermute_b32 v119, v122, v115
	s_waitcnt lgkmcnt(0)
	v_add_f32_e32 v112, v112, v116
	v_add_f32_e32 v113, v113, v117
	v_add_f32_e32 v114, v114, v118
	v_add_f32_e32 v115, v115, v119
	ds_bpermute_b32 v116, v123, v112
	ds_bpermute_b32 v117, v123, v113
	ds_bpermute_b32 v118, v123, v114
	ds_bpermute_b32 v119, v123, v115
	s_waitcnt lgkmcnt(0)
	v_add_f32_e32 v112, v112, v116
	v_add_f32_e32 v113, v113, v117
	v_add_f32_e32 v114, v114, v118
	v_add_f32_e32 v115, v115, v119
	ds_bpermute_b32 v116, v124, v112
	ds_bpermute_b32 v117, v124, v113
	ds_bpermute_b32 v118, v124, v114
	ds_bpermute_b32 v119, v124, v115
	s_waitcnt lgkmcnt(0)
	v_add_f32_e32 v112, v112, v116
	v_add_f32_e32 v113, v113, v117
	v_add_f32_e32 v114, v114, v118
	v_add_f32_e32 v115, v115, v119
	ds_bpermute_b32 v116, v125, v112
	ds_bpermute_b32 v117, v125, v113
	ds_bpermute_b32 v118, v125, v114
	ds_bpermute_b32 v119, v125, v115
	s_waitcnt lgkmcnt(0)
	v_add_f32_e32 v112, v112, v116
	v_add_f32_e32 v113, v113, v117
	v_add_f32_e32 v114, v114, v118
	v_add_f32_e32 v115, v115, v119
	ds_bpermute_b32 v116, v126, v112
	ds_bpermute_b32 v117, v126, v113
	ds_bpermute_b32 v118, v126, v114
	ds_bpermute_b32 v119, v126, v115
	s_waitcnt lgkmcnt(0)
	v_add_f32_e32 v112, v112, v116
	v_add_f32_e32 v113, v113, v117
	v_add_f32_e32 v114, v114, v118
	v_add_f32_e32 v115, v115, v119
	ds_bpermute_b32 v116, v127, v112
	ds_bpermute_b32 v117, v127, v113
	ds_bpermute_b32 v118, v127, v114
	ds_bpermute_b32 v119, v127, v115
	s_waitcnt lgkmcnt(0)
	v_add_f32_e32 v112, v112, v116
	v_add_f32_e32 v113, v113, v117
	v_add_f32_e32 v114, v114, v118
	v_add_f32_e32 v115, v115, v119
	v_fmamk_f32 v112, v112, 0x3a800000, v208
	v_fmamk_f32 v113, v113, 0x3a800000, v208
	v_fmamk_f32 v114, v114, 0x3a800000, v208
	v_fmamk_f32 v115, v115, 0x3a800000, v208
	v_rsq_f32_e32 v112, v112
	v_rsq_f32_e32 v113, v113
	v_rsq_f32_e32 v114, v114
	v_rsq_f32_e32 v115, v115
	s_nop 1
	v_mul_f32_e32 v132, v132, v112
	v_mul_f32_e32 v133, v133, v112
	v_mul_f32_e32 v134, v134, v112
	v_mul_f32_e32 v135, v135, v112
	v_mul_f32_e32 v132, v0, v132
	v_mul_f32_e32 v133, v1, v133
	v_mul_f32_e32 v134, v2, v134
	v_mul_f32_e32 v135, v3, v135
	v_fma_f32 v132, v132, v16, v32
	v_fma_f32 v133, v133, v17, v33
	v_fma_f32 v134, v134, v18, v34
	v_fma_f32 v135, v135, v19, v35
	v_cvt_pk_bf16_f32 v128, v132, v133
	v_cvt_pk_bf16_f32 v129, v134, v135
	global_store_dwordx2 v121, v[128:129], s[8:9] offset:0
	v_mul_f32_e32 v136, v136, v112
	v_mul_f32_e32 v137, v137, v112
	v_mul_f32_e32 v138, v138, v112
	v_mul_f32_e32 v139, v139, v112
	v_mul_f32_e32 v136, v4, v136
	v_mul_f32_e32 v137, v5, v137
	v_mul_f32_e32 v138, v6, v138
	v_mul_f32_e32 v139, v7, v139
	v_fma_f32 v136, v136, v20, v36
	v_fma_f32 v137, v137, v21, v37
	v_fma_f32 v138, v138, v22, v38
	v_fma_f32 v139, v139, v23, v39
	v_cvt_pk_bf16_f32 v130, v136, v137
	v_cvt_pk_bf16_f32 v131, v138, v139
	global_store_dwordx2 v121, v[130:131], s[8:9] offset:512
	v_mul_f32_e32 v140, v140, v112
	v_mul_f32_e32 v141, v141, v112
	v_mul_f32_e32 v142, v142, v112
	v_mul_f32_e32 v143, v143, v112
	v_mul_f32_e32 v140, v8, v140
	v_mul_f32_e32 v141, v9, v141
	v_mul_f32_e32 v142, v10, v142
	v_mul_f32_e32 v143, v11, v143
	v_fma_f32 v140, v140, v24, v40
	v_fma_f32 v141, v141, v25, v41
	v_fma_f32 v142, v142, v26, v42
	v_fma_f32 v143, v143, v27, v43
	v_cvt_pk_bf16_f32 v128, v140, v141
	v_cvt_pk_bf16_f32 v129, v142, v143
	global_store_dwordx2 v121, v[128:129], s[8:9] offset:1024
	v_mul_f32_e32 v144, v144, v112
	v_mul_f32_e32 v145, v145, v112
	v_mul_f32_e32 v146, v146, v112
	v_mul_f32_e32 v147, v147, v112
	v_mul_f32_e32 v144, v12, v144
	v_mul_f32_e32 v145, v13, v145
	v_mul_f32_e32 v146, v14, v146
	v_mul_f32_e32 v147, v15, v147
	v_fma_f32 v144, v144, v28, v44
	v_fma_f32 v145, v145, v29, v45
	v_fma_f32 v146, v146, v30, v46
	v_fma_f32 v147, v147, v31, v47
	v_cvt_pk_bf16_f32 v130, v144, v145
	v_cvt_pk_bf16_f32 v131, v146, v147
	global_store_dwordx2 v121, v[130:131], s[8:9] offset:1536
	s_add_u32 s8, s8, 0x20000
	s_addc_u32 s9, s9, 0
	v_mul_f32_e32 v166, v166, v113
	v_mul_f32_e32 v167, v167, v113
	v_mul_f32_e32 v168, v168, v113
	v_mul_f32_e32 v169, v169, v113
	v_mul_f32_e32 v166, v0, v166
	v_mul_f32_e32 v167, v1, v167
	v_mul_f32_e32 v168, v2, v168
	v_mul_f32_e32 v169, v3, v169
	v_fma_f32 v166, v166, v16, v32
	v_fma_f32 v167, v167, v17, v33
	v_fma_f32 v168, v168, v18, v34
	v_fma_f32 v169, v169, v19, v35
	v_cvt_pk_bf16_f32 v128, v166, v167
	v_cvt_pk_bf16_f32 v129, v168, v169
	global_store_dwordx2 v121, v[128:129], s[8:9] offset:0
	v_mul_f32_e32 v170, v170, v113
	v_mul_f32_e32 v171, v171, v113
	v_mul_f32_e32 v172, v172, v113
	v_mul_f32_e32 v173, v173, v113
	v_mul_f32_e32 v170, v4, v170
	v_mul_f32_e32 v171, v5, v171
	v_mul_f32_e32 v172, v6, v172
	v_mul_f32_e32 v173, v7, v173
	v_fma_f32 v170, v170, v20, v36
	v_fma_f32 v171, v171, v21, v37
	v_fma_f32 v172, v172, v22, v38
	v_fma_f32 v173, v173, v23, v39
	v_cvt_pk_bf16_f32 v130, v170, v171
	v_cvt_pk_bf16_f32 v131, v172, v173
	global_store_dwordx2 v121, v[130:131], s[8:9] offset:512
	v_mul_f32_e32 v174, v174, v113
	v_mul_f32_e32 v175, v175, v113
	v_mul_f32_e32 v176, v176, v113
	v_mul_f32_e32 v177, v177, v113
	v_mul_f32_e32 v174, v8, v174
	v_mul_f32_e32 v175, v9, v175
	v_mul_f32_e32 v176, v10, v176
	v_mul_f32_e32 v177, v11, v177
	v_fma_f32 v174, v174, v24, v40
	v_fma_f32 v175, v175, v25, v41
	v_fma_f32 v176, v176, v26, v42
	v_fma_f32 v177, v177, v27, v43
	v_cvt_pk_bf16_f32 v128, v174, v175
	v_cvt_pk_bf16_f32 v129, v176, v177
	global_store_dwordx2 v121, v[128:129], s[8:9] offset:1024
	v_mul_f32_e32 v178, v178, v113
	v_mul_f32_e32 v179, v179, v113
	v_mul_f32_e32 v180, v180, v113
	v_mul_f32_e32 v181, v181, v113
	v_mul_f32_e32 v178, v12, v178
	v_mul_f32_e32 v179, v13, v179
	v_mul_f32_e32 v180, v14, v180
	v_mul_f32_e32 v181, v15, v181
	v_fma_f32 v178, v178, v28, v44
	v_fma_f32 v179, v179, v29, v45
	v_fma_f32 v180, v180, v30, v46
	v_fma_f32 v181, v181, v31, v47
	v_cvt_pk_bf16_f32 v130, v178, v179
	v_cvt_pk_bf16_f32 v131, v180, v181
	global_store_dwordx2 v121, v[130:131], s[8:9] offset:1536
	s_add_u32 s8, s8, 0x20000
	s_addc_u32 s9, s9, 0
	v_mul_f32_e32 v182, v182, v114
	v_mul_f32_e32 v183, v183, v114
	v_mul_f32_e32 v184, v184, v114
	v_mul_f32_e32 v185, v185, v114
	v_mul_f32_e32 v182, v0, v182
	v_mul_f32_e32 v183, v1, v183
	v_mul_f32_e32 v184, v2, v184
	v_mul_f32_e32 v185, v3, v185
	v_fma_f32 v182, v182, v16, v32
	v_fma_f32 v183, v183, v17, v33
	v_fma_f32 v184, v184, v18, v34
	v_fma_f32 v185, v185, v19, v35
	v_cvt_pk_bf16_f32 v128, v182, v183
	v_cvt_pk_bf16_f32 v129, v184, v185
	global_store_dwordx2 v121, v[128:129], s[8:9] offset:0
	v_mul_f32_e32 v186, v186, v114
	v_mul_f32_e32 v187, v187, v114
	v_mul_f32_e32 v188, v188, v114
	v_mul_f32_e32 v189, v189, v114
	v_mul_f32_e32 v186, v4, v186
	v_mul_f32_e32 v187, v5, v187
	v_mul_f32_e32 v188, v6, v188
	v_mul_f32_e32 v189, v7, v189
	v_fma_f32 v186, v186, v20, v36
	v_fma_f32 v187, v187, v21, v37
	v_fma_f32 v188, v188, v22, v38
	v_fma_f32 v189, v189, v23, v39
	v_cvt_pk_bf16_f32 v130, v186, v187
	v_cvt_pk_bf16_f32 v131, v188, v189
	global_store_dwordx2 v121, v[130:131], s[8:9] offset:512
	v_mul_f32_e32 v190, v190, v114
	v_mul_f32_e32 v191, v191, v114
	v_mul_f32_e32 v192, v192, v114
	v_mul_f32_e32 v193, v193, v114
	v_mul_f32_e32 v190, v8, v190
	v_mul_f32_e32 v191, v9, v191
	v_mul_f32_e32 v192, v10, v192
	v_mul_f32_e32 v193, v11, v193
	v_fma_f32 v190, v190, v24, v40
	v_fma_f32 v191, v191, v25, v41
	v_fma_f32 v192, v192, v26, v42
	v_fma_f32 v193, v193, v27, v43
	v_cvt_pk_bf16_f32 v128, v190, v191
	v_cvt_pk_bf16_f32 v129, v192, v193
	global_store_dwordx2 v121, v[128:129], s[8:9] offset:1024
	v_mul_f32_e32 v194, v194, v114
	v_mul_f32_e32 v195, v195, v114
	v_mul_f32_e32 v196, v196, v114
	v_mul_f32_e32 v197, v197, v114
	v_mul_f32_e32 v194, v12, v194
	v_mul_f32_e32 v195, v13, v195
	v_mul_f32_e32 v196, v14, v196
	v_mul_f32_e32 v197, v15, v197
	v_fma_f32 v194, v194, v28, v44
	v_fma_f32 v195, v195, v29, v45
	v_fma_f32 v196, v196, v30, v46
	v_fma_f32 v197, v197, v31, v47
	v_cvt_pk_bf16_f32 v130, v194, v195
	v_cvt_pk_bf16_f32 v131, v196, v197
	global_store_dwordx2 v121, v[130:131], s[8:9] offset:1536
	s_add_u32 s8, s8, 0x20000
	s_addc_u32 s9, s9, 0
	v_mul_f32_e32 v228, v228, v115
	v_mul_f32_e32 v229, v229, v115
	v_mul_f32_e32 v230, v230, v115
	v_mul_f32_e32 v231, v231, v115
	v_mul_f32_e32 v228, v0, v228
	v_mul_f32_e32 v229, v1, v229
	v_mul_f32_e32 v230, v2, v230
	v_mul_f32_e32 v231, v3, v231
	v_fma_f32 v228, v228, v16, v32
	v_fma_f32 v229, v229, v17, v33
	v_fma_f32 v230, v230, v18, v34
	v_fma_f32 v231, v231, v19, v35
	v_cvt_pk_bf16_f32 v128, v228, v229
	v_cvt_pk_bf16_f32 v129, v230, v231
	global_store_dwordx2 v121, v[128:129], s[8:9] offset:0
	v_mul_f32_e32 v232, v232, v115
	v_mul_f32_e32 v233, v233, v115
	v_mul_f32_e32 v234, v234, v115
	v_mul_f32_e32 v235, v235, v115
	v_mul_f32_e32 v232, v4, v232
	v_mul_f32_e32 v233, v5, v233
	v_mul_f32_e32 v234, v6, v234
	v_mul_f32_e32 v235, v7, v235
	v_fma_f32 v232, v232, v20, v36
	v_fma_f32 v233, v233, v21, v37
	v_fma_f32 v234, v234, v22, v38
	v_fma_f32 v235, v235, v23, v39
	v_cvt_pk_bf16_f32 v130, v232, v233
	v_cvt_pk_bf16_f32 v131, v234, v235
	global_store_dwordx2 v121, v[130:131], s[8:9] offset:512
	v_mul_f32_e32 v236, v236, v115
	v_mul_f32_e32 v237, v237, v115
	v_mul_f32_e32 v238, v238, v115
	v_mul_f32_e32 v239, v239, v115
	v_mul_f32_e32 v236, v8, v236
	v_mul_f32_e32 v237, v9, v237
	v_mul_f32_e32 v238, v10, v238
	v_mul_f32_e32 v239, v11, v239
	v_fma_f32 v236, v236, v24, v40
	v_fma_f32 v237, v237, v25, v41
	v_fma_f32 v238, v238, v26, v42
	v_fma_f32 v239, v239, v27, v43
	v_cvt_pk_bf16_f32 v128, v236, v237
	v_cvt_pk_bf16_f32 v129, v238, v239
	global_store_dwordx2 v121, v[128:129], s[8:9] offset:1024
	v_mul_f32_e32 v240, v240, v115
	v_mul_f32_e32 v241, v241, v115
	v_mul_f32_e32 v242, v242, v115
	v_mul_f32_e32 v243, v243, v115
	v_mul_f32_e32 v240, v12, v240
	v_mul_f32_e32 v241, v13, v241
	v_mul_f32_e32 v242, v14, v242
	v_mul_f32_e32 v243, v15, v243
	v_fma_f32 v240, v240, v28, v44
	v_fma_f32 v241, v241, v29, v45
	v_fma_f32 v242, v242, v30, v46
	v_fma_f32 v243, v243, v31, v47
	v_cvt_pk_bf16_f32 v130, v240, v241
	v_cvt_pk_bf16_f32 v131, v242, v243
	global_store_dwordx2 v121, v[130:131], s[8:9] offset:1536
	s_add_u32 s8, s8, 0x20000
	s_addc_u32 s9, s9, 0
	global_load_dwordx4 v[132:135], v120, s[6:7] offset:0
	global_load_dwordx4 v[136:139], v120, s[6:7] offset:1024
	global_load_dwordx4 v[140:143], v120, s[6:7] offset:2048
	global_load_dwordx4 v[144:147], v120, s[6:7] offset:3072
	s_add_u32 s6, s6, 0x40000
	s_addc_u32 s7, s7, 0
	global_load_dwordx4 v[166:169], v120, s[6:7] offset:0
	global_load_dwordx4 v[170:173], v120, s[6:7] offset:1024
	global_load_dwordx4 v[174:177], v120, s[6:7] offset:2048
	global_load_dwordx4 v[178:181], v120, s[6:7] offset:3072
	s_add_u32 s6, s6, 0x40000
	s_addc_u32 s7, s7, 0
	global_load_dwordx4 v[182:185], v120, s[6:7] offset:0
	global_load_dwordx4 v[186:189], v120, s[6:7] offset:1024
	global_load_dwordx4 v[190:193], v120, s[6:7] offset:2048
	global_load_dwordx4 v[194:197], v120, s[6:7] offset:3072
	s_add_u32 s6, s6, 0x40000
	s_addc_u32 s7, s7, 0
	global_load_dwordx4 v[228:231], v120, s[6:7] offset:0
	global_load_dwordx4 v[232:235], v120, s[6:7] offset:1024
	global_load_dwordx4 v[236:239], v120, s[6:7] offset:2048
	global_load_dwordx4 v[240:243], v120, s[6:7] offset:3072
	s_add_u32 s6, s6, 0x40000
	s_addc_u32 s7, s7, 0
	s_waitcnt vmcnt(44)
	v_mul_f32_e32 v112, v48, v48
	v_fmac_f32_e32 v112, v49, v49
	v_fmac_f32_e32 v112, v50, v50
	v_fmac_f32_e32 v112, v51, v51
	v_fmac_f32_e32 v112, v52, v52
	v_fmac_f32_e32 v112, v53, v53
	v_fmac_f32_e32 v112, v54, v54
	v_fmac_f32_e32 v112, v55, v55
	v_fmac_f32_e32 v112, v56, v56
	v_fmac_f32_e32 v112, v57, v57
	v_fmac_f32_e32 v112, v58, v58
	v_fmac_f32_e32 v112, v59, v59
	v_fmac_f32_e32 v112, v60, v60
	v_fmac_f32_e32 v112, v61, v61
	v_fmac_f32_e32 v112, v62, v62
	v_fmac_f32_e32 v112, v63, v63
	s_waitcnt vmcnt(40)
	v_mul_f32_e32 v113, v64, v64
	v_fmac_f32_e32 v113, v65, v65
	v_fmac_f32_e32 v113, v66, v66
	v_fmac_f32_e32 v113, v67, v67
	v_fmac_f32_e32 v113, v68, v68
	v_fmac_f32_e32 v113, v69, v69
	v_fmac_f32_e32 v113, v70, v70
	v_fmac_f32_e32 v113, v71, v71
	v_fmac_f32_e32 v113, v72, v72
	v_fmac_f32_e32 v113, v73, v73
	v_fmac_f32_e32 v113, v74, v74
	v_fmac_f32_e32 v113, v75, v75
	v_fmac_f32_e32 v113, v76, v76
	v_fmac_f32_e32 v113, v77, v77
	v_fmac_f32_e32 v113, v78, v78
	v_fmac_f32_e32 v113, v79, v79
	s_waitcnt vmcnt(36)
	v_mul_f32_e32 v114, v80, v80
	v_fmac_f32_e32 v114, v81, v81
	v_fmac_f32_e32 v114, v82, v82
	v_fmac_f32_e32 v114, v83, v83
	v_fmac_f32_e32 v114, v84, v84
	v_fmac_f32_e32 v114, v85, v85
	v_fmac_f32_e32 v114, v86, v86
	v_fmac_f32_e32 v114, v87, v87
	v_fmac_f32_e32 v114, v88, v88
	v_fmac_f32_e32 v114, v89, v89
	v_fmac_f32_e32 v114, v90, v90
	v_fmac_f32_e32 v114, v91, v91
	v_fmac_f32_e32 v114, v92, v92
	v_fmac_f32_e32 v114, v93, v93
	v_fmac_f32_e32 v114, v94, v94
	v_fmac_f32_e32 v114, v95, v95
	s_waitcnt vmcnt(32)
	v_mul_f32_e32 v115, v96, v96
	v_fmac_f32_e32 v115, v97, v97
	v_fmac_f32_e32 v115, v98, v98
	v_fmac_f32_e32 v115, v99, v99
	v_fmac_f32_e32 v115, v100, v100
	v_fmac_f32_e32 v115, v101, v101
	v_fmac_f32_e32 v115, v102, v102
	v_fmac_f32_e32 v115, v103, v103
	v_fmac_f32_e32 v115, v104, v104
	v_fmac_f32_e32 v115, v105, v105
	v_fmac_f32_e32 v115, v106, v106
	v_fmac_f32_e32 v115, v107, v107
	v_fmac_f32_e32 v115, v108, v108
	v_fmac_f32_e32 v115, v109, v109
	v_fmac_f32_e32 v115, v110, v110
	v_fmac_f32_e32 v115, v111, v111
	ds_bpermute_b32 v116, v122, v112
	ds_bpermute_b32 v117, v122, v113
	ds_bpermute_b32 v118, v122, v114
	ds_bpermute_b32 v119, v122, v115
	s_waitcnt lgkmcnt(0)
	v_add_f32_e32 v112, v112, v116
	v_add_f32_e32 v113, v113, v117
	v_add_f32_e32 v114, v114, v118
	v_add_f32_e32 v115, v115, v119
	ds_bpermute_b32 v116, v123, v112
	ds_bpermute_b32 v117, v123, v113
	ds_bpermute_b32 v118, v123, v114
	ds_bpermute_b32 v119, v123, v115
	s_waitcnt lgkmcnt(0)
	v_add_f32_e32 v112, v112, v116
	v_add_f32_e32 v113, v113, v117
	v_add_f32_e32 v114, v114, v118
	v_add_f32_e32 v115, v115, v119
	ds_bpermute_b32 v116, v124, v112
	ds_bpermute_b32 v117, v124, v113
	ds_bpermute_b32 v118, v124, v114
	ds_bpermute_b32 v119, v124, v115
	s_waitcnt lgkmcnt(0)
	v_add_f32_e32 v112, v112, v116
	v_add_f32_e32 v113, v113, v117
	v_add_f32_e32 v114, v114, v118
	v_add_f32_e32 v115, v115, v119
	ds_bpermute_b32 v116, v125, v112
	ds_bpermute_b32 v117, v125, v113
	ds_bpermute_b32 v118, v125, v114
	ds_bpermute_b32 v119, v125, v115
	s_waitcnt lgkmcnt(0)
	v_add_f32_e32 v112, v112, v116
	v_add_f32_e32 v113, v113, v117
	v_add_f32_e32 v114, v114, v118
	v_add_f32_e32 v115, v115, v119
	ds_bpermute_b32 v116, v126, v112
	ds_bpermute_b32 v117, v126, v113
	ds_bpermute_b32 v118, v126, v114
	ds_bpermute_b32 v119, v126, v115
	s_waitcnt lgkmcnt(0)
	v_add_f32_e32 v112, v112, v116
	v_add_f32_e32 v113, v113, v117
	v_add_f32_e32 v114, v114, v118
	v_add_f32_e32 v115, v115, v119
	ds_bpermute_b32 v116, v127, v112
	ds_bpermute_b32 v117, v127, v113
	ds_bpermute_b32 v118, v127, v114
	ds_bpermute_b32 v119, v127, v115
	s_waitcnt lgkmcnt(0)
	v_add_f32_e32 v112, v112, v116
	v_add_f32_e32 v113, v113, v117
	v_add_f32_e32 v114, v114, v118
	v_add_f32_e32 v115, v115, v119
	v_fmamk_f32 v112, v112, 0x3a800000, v208
	v_fmamk_f32 v113, v113, 0x3a800000, v208
	v_fmamk_f32 v114, v114, 0x3a800000, v208
	v_fmamk_f32 v115, v115, 0x3a800000, v208
	v_rsq_f32_e32 v112, v112
	v_rsq_f32_e32 v113, v113
	v_rsq_f32_e32 v114, v114
	v_rsq_f32_e32 v115, v115
	s_nop 1
	v_mul_f32_e32 v48, v48, v112
	v_mul_f32_e32 v49, v49, v112
	v_mul_f32_e32 v50, v50, v112
	v_mul_f32_e32 v51, v51, v112
	v_mul_f32_e32 v48, v0, v48
	v_mul_f32_e32 v49, v1, v49
	v_mul_f32_e32 v50, v2, v50
	v_mul_f32_e32 v51, v3, v51
	v_fma_f32 v48, v48, v16, v32
	v_fma_f32 v49, v49, v17, v33
	v_fma_f32 v50, v50, v18, v34
	v_fma_f32 v51, v51, v19, v35
	v_cvt_pk_bf16_f32 v128, v48, v49
	v_cvt_pk_bf16_f32 v129, v50, v51
	global_store_dwordx2 v121, v[128:129], s[8:9] offset:0
	v_mul_f32_e32 v52, v52, v112
	v_mul_f32_e32 v53, v53, v112
	v_mul_f32_e32 v54, v54, v112
	v_mul_f32_e32 v55, v55, v112
	v_mul_f32_e32 v52, v4, v52
	v_mul_f32_e32 v53, v5, v53
	v_mul_f32_e32 v54, v6, v54
	v_mul_f32_e32 v55, v7, v55
	v_fma_f32 v52, v52, v20, v36
	v_fma_f32 v53, v53, v21, v37
	v_fma_f32 v54, v54, v22, v38
	v_fma_f32 v55, v55, v23, v39
	v_cvt_pk_bf16_f32 v130, v52, v53
	v_cvt_pk_bf16_f32 v131, v54, v55
	global_store_dwordx2 v121, v[130:131], s[8:9] offset:512
	v_mul_f32_e32 v56, v56, v112
	v_mul_f32_e32 v57, v57, v112
	v_mul_f32_e32 v58, v58, v112
	v_mul_f32_e32 v59, v59, v112
	v_mul_f32_e32 v56, v8, v56
	v_mul_f32_e32 v57, v9, v57
	v_mul_f32_e32 v58, v10, v58
	v_mul_f32_e32 v59, v11, v59
	v_fma_f32 v56, v56, v24, v40
	v_fma_f32 v57, v57, v25, v41
	v_fma_f32 v58, v58, v26, v42
	v_fma_f32 v59, v59, v27, v43
	v_cvt_pk_bf16_f32 v128, v56, v57
	v_cvt_pk_bf16_f32 v129, v58, v59
	global_store_dwordx2 v121, v[128:129], s[8:9] offset:1024
	v_mul_f32_e32 v60, v60, v112
	v_mul_f32_e32 v61, v61, v112
	v_mul_f32_e32 v62, v62, v112
	v_mul_f32_e32 v63, v63, v112
	v_mul_f32_e32 v60, v12, v60
	v_mul_f32_e32 v61, v13, v61
	v_mul_f32_e32 v62, v14, v62
	v_mul_f32_e32 v63, v15, v63
	v_fma_f32 v60, v60, v28, v44
	v_fma_f32 v61, v61, v29, v45
	v_fma_f32 v62, v62, v30, v46
	v_fma_f32 v63, v63, v31, v47
	v_cvt_pk_bf16_f32 v130, v60, v61
	v_cvt_pk_bf16_f32 v131, v62, v63
	global_store_dwordx2 v121, v[130:131], s[8:9] offset:1536
	s_add_u32 s8, s8, 0x20000
	s_addc_u32 s9, s9, 0
	v_mul_f32_e32 v64, v64, v113
	v_mul_f32_e32 v65, v65, v113
	v_mul_f32_e32 v66, v66, v113
	v_mul_f32_e32 v67, v67, v113
	v_mul_f32_e32 v64, v0, v64
	v_mul_f32_e32 v65, v1, v65
	v_mul_f32_e32 v66, v2, v66
	v_mul_f32_e32 v67, v3, v67
	v_fma_f32 v64, v64, v16, v32
	v_fma_f32 v65, v65, v17, v33
	v_fma_f32 v66, v66, v18, v34
	v_fma_f32 v67, v67, v19, v35
	v_cvt_pk_bf16_f32 v128, v64, v65
	v_cvt_pk_bf16_f32 v129, v66, v67
	global_store_dwordx2 v121, v[128:129], s[8:9] offset:0
	v_mul_f32_e32 v68, v68, v113
	v_mul_f32_e32 v69, v69, v113
	v_mul_f32_e32 v70, v70, v113
	v_mul_f32_e32 v71, v71, v113
	v_mul_f32_e32 v68, v4, v68
	v_mul_f32_e32 v69, v5, v69
	v_mul_f32_e32 v70, v6, v70
	v_mul_f32_e32 v71, v7, v71
	v_fma_f32 v68, v68, v20, v36
	v_fma_f32 v69, v69, v21, v37
	v_fma_f32 v70, v70, v22, v38
	v_fma_f32 v71, v71, v23, v39
	v_cvt_pk_bf16_f32 v130, v68, v69
	v_cvt_pk_bf16_f32 v131, v70, v71
	global_store_dwordx2 v121, v[130:131], s[8:9] offset:512
	v_mul_f32_e32 v72, v72, v113
	v_mul_f32_e32 v73, v73, v113
	v_mul_f32_e32 v74, v74, v113
	v_mul_f32_e32 v75, v75, v113
	v_mul_f32_e32 v72, v8, v72
	v_mul_f32_e32 v73, v9, v73
	v_mul_f32_e32 v74, v10, v74
	v_mul_f32_e32 v75, v11, v75
	v_fma_f32 v72, v72, v24, v40
	v_fma_f32 v73, v73, v25, v41
	v_fma_f32 v74, v74, v26, v42
	v_fma_f32 v75, v75, v27, v43
	v_cvt_pk_bf16_f32 v128, v72, v73
	v_cvt_pk_bf16_f32 v129, v74, v75
	global_store_dwordx2 v121, v[128:129], s[8:9] offset:1024
	v_mul_f32_e32 v76, v76, v113
	v_mul_f32_e32 v77, v77, v113
	v_mul_f32_e32 v78, v78, v113
	v_mul_f32_e32 v79, v79, v113
	v_mul_f32_e32 v76, v12, v76
	v_mul_f32_e32 v77, v13, v77
	v_mul_f32_e32 v78, v14, v78
	v_mul_f32_e32 v79, v15, v79
	v_fma_f32 v76, v76, v28, v44
	v_fma_f32 v77, v77, v29, v45
	v_fma_f32 v78, v78, v30, v46
	v_fma_f32 v79, v79, v31, v47
	v_cvt_pk_bf16_f32 v130, v76, v77
	v_cvt_pk_bf16_f32 v131, v78, v79
	global_store_dwordx2 v121, v[130:131], s[8:9] offset:1536
	s_add_u32 s8, s8, 0x20000
	s_addc_u32 s9, s9, 0
	v_mul_f32_e32 v80, v80, v114
	v_mul_f32_e32 v81, v81, v114
	v_mul_f32_e32 v82, v82, v114
	v_mul_f32_e32 v83, v83, v114
	v_mul_f32_e32 v80, v0, v80
	v_mul_f32_e32 v81, v1, v81
	v_mul_f32_e32 v82, v2, v82
	v_mul_f32_e32 v83, v3, v83
	v_fma_f32 v80, v80, v16, v32
	v_fma_f32 v81, v81, v17, v33
	v_fma_f32 v82, v82, v18, v34
	v_fma_f32 v83, v83, v19, v35
	v_cvt_pk_bf16_f32 v128, v80, v81
	v_cvt_pk_bf16_f32 v129, v82, v83
	global_store_dwordx2 v121, v[128:129], s[8:9] offset:0
	v_mul_f32_e32 v84, v84, v114
	v_mul_f32_e32 v85, v85, v114
	v_mul_f32_e32 v86, v86, v114
	v_mul_f32_e32 v87, v87, v114
	v_mul_f32_e32 v84, v4, v84
	v_mul_f32_e32 v85, v5, v85
	v_mul_f32_e32 v86, v6, v86
	v_mul_f32_e32 v87, v7, v87
	v_fma_f32 v84, v84, v20, v36
	v_fma_f32 v85, v85, v21, v37
	v_fma_f32 v86, v86, v22, v38
	v_fma_f32 v87, v87, v23, v39
	v_cvt_pk_bf16_f32 v130, v84, v85
	v_cvt_pk_bf16_f32 v131, v86, v87
	global_store_dwordx2 v121, v[130:131], s[8:9] offset:512
	v_mul_f32_e32 v88, v88, v114
	v_mul_f32_e32 v89, v89, v114
	v_mul_f32_e32 v90, v90, v114
	v_mul_f32_e32 v91, v91, v114
	v_mul_f32_e32 v88, v8, v88
	v_mul_f32_e32 v89, v9, v89
	v_mul_f32_e32 v90, v10, v90
	v_mul_f32_e32 v91, v11, v91
	v_fma_f32 v88, v88, v24, v40
	v_fma_f32 v89, v89, v25, v41
	v_fma_f32 v90, v90, v26, v42
	v_fma_f32 v91, v91, v27, v43
	v_cvt_pk_bf16_f32 v128, v88, v89
	v_cvt_pk_bf16_f32 v129, v90, v91
	global_store_dwordx2 v121, v[128:129], s[8:9] offset:1024
	v_mul_f32_e32 v92, v92, v114
	v_mul_f32_e32 v93, v93, v114
	v_mul_f32_e32 v94, v94, v114
	v_mul_f32_e32 v95, v95, v114
	v_mul_f32_e32 v92, v12, v92
	v_mul_f32_e32 v93, v13, v93
	v_mul_f32_e32 v94, v14, v94
	v_mul_f32_e32 v95, v15, v95
	v_fma_f32 v92, v92, v28, v44
	v_fma_f32 v93, v93, v29, v45
	v_fma_f32 v94, v94, v30, v46
	v_fma_f32 v95, v95, v31, v47
	v_cvt_pk_bf16_f32 v130, v92, v93
	v_cvt_pk_bf16_f32 v131, v94, v95
	global_store_dwordx2 v121, v[130:131], s[8:9] offset:1536
	s_add_u32 s8, s8, 0x20000
	s_addc_u32 s9, s9, 0
	v_mul_f32_e32 v96, v96, v115
	v_mul_f32_e32 v97, v97, v115
	v_mul_f32_e32 v98, v98, v115
	v_mul_f32_e32 v99, v99, v115
	v_mul_f32_e32 v96, v0, v96
	v_mul_f32_e32 v97, v1, v97
	v_mul_f32_e32 v98, v2, v98
	v_mul_f32_e32 v99, v3, v99
	v_fma_f32 v96, v96, v16, v32
	v_fma_f32 v97, v97, v17, v33
	v_fma_f32 v98, v98, v18, v34
	v_fma_f32 v99, v99, v19, v35
	v_cvt_pk_bf16_f32 v128, v96, v97
	v_cvt_pk_bf16_f32 v129, v98, v99
	global_store_dwordx2 v121, v[128:129], s[8:9] offset:0
	v_mul_f32_e32 v100, v100, v115
	v_mul_f32_e32 v101, v101, v115
	v_mul_f32_e32 v102, v102, v115
	v_mul_f32_e32 v103, v103, v115
	v_mul_f32_e32 v100, v4, v100
	v_mul_f32_e32 v101, v5, v101
	v_mul_f32_e32 v102, v6, v102
	v_mul_f32_e32 v103, v7, v103
	v_fma_f32 v100, v100, v20, v36
	v_fma_f32 v101, v101, v21, v37
	v_fma_f32 v102, v102, v22, v38
	v_fma_f32 v103, v103, v23, v39
	v_cvt_pk_bf16_f32 v130, v100, v101
	v_cvt_pk_bf16_f32 v131, v102, v103
	global_store_dwordx2 v121, v[130:131], s[8:9] offset:512
	v_mul_f32_e32 v104, v104, v115
	v_mul_f32_e32 v105, v105, v115
	v_mul_f32_e32 v106, v106, v115
	v_mul_f32_e32 v107, v107, v115
	v_mul_f32_e32 v104, v8, v104
	v_mul_f32_e32 v105, v9, v105
	v_mul_f32_e32 v106, v10, v106
	v_mul_f32_e32 v107, v11, v107
	v_fma_f32 v104, v104, v24, v40
	v_fma_f32 v105, v105, v25, v41
	v_fma_f32 v106, v106, v26, v42
	v_fma_f32 v107, v107, v27, v43
	v_cvt_pk_bf16_f32 v128, v104, v105
	v_cvt_pk_bf16_f32 v129, v106, v107
	global_store_dwordx2 v121, v[128:129], s[8:9] offset:1024
	v_mul_f32_e32 v108, v108, v115
	v_mul_f32_e32 v109, v109, v115
	v_mul_f32_e32 v110, v110, v115
	v_mul_f32_e32 v111, v111, v115
	v_mul_f32_e32 v108, v12, v108
	v_mul_f32_e32 v109, v13, v109
	v_mul_f32_e32 v110, v14, v110
	v_mul_f32_e32 v111, v15, v111
	v_fma_f32 v108, v108, v28, v44
	v_fma_f32 v109, v109, v29, v45
	v_fma_f32 v110, v110, v30, v46
	v_fma_f32 v111, v111, v31, v47
	v_cvt_pk_bf16_f32 v130, v108, v109
	v_cvt_pk_bf16_f32 v131, v110, v111
	global_store_dwordx2 v121, v[130:131], s[8:9] offset:1536
	s_add_u32 s8, s8, 0x20000
	s_addc_u32 s9, s9, 0
	s_sub_u32 s2, s2, 1
	s_cmp_lg_u32 s2, 0
	s_cbranch_scc1 .Lrms_sub6_loop
	s_waitcnt vmcnt(28)
	v_mul_f32_e32 v112, v132, v132
	v_fmac_f32_e32 v112, v133, v133
	v_fmac_f32_e32 v112, v134, v134
	v_fmac_f32_e32 v112, v135, v135
	v_fmac_f32_e32 v112, v136, v136
	v_fmac_f32_e32 v112, v137, v137
	v_fmac_f32_e32 v112, v138, v138
	v_fmac_f32_e32 v112, v139, v139
	v_fmac_f32_e32 v112, v140, v140
	v_fmac_f32_e32 v112, v141, v141
	v_fmac_f32_e32 v112, v142, v142
	v_fmac_f32_e32 v112, v143, v143
	v_fmac_f32_e32 v112, v144, v144
	v_fmac_f32_e32 v112, v145, v145
	v_fmac_f32_e32 v112, v146, v146
	v_fmac_f32_e32 v112, v147, v147
	s_waitcnt vmcnt(24)
	v_mul_f32_e32 v113, v166, v166
	v_fmac_f32_e32 v113, v167, v167
	v_fmac_f32_e32 v113, v168, v168
	v_fmac_f32_e32 v113, v169, v169
	v_fmac_f32_e32 v113, v170, v170
	v_fmac_f32_e32 v113, v171, v171
	v_fmac_f32_e32 v113, v172, v172
	v_fmac_f32_e32 v113, v173, v173
	v_fmac_f32_e32 v113, v174, v174
	v_fmac_f32_e32 v113, v175, v175
	v_fmac_f32_e32 v113, v176, v176
	v_fmac_f32_e32 v113, v177, v177
	v_fmac_f32_e32 v113, v178, v178
	v_fmac_f32_e32 v113, v179, v179
	v_fmac_f32_e32 v113, v180, v180
	v_fmac_f32_e32 v113, v181, v181
	s_waitcnt vmcnt(20)
	v_mul_f32_e32 v114, v182, v182
	v_fmac_f32_e32 v114, v183, v183
	v_fmac_f32_e32 v114, v184, v184
	v_fmac_f32_e32 v114, v185, v185
	v_fmac_f32_e32 v114, v186, v186
	v_fmac_f32_e32 v114, v187, v187
	v_fmac_f32_e32 v114, v188, v188
	v_fmac_f32_e32 v114, v189, v189
	v_fmac_f32_e32 v114, v190, v190
	v_fmac_f32_e32 v114, v191, v191
	v_fmac_f32_e32 v114, v192, v192
	v_fmac_f32_e32 v114, v193, v193
	v_fmac_f32_e32 v114, v194, v194
	v_fmac_f32_e32 v114, v195, v195
	v_fmac_f32_e32 v114, v196, v196
	v_fmac_f32_e32 v114, v197, v197
	s_waitcnt vmcnt(16)
	v_mul_f32_e32 v115, v228, v228
	v_fmac_f32_e32 v115, v229, v229
	v_fmac_f32_e32 v115, v230, v230
	v_fmac_f32_e32 v115, v231, v231
	v_fmac_f32_e32 v115, v232, v232
	v_fmac_f32_e32 v115, v233, v233
	v_fmac_f32_e32 v115, v234, v234
	v_fmac_f32_e32 v115, v235, v235
	v_fmac_f32_e32 v115, v236, v236
	v_fmac_f32_e32 v115, v237, v237
	v_fmac_f32_e32 v115, v238, v238
	v_fmac_f32_e32 v115, v239, v239
	v_fmac_f32_e32 v115, v240, v240
	v_fmac_f32_e32 v115, v241, v241
	v_fmac_f32_e32 v115, v242, v242
	v_fmac_f32_e32 v115, v243, v243
	ds_bpermute_b32 v116, v122, v112
	ds_bpermute_b32 v117, v122, v113
	ds_bpermute_b32 v118, v122, v114
	ds_bpermute_b32 v119, v122, v115
	s_waitcnt lgkmcnt(0)
	v_add_f32_e32 v112, v112, v116
	v_add_f32_e32 v113, v113, v117
	v_add_f32_e32 v114, v114, v118
	v_add_f32_e32 v115, v115, v119
	ds_bpermute_b32 v116, v123, v112
	ds_bpermute_b32 v117, v123, v113
	ds_bpermute_b32 v118, v123, v114
	ds_bpermute_b32 v119, v123, v115
	s_waitcnt lgkmcnt(0)
	v_add_f32_e32 v112, v112, v116
	v_add_f32_e32 v113, v113, v117
	v_add_f32_e32 v114, v114, v118
	v_add_f32_e32 v115, v115, v119
	ds_bpermute_b32 v116, v124, v112
	ds_bpermute_b32 v117, v124, v113
	ds_bpermute_b32 v118, v124, v114
	ds_bpermute_b32 v119, v124, v115
	s_waitcnt lgkmcnt(0)
	v_add_f32_e32 v112, v112, v116
	v_add_f32_e32 v113, v113, v117
	v_add_f32_e32 v114, v114, v118
	v_add_f32_e32 v115, v115, v119
	ds_bpermute_b32 v116, v125, v112
	ds_bpermute_b32 v117, v125, v113
	ds_bpermute_b32 v118, v125, v114
	ds_bpermute_b32 v119, v125, v115
	s_waitcnt lgkmcnt(0)
	v_add_f32_e32 v112, v112, v116
	v_add_f32_e32 v113, v113, v117
	v_add_f32_e32 v114, v114, v118
	v_add_f32_e32 v115, v115, v119
	ds_bpermute_b32 v116, v126, v112
	ds_bpermute_b32 v117, v126, v113
	ds_bpermute_b32 v118, v126, v114
	ds_bpermute_b32 v119, v126, v115
	s_waitcnt lgkmcnt(0)
	v_add_f32_e32 v112, v112, v116
	v_add_f32_e32 v113, v113, v117
	v_add_f32_e32 v114, v114, v118
	v_add_f32_e32 v115, v115, v119
	ds_bpermute_b32 v116, v127, v112
	ds_bpermute_b32 v117, v127, v113
	ds_bpermute_b32 v118, v127, v114
	ds_bpermute_b32 v119, v127, v115
	s_waitcnt lgkmcnt(0)
	v_add_f32_e32 v112, v112, v116
	v_add_f32_e32 v113, v113, v117
	v_add_f32_e32 v114, v114, v118
	v_add_f32_e32 v115, v115, v119
	v_fmamk_f32 v112, v112, 0x3a800000, v208
	v_fmamk_f32 v113, v113, 0x3a800000, v208
	v_fmamk_f32 v114, v114, 0x3a800000, v208
	v_fmamk_f32 v115, v115, 0x3a800000, v208
	v_rsq_f32_e32 v112, v112
	v_rsq_f32_e32 v113, v113
	v_rsq_f32_e32 v114, v114
	v_rsq_f32_e32 v115, v115
	s_nop 1
	v_mul_f32_e32 v132, v132, v112
	v_mul_f32_e32 v133, v133, v112
	v_mul_f32_e32 v134, v134, v112
	v_mul_f32_e32 v135, v135, v112
	v_mul_f32_e32 v132, v0, v132
	v_mul_f32_e32 v133, v1, v133
	v_mul_f32_e32 v134, v2, v134
	v_mul_f32_e32 v135, v3, v135
	v_fma_f32 v132, v132, v16, v32
	v_fma_f32 v133, v133, v17, v33
	v_fma_f32 v134, v134, v18, v34
	v_fma_f32 v135, v135, v19, v35
	v_cvt_pk_bf16_f32 v128, v132, v133
	v_cvt_pk_bf16_f32 v129, v134, v135
	global_store_dwordx2 v121, v[128:129], s[8:9] offset:0
	v_mul_f32_e32 v136, v136, v112
	v_mul_f32_e32 v137, v137, v112
	v_mul_f32_e32 v138, v138, v112
	v_mul_f32_e32 v139, v139, v112
	v_mul_f32_e32 v136, v4, v136
	v_mul_f32_e32 v137, v5, v137
	v_mul_f32_e32 v138, v6, v138
	v_mul_f32_e32 v139, v7, v139
	v_fma_f32 v136, v136, v20, v36
	v_fma_f32 v137, v137, v21, v37
	v_fma_f32 v138, v138, v22, v38
	v_fma_f32 v139, v139, v23, v39
	v_cvt_pk_bf16_f32 v130, v136, v137
	v_cvt_pk_bf16_f32 v131, v138, v139
	global_store_dwordx2 v121, v[130:131], s[8:9] offset:512
	v_mul_f32_e32 v140, v140, v112
	v_mul_f32_e32 v141, v141, v112
	v_mul_f32_e32 v142, v142, v112
	v_mul_f32_e32 v143, v143, v112
	v_mul_f32_e32 v140, v8, v140
	v_mul_f32_e32 v141, v9, v141
	v_mul_f32_e32 v142, v10, v142
	v_mul_f32_e32 v143, v11, v143
	v_fma_f32 v140, v140, v24, v40
	v_fma_f32 v141, v141, v25, v41
	v_fma_f32 v142, v142, v26, v42
	v_fma_f32 v143, v143, v27, v43
	v_cvt_pk_bf16_f32 v128, v140, v141
	v_cvt_pk_bf16_f32 v129, v142, v143
	global_store_dwordx2 v121, v[128:129], s[8:9] offset:1024
	v_mul_f32_e32 v144, v144, v112
	v_mul_f32_e32 v145, v145, v112
	v_mul_f32_e32 v146, v146, v112
	v_mul_f32_e32 v147, v147, v112
	v_mul_f32_e32 v144, v12, v144
	v_mul_f32_e32 v145, v13, v145
	v_mul_f32_e32 v146, v14, v146
	v_mul_f32_e32 v147, v15, v147
	v_fma_f32 v144, v144, v28, v44
	v_fma_f32 v145, v145, v29, v45
	v_fma_f32 v146, v146, v30, v46
	v_fma_f32 v147, v147, v31, v47
	v_cvt_pk_bf16_f32 v130, v144, v145
	v_cvt_pk_bf16_f32 v131, v146, v147
	global_store_dwordx2 v121, v[130:131], s[8:9] offset:1536
	s_add_u32 s8, s8, 0x20000
	s_addc_u32 s9, s9, 0
	v_mul_f32_e32 v166, v166, v113
	v_mul_f32_e32 v167, v167, v113
	v_mul_f32_e32 v168, v168, v113
	v_mul_f32_e32 v169, v169, v113
	v_mul_f32_e32 v166, v0, v166
	v_mul_f32_e32 v167, v1, v167
	v_mul_f32_e32 v168, v2, v168
	v_mul_f32_e32 v169, v3, v169
	v_fma_f32 v166, v166, v16, v32
	v_fma_f32 v167, v167, v17, v33
	v_fma_f32 v168, v168, v18, v34
	v_fma_f32 v169, v169, v19, v35
	v_cvt_pk_bf16_f32 v128, v166, v167
	v_cvt_pk_bf16_f32 v129, v168, v169
	global_store_dwordx2 v121, v[128:129], s[8:9] offset:0
	v_mul_f32_e32 v170, v170, v113
	v_mul_f32_e32 v171, v171, v113
	v_mul_f32_e32 v172, v172, v113
	v_mul_f32_e32 v173, v173, v113
	v_mul_f32_e32 v170, v4, v170
	v_mul_f32_e32 v171, v5, v171
	v_mul_f32_e32 v172, v6, v172
	v_mul_f32_e32 v173, v7, v173
	v_fma_f32 v170, v170, v20, v36
	v_fma_f32 v171, v171, v21, v37
	v_fma_f32 v172, v172, v22, v38
	v_fma_f32 v173, v173, v23, v39
	v_cvt_pk_bf16_f32 v130, v170, v171
	v_cvt_pk_bf16_f32 v131, v172, v173
	global_store_dwordx2 v121, v[130:131], s[8:9] offset:512
	v_mul_f32_e32 v174, v174, v113
	v_mul_f32_e32 v175, v175, v113
	v_mul_f32_e32 v176, v176, v113
	v_mul_f32_e32 v177, v177, v113
	v_mul_f32_e32 v174, v8, v174
	v_mul_f32_e32 v175, v9, v175
	v_mul_f32_e32 v176, v10, v176
	v_mul_f32_e32 v177, v11, v177
	v_fma_f32 v174, v174, v24, v40
	v_fma_f32 v175, v175, v25, v41
	v_fma_f32 v176, v176, v26, v42
	v_fma_f32 v177, v177, v27, v43
	v_cvt_pk_bf16_f32 v128, v174, v175
	v_cvt_pk_bf16_f32 v129, v176, v177
	global_store_dwordx2 v121, v[128:129], s[8:9] offset:1024
	v_mul_f32_e32 v178, v178, v113
	v_mul_f32_e32 v179, v179, v113
	v_mul_f32_e32 v180, v180, v113
	v_mul_f32_e32 v181, v181, v113
	v_mul_f32_e32 v178, v12, v178
	v_mul_f32_e32 v179, v13, v179
	v_mul_f32_e32 v180, v14, v180
	v_mul_f32_e32 v181, v15, v181
	v_fma_f32 v178, v178, v28, v44
	v_fma_f32 v179, v179, v29, v45
	v_fma_f32 v180, v180, v30, v46
	v_fma_f32 v181, v181, v31, v47
	v_cvt_pk_bf16_f32 v130, v178, v179
	v_cvt_pk_bf16_f32 v131, v180, v181
	global_store_dwordx2 v121, v[130:131], s[8:9] offset:1536
	s_add_u32 s8, s8, 0x20000
	s_addc_u32 s9, s9, 0
	v_mul_f32_e32 v182, v182, v114
	v_mul_f32_e32 v183, v183, v114
	v_mul_f32_e32 v184, v184, v114
	v_mul_f32_e32 v185, v185, v114
	v_mul_f32_e32 v182, v0, v182
	v_mul_f32_e32 v183, v1, v183
	v_mul_f32_e32 v184, v2, v184
	v_mul_f32_e32 v185, v3, v185
	v_fma_f32 v182, v182, v16, v32
	v_fma_f32 v183, v183, v17, v33
	v_fma_f32 v184, v184, v18, v34
	v_fma_f32 v185, v185, v19, v35
	v_cvt_pk_bf16_f32 v128, v182, v183
	v_cvt_pk_bf16_f32 v129, v184, v185
	global_store_dwordx2 v121, v[128:129], s[8:9] offset:0
	v_mul_f32_e32 v186, v186, v114
	v_mul_f32_e32 v187, v187, v114
	v_mul_f32_e32 v188, v188, v114
	v_mul_f32_e32 v189, v189, v114
	v_mul_f32_e32 v186, v4, v186
	v_mul_f32_e32 v187, v5, v187
	v_mul_f32_e32 v188, v6, v188
	v_mul_f32_e32 v189, v7, v189
	v_fma_f32 v186, v186, v20, v36
	v_fma_f32 v187, v187, v21, v37
	v_fma_f32 v188, v188, v22, v38
	v_fma_f32 v189, v189, v23, v39
	v_cvt_pk_bf16_f32 v130, v186, v187
	v_cvt_pk_bf16_f32 v131, v188, v189
	global_store_dwordx2 v121, v[130:131], s[8:9] offset:512
	v_mul_f32_e32 v190, v190, v114
	v_mul_f32_e32 v191, v191, v114
	v_mul_f32_e32 v192, v192, v114
	v_mul_f32_e32 v193, v193, v114
	v_mul_f32_e32 v190, v8, v190
	v_mul_f32_e32 v191, v9, v191
	v_mul_f32_e32 v192, v10, v192
	v_mul_f32_e32 v193, v11, v193
	v_fma_f32 v190, v190, v24, v40
	v_fma_f32 v191, v191, v25, v41
	v_fma_f32 v192, v192, v26, v42
	v_fma_f32 v193, v193, v27, v43
	v_cvt_pk_bf16_f32 v128, v190, v191
	v_cvt_pk_bf16_f32 v129, v192, v193
	global_store_dwordx2 v121, v[128:129], s[8:9] offset:1024
	v_mul_f32_e32 v194, v194, v114
	v_mul_f32_e32 v195, v195, v114
	v_mul_f32_e32 v196, v196, v114
	v_mul_f32_e32 v197, v197, v114
	v_mul_f32_e32 v194, v12, v194
	v_mul_f32_e32 v195, v13, v195
	v_mul_f32_e32 v196, v14, v196
	v_mul_f32_e32 v197, v15, v197
	v_fma_f32 v194, v194, v28, v44
	v_fma_f32 v195, v195, v29, v45
	v_fma_f32 v196, v196, v30, v46
	v_fma_f32 v197, v197, v31, v47
	v_cvt_pk_bf16_f32 v130, v194, v195
	v_cvt_pk_bf16_f32 v131, v196, v197
	global_store_dwordx2 v121, v[130:131], s[8:9] offset:1536
	s_add_u32 s8, s8, 0x20000
	s_addc_u32 s9, s9, 0
	v_mul_f32_e32 v228, v228, v115
	v_mul_f32_e32 v229, v229, v115
	v_mul_f32_e32 v230, v230, v115
	v_mul_f32_e32 v231, v231, v115
	v_mul_f32_e32 v228, v0, v228
	v_mul_f32_e32 v229, v1, v229
	v_mul_f32_e32 v230, v2, v230
	v_mul_f32_e32 v231, v3, v231
	v_fma_f32 v228, v228, v16, v32
	v_fma_f32 v229, v229, v17, v33
	v_fma_f32 v230, v230, v18, v34
	v_fma_f32 v231, v231, v19, v35
	v_cvt_pk_bf16_f32 v128, v228, v229
	v_cvt_pk_bf16_f32 v129, v230, v231
	global_store_dwordx2 v121, v[128:129], s[8:9] offset:0
	v_mul_f32_e32 v232, v232, v115
	v_mul_f32_e32 v233, v233, v115
	v_mul_f32_e32 v234, v234, v115
	v_mul_f32_e32 v235, v235, v115
	v_mul_f32_e32 v232, v4, v232
	v_mul_f32_e32 v233, v5, v233
	v_mul_f32_e32 v234, v6, v234
	v_mul_f32_e32 v235, v7, v235
	v_fma_f32 v232, v232, v20, v36
	v_fma_f32 v233, v233, v21, v37
	v_fma_f32 v234, v234, v22, v38
	v_fma_f32 v235, v235, v23, v39
	v_cvt_pk_bf16_f32 v130, v232, v233
	v_cvt_pk_bf16_f32 v131, v234, v235
	global_store_dwordx2 v121, v[130:131], s[8:9] offset:512
	v_mul_f32_e32 v236, v236, v115
	v_mul_f32_e32 v237, v237, v115
	v_mul_f32_e32 v238, v238, v115
	v_mul_f32_e32 v239, v239, v115
	v_mul_f32_e32 v236, v8, v236
	v_mul_f32_e32 v237, v9, v237
	v_mul_f32_e32 v238, v10, v238
	v_mul_f32_e32 v239, v11, v239
	v_fma_f32 v236, v236, v24, v40
	v_fma_f32 v237, v237, v25, v41
	v_fma_f32 v238, v238, v26, v42
	v_fma_f32 v239, v239, v27, v43
	v_cvt_pk_bf16_f32 v128, v236, v237
	v_cvt_pk_bf16_f32 v129, v238, v239
	global_store_dwordx2 v121, v[128:129], s[8:9] offset:1024
	v_mul_f32_e32 v240, v240, v115
	v_mul_f32_e32 v241, v241, v115
	v_mul_f32_e32 v242, v242, v115
	v_mul_f32_e32 v243, v243, v115
	v_mul_f32_e32 v240, v12, v240
	v_mul_f32_e32 v241, v13, v241
	v_mul_f32_e32 v242, v14, v242
	v_mul_f32_e32 v243, v15, v243
	v_fma_f32 v240, v240, v28, v44
	v_fma_f32 v241, v241, v29, v45
	v_fma_f32 v242, v242, v30, v46
	v_fma_f32 v243, v243, v31, v47
	v_cvt_pk_bf16_f32 v130, v240, v241
	v_cvt_pk_bf16_f32 v131, v242, v243
	global_store_dwordx2 v121, v[130:131], s[8:9] offset:1536
	s_add_u32 s8, s8, 0x20000
	s_addc_u32 s9, s9, 0

.LBB0_188:
	v_lshl_add_u64 v[0:1], s[86:87], 0, v[104:105]
	s_mov_b32 s1, 0x15200000
	v_add_co_u32_e32 v0, vcc, s1, v0
	v_cvt_f32_u32_e32 v107, s82
	s_nop 0
	v_addc_co_u32_e32 v1, vcc, 0, v1, vcc
	global_load_dwordx4 v[4:7], v[0:1], off
	s_nop 0
	global_load_dwordx4 v[0:3], v[0:1], off offset:64
	v_cmp_lt_f32_e32 vcc, s72, v107
	s_nop 1
	v_cndmask_b32_e32 v108, 0, v220, vcc
	v_sub_f32_e32 v107, v108, v107
	v_exp_f32_e32 v107, v107
	s_and_b64 vcc, vcc, exec
	s_cselect_b32 s1, 0xffffffc0, 0
	v_ldexp_f32 v152, v107, s1
	global_load_dwordx4 v[108:111], v[16:17], off
	global_load_dwordx4 v[196:199], v[16:17], off offset:64
	global_load_dwordx4 v[112:115], v[16:17], off offset:2048
	global_load_dwordx4 v[200:203], v[16:17], off offset:2112
	global_load_dwordx4 v[116:119], v[26:27], off
	global_load_dwordx4 v[204:207], v[28:29], off
	global_load_dwordx4 v[120:123], v[36:37], off
	global_load_dwordx4 v[228:231], v[38:39], off
	global_load_dwordx4 v[124:127], v[44:45], off
	global_load_dwordx4 v[232:235], v[46:47], off
	global_load_dwordx4 v[128:131], v[52:53], off
	global_load_dwordx4 v[236:239], v[54:55], off
	global_load_dwordx4 v[132:135], v[60:61], off
	global_load_dwordx4 v[136:139], v[68:69], off
	global_load_dwordx4 v[140:143], v[62:63], off
	global_load_dwordx4 v[148:151], v[70:71], off
	s_waitcnt vmcnt(14) lgkmcnt(0)
	v_mfma_f32_16x16x32_bf16 v[108:111], v[108:111], v[4:7], 0
	v_mfma_f32_16x16x32_bf16 v[108:111], v[196:199], v[0:3], v[108:111]
	s_waitcnt vmcnt(12)
	v_mfma_f32_16x16x32_bf16 v[112:115], v[112:115], v[4:7], 0
	v_mfma_f32_16x16x32_bf16 v[112:115], v[200:203], v[0:3], v[112:115]
	s_waitcnt vmcnt(10)
	v_mfma_f32_16x16x32_bf16 v[116:119], v[116:119], v[4:7], 0
	v_mfma_f32_16x16x32_bf16 v[116:119], v[204:207], v[0:3], v[116:119]
	s_waitcnt vmcnt(8)
	v_mfma_f32_16x16x32_bf16 v[120:123], v[120:123], v[4:7], 0
	v_mfma_f32_16x16x32_bf16 v[120:123], v[228:231], v[0:3], v[120:123]
	s_waitcnt vmcnt(6)
	v_mfma_f32_16x16x32_bf16 v[124:127], v[124:127], v[4:7], 0
	v_mfma_f32_16x16x32_bf16 v[124:127], v[232:235], v[0:3], v[124:127]
	s_waitcnt vmcnt(4)
	v_mfma_f32_16x16x32_bf16 v[128:131], v[128:131], v[4:7], 0
	v_mfma_f32_16x16x32_bf16 v[128:131], v[236:239], v[0:3], v[128:131]
	v_pk_mul_f32 v[154:155], v[22:23], v[152:153] op_sel_hi:[1,0]
	v_pk_mul_f32 v[156:157], v[24:25], v[152:153] op_sel_hi:[1,0]
	v_pk_mul_f32 v[180:181], v[40:41], v[152:153] op_sel_hi:[1,0]
	v_pk_mul_f32 v[182:183], v[42:43], v[152:153] op_sel_hi:[1,0]
	v_pk_mul_f32 v[188:189], v[18:19], v[152:153] op_sel_hi:[1,0]
	v_pk_mul_f32 v[158:159], v[72:73], v[152:153] op_sel_hi:[1,0]
	v_pk_mul_f32 v[166:167], v[74:75], v[152:153] op_sel_hi:[1,0]
	v_pk_mul_f32 v[168:169], v[64:65], v[152:153] op_sel_hi:[1,0]
	v_pk_mul_f32 v[170:171], v[66:67], v[152:153] op_sel_hi:[1,0]
	v_pk_mul_f32 v[172:173], v[56:57], v[152:153] op_sel_hi:[1,0]
	v_pk_mul_f32 v[174:175], v[58:59], v[152:153] op_sel_hi:[1,0]
	v_pk_mul_f32 v[176:177], v[48:49], v[152:153] op_sel_hi:[1,0]
	v_pk_mul_f32 v[178:179], v[50:51], v[152:153] op_sel_hi:[1,0]
	v_pk_mul_f32 v[184:185], v[30:31], v[152:153] op_sel_hi:[1,0]
	v_pk_mul_f32 v[186:187], v[34:35], v[152:153] op_sel_hi:[1,0]
	v_pk_mul_f32 v[152:153], v[20:21], v[152:153] op_sel_hi:[1,0]
	v_pk_fma_f32 v[112:113], v[112:113], s[90:91], v[154:155] op_sel_hi:[1,0,1] neg_lo:[0,0,1] neg_hi:[0,0,1]
	v_pk_fma_f32 v[114:115], v[114:115], s[90:91], v[156:157] op_sel_hi:[1,0,1] neg_lo:[0,0,1] neg_hi:[0,0,1]
	v_pk_fma_f32 v[120:121], v[120:121], s[90:91], v[180:181] op_sel_hi:[1,0,1] neg_lo:[0,0,1] neg_hi:[0,0,1]
	v_pk_fma_f32 v[122:123], v[122:123], s[90:91], v[182:183] op_sel_hi:[1,0,1] neg_lo:[0,0,1] neg_hi:[0,0,1]
	v_pk_fma_f32 v[108:109], v[108:109], s[90:91], v[188:189] op_sel_hi:[1,0,1] neg_lo:[0,0,1] neg_hi:[0,0,1]
	v_pk_fma_f32 v[110:111], v[110:111], s[90:91], v[152:153] op_sel_hi:[1,0,1] neg_lo:[0,0,1] neg_hi:[0,0,1]
	v_cndmask_b32_e64 v107, v221, v113, s[14:15]
	v_cndmask_b32_e64 v113, v221, v115, s[16:17]
	v_cndmask_b32_e64 v115, v221, v121, s[34:35]
	v_cndmask_b32_e64 v121, v221, v123, s[36:37]
	v_cndmask_b32_e64 v123, v221, v109, s[6:7]
	v_cndmask_b32_e64 v152, v221, v108, s[4:5]
	v_cndmask_b32_e64 v153, v221, v111, s[8:9]
	v_cndmask_b32_e64 v154, v221, v110, s[10:11]
	v_max3_f32 v108, v152, s73, v123
	v_cndmask_b32_e64 v112, v221, v112, s[12:13]
	v_max3_f32 v108, v108, v154, v153
	v_pk_fma_f32 v[116:117], v[116:117], s[90:91], v[184:185] op_sel_hi:[1,0,1] neg_lo:[0,0,1] neg_hi:[0,0,1]
	v_cndmask_b32_e64 v114, v221, v114, s[20:21]
	v_max3_f32 v155, v108, v112, v107
	v_pk_fma_f32 v[118:119], v[118:119], s[90:91], v[186:187] op_sel_hi:[1,0,1] neg_lo:[0,0,1] neg_hi:[0,0,1]
	v_cndmask_b32_e64 v117, v221, v117, s[24:25]
	v_cndmask_b32_e64 v116, v221, v116, s[22:23]
	v_cndmask_b32_e64 v119, v221, v119, s[26:27]
	v_cndmask_b32_e64 v118, v221, v118, s[28:29]
	v_cndmask_b32_e64 v120, v221, v120, s[30:31]
	v_pk_fma_f32 v[124:125], v[124:125], s[90:91], v[176:177] op_sel_hi:[1,0,1] neg_lo:[0,0,1] neg_hi:[0,0,1]
	v_cndmask_b32_e64 v122, v221, v122, s[38:39]
	v_pk_fma_f32 v[126:127], v[126:127], s[90:91], v[178:179] op_sel_hi:[1,0,1] neg_lo:[0,0,1] neg_hi:[0,0,1]
	v_cndmask_b32_e64 v125, v221, v125, s[44:45]
	v_cndmask_b32_e64 v124, v221, v124, s[42:43]
	v_pk_fma_f32 v[128:129], v[128:129], s[90:91], v[172:173] op_sel_hi:[1,0,1] neg_lo:[0,0,1] neg_hi:[0,0,1]
	v_cndmask_b32_e64 v127, v221, v127, s[40:41]
	v_cndmask_b32_e64 v126, v221, v126, s[46:47]
	v_pk_fma_f32 v[130:131], v[130:131], s[90:91], v[174:175] op_sel_hi:[1,0,1] neg_lo:[0,0,1] neg_hi:[0,0,1]
	v_cndmask_b32_e64 v129, v221, v129, s[52:53]
	v_cndmask_b32_e64 v128, v221, v128, s[50:51]
	v_cndmask_b32_e64 v131, v221, v131, s[48:49]
	v_cndmask_b32_e64 v130, v221, v130, s[54:55]
	v_cmp_lt_f32_e32 vcc, s92, v123
	s_waitcnt vmcnt(0) lgkmcnt(0)
	v_mfma_f32_16x16x32_bf16 v[108:111], v[132:135], v[4:7], 0
	v_max3_f32 v132, v155, v114, v113
	v_max3_f32 v132, v132, v116, v117
	v_max3_f32 v132, v132, v118, v119
	v_mfma_f32_16x16x32_bf16 v[4:7], v[136:139], v[4:7], 0
	v_max3_f32 v132, v132, v120, v115
	v_max3_f32 v132, v132, v122, v121
	v_max3_f32 v132, v132, v124, v125
	v_mfma_f32_16x16x32_bf16 v[108:111], v[140:143], v[0:3], v[108:111]
	v_max3_f32 v132, v132, v126, v127
	v_max3_f32 v132, v132, v128, v129
	v_max3_f32 v132, v132, v130, v131
	v_mfma_f32_16x16x32_bf16 v[0:3], v[148:151], v[0:3], v[4:7]
	s_nop 3
	v_fma_f32 v4, v108, s90, -v168
	v_fma_f32 v5, v109, s90, -v169
	s_nop 1
	v_pk_fma_f32 v[0:1], v[0:1], s[90:91], v[158:159] op_sel_hi:[1,0,1] neg_lo:[0,0,1] neg_hi:[0,0,1]
	v_pk_fma_f32 v[6:7], v[110:111], s[90:91], v[170:171] op_sel_hi:[1,0,1] neg_lo:[0,0,1] neg_hi:[0,0,1]
	v_cndmask_b32_e64 v137, v221, v5, s[60:61]
	v_cndmask_b32_e64 v138, v221, v4, s[58:59]
	v_cndmask_b32_e64 v134, v221, v0, s[66:67]
	v_cndmask_b32_e64 v139, v221, v7, s[56:57]
	v_cndmask_b32_e64 v140, v221, v6, s[62:63]
	v_max3_f32 v0, v132, v138, v137
	v_pk_fma_f32 v[2:3], v[2:3], s[90:91], v[166:167] op_sel_hi:[1,0,1] neg_lo:[0,0,1] neg_hi:[0,0,1]
	v_cndmask_b32_e64 v133, v221, v1, s[68:69]
	v_max3_f32 v0, v0, v140, v139
	v_cndmask_b32_e64 v135, v221, v3, s[64:65]
	v_cndmask_b32_e64 v136, v221, v2, s[70:71]
	v_max3_f32 v0, v0, v134, v133
	v_max3_f32 v0, v0, v136, v135
	ds_bpermute_b32 v1, v193, v0
	s_waitcnt lgkmcnt(0)
	v_max_f32_e32 v1, v1, v1
	v_max_f32_e32 v0, v0, v1
	ds_bpermute_b32 v1, v194, v0
	s_waitcnt lgkmcnt(0)
	v_max_f32_e32 v1, v1, v1
	v_max_f32_e32 v132, v0, v1
	v_sub_f32_e32 v1, v123, v132
	v_sub_f32_e32 v0, v152, v132
	v_mul_f32_e32 v1, 0x3fb8aa3b, v1
	v_sub_f32_e32 v3, v153, v132
	v_mul_f32_e32 v0, 0x3fb8aa3b, v0
	v_exp_f32_e32 v1, v1
	v_sub_f32_e32 v2, v154, v132
	v_mul_f32_e32 v3, 0x3fb8aa3b, v3
	v_exp_f32_e32 v0, v0
	v_sub_f32_e32 v5, v107, v132
	v_mul_f32_e32 v2, 0x3fb8aa3b, v2
	v_exp_f32_e32 v3, v3
	v_sub_f32_e32 v4, v112, v132
	v_mul_f32_e32 v5, 0x3fb8aa3b, v5
	v_exp_f32_e32 v2, v2
	v_mul_f32_e32 v4, 0x3fb8aa3b, v4
	v_exp_f32_e32 v5, v5
	v_cndmask_b32_e32 v1, 0, v1, vcc
	v_cmp_lt_f32_e32 vcc, s92, v152
	v_exp_f32_e32 v4, v4
	v_sub_f32_e32 v7, v113, v132
	v_cndmask_b32_e32 v0, 0, v0, vcc
	v_cmp_lt_f32_e32 vcc, s92, v153
	v_add_f32_e32 v6, 0, v0
	v_add_f32_e32 v6, v1, v6
	v_cndmask_b32_e32 v3, 0, v3, vcc
	v_cmp_lt_f32_e32 vcc, s92, v154
	v_mul_f32_e32 v7, 0x3fb8aa3b, v7
	v_exp_f32_e32 v7, v7
	v_cndmask_b32_e32 v2, 0, v2, vcc
	v_cmp_lt_f32_e32 vcc, s92, v107
	v_add_f32_e32 v6, v2, v6
	v_add_f32_e32 v6, v3, v6
	v_cndmask_b32_e32 v5, 0, v5, vcc
	v_cmp_lt_f32_e32 vcc, s92, v112
	v_sub_f32_e32 v109, v117, v132
	v_sub_f32_e32 v108, v116, v132
	v_cndmask_b32_e32 v4, 0, v4, vcc
	v_add_f32_e32 v6, v4, v6
	v_add_f32_e32 v107, v5, v6
	v_sub_f32_e32 v6, v114, v132
	v_mul_f32_e32 v6, 0x3fb8aa3b, v6
	v_exp_f32_e32 v6, v6
	v_mul_f32_e32 v109, 0x3fb8aa3b, v109
	v_exp_f32_e32 v109, v109
	v_mul_f32_e32 v108, 0x3fb8aa3b, v108
	v_sub_f32_e32 v111, v119, v132
	v_cmp_lt_f32_e32 vcc, s92, v113
	v_exp_f32_e32 v108, v108
	v_sub_f32_e32 v110, v118, v132
	v_mul_f32_e32 v111, 0x3fb8aa3b, v111
	v_cndmask_b32_e32 v7, 0, v7, vcc
	v_cmp_lt_f32_e32 vcc, s92, v114
	v_exp_f32_e32 v111, v111
	v_mul_f32_e32 v110, 0x3fb8aa3b, v110
	v_cndmask_b32_e32 v6, 0, v6, vcc
	v_cmp_lt_f32_e32 vcc, s92, v117
	v_exp_f32_e32 v110, v110
	v_sub_f32_e32 v113, v115, v132
	v_cndmask_b32_e32 v109, 0, v109, vcc
	v_cmp_lt_f32_e32 vcc, s92, v116
	v_sub_f32_e32 v112, v120, v132
	v_mul_f32_e32 v113, 0x3fb8aa3b, v113
	v_cndmask_b32_e32 v108, 0, v108, vcc
	v_cmp_lt_f32_e32 vcc, s92, v119
	v_add_f32_e32 v107, v6, v107
	v_exp_f32_e32 v113, v113
	v_cndmask_b32_e32 v111, 0, v111, vcc
	v_cmp_lt_f32_e32 vcc, s92, v118
	v_mul_f32_e32 v112, 0x3fb8aa3b, v112
	v_add_f32_e32 v107, v7, v107
	v_cndmask_b32_e32 v110, 0, v110, vcc
	v_cmp_lt_f32_e32 vcc, s92, v115
	v_sub_f32_e32 v115, v121, v132
	v_exp_f32_e32 v112, v112
	v_sub_f32_e32 v114, v122, v132
	v_mul_f32_e32 v115, 0x3fb8aa3b, v115
	v_add_f32_e32 v107, v108, v107
	v_exp_f32_e32 v115, v115
	v_mul_f32_e32 v114, 0x3fb8aa3b, v114
	v_sub_f32_e32 v117, v125, v132
	v_add_f32_e32 v107, v109, v107
	v_exp_f32_e32 v114, v114
	v_sub_f32_e32 v116, v124, v132
	v_mul_f32_e32 v117, 0x3fb8aa3b, v117
	v_add_f32_e32 v107, v110, v107
	v_cndmask_b32_e32 v113, 0, v113, vcc
	v_cmp_lt_f32_e32 vcc, s92, v120
	v_exp_f32_e32 v117, v117
	v_mul_f32_e32 v116, 0x3fb8aa3b, v116
	v_sub_f32_e32 v119, v127, v132
	v_add_f32_e32 v107, v111, v107
	v_cndmask_b32_e32 v112, 0, v112, vcc
	v_cmp_lt_f32_e32 vcc, s92, v121
	v_exp_f32_e32 v116, v116
	v_sub_f32_e32 v118, v126, v132
	v_mul_f32_e32 v119, 0x3fb8aa3b, v119
	v_add_f32_e32 v107, v112, v107
	v_cndmask_b32_e32 v115, 0, v115, vcc
	v_cmp_lt_f32_e32 vcc, s92, v122
	v_exp_f32_e32 v119, v119
	v_mul_f32_e32 v118, 0x3fb8aa3b, v118
	v_sub_f32_e32 v121, v129, v132
	v_add_f32_e32 v107, v113, v107
	v_cndmask_b32_e32 v114, 0, v114, vcc
	v_cmp_lt_f32_e32 vcc, s92, v125
	v_exp_f32_e32 v118, v118
	v_sub_f32_e32 v120, v128, v132
	v_mul_f32_e32 v121, 0x3fb8aa3b, v121
	v_add_f32_e32 v107, v114, v107
	v_cndmask_b32_e32 v117, 0, v117, vcc
	v_cmp_lt_f32_e32 vcc, s92, v124
	v_exp_f32_e32 v121, v121
	v_mul_f32_e32 v120, 0x3fb8aa3b, v120
	v_sub_f32_e32 v123, v131, v132
	v_add_f32_e32 v107, v115, v107
	v_cndmask_b32_e32 v116, 0, v116, vcc
	v_cmp_lt_f32_e32 vcc, s92, v127
	v_exp_f32_e32 v120, v120
	v_sub_f32_e32 v122, v130, v132
	v_mul_f32_e32 v123, 0x3fb8aa3b, v123
	v_add_f32_e32 v107, v116, v107
	v_cndmask_b32_e32 v119, 0, v119, vcc
	v_cmp_lt_f32_e32 vcc, s92, v126
	v_exp_f32_e32 v123, v123
	v_mul_f32_e32 v122, 0x3fb8aa3b, v122
	v_sub_f32_e32 v125, v137, v132
	v_add_f32_e32 v107, v117, v107
	v_cndmask_b32_e32 v118, 0, v118, vcc
	v_cmp_lt_f32_e32 vcc, s92, v129
	v_exp_f32_e32 v122, v122
	v_sub_f32_e32 v124, v138, v132
	v_mul_f32_e32 v125, 0x3fb8aa3b, v125
	v_add_f32_e32 v107, v118, v107
	v_cndmask_b32_e32 v121, 0, v121, vcc
	v_cmp_lt_f32_e32 vcc, s92, v128
	v_exp_f32_e32 v125, v125
	v_mul_f32_e32 v124, 0x3fb8aa3b, v124
	v_sub_f32_e32 v127, v139, v132
	v_add_f32_e32 v107, v119, v107
	v_cndmask_b32_e32 v120, 0, v120, vcc
	v_cmp_lt_f32_e32 vcc, s92, v131
	v_exp_f32_e32 v124, v124
	v_sub_f32_e32 v126, v140, v132
	v_mul_f32_e32 v127, 0x3fb8aa3b, v127
	v_add_f32_e32 v107, v120, v107
	v_cndmask_b32_e32 v123, 0, v123, vcc
	v_cmp_lt_f32_e32 vcc, s92, v130
	v_exp_f32_e32 v127, v127
	v_mul_f32_e32 v126, 0x3fb8aa3b, v126
	v_sub_f32_e32 v129, v133, v132
	v_add_f32_e32 v107, v121, v107
	v_cndmask_b32_e32 v122, 0, v122, vcc
	v_cmp_lt_f32_e32 vcc, s92, v137
	v_exp_f32_e32 v126, v126
	v_sub_f32_e32 v128, v134, v132
	v_mul_f32_e32 v129, 0x3fb8aa3b, v129
	v_add_f32_e32 v107, v122, v107
	v_cndmask_b32_e32 v125, 0, v125, vcc
	v_cmp_lt_f32_e32 vcc, s92, v138
	v_exp_f32_e32 v129, v129
	v_mul_f32_e32 v128, 0x3fb8aa3b, v128
	v_sub_f32_e32 v131, v135, v132
	v_add_f32_e32 v107, v123, v107
	v_cndmask_b32_e32 v124, 0, v124, vcc
	v_cmp_lt_f32_e32 vcc, s92, v139
	v_exp_f32_e32 v128, v128
	v_sub_f32_e32 v130, v136, v132
	v_mul_f32_e32 v131, 0x3fb8aa3b, v131
	v_add_f32_e32 v107, v124, v107
	v_cndmask_b32_e32 v127, 0, v127, vcc
	v_cmp_lt_f32_e32 vcc, s92, v140
	v_exp_f32_e32 v131, v131
	v_mul_f32_e32 v130, 0x3fb8aa3b, v130
	v_add_f32_e32 v107, v125, v107
	v_cndmask_b32_e32 v126, 0, v126, vcc
	v_cmp_lt_f32_e32 vcc, s92, v133
	v_exp_f32_e32 v130, v130
	v_add_f32_e32 v107, v126, v107
	v_cndmask_b32_e32 v129, 0, v129, vcc
	v_cmp_lt_f32_e32 vcc, s92, v134
	v_add_f32_e32 v107, v127, v107
	s_nop 0
	v_cndmask_b32_e32 v128, 0, v128, vcc
	v_cmp_lt_f32_e32 vcc, s92, v135
	v_add_f32_e32 v107, v128, v107
	v_add_f32_e32 v107, v129, v107
	v_cndmask_b32_e32 v131, 0, v131, vcc
	v_cmp_lt_f32_e32 vcc, s92, v136
	s_nop 1
	v_cndmask_b32_e32 v130, 0, v130, vcc
	v_add_f32_e32 v107, v130, v107
	v_add_f32_e32 v107, v131, v107
	ds_bpermute_b32 v132, v193, v107
	s_waitcnt lgkmcnt(0)
	v_add_f32_e32 v107, v107, v132
	ds_bpermute_b32 v132, v194, v107
	s_waitcnt lgkmcnt(0)
	v_add_f32_e32 v107, v107, v132
	v_div_scale_f32 v132, vcc, v107, v107, 1.0
	v_rcp_f32_e32 v133, v132
	s_nop 0
	v_fma_f32 v134, -v132, v133, 1.0
	v_fmac_f32_e32 v133, v134, v133
	v_div_scale_f32 v134, vcc, 1.0, v107, 1.0
	v_mul_f32_e32 v135, v134, v133
	v_fma_f32 v136, -v132, v135, v134
	v_fmac_f32_e32 v135, v136, v133
	v_fma_f32 v132, -v132, v135, v134
	v_div_fmas_f32 v132, v132, v133, v135
	v_div_fixup_f32 v132, v132, v107, 1.0
	v_cmp_lt_f32_e32 vcc, 0, v107
	s_nop 1
	v_cndmask_b32_e32 v132, 0, v132, vcc
	v_pk_mul_f32 v[134:135], v[2:3], v[132:133] op_sel_hi:[1,0]
	v_pk_mul_f32 v[136:137], v[6:7], v[132:133] op_sel_hi:[1,0]
	ds_bpermute_b32 v2, v33, v135
	ds_bpermute_b32 v107, v33, v137
	v_pk_mul_f32 v[138:139], v[0:1], v[132:133] op_sel_hi:[1,0]
	v_pk_mul_f32 v[140:141], v[4:5], v[132:133] op_sel_hi:[1,0]
	v_mov_b32_e32 v4, v139
	s_waitcnt lgkmcnt(1)
	v_cndmask_b32_e64 v0, 0, v2, s[18:19]
	s_waitcnt lgkmcnt(0)
	v_cndmask_b32_e64 v1, v2, v107, s[18:19]
	v_mov_b32_e32 v2, v138
	v_mov_b32_e32 v3, v140
	v_mov_b32_e32 v5, v141
	v_pk_add_f32 v[2:3], v[2:3], v[4:5]
	v_mov_b32_e32 v4, v134
	v_mov_b32_e32 v5, v136
	v_mov_b32_e32 v6, v135
	v_mov_b32_e32 v7, v137
	v_pk_add_f32 v[4:5], v[4:5], v[6:7]
	v_pk_mul_f32 v[148:149], v[110:111], v[132:133] op_sel_hi:[1,0]
	v_pk_mul_f32 v[152:153], v[114:115], v[132:133] op_sel_hi:[1,0]
	v_pk_add_f32 v[2:3], v[2:3], v[4:5]
	ds_bpermute_b32 v6, v33, v149
	ds_bpermute_b32 v7, v33, v153
	v_pk_add_f32 v[0:1], v[0:1], v[2:3]
	v_pk_mul_f32 v[142:143], v[108:109], v[132:133] op_sel_hi:[1,0]
	v_pk_mul_f32 v[150:151], v[112:113], v[132:133] op_sel_hi:[1,0]
	v_pk_add_f32 v[14:15], v[14:15], v[0:1]
	v_mov_b32_e32 v0, v142
	v_mov_b32_e32 v1, v150
	v_mov_b32_e32 v2, v143
	v_mov_b32_e32 v3, v151
	v_pk_add_f32 v[0:1], v[0:1], v[2:3]
	v_mov_b32_e32 v2, v148
	v_mov_b32_e32 v3, v152
	v_mov_b32_e32 v4, v149
	v_mov_b32_e32 v5, v153
	v_pk_add_f32 v[2:3], v[2:3], v[4:5]
	v_pk_mul_f32 v[156:157], v[118:119], v[132:133] op_sel_hi:[1,0]
	v_pk_mul_f32 v[166:167], v[122:123], v[132:133] op_sel_hi:[1,0]
	v_pk_add_f32 v[0:1], v[0:1], v[2:3]
	s_waitcnt lgkmcnt(0)
	v_cndmask_b32_e64 v3, v6, v7, s[18:19]
	v_cndmask_b32_e64 v2, v107, v6, s[18:19]
	ds_bpermute_b32 v6, v33, v157
	ds_bpermute_b32 v107, v33, v167
	v_pk_add_f32 v[0:1], v[0:1], v[2:3]
	v_pk_mul_f32 v[154:155], v[116:117], v[132:133] op_sel_hi:[1,0]
	v_pk_mul_f32 v[158:159], v[120:121], v[132:133] op_sel_hi:[1,0]
	v_pk_add_f32 v[12:13], v[12:13], v[0:1]
	v_mov_b32_e32 v0, v154
	v_mov_b32_e32 v1, v158
	v_mov_b32_e32 v2, v155
	v_mov_b32_e32 v3, v159
	v_pk_add_f32 v[0:1], v[0:1], v[2:3]
	v_mov_b32_e32 v2, v156
	v_mov_b32_e32 v3, v166
	v_mov_b32_e32 v4, v157
	v_mov_b32_e32 v5, v167
	v_pk_add_f32 v[2:3], v[2:3], v[4:5]
	v_pk_mul_f32 v[4:5], v[128:129], v[132:133] op_sel_hi:[1,0]
	v_pk_add_f32 v[0:1], v[0:1], v[2:3]
	s_waitcnt lgkmcnt(0)
	v_cndmask_b32_e64 v3, v6, v107, s[18:19]
	v_cndmask_b32_e64 v2, v7, v6, s[18:19]
	v_pk_add_f32 v[0:1], v[0:1], v[2:3]
	v_pk_mul_f32 v[2:3], v[126:127], v[132:133] op_sel_hi:[1,0]
	v_pk_mul_f32 v[6:7], v[130:131], v[132:133] op_sel_hi:[1,0]
	ds_bpermute_b32 v114, v33, v3
	ds_bpermute_b32 v115, v33, v7
	v_pk_add_f32 v[10:11], v[10:11], v[0:1]
	v_pk_mul_f32 v[0:1], v[124:125], v[132:133] op_sel_hi:[1,0]
	v_mov_b32_e32 v109, v4
	v_mov_b32_e32 v108, v0
	v_mov_b32_e32 v110, v1
	v_mov_b32_e32 v111, v5
	v_pk_add_f32 v[108:109], v[108:109], v[110:111]
	v_mov_b32_e32 v110, v2
	v_mov_b32_e32 v111, v6
	v_mov_b32_e32 v112, v3
	v_mov_b32_e32 v113, v7
	v_pk_add_f32 v[110:111], v[110:111], v[112:113]
	s_nop 0
	v_pk_add_f32 v[108:109], v[108:109], v[110:111]
	s_waitcnt lgkmcnt(0)
	v_cndmask_b32_e64 v111, v114, v115, s[18:19]
	v_cndmask_b32_e64 v110, v107, v114, s[18:19]
	v_pk_add_f32 v[108:109], v[108:109], v[110:111]
	s_nop 0
	v_pk_add_f32 v[8:9], v[8:9], v[108:109]
	global_load_dwordx2 v[108:109], v[76:77], off
	global_load_dwordx2 v[110:111], v[76:77], off offset:32
	global_load_dwordx2 v[112:113], v[78:79], off
	global_load_dwordx2 v[114:115], v[78:79], off offset:32
	global_load_dwordx2 v[120:121], v[80:81], off
	global_load_dwordx2 v[122:123], v[80:81], off offset:32
	global_load_dwordx2 v[124:125], v[82:83], off
	global_load_dwordx2 v[126:127], v[82:83], off offset:32
	global_load_dwordx2 v[128:129], v[76:77], off offset:64
	global_load_dwordx2 v[130:131], v[76:77], off offset:96
	global_load_dwordx2 v[196:197], v[84:85], off
	global_load_dwordx2 v[198:199], v[84:85], off offset:32
	global_load_dwordx2 v[200:201], v[86:87], off
	global_load_dwordx2 v[202:203], v[86:87], off offset:32
	global_load_dwordx2 v[204:205], v[88:89], off
	global_load_dwordx2 v[206:207], v[88:89], off offset:32
	global_load_dwordx2 v[228:229], v[76:77], off offset:128
	global_load_dwordx2 v[230:231], v[76:77], off offset:160
	global_load_dwordx2 v[232:233], v[90:91], off
	global_load_dwordx2 v[234:235], v[90:91], off offset:32
	global_load_dwordx2 v[236:237], v[92:93], off
	global_load_dwordx2 v[238:239], v[92:93], off offset:32
	global_load_dwordx2 v[240:241], v[94:95], off
	global_load_dwordx2 v[242:243], v[94:95], off offset:32
	global_load_dwordx2 v[244:245], v[76:77], off offset:192
	global_load_dwordx2 v[246:247], v[76:77], off offset:224
	global_load_dwordx2 v[248:249], v[96:97], off
	global_load_dwordx2 v[250:251], v[96:97], off offset:32
	v_cvt_pk_bf16_f32 v116, v138, v139
	v_cvt_pk_bf16_f32 v117, v134, v135
	v_cvt_pk_bf16_f32 v118, v140, v141
	v_cvt_pk_bf16_f32 v119, v136, v137
	s_waitcnt vmcnt(20) lgkmcnt(0)
	s_nop 0
	v_mfma_f32_16x16x32_bf16 v[108:111], v[108:111], v[116:119], 0
	v_mfma_f32_16x16x32_bf16 v[112:115], v[112:115], v[116:119], 0
	v_mfma_f32_16x16x32_bf16 v[120:123], v[120:123], v[116:119], 0
	v_mfma_f32_16x16x32_bf16 v[116:119], v[124:127], v[116:119], 0
	v_cvt_pk_bf16_f32 v124, v142, v143
	v_cvt_pk_bf16_f32 v125, v148, v149
	v_cvt_pk_bf16_f32 v126, v150, v151
	v_cvt_pk_bf16_f32 v127, v152, v153
	s_waitcnt vmcnt(12)
	s_nop 0
	v_mfma_f32_16x16x32_bf16 v[108:111], v[128:131], v[124:127], v[108:111]
	v_mfma_f32_16x16x32_bf16 v[112:115], v[196:199], v[124:127], v[112:115]
	v_mfma_f32_16x16x32_bf16 v[120:123], v[200:203], v[124:127], v[120:123]
	v_mfma_f32_16x16x32_bf16 v[116:119], v[204:207], v[124:127], v[116:119]
	global_load_dwordx2 v[196:197], v[98:99], off
	global_load_dwordx2 v[198:199], v[98:99], off offset:32
	global_load_dwordx2 v[200:201], v[100:101], off
	global_load_dwordx2 v[202:203], v[100:101], off offset:32
	global_load_dword v107, v102, s[86:87]
	v_cvt_pk_bf16_f32 v124, v154, v155
	v_cvt_pk_bf16_f32 v125, v156, v157
	v_cvt_pk_bf16_f32 v126, v158, v159
	v_cvt_pk_bf16_f32 v127, v166, v167
	s_waitcnt vmcnt(9)
	s_nop 0
	v_mfma_f32_16x16x32_bf16 v[108:111], v[228:231], v[124:127], v[108:111]
	v_mfma_f32_16x16x32_bf16 v[112:115], v[232:235], v[124:127], v[112:115]
	v_mfma_f32_16x16x32_bf16 v[120:123], v[236:239], v[124:127], v[120:123]
	v_mfma_f32_16x16x32_bf16 v[116:119], v[240:243], v[124:127], v[116:119]
	v_cvt_pk_bf16_f32 v0, v0, v1
	v_cvt_pk_bf16_f32 v1, v2, v3
	v_cvt_pk_bf16_f32 v2, v4, v5
	v_cvt_pk_bf16_f32 v3, v6, v7
	s_waitcnt vmcnt(5)
	s_nop 0
	v_mfma_f32_16x16x32_bf16 v[4:7], v[244:247], v[0:3], v[108:111]
	s_nop 2
	v_mfma_f32_16x16x32_bf16 v[108:111], v[248:251], v[0:3], v[112:115]
	s_waitcnt vmcnt(1)
	s_nop 1
	v_mfma_f32_16x16x32_bf16 v[112:115], v[196:199], v[0:3], v[120:123]
	v_mfma_f32_16x16x32_bf16 v[0:3], v[200:203], v[0:3], v[116:119]
	s_nop 2
	v_add_u32_e32 v116, s0, v192
	s_waitcnt vmcnt(0) lgkmcnt(0)
	v_mul_f32_e32 v107, 0xbfb8aa3b, v107
	v_exp_f32_e32 v107, v107
	s_nop 0
	v_add_f32_e32 v107, 1.0, v107
	v_rcp_f32_e32 v107, v107
	s_nop 0
	v_mul_f32_e32 v4, v4, v107
	v_mul_f32_e32 v5, v5, v107
	ds_write2st64_b32 v116, v4, v5 offset1:1
	v_mul_f32_e32 v4, v6, v107
	v_mul_f32_e32 v5, v7, v107
	ds_write2st64_b32 v116, v4, v5 offset0:2 offset1:3
	v_mul_f32_e32 v4, v108, v107
	v_mul_f32_e32 v5, v109, v107
	ds_write2st64_b32 v116, v4, v5 offset0:4 offset1:5
	v_mul_f32_e32 v4, v110, v107
	v_mul_f32_e32 v5, v111, v107
	ds_write2st64_b32 v116, v4, v5 offset0:6 offset1:7
	v_mul_f32_e32 v4, v112, v107
	v_mul_f32_e32 v5, v113, v107
	v_mul_f32_e32 v0, v0, v107
	v_mul_f32_e32 v1, v1, v107
	ds_write2st64_b32 v116, v4, v5 offset0:8 offset1:9
	v_mul_f32_e32 v4, v114, v107
	v_mul_f32_e32 v5, v115, v107
	ds_write2st64_b32 v116, v0, v1 offset0:12 offset1:13
	v_mul_f32_e32 v0, v2, v107
	v_mul_f32_e32 v1, v3, v107
	ds_write2st64_b32 v116, v4, v5 offset0:10 offset1:11
	ds_write2st64_b32 v116, v0, v1 offset0:14 offset1:15
	s_addk_i32 s0, 0x1000
	s_add_i32 s82, s82, 1
	v_lshl_add_u64 v[102:103], v[102:103], 0, 12
	s_cmpk_eq_i32 s0, 0x4000
	v_lshl_add_u64 v[104:105], v[104:105], 0, s[96:97]
	s_cbranch_scc0 .LBB0_188
	s_or_b32 s0, s95, s81
	v_or_b32_e32 v0, s0, v190
	v_ashrrev_i32_e32 v1, 31, v0
	v_lshlrev_b64 v[2:3], 7, v[0:1]
	v_lshl_add_u64 v[2:3], s[86:87], 0, v[2:3]
	s_mul_i32 s82, s2, 48
	v_lshl_add_u64 v[2:3], v[2:3], 0, s[82:83]
	s_mov_b64 s[0:1], 0x2f200020
	v_lshl_add_u64 v[148:149], v[2:3], 0, s[0:1]
	s_lshl_b32 s0, s2, 2
	s_or_b32 s1, s0, 1
	v_cvt_f32_ubyte0_e32 v2, s1
	v_cmp_lt_f32_e32 vcc, s72, v2
	s_or_b32 s1, s0, 2
	v_cvt_f32_ubyte0_e32 v3, s1
	v_cndmask_b32_e32 v6, 0, v220, vcc
	v_sub_f32_e32 v2, v6, v2
	v_exp_f32_e32 v2, v2
	s_or_b32 s1, s0, 3
	s_add_i32 s0, s0, 4
	v_cvt_f32_ubyte0_e32 v4, s1
	v_cvt_f32_ubyte0_e32 v5, s0
	s_and_b64 s[0:1], vcc, exec
	s_cselect_b32 s0, 0xffffffc0, 0
	v_cmp_lt_f32_e32 vcc, s72, v3
	v_ldexp_f32 v34, v2, s0
	s_and_b64 s[0:1], vcc, exec
	v_cndmask_b32_e32 v2, 0, v220, vcc
	v_sub_f32_e32 v2, v2, v3
	v_exp_f32_e32 v2, v2
	s_cselect_b32 s0, 0xffffffc0, 0
	v_cmp_lt_f32_e32 vcc, s72, v4
	v_and_or_b32 v17, v211, 64, v190
	v_ldexp_f32 v35, v2, s0
	v_cndmask_b32_e32 v2, 0, v220, vcc
	v_sub_f32_e32 v2, v2, v4
	v_exp_f32_e32 v2, v2
	s_and_b64 s[0:1], vcc, exec
	s_cselect_b32 s0, 0xffffffc0, 0
	v_cmp_lt_f32_e32 vcc, s72, v5
	v_ldexp_f32 v36, v2, s0
	s_and_b64 s[0:1], vcc, exec
	v_cndmask_b32_e32 v2, 0, v220, vcc
	v_sub_f32_e32 v2, v2, v5
	v_exp_f32_e32 v2, v2
	s_cselect_b32 s0, 0xffffffc0, 0
	s_lshr_b32 s20, s81, 6
	s_add_i32 s22, s20, -1
	v_cmp_eq_u32_e64 s[4:5], s20, v32
	v_cmp_eq_u32_e64 s[6:7], s22, v32
	v_ldexp_f32 v37, v2, s0
	v_cmp_gt_u32_e64 s[0:1], 16, v106
	s_or_b64 s[4:5], s[4:5], s[6:7]
	s_or_b64 s[0:1], s[4:5], s[0:1]
	v_cmp_lt_i32_e32 vcc, s20, v32
	v_cndmask_b32_e64 v2, v14, v222, s[0:1]
	v_lshlrev_b32_e32 v17, 2, v17
	v_cndmask_b32_e32 v14, v2, v221, vcc
	v_add_u32_e32 v2, 4, v32
	v_cmp_eq_u32_e64 s[0:1], 0, v2
	v_cmp_eq_u32_e64 s[6:7], s20, v2
	s_or_b64 s[6:7], s[0:1], s[6:7]
	v_cmp_eq_u32_e64 s[0:1], s22, v2
	s_or_b64 s[0:1], s[6:7], s[0:1]
	v_cmp_lt_i32_e64 s[4:5], s20, v2
	v_cndmask_b32_e64 v3, v15, v222, s[0:1]
	ds_bpermute_b32 v18, v17, v14
	v_cndmask_b32_e64 v15, v3, v221, s[4:5]
	v_add_u32_e32 v3, 8, v32
	v_cmp_eq_u32_e64 s[0:1], 0, v3
	v_cmp_eq_u32_e64 s[8:9], s20, v3
	s_or_b64 s[8:9], s[0:1], s[8:9]
	v_cmp_eq_u32_e64 s[0:1], s22, v3
	s_or_b64 s[0:1], s[8:9], s[0:1]
	v_cmp_lt_i32_e64 s[6:7], s20, v3
	v_cndmask_b32_e64 v4, v12, v222, s[0:1]
	v_cmp_lt_i32_e64 s[24:25], -8, v32
	v_cndmask_b32_e64 v12, v4, v221, s[6:7]
	v_add_u32_e32 v4, 12, v32
	v_cmp_eq_u32_e64 s[0:1], 0, v4
	v_cmp_eq_u32_e64 s[10:11], s20, v4
	s_or_b64 s[10:11], s[0:1], s[10:11]
	v_cmp_eq_u32_e64 s[0:1], s22, v4
	s_or_b64 s[0:1], s[10:11], s[0:1]
	v_cmp_lt_i32_e64 s[8:9], s20, v4
	v_cndmask_b32_e64 v5, v13, v222, s[0:1]
	v_cmp_lt_i32_e64 s[28:29], -12, v32
	v_cndmask_b32_e64 v13, v5, v221, s[8:9]
	v_add_u32_e32 v5, 16, v32
	v_cmp_eq_u32_e64 s[0:1], 0, v5
	v_cmp_eq_u32_e64 s[12:13], s20, v5
	s_or_b64 s[12:13], s[0:1], s[12:13]
	v_cmp_eq_u32_e64 s[0:1], s22, v5
	s_or_b64 s[0:1], s[12:13], s[0:1]
	v_cmp_lt_i32_e64 s[10:11], s20, v5
	v_cndmask_b32_e64 v6, v10, v222, s[0:1]
	v_cmp_lt_i32_e64 s[34:35], -16, v32
	v_cndmask_b32_e64 v10, v6, v221, s[10:11]
	v_add_u32_e32 v6, 20, v32
	v_cmp_eq_u32_e64 s[0:1], 0, v6
	v_cmp_eq_u32_e64 s[14:15], s20, v6
	s_or_b64 s[14:15], s[0:1], s[14:15]
	v_cmp_eq_u32_e64 s[0:1], s22, v6
	s_or_b64 s[0:1], s[14:15], s[0:1]
	v_cmp_lt_i32_e64 s[12:13], s20, v6
	v_cndmask_b32_e64 v7, v11, v222, s[0:1]
	s_movk_i32 s30, 0xffe8
	v_cndmask_b32_e64 v11, v7, v221, s[12:13]
	v_add_u32_e32 v7, 24, v32
	v_cmp_eq_u32_e64 s[0:1], 0, v7
	v_cmp_eq_u32_e64 s[16:17], s20, v7
	s_or_b64 s[16:17], s[0:1], s[16:17]
	v_cmp_eq_u32_e64 s[0:1], s22, v7
	s_or_b64 s[0:1], s[16:17], s[0:1]
	v_cmp_lt_i32_e64 s[14:15], s20, v7
	v_cndmask_b32_e64 v8, v8, v222, s[0:1]
	s_waitcnt lgkmcnt(0)
	v_cmp_eq_f32_e64 s[26:27], v11, v18
	v_cndmask_b32_e64 v16, v8, v221, s[14:15]
	v_add_u32_e32 v8, 28, v32
	v_cmp_lt_i32_e64 s[16:17], s20, v8
	v_cmp_eq_u32_e64 s[0:1], 0, v8
	v_cmp_eq_u32_e64 s[20:21], s20, v8
	s_or_b64 s[20:21], s[0:1], s[20:21]
	v_cmp_eq_u32_e64 s[0:1], s22, v8
	s_or_b64 s[0:1], s[20:21], s[0:1]
	v_cmp_eq_f32_e64 s[20:21], v14, v18
	v_cndmask_b32_e64 v9, v9, v222, s[0:1]
	v_cmp_lt_f32_e64 s[0:1], v14, v18
	s_and_b64 s[20:21], s[18:19], s[20:21]
	s_or_b64 s[0:1], s[0:1], s[20:21]
	v_cmp_eq_f32_e64 s[22:23], v15, v18
	v_cmp_lt_i32_e64 s[20:21], -4, v32
	v_cndmask_b32_e64 v19, 0, 1, s[0:1]
	v_cmp_lt_f32_e64 s[0:1], v15, v18
	s_and_b64 s[22:23], s[20:21], s[22:23]
	s_or_b64 s[0:1], s[0:1], s[22:23]
	v_cmp_eq_f32_e64 s[22:23], v12, v18
	v_cndmask_b32_e64 v20, 0, 1, s[0:1]
	v_cmp_lt_f32_e64 s[0:1], v12, v18
	s_and_b64 s[22:23], s[24:25], s[22:23]
	s_or_b64 s[0:1], s[0:1], s[22:23]
	v_cmp_eq_f32_e64 s[22:23], v13, v18
	v_cndmask_b32_e64 v21, 0, 1, s[0:1]
	v_cmp_lt_f32_e64 s[0:1], v13, v18
	s_and_b64 s[22:23], s[28:29], s[22:23]
	s_or_b64 s[0:1], s[0:1], s[22:23]
	v_cmp_eq_f32_e64 s[22:23], v10, v18
	v_cndmask_b32_e64 v22, 0, 1, s[0:1]
	v_cmp_lt_f32_e64 s[0:1], v10, v18
	s_and_b64 s[22:23], s[34:35], s[22:23]
	s_or_b64 s[0:1], s[0:1], s[22:23]
	v_cndmask_b32_e64 v23, 0, 1, s[0:1]
	s_movk_i32 s0, 0xffec
	v_cmp_lt_i32_e64 s[0:1], s0, v32
	v_cmp_lt_f32_e64 s[22:23], v11, v18
	s_and_b64 s[26:27], s[0:1], s[26:27]
	s_or_b64 s[22:23], s[22:23], s[26:27]
	v_cmp_eq_f32_e64 s[26:27], v16, v18
	v_cmp_lt_i32_e64 s[30:31], s30, v32
	ds_bpermute_b32 v26, v17, v15
	v_cndmask_b32_e64 v9, v9, v221, s[16:17]
	v_cndmask_b32_e64 v24, 0, 1, s[22:23]
	v_cmp_lt_f32_e64 s[22:23], v16, v18
	s_and_b64 s[26:27], s[30:31], s[26:27]
	s_movk_i32 s36, 0xffe4
	s_or_b64 s[22:23], s[22:23], s[26:27]
	v_cmp_eq_f32_e64 s[26:27], v9, v18
	v_cmp_lt_i32_e64 s[36:37], s36, v32
	v_cndmask_b32_e64 v25, 0, 1, s[22:23]
	v_cmp_lt_f32_e64 s[22:23], v9, v18
	s_and_b64 s[26:27], s[36:37], s[26:27]
	s_or_b64 s[22:23], s[22:23], s[26:27]
	v_cndmask_b32_e64 v18, 0, 1, s[22:23]
	s_waitcnt lgkmcnt(0)
	v_cmp_eq_f32_e64 s[36:37], v14, v26
	v_cmp_lt_i32_e64 s[22:23], 4, v32
	v_cmp_lt_f32_e64 s[26:27], v14, v26
	s_and_b64 s[36:37], s[22:23], s[36:37]
	s_or_b64 s[26:27], s[26:27], s[36:37]
	v_addc_co_u32_e64 v19, s[26:27], 0, v19, s[26:27]
	v_cmp_eq_f32_e64 s[36:37], v15, v26
	v_cmp_lt_f32_e64 s[26:27], v15, v26
	s_and_b64 s[36:37], s[18:19], s[36:37]
	s_or_b64 s[26:27], s[26:27], s[36:37]
	v_cmp_eq_f32_e64 s[36:37], v12, v26
	v_cndmask_b32_e64 v27, 0, 1, s[26:27]
	v_cmp_lt_f32_e64 s[26:27], v12, v26
	s_and_b64 s[36:37], s[20:21], s[36:37]
	s_or_b64 s[26:27], s[26:27], s[36:37]
	v_addc_co_u32_e64 v21, s[26:27], 0, v21, s[26:27]
	v_cmp_eq_f32_e64 s[36:37], v13, v26
	v_cmp_lt_f32_e64 s[26:27], v13, v26
	s_and_b64 s[36:37], s[24:25], s[36:37]
	s_or_b64 s[26:27], s[26:27], s[36:37]
	v_cmp_eq_f32_e64 s[36:37], v10, v26
	v_add_u32_e32 v20, v27, v20
	v_cndmask_b32_e64 v27, 0, 1, s[26:27]
	v_cmp_lt_f32_e64 s[26:27], v10, v26
	s_and_b64 s[36:37], s[28:29], s[36:37]
	s_or_b64 s[26:27], s[26:27], s[36:37]
	v_addc_co_u32_e64 v23, s[26:27], 0, v23, s[26:27]
	v_cmp_eq_f32_e64 s[36:37], v11, v26
	v_cmp_lt_f32_e64 s[26:27], v11, v26
	s_and_b64 s[36:37], s[34:35], s[36:37]
	s_or_b64 s[26:27], s[26:27], s[36:37]
	v_cmp_eq_f32_e64 s[36:37], v16, v26
	v_cndmask_b32_e64 v28, 0, 1, s[26:27]
	v_cmp_lt_f32_e64 s[26:27], v16, v26
	s_and_b64 s[36:37], s[0:1], s[36:37]
	ds_bpermute_b32 v29, v17, v12
	s_or_b64 s[26:27], s[26:27], s[36:37]
	v_addc_co_u32_e64 v25, s[26:27], 0, v25, s[26:27]
	v_cmp_eq_f32_e64 s[36:37], v9, v26
	v_cmp_lt_f32_e64 s[26:27], v9, v26
	s_and_b64 s[30:31], s[30:31], s[36:37]
	s_or_b64 s[26:27], s[26:27], s[30:31]
	v_cndmask_b32_e64 v26, 0, 1, s[26:27]
	s_waitcnt lgkmcnt(0)
	v_cmp_eq_f32_e64 s[36:37], v14, v29
	v_cmp_lt_i32_e64 s[26:27], 8, v32
	v_cmp_lt_f32_e64 s[30:31], v14, v29
	s_and_b64 s[36:37], s[26:27], s[36:37]
	s_or_b64 s[30:31], s[30:31], s[36:37]
	v_cmp_eq_f32_e64 s[36:37], v15, v29
	v_cndmask_b32_e64 v30, 0, 1, s[30:31]
	v_cmp_lt_f32_e64 s[30:31], v15, v29
	s_and_b64 s[36:37], s[22:23], s[36:37]
	s_or_b64 s[30:31], s[30:31], s[36:37]
	v_cmp_eq_f32_e64 s[36:37], v12, v29
	v_cndmask_b32_e64 v31, 0, 1, s[30:31]
	v_cmp_lt_f32_e64 s[30:31], v12, v29
	s_and_b64 s[36:37], s[18:19], s[36:37]
	s_or_b64 s[30:31], s[30:31], s[36:37]
	v_cmp_eq_f32_e64 s[36:37], v13, v29
	v_cndmask_b32_e64 v38, 0, 1, s[30:31]
	v_cmp_lt_f32_e64 s[30:31], v13, v29
	s_and_b64 s[36:37], s[20:21], s[36:37]
	s_or_b64 s[30:31], s[30:31], s[36:37]
	v_addc_co_u32_e64 v22, s[30:31], v27, v22, s[30:31]
	v_cmp_eq_f32_e64 s[36:37], v10, v29
	v_cmp_lt_f32_e64 s[30:31], v10, v29
	s_and_b64 s[36:37], s[24:25], s[36:37]
	s_or_b64 s[30:31], s[30:31], s[36:37]
	v_cmp_eq_f32_e64 s[36:37], v11, v29
	v_cndmask_b32_e64 v27, 0, 1, s[30:31]
	v_cmp_lt_f32_e64 s[30:31], v11, v29
	s_and_b64 s[36:37], s[28:29], s[36:37]
	s_or_b64 s[30:31], s[30:31], s[36:37]
	v_addc_co_u32_e64 v24, s[30:31], v28, v24, s[30:31]
	v_cmp_eq_f32_e64 s[36:37], v16, v29
	v_cmp_lt_f32_e64 s[30:31], v16, v29
	s_and_b64 s[36:37], s[34:35], s[36:37]
	s_or_b64 s[30:31], s[30:31], s[36:37]
	v_cmp_eq_f32_e64 s[36:37], v9, v29
	v_cndmask_b32_e64 v28, 0, 1, s[30:31]
	v_cmp_lt_f32_e64 s[30:31], v9, v29
	s_and_b64 s[0:1], s[0:1], s[36:37]
	s_or_b64 s[0:1], s[30:31], s[0:1]
	v_addc_co_u32_e64 v18, s[0:1], v26, v18, s[0:1]
	ds_bpermute_b32 v26, v17, v13
	v_cmp_lt_i32_e64 s[30:31], 12, v32
	v_lshlrev_b32_e64 v2, v2, 1
	v_lshlrev_b32_e64 v3, v3, 1
	v_lshlrev_b32_e64 v4, v4, 1
	s_waitcnt lgkmcnt(0)
	v_cmp_eq_f32_e64 s[36:37], v14, v26
	v_cmp_lt_f32_e64 s[0:1], v14, v26
	s_and_b64 s[36:37], s[30:31], s[36:37]
	s_or_b64 s[0:1], s[0:1], s[36:37]
	v_addc_co_u32_e64 v19, s[0:1], v19, v30, s[0:1]
	v_cmp_eq_f32_e64 s[36:37], v15, v26
	v_cmp_lt_f32_e64 s[0:1], v15, v26
	s_and_b64 s[36:37], s[26:27], s[36:37]
	s_or_b64 s[0:1], s[0:1], s[36:37]
	v_addc_co_u32_e64 v20, s[0:1], v20, v31, s[0:1]
	v_cmp_eq_f32_e64 s[36:37], v12, v26
	v_cmp_lt_f32_e64 s[0:1], v12, v26
	s_and_b64 s[36:37], s[22:23], s[36:37]
	s_or_b64 s[0:1], s[0:1], s[36:37]
	v_addc_co_u32_e64 v21, s[0:1], v21, v38, s[0:1]
	v_cmp_eq_f32_e64 s[36:37], v13, v26
	v_cmp_lt_f32_e64 s[0:1], v13, v26
	s_and_b64 s[36:37], s[18:19], s[36:37]
	s_or_b64 s[0:1], s[0:1], s[36:37]
	v_cmp_eq_f32_e64 s[36:37], v10, v26
	v_cndmask_b32_e64 v29, 0, 1, s[0:1]
	v_cmp_lt_f32_e64 s[0:1], v10, v26
	s_and_b64 s[36:37], s[20:21], s[36:37]
	s_or_b64 s[0:1], s[0:1], s[36:37]
	v_addc_co_u32_e64 v23, s[0:1], v23, v27, s[0:1]
	v_cmp_eq_f32_e64 s[36:37], v11, v26
	v_cmp_lt_f32_e64 s[0:1], v11, v26
	s_and_b64 s[36:37], s[24:25], s[36:37]
	s_or_b64 s[0:1], s[0:1], s[36:37]
	v_cmp_eq_f32_e64 s[36:37], v16, v26
	v_cndmask_b32_e64 v27, 0, 1, s[0:1]
	v_cmp_lt_f32_e64 s[0:1], v16, v26
	s_and_b64 s[36:37], s[28:29], s[36:37]
	s_or_b64 s[0:1], s[0:1], s[36:37]
	v_addc_co_u32_e64 v25, s[0:1], v25, v28, s[0:1]
	ds_bpermute_b32 v28, v17, v10
	v_cmp_eq_f32_e64 s[36:37], v9, v26
	v_cmp_lt_f32_e64 s[0:1], v9, v26
	s_and_b64 s[34:35], s[34:35], s[36:37]
	s_or_b64 s[0:1], s[0:1], s[34:35]
	s_waitcnt lgkmcnt(0)
	v_cmp_eq_f32_e64 s[36:37], v14, v28
	v_cmp_lt_i32_e64 s[34:35], 16, v32
	v_cndmask_b32_e64 v26, 0, 1, s[0:1]
	v_cmp_lt_f32_e64 s[0:1], v14, v28
	s_and_b64 s[36:37], s[34:35], s[36:37]
	s_or_b64 s[0:1], s[0:1], s[36:37]
	v_cmp_eq_f32_e64 s[36:37], v15, v28
	v_add_u32_e32 v22, v22, v29
	v_cndmask_b32_e64 v29, 0, 1, s[0:1]
	v_cmp_lt_f32_e64 s[0:1], v15, v28
	s_and_b64 s[36:37], s[30:31], s[36:37]
	s_or_b64 s[0:1], s[0:1], s[36:37]
	v_cmp_eq_f32_e64 s[36:37], v12, v28
	v_cndmask_b32_e64 v30, 0, 1, s[0:1]
	v_cmp_lt_f32_e64 s[0:1], v12, v28
	s_and_b64 s[36:37], s[26:27], s[36:37]
	s_or_b64 s[0:1], s[0:1], s[36:37]
	v_cmp_eq_f32_e64 s[36:37], v13, v28
	v_cndmask_b32_e64 v31, 0, 1, s[0:1]
	v_cmp_lt_f32_e64 s[0:1], v13, v28
	s_and_b64 s[36:37], s[22:23], s[36:37]
	s_or_b64 s[0:1], s[0:1], s[36:37]
	v_cmp_eq_f32_e64 s[36:37], v10, v28
	v_cndmask_b32_e64 v38, 0, 1, s[0:1]
	v_cmp_lt_f32_e64 s[0:1], v10, v28
	s_and_b64 s[36:37], s[18:19], s[36:37]
	s_or_b64 s[0:1], s[0:1], s[36:37]
	v_cmp_eq_f32_e64 s[36:37], v11, v28
	v_cndmask_b32_e64 v39, 0, 1, s[0:1]
	v_cmp_lt_f32_e64 s[0:1], v11, v28
	s_and_b64 s[36:37], s[20:21], s[36:37]
	s_or_b64 s[0:1], s[0:1], s[36:37]
	v_addc_co_u32_e64 v24, s[0:1], v24, v27, s[0:1]
	v_cmp_eq_f32_e64 s[36:37], v16, v28
	v_cmp_lt_f32_e64 s[0:1], v16, v28
	s_and_b64 s[36:37], s[24:25], s[36:37]
	s_or_b64 s[0:1], s[0:1], s[36:37]
	v_cmp_eq_f32_e64 s[36:37], v9, v28
	v_cndmask_b32_e64 v27, 0, 1, s[0:1]
	v_cmp_lt_f32_e64 s[0:1], v9, v28
	s_and_b64 s[28:29], s[28:29], s[36:37]
	s_or_b64 s[0:1], s[0:1], s[28:29]
	v_addc_co_u32_e64 v18, s[0:1], v18, v26, s[0:1]
	ds_bpermute_b32 v26, v17, v11
	v_cmp_lt_i32_e64 s[0:1], 20, v32
	v_lshlrev_b64 v[0:1], 10, v[0:1]
	s_mov_b32 s38, 1
	v_lshl_add_u64 v[0:1], s[86:87], 0, v[0:1]
	s_waitcnt lgkmcnt(0)
	v_cmp_eq_f32_e64 s[36:37], v14, v26
	v_cmp_lt_f32_e64 s[28:29], v14, v26
	s_and_b64 s[36:37], s[0:1], s[36:37]
	s_or_b64 s[28:29], s[28:29], s[36:37]
	v_addc_co_u32_e64 v19, s[28:29], v19, v29, s[28:29]
	v_cmp_eq_f32_e64 s[36:37], v15, v26
	v_cmp_lt_f32_e64 s[28:29], v15, v26
	s_and_b64 s[36:37], s[34:35], s[36:37]
	s_or_b64 s[28:29], s[28:29], s[36:37]
	v_addc_co_u32_e64 v20, s[28:29], v20, v30, s[28:29]
	v_cmp_eq_f32_e64 s[36:37], v12, v26
	v_cmp_lt_f32_e64 s[28:29], v12, v26
	s_and_b64 s[36:37], s[30:31], s[36:37]
	s_or_b64 s[28:29], s[28:29], s[36:37]
	v_addc_co_u32_e64 v21, s[28:29], v21, v31, s[28:29]
	v_cmp_eq_f32_e64 s[36:37], v13, v26
	v_cmp_lt_f32_e64 s[28:29], v13, v26
	s_and_b64 s[36:37], s[26:27], s[36:37]
	s_or_b64 s[28:29], s[28:29], s[36:37]
	v_addc_co_u32_e64 v22, s[28:29], v22, v38, s[28:29]
	v_cmp_eq_f32_e64 s[36:37], v10, v26
	v_cmp_lt_f32_e64 s[28:29], v10, v26
	s_and_b64 s[36:37], s[22:23], s[36:37]
	s_or_b64 s[28:29], s[28:29], s[36:37]
	v_addc_co_u32_e64 v23, s[28:29], v23, v39, s[28:29]
	v_cmp_eq_f32_e64 s[36:37], v11, v26
	v_cmp_lt_f32_e64 s[28:29], v11, v26
	s_and_b64 s[36:37], s[18:19], s[36:37]
	s_or_b64 s[28:29], s[28:29], s[36:37]
	v_cmp_eq_f32_e64 s[36:37], v16, v26
	v_cndmask_b32_e64 v28, 0, 1, s[28:29]
	v_cmp_lt_f32_e64 s[28:29], v16, v26
	s_and_b64 s[36:37], s[20:21], s[36:37]
	s_or_b64 s[28:29], s[28:29], s[36:37]
	v_addc_co_u32_e64 v25, s[28:29], v25, v27, s[28:29]
	ds_bpermute_b32 v27, v17, v16
	v_cmp_eq_f32_e64 s[36:37], v9, v26
	v_cmp_lt_f32_e64 s[28:29], v9, v26
	s_and_b64 s[24:25], s[24:25], s[36:37]
	s_or_b64 s[24:25], s[28:29], s[24:25]
	s_waitcnt lgkmcnt(0)
	v_cmp_eq_f32_e64 s[28:29], v14, v27
	v_cmp_lt_i32_e64 s[36:37], 24, v32
	v_cndmask_b32_e64 v26, 0, 1, s[24:25]
	v_cmp_lt_f32_e64 s[24:25], v14, v27
	s_and_b64 s[28:29], s[36:37], s[28:29]
	s_or_b64 s[24:25], s[24:25], s[28:29]
	v_cmp_eq_f32_e64 s[28:29], v15, v27
	v_add_u32_e32 v24, v24, v28
	v_cndmask_b32_e64 v28, 0, 1, s[24:25]
	v_cmp_lt_f32_e64 s[24:25], v15, v27
	s_and_b64 s[28:29], s[0:1], s[28:29]
	s_or_b64 s[24:25], s[24:25], s[28:29]
	v_cmp_eq_f32_e64 s[28:29], v12, v27
	v_cndmask_b32_e64 v29, 0, 1, s[24:25]
	v_cmp_lt_f32_e64 s[24:25], v12, v27
	s_and_b64 s[28:29], s[34:35], s[28:29]
	s_or_b64 s[24:25], s[24:25], s[28:29]
	v_cmp_eq_f32_e64 s[28:29], v13, v27
	v_cndmask_b32_e64 v30, 0, 1, s[24:25]
	v_cmp_lt_f32_e64 s[24:25], v13, v27
	s_and_b64 s[28:29], s[30:31], s[28:29]
	s_or_b64 s[24:25], s[24:25], s[28:29]
	v_cmp_eq_f32_e64 s[28:29], v10, v27
	v_cndmask_b32_e64 v31, 0, 1, s[24:25]
	v_cmp_lt_f32_e64 s[24:25], v10, v27
	s_and_b64 s[28:29], s[26:27], s[28:29]
	s_or_b64 s[24:25], s[24:25], s[28:29]
	v_cmp_eq_f32_e64 s[28:29], v11, v27
	v_cndmask_b32_e64 v38, 0, 1, s[24:25]
	v_cmp_lt_f32_e64 s[24:25], v11, v27
	s_and_b64 s[28:29], s[22:23], s[28:29]
	s_or_b64 s[24:25], s[24:25], s[28:29]
	v_cmp_eq_f32_e64 s[28:29], v16, v27
	v_cndmask_b32_e64 v39, 0, 1, s[24:25]
	v_cmp_lt_f32_e64 s[24:25], v16, v27
	s_and_b64 s[28:29], s[18:19], s[28:29]
	s_or_b64 s[24:25], s[24:25], s[28:29]
	v_cmp_eq_f32_e64 s[28:29], v9, v27
	v_cndmask_b32_e64 v40, 0, 1, s[24:25]
	v_cmp_lt_f32_e64 s[24:25], v9, v27
	s_and_b64 s[20:21], s[20:21], s[28:29]
	s_or_b64 s[20:21], s[24:25], s[20:21]
	v_addc_co_u32_e64 v18, s[20:21], v18, v26, s[20:21]
	ds_bpermute_b32 v26, v17, v9
	v_cmp_lt_i32_e64 s[28:29], 28, v32
	v_ashrrev_i32_e32 v33, 31, v32
	s_waitcnt lgkmcnt(0)
	v_cmp_eq_f32_e64 s[24:25], v14, v26
	v_cmp_lt_f32_e64 s[20:21], v14, v26
	s_and_b64 s[24:25], s[28:29], s[24:25]
	s_or_b64 s[20:21], s[20:21], s[24:25]
	v_addc_co_u32_e64 v19, s[20:21], v19, v28, s[20:21]
	v_cmp_eq_f32_e64 s[24:25], v15, v26
	v_cmp_lt_f32_e64 s[20:21], v15, v26
	s_and_b64 s[24:25], s[36:37], s[24:25]
	s_or_b64 s[20:21], s[20:21], s[24:25]
	v_addc_co_u32_e64 v20, s[20:21], v20, v29, s[20:21]
	v_cmp_eq_f32_e64 s[24:25], v12, v26
	v_cmp_lt_f32_e64 s[20:21], v12, v26
	s_and_b64 s[0:1], s[0:1], s[24:25]
	s_or_b64 s[0:1], s[20:21], s[0:1]
	v_addc_co_u32_e64 v21, s[0:1], v21, v30, s[0:1]
	v_cmp_eq_f32_e64 s[20:21], v13, v26
	v_cmp_lt_f32_e64 s[0:1], v13, v26
	s_and_b64 s[20:21], s[34:35], s[20:21]
	s_or_b64 s[0:1], s[0:1], s[20:21]
	v_addc_co_u32_e64 v22, s[0:1], v22, v31, s[0:1]
	v_cmp_eq_f32_e64 s[20:21], v10, v26
	v_cmp_lt_f32_e64 s[0:1], v10, v26
	s_and_b64 s[20:21], s[30:31], s[20:21]
	s_or_b64 s[0:1], s[0:1], s[20:21]
	v_addc_co_u32_e64 v23, s[0:1], v23, v38, s[0:1]
	v_cmp_eq_f32_e64 s[20:21], v11, v26
	v_cmp_lt_f32_e64 s[0:1], v11, v26
	s_and_b64 s[20:21], s[26:27], s[20:21]
	s_or_b64 s[0:1], s[0:1], s[20:21]
	v_addc_co_u32_e64 v24, s[0:1], v24, v39, s[0:1]
	v_cmp_eq_f32_e64 s[20:21], v16, v26
	v_cmp_lt_f32_e64 s[0:1], v16, v26
	s_and_b64 s[20:21], s[22:23], s[20:21]
	s_or_b64 s[0:1], s[0:1], s[20:21]
	v_addc_co_u32_e64 v25, s[0:1], v25, v40, s[0:1]
	v_cmp_eq_f32_e64 s[20:21], v9, v26
	v_cmp_lt_f32_e64 s[0:1], v9, v26
	s_and_b64 s[18:19], s[18:19], s[20:21]
	s_or_b64 s[0:1], s[0:1], s[18:19]
	v_cndmask_b32_e64 v26, 0, 1, s[0:1]
	v_add_u32_e32 v18, v18, v26
	ds_bpermute_b32 v26, v17, v14 offset:64
	v_cmp_lt_i32_e64 s[18:19], 1, v32
	v_cmp_lt_i32_e64 s[24:25], -7, v32
	v_cmp_lt_i32_e64 s[28:29], -11, v32
	v_cmp_lt_i32_e64 s[34:35], -15, v32
	s_waitcnt lgkmcnt(0)
	v_cmp_eq_f32_e64 s[20:21], v14, v26
	v_cmp_lt_f32_e64 s[0:1], v14, v26
	s_and_b64 s[20:21], s[18:19], s[20:21]
	s_or_b64 s[0:1], s[0:1], s[20:21]
	v_cmp_eq_f32_e64 s[22:23], v15, v26
	v_cmp_lt_i32_e64 s[20:21], -3, v32
	v_cndmask_b32_e64 v27, 0, 1, s[0:1]
	v_cmp_lt_f32_e64 s[0:1], v15, v26
	s_and_b64 s[22:23], s[20:21], s[22:23]
	s_or_b64 s[0:1], s[0:1], s[22:23]
	v_cmp_eq_f32_e64 s[22:23], v12, v26
	v_cndmask_b32_e64 v28, 0, 1, s[0:1]
	v_cmp_lt_f32_e64 s[0:1], v12, v26
	s_and_b64 s[22:23], s[24:25], s[22:23]
	s_or_b64 s[0:1], s[0:1], s[22:23]
	v_cmp_eq_f32_e64 s[22:23], v13, v26
	v_cndmask_b32_e64 v29, 0, 1, s[0:1]
	v_cmp_lt_f32_e64 s[0:1], v13, v26
	s_and_b64 s[22:23], s[28:29], s[22:23]
	s_or_b64 s[0:1], s[0:1], s[22:23]
	v_cmp_eq_f32_e64 s[22:23], v10, v26
	v_cndmask_b32_e64 v30, 0, 1, s[0:1]
	v_cmp_lt_f32_e64 s[0:1], v10, v26
	s_and_b64 s[22:23], s[34:35], s[22:23]
	s_or_b64 s[0:1], s[0:1], s[22:23]
	v_cndmask_b32_e64 v31, 0, 1, s[0:1]
	s_movk_i32 s0, 0xffed
	v_cmp_eq_f32_e64 s[26:27], v11, v26
	v_cmp_lt_i32_e64 s[0:1], s0, v32
	v_cmp_lt_f32_e64 s[22:23], v11, v26
	s_and_b64 s[26:27], s[0:1], s[26:27]
	s_movk_i32 s30, 0xffe9
	s_or_b64 s[22:23], s[22:23], s[26:27]
	v_cmp_eq_f32_e64 s[26:27], v16, v26
	v_cmp_lt_i32_e64 s[30:31], s30, v32
	ds_bpermute_b32 v40, v17, v15 offset:64
	v_cndmask_b32_e64 v38, 0, 1, s[22:23]
	v_cmp_lt_f32_e64 s[22:23], v16, v26
	s_and_b64 s[26:27], s[30:31], s[26:27]
	s_movk_i32 s36, 0xffe5
	s_or_b64 s[22:23], s[22:23], s[26:27]
	v_cmp_eq_f32_e64 s[26:27], v9, v26
	v_cmp_lt_i32_e64 s[36:37], s36, v32
	v_cndmask_b32_e64 v39, 0, 1, s[22:23]
	v_cmp_lt_f32_e64 s[22:23], v9, v26
	s_and_b64 s[26:27], s[36:37], s[26:27]
	s_or_b64 s[22:23], s[22:23], s[26:27]
	v_cndmask_b32_e64 v26, 0, 1, s[22:23]
	s_waitcnt lgkmcnt(0)
	v_cmp_eq_f32_e64 s[36:37], v14, v40
	v_cmp_lt_i32_e64 s[22:23], 5, v32
	v_cmp_lt_f32_e64 s[26:27], v14, v40
	s_and_b64 s[36:37], s[22:23], s[36:37]
	s_or_b64 s[26:27], s[26:27], s[36:37]
	v_addc_co_u32_e64 v19, s[26:27], v19, v27, s[26:27]
	v_cmp_eq_f32_e64 s[36:37], v15, v40
	v_cmp_lt_f32_e64 s[26:27], v15, v40
	s_and_b64 s[36:37], s[18:19], s[36:37]
	s_or_b64 s[26:27], s[26:27], s[36:37]
	v_addc_co_u32_e64 v20, s[26:27], v20, v28, s[26:27]
	v_cmp_eq_f32_e64 s[36:37], v12, v40
	v_cmp_lt_f32_e64 s[26:27], v12, v40
	s_and_b64 s[36:37], s[20:21], s[36:37]
	s_or_b64 s[26:27], s[26:27], s[36:37]
	v_addc_co_u32_e64 v21, s[26:27], v21, v29, s[26:27]
	v_cmp_eq_f32_e64 s[36:37], v13, v40
	v_cmp_lt_f32_e64 s[26:27], v13, v40
	s_and_b64 s[36:37], s[24:25], s[36:37]
	s_or_b64 s[26:27], s[26:27], s[36:37]
	v_addc_co_u32_e64 v22, s[26:27], v22, v30, s[26:27]
	v_cmp_eq_f32_e64 s[36:37], v10, v40
	v_cmp_lt_f32_e64 s[26:27], v10, v40
	s_and_b64 s[36:37], s[28:29], s[36:37]
	s_or_b64 s[26:27], s[26:27], s[36:37]
	v_addc_co_u32_e64 v23, s[26:27], v23, v31, s[26:27]
	v_cmp_eq_f32_e64 s[36:37], v11, v40
	v_cmp_lt_f32_e64 s[26:27], v11, v40
	s_and_b64 s[36:37], s[34:35], s[36:37]
	s_or_b64 s[26:27], s[26:27], s[36:37]
	v_addc_co_u32_e64 v24, s[26:27], v24, v38, s[26:27]
	v_cmp_eq_f32_e64 s[36:37], v16, v40
	v_cmp_lt_f32_e64 s[26:27], v16, v40
	s_and_b64 s[36:37], s[0:1], s[36:37]
	s_or_b64 s[26:27], s[26:27], s[36:37]
	v_addc_co_u32_e64 v25, s[26:27], v25, v39, s[26:27]
	v_cmp_eq_f32_e64 s[36:37], v9, v40
	v_cmp_lt_f32_e64 s[26:27], v9, v40
	s_and_b64 s[30:31], s[30:31], s[36:37]
	s_or_b64 s[26:27], s[26:27], s[30:31]
	v_addc_co_u32_e64 v18, s[26:27], v18, v26, s[26:27]
	ds_bpermute_b32 v26, v17, v12 offset:64
	v_cmp_lt_i32_e64 s[26:27], 9, v32
	ds_bpermute_b32 v40, v17, v13 offset:64
	s_waitcnt lgkmcnt(1)
	v_cmp_eq_f32_e64 s[36:37], v14, v26
	v_cmp_lt_f32_e64 s[30:31], v14, v26
	s_and_b64 s[36:37], s[26:27], s[36:37]
	s_or_b64 s[30:31], s[30:31], s[36:37]
	v_cmp_eq_f32_e64 s[36:37], v15, v26
	v_cndmask_b32_e64 v27, 0, 1, s[30:31]
	v_cmp_lt_f32_e64 s[30:31], v15, v26
	s_and_b64 s[36:37], s[22:23], s[36:37]
	s_or_b64 s[30:31], s[30:31], s[36:37]
	v_cmp_eq_f32_e64 s[36:37], v12, v26
	v_cndmask_b32_e64 v28, 0, 1, s[30:31]
	v_cmp_lt_f32_e64 s[30:31], v12, v26
	s_and_b64 s[36:37], s[18:19], s[36:37]
	s_or_b64 s[30:31], s[30:31], s[36:37]
	v_cmp_eq_f32_e64 s[36:37], v13, v26
	v_cndmask_b32_e64 v29, 0, 1, s[30:31]
	v_cmp_lt_f32_e64 s[30:31], v13, v26
	s_and_b64 s[36:37], s[20:21], s[36:37]
	s_or_b64 s[30:31], s[30:31], s[36:37]
	v_cmp_eq_f32_e64 s[36:37], v10, v26
	v_cndmask_b32_e64 v30, 0, 1, s[30:31]
	v_cmp_lt_f32_e64 s[30:31], v10, v26
	s_and_b64 s[36:37], s[24:25], s[36:37]
	s_or_b64 s[30:31], s[30:31], s[36:37]
	v_cmp_eq_f32_e64 s[36:37], v11, v26
	v_cndmask_b32_e64 v31, 0, 1, s[30:31]
	v_cmp_lt_f32_e64 s[30:31], v11, v26
	s_and_b64 s[36:37], s[28:29], s[36:37]
	s_or_b64 s[30:31], s[30:31], s[36:37]
	v_cmp_eq_f32_e64 s[36:37], v16, v26
	v_cndmask_b32_e64 v38, 0, 1, s[30:31]
	v_cmp_lt_f32_e64 s[30:31], v16, v26
	s_and_b64 s[36:37], s[34:35], s[36:37]
	s_or_b64 s[30:31], s[30:31], s[36:37]
	v_cmp_eq_f32_e64 s[36:37], v9, v26
	v_cndmask_b32_e64 v39, 0, 1, s[30:31]
	v_cmp_lt_f32_e64 s[30:31], v9, v26
	s_and_b64 s[0:1], s[0:1], s[36:37]
	s_or_b64 s[0:1], s[30:31], s[0:1]
	s_waitcnt lgkmcnt(0)
	v_cmp_eq_f32_e64 s[36:37], v14, v40
	v_cmp_lt_i32_e64 s[30:31], 13, v32
	v_cndmask_b32_e64 v26, 0, 1, s[0:1]
	v_cmp_lt_f32_e64 s[0:1], v14, v40
	s_and_b64 s[36:37], s[30:31], s[36:37]
	s_or_b64 s[0:1], s[0:1], s[36:37]
	v_addc_co_u32_e64 v19, s[0:1], v19, v27, s[0:1]
	v_cmp_eq_f32_e64 s[36:37], v15, v40
	v_cmp_lt_f32_e64 s[0:1], v15, v40
	s_and_b64 s[36:37], s[26:27], s[36:37]
	s_or_b64 s[0:1], s[0:1], s[36:37]
	v_addc_co_u32_e64 v20, s[0:1], v20, v28, s[0:1]
	v_cmp_eq_f32_e64 s[36:37], v12, v40
	v_cmp_lt_f32_e64 s[0:1], v12, v40
	s_and_b64 s[36:37], s[22:23], s[36:37]
	s_or_b64 s[0:1], s[0:1], s[36:37]
	v_addc_co_u32_e64 v21, s[0:1], v21, v29, s[0:1]
	v_cmp_eq_f32_e64 s[36:37], v13, v40
	v_cmp_lt_f32_e64 s[0:1], v13, v40
	s_and_b64 s[36:37], s[18:19], s[36:37]
	s_or_b64 s[0:1], s[0:1], s[36:37]
	v_addc_co_u32_e64 v22, s[0:1], v22, v30, s[0:1]
	v_cmp_eq_f32_e64 s[36:37], v10, v40
	v_cmp_lt_f32_e64 s[0:1], v10, v40
	s_and_b64 s[36:37], s[20:21], s[36:37]
	s_or_b64 s[0:1], s[0:1], s[36:37]
	v_addc_co_u32_e64 v23, s[0:1], v23, v31, s[0:1]
	v_cmp_eq_f32_e64 s[36:37], v11, v40
	v_cmp_lt_f32_e64 s[0:1], v11, v40
	s_and_b64 s[36:37], s[24:25], s[36:37]
	s_or_b64 s[0:1], s[0:1], s[36:37]
	v_addc_co_u32_e64 v24, s[0:1], v24, v38, s[0:1]
	v_cmp_eq_f32_e64 s[36:37], v16, v40
	v_cmp_lt_f32_e64 s[0:1], v16, v40
	s_and_b64 s[36:37], s[28:29], s[36:37]
	s_or_b64 s[0:1], s[0:1], s[36:37]
	v_addc_co_u32_e64 v25, s[0:1], v25, v39, s[0:1]
	v_cmp_eq_f32_e64 s[36:37], v9, v40
	v_cmp_lt_f32_e64 s[0:1], v9, v40
	s_and_b64 s[34:35], s[34:35], s[36:37]
	s_or_b64 s[0:1], s[0:1], s[34:35]
	v_addc_co_u32_e64 v18, s[0:1], v18, v26, s[0:1]
	ds_bpermute_b32 v26, v17, v10 offset:64
	v_cmp_lt_i32_e64 s[34:35], 17, v32
	ds_bpermute_b32 v40, v17, v11 offset:64
	s_waitcnt lgkmcnt(1)
	v_cmp_eq_f32_e64 s[36:37], v14, v26
	v_cmp_lt_f32_e64 s[0:1], v14, v26
	s_and_b64 s[36:37], s[34:35], s[36:37]
	s_or_b64 s[0:1], s[0:1], s[36:37]
	v_cmp_eq_f32_e64 s[36:37], v15, v26
	v_cndmask_b32_e64 v27, 0, 1, s[0:1]
	v_cmp_lt_f32_e64 s[0:1], v15, v26
	s_and_b64 s[36:37], s[30:31], s[36:37]
	s_or_b64 s[0:1], s[0:1], s[36:37]
	v_cmp_eq_f32_e64 s[36:37], v12, v26
	v_cndmask_b32_e64 v28, 0, 1, s[0:1]
	v_cmp_lt_f32_e64 s[0:1], v12, v26
	s_and_b64 s[36:37], s[26:27], s[36:37]
	s_or_b64 s[0:1], s[0:1], s[36:37]
	v_cmp_eq_f32_e64 s[36:37], v13, v26
	v_cndmask_b32_e64 v29, 0, 1, s[0:1]
	v_cmp_lt_f32_e64 s[0:1], v13, v26
	s_and_b64 s[36:37], s[22:23], s[36:37]
	s_or_b64 s[0:1], s[0:1], s[36:37]
	v_cmp_eq_f32_e64 s[36:37], v10, v26
	v_cndmask_b32_e64 v30, 0, 1, s[0:1]
	v_cmp_lt_f32_e64 s[0:1], v10, v26
	s_and_b64 s[36:37], s[18:19], s[36:37]
	s_or_b64 s[0:1], s[0:1], s[36:37]
	v_cmp_eq_f32_e64 s[36:37], v11, v26
	v_cndmask_b32_e64 v31, 0, 1, s[0:1]
	v_cmp_lt_f32_e64 s[0:1], v11, v26
	s_and_b64 s[36:37], s[20:21], s[36:37]
	s_or_b64 s[0:1], s[0:1], s[36:37]
	v_cmp_eq_f32_e64 s[36:37], v16, v26
	v_cndmask_b32_e64 v38, 0, 1, s[0:1]
	v_cmp_lt_f32_e64 s[0:1], v16, v26
	s_and_b64 s[36:37], s[24:25], s[36:37]
	s_or_b64 s[0:1], s[0:1], s[36:37]
	v_cmp_eq_f32_e64 s[36:37], v9, v26
	v_cndmask_b32_e64 v39, 0, 1, s[0:1]
	v_cmp_lt_f32_e64 s[0:1], v9, v26
	s_and_b64 s[28:29], s[28:29], s[36:37]
	s_or_b64 s[0:1], s[0:1], s[28:29]
	v_cndmask_b32_e64 v26, 0, 1, s[0:1]
	s_waitcnt lgkmcnt(0)
	v_cmp_eq_f32_e64 s[36:37], v14, v40
	v_cmp_lt_i32_e64 s[0:1], 21, v32
	v_cmp_lt_f32_e64 s[28:29], v14, v40
	s_and_b64 s[36:37], s[0:1], s[36:37]
	s_or_b64 s[28:29], s[28:29], s[36:37]
	v_addc_co_u32_e64 v19, s[28:29], v19, v27, s[28:29]
	v_cmp_eq_f32_e64 s[36:37], v15, v40
	v_cmp_lt_f32_e64 s[28:29], v15, v40
	s_and_b64 s[36:37], s[34:35], s[36:37]
	s_or_b64 s[28:29], s[28:29], s[36:37]
	v_addc_co_u32_e64 v20, s[28:29], v20, v28, s[28:29]
	v_cmp_eq_f32_e64 s[36:37], v12, v40
	v_cmp_lt_f32_e64 s[28:29], v12, v40
	s_and_b64 s[36:37], s[30:31], s[36:37]
	s_or_b64 s[28:29], s[28:29], s[36:37]
	v_addc_co_u32_e64 v21, s[28:29], v21, v29, s[28:29]
	v_cmp_eq_f32_e64 s[36:37], v13, v40
	v_cmp_lt_f32_e64 s[28:29], v13, v40
	s_and_b64 s[36:37], s[26:27], s[36:37]
	s_or_b64 s[28:29], s[28:29], s[36:37]
	v_addc_co_u32_e64 v22, s[28:29], v22, v30, s[28:29]
	v_cmp_eq_f32_e64 s[36:37], v10, v40
	v_cmp_lt_f32_e64 s[28:29], v10, v40
	s_and_b64 s[36:37], s[22:23], s[36:37]
	s_or_b64 s[28:29], s[28:29], s[36:37]
	v_addc_co_u32_e64 v23, s[28:29], v23, v31, s[28:29]
	v_cmp_eq_f32_e64 s[36:37], v11, v40
	v_cmp_lt_f32_e64 s[28:29], v11, v40
	s_and_b64 s[36:37], s[18:19], s[36:37]
	s_or_b64 s[28:29], s[28:29], s[36:37]
	v_addc_co_u32_e64 v24, s[28:29], v24, v38, s[28:29]
	v_cmp_eq_f32_e64 s[36:37], v16, v40
	v_cmp_lt_f32_e64 s[28:29], v16, v40
	s_and_b64 s[36:37], s[20:21], s[36:37]
	s_or_b64 s[28:29], s[28:29], s[36:37]
	v_addc_co_u32_e64 v25, s[28:29], v25, v39, s[28:29]
	v_cmp_eq_f32_e64 s[36:37], v9, v40
	v_cmp_lt_f32_e64 s[28:29], v9, v40
	s_and_b64 s[24:25], s[24:25], s[36:37]
	s_or_b64 s[24:25], s[28:29], s[24:25]
	v_addc_co_u32_e64 v18, s[24:25], v18, v26, s[24:25]
	ds_bpermute_b32 v26, v17, v16 offset:64
	v_cmp_lt_i32_e64 s[36:37], 25, v32
	ds_bpermute_b32 v40, v17, v9 offset:64
	s_waitcnt lgkmcnt(1)
	v_cmp_eq_f32_e64 s[28:29], v14, v26
	v_cmp_lt_f32_e64 s[24:25], v14, v26
	s_and_b64 s[28:29], s[36:37], s[28:29]
	s_or_b64 s[24:25], s[24:25], s[28:29]
	v_cmp_eq_f32_e64 s[28:29], v15, v26
	v_cndmask_b32_e64 v27, 0, 1, s[24:25]
	v_cmp_lt_f32_e64 s[24:25], v15, v26
	s_and_b64 s[28:29], s[0:1], s[28:29]
	s_or_b64 s[24:25], s[24:25], s[28:29]
	v_cmp_eq_f32_e64 s[28:29], v12, v26
	v_cndmask_b32_e64 v28, 0, 1, s[24:25]
	v_cmp_lt_f32_e64 s[24:25], v12, v26
	s_and_b64 s[28:29], s[34:35], s[28:29]
	s_or_b64 s[24:25], s[24:25], s[28:29]
	v_cmp_eq_f32_e64 s[28:29], v13, v26
	v_cndmask_b32_e64 v29, 0, 1, s[24:25]
	v_cmp_lt_f32_e64 s[24:25], v13, v26
	s_and_b64 s[28:29], s[30:31], s[28:29]
	s_or_b64 s[24:25], s[24:25], s[28:29]
	v_cmp_eq_f32_e64 s[28:29], v10, v26
	v_cndmask_b32_e64 v30, 0, 1, s[24:25]
	v_cmp_lt_f32_e64 s[24:25], v10, v26
	s_and_b64 s[28:29], s[26:27], s[28:29]
	s_or_b64 s[24:25], s[24:25], s[28:29]
	v_cmp_eq_f32_e64 s[28:29], v11, v26
	v_cndmask_b32_e64 v31, 0, 1, s[24:25]
	v_cmp_lt_f32_e64 s[24:25], v11, v26
	s_and_b64 s[28:29], s[22:23], s[28:29]
	s_or_b64 s[24:25], s[24:25], s[28:29]
	v_cmp_eq_f32_e64 s[28:29], v16, v26
	v_cndmask_b32_e64 v38, 0, 1, s[24:25]
	v_cmp_lt_f32_e64 s[24:25], v16, v26
	s_and_b64 s[28:29], s[18:19], s[28:29]
	s_or_b64 s[24:25], s[24:25], s[28:29]
	v_cmp_eq_f32_e64 s[28:29], v9, v26
	v_cndmask_b32_e64 v39, 0, 1, s[24:25]
	v_cmp_lt_f32_e64 s[24:25], v9, v26
	s_and_b64 s[20:21], s[20:21], s[28:29]
	s_or_b64 s[20:21], s[24:25], s[20:21]
	s_waitcnt lgkmcnt(0)
	v_cmp_eq_f32_e64 s[24:25], v14, v40
	v_cmp_lt_i32_e64 s[28:29], 29, v32
	v_cndmask_b32_e64 v26, 0, 1, s[20:21]
	v_cmp_lt_f32_e64 s[20:21], v14, v40
	s_and_b64 s[24:25], s[28:29], s[24:25]
	s_or_b64 s[20:21], s[20:21], s[24:25]
	v_addc_co_u32_e64 v19, s[20:21], v19, v27, s[20:21]
	v_cmp_eq_f32_e64 s[24:25], v15, v40
	v_cmp_lt_f32_e64 s[20:21], v15, v40
	s_and_b64 s[24:25], s[36:37], s[24:25]
	s_or_b64 s[20:21], s[20:21], s[24:25]
	v_addc_co_u32_e64 v20, s[20:21], v20, v28, s[20:21]
	v_cmp_eq_f32_e64 s[24:25], v12, v40
	v_cmp_lt_f32_e64 s[20:21], v12, v40
	s_and_b64 s[0:1], s[0:1], s[24:25]
	s_or_b64 s[0:1], s[20:21], s[0:1]
	v_addc_co_u32_e64 v21, s[0:1], v21, v29, s[0:1]
	v_cmp_eq_f32_e64 s[20:21], v13, v40
	v_cmp_lt_f32_e64 s[0:1], v13, v40
	s_and_b64 s[20:21], s[34:35], s[20:21]
	s_or_b64 s[0:1], s[0:1], s[20:21]
	v_addc_co_u32_e64 v22, s[0:1], v22, v30, s[0:1]
	v_cmp_eq_f32_e64 s[20:21], v10, v40
	v_cmp_lt_f32_e64 s[0:1], v10, v40
	s_and_b64 s[20:21], s[30:31], s[20:21]
	s_or_b64 s[0:1], s[0:1], s[20:21]
	v_addc_co_u32_e64 v23, s[0:1], v23, v31, s[0:1]
	v_cmp_eq_f32_e64 s[20:21], v11, v40
	v_cmp_lt_f32_e64 s[0:1], v11, v40
	s_and_b64 s[20:21], s[26:27], s[20:21]
	s_or_b64 s[0:1], s[0:1], s[20:21]
	v_addc_co_u32_e64 v24, s[0:1], v24, v38, s[0:1]
	v_cmp_eq_f32_e64 s[20:21], v16, v40
	v_cmp_lt_f32_e64 s[0:1], v16, v40
	s_and_b64 s[20:21], s[22:23], s[20:21]
	s_or_b64 s[0:1], s[0:1], s[20:21]
	v_addc_co_u32_e64 v25, s[0:1], v25, v39, s[0:1]
	v_cmp_eq_f32_e64 s[20:21], v9, v40
	v_cmp_lt_f32_e64 s[0:1], v9, v40
	s_and_b64 s[18:19], s[18:19], s[20:21]
	s_or_b64 s[0:1], s[0:1], s[18:19]
	v_addc_co_u32_e64 v18, s[0:1], v18, v26, s[0:1]
	ds_bpermute_b32 v26, v17, v14 offset:128
	v_cmp_lt_i32_e64 s[18:19], 2, v32
	v_cmp_lt_i32_e64 s[24:25], -6, v32
	v_cmp_lt_i32_e64 s[28:29], -10, v32
	v_cmp_lt_i32_e64 s[34:35], -14, v32
	s_waitcnt lgkmcnt(0)
	v_cmp_eq_f32_e64 s[20:21], v14, v26
	v_cmp_lt_f32_e64 s[0:1], v14, v26
	s_and_b64 s[20:21], s[18:19], s[20:21]
	s_or_b64 s[0:1], s[0:1], s[20:21]
	v_cmp_eq_f32_e64 s[22:23], v15, v26
	v_cmp_lt_i32_e64 s[20:21], -2, v32
	v_cndmask_b32_e64 v27, 0, 1, s[0:1]
	v_cmp_lt_f32_e64 s[0:1], v15, v26
	s_and_b64 s[22:23], s[20:21], s[22:23]
	s_or_b64 s[0:1], s[0:1], s[22:23]
	v_cmp_eq_f32_e64 s[22:23], v12, v26
	v_cndmask_b32_e64 v28, 0, 1, s[0:1]
	v_cmp_lt_f32_e64 s[0:1], v12, v26
	s_and_b64 s[22:23], s[24:25], s[22:23]
	s_or_b64 s[0:1], s[0:1], s[22:23]
	v_cmp_eq_f32_e64 s[22:23], v13, v26
	v_cndmask_b32_e64 v29, 0, 1, s[0:1]
	v_cmp_lt_f32_e64 s[0:1], v13, v26
	s_and_b64 s[22:23], s[28:29], s[22:23]
	s_or_b64 s[0:1], s[0:1], s[22:23]
	v_cmp_eq_f32_e64 s[22:23], v10, v26
	v_cndmask_b32_e64 v30, 0, 1, s[0:1]
	v_cmp_lt_f32_e64 s[0:1], v10, v26
	s_and_b64 s[22:23], s[34:35], s[22:23]
	s_or_b64 s[0:1], s[0:1], s[22:23]
	v_cndmask_b32_e64 v31, 0, 1, s[0:1]
	s_movk_i32 s0, 0xffee
	v_cmp_eq_f32_e64 s[26:27], v11, v26
	v_cmp_lt_i32_e64 s[0:1], s0, v32
	v_cmp_lt_f32_e64 s[22:23], v11, v26
	s_and_b64 s[26:27], s[0:1], s[26:27]
	s_movk_i32 s30, 0xffea
	s_or_b64 s[22:23], s[22:23], s[26:27]
	v_cmp_eq_f32_e64 s[26:27], v16, v26
	v_cmp_lt_i32_e64 s[30:31], s30, v32
	ds_bpermute_b32 v40, v17, v15 offset:128
	v_cndmask_b32_e64 v38, 0, 1, s[22:23]
	v_cmp_lt_f32_e64 s[22:23], v16, v26
	s_and_b64 s[26:27], s[30:31], s[26:27]
	s_movk_i32 s36, 0xffe6
	s_or_b64 s[22:23], s[22:23], s[26:27]
	v_cmp_eq_f32_e64 s[26:27], v9, v26
	v_cmp_lt_i32_e64 s[36:37], s36, v32
	v_cndmask_b32_e64 v39, 0, 1, s[22:23]
	v_cmp_lt_f32_e64 s[22:23], v9, v26
	s_and_b64 s[26:27], s[36:37], s[26:27]
	s_or_b64 s[22:23], s[22:23], s[26:27]
	v_cndmask_b32_e64 v26, 0, 1, s[22:23]
	s_waitcnt lgkmcnt(0)
	v_cmp_eq_f32_e64 s[36:37], v14, v40
	v_cmp_lt_i32_e64 s[22:23], 6, v32
	v_cmp_lt_f32_e64 s[26:27], v14, v40
	s_and_b64 s[36:37], s[22:23], s[36:37]
	s_or_b64 s[26:27], s[26:27], s[36:37]
	v_addc_co_u32_e64 v19, s[26:27], v19, v27, s[26:27]
	v_cmp_eq_f32_e64 s[36:37], v15, v40
	v_cmp_lt_f32_e64 s[26:27], v15, v40
	s_and_b64 s[36:37], s[18:19], s[36:37]
	s_or_b64 s[26:27], s[26:27], s[36:37]
	v_addc_co_u32_e64 v20, s[26:27], v20, v28, s[26:27]
	v_cmp_eq_f32_e64 s[36:37], v12, v40
	v_cmp_lt_f32_e64 s[26:27], v12, v40
	s_and_b64 s[36:37], s[20:21], s[36:37]
	s_or_b64 s[26:27], s[26:27], s[36:37]
	v_addc_co_u32_e64 v21, s[26:27], v21, v29, s[26:27]
	v_cmp_eq_f32_e64 s[36:37], v13, v40
	v_cmp_lt_f32_e64 s[26:27], v13, v40
	s_and_b64 s[36:37], s[24:25], s[36:37]
	s_or_b64 s[26:27], s[26:27], s[36:37]
	v_addc_co_u32_e64 v22, s[26:27], v22, v30, s[26:27]
	v_cmp_eq_f32_e64 s[36:37], v10, v40
	v_cmp_lt_f32_e64 s[26:27], v10, v40
	s_and_b64 s[36:37], s[28:29], s[36:37]
	s_or_b64 s[26:27], s[26:27], s[36:37]
	v_addc_co_u32_e64 v23, s[26:27], v23, v31, s[26:27]
	v_cmp_eq_f32_e64 s[36:37], v11, v40
	v_cmp_lt_f32_e64 s[26:27], v11, v40
	s_and_b64 s[36:37], s[34:35], s[36:37]
	s_or_b64 s[26:27], s[26:27], s[36:37]
	v_addc_co_u32_e64 v24, s[26:27], v24, v38, s[26:27]
	v_cmp_eq_f32_e64 s[36:37], v16, v40
	v_cmp_lt_f32_e64 s[26:27], v16, v40
	s_and_b64 s[36:37], s[0:1], s[36:37]
	s_or_b64 s[26:27], s[26:27], s[36:37]
	v_addc_co_u32_e64 v25, s[26:27], v25, v39, s[26:27]
	v_cmp_eq_f32_e64 s[36:37], v9, v40
	v_cmp_lt_f32_e64 s[26:27], v9, v40
	s_and_b64 s[30:31], s[30:31], s[36:37]
	s_or_b64 s[26:27], s[26:27], s[30:31]
	v_addc_co_u32_e64 v18, s[26:27], v18, v26, s[26:27]
	ds_bpermute_b32 v26, v17, v12 offset:128
	v_cmp_lt_i32_e64 s[26:27], 10, v32
	ds_bpermute_b32 v40, v17, v13 offset:128
	s_waitcnt lgkmcnt(1)
	v_cmp_eq_f32_e64 s[36:37], v14, v26
	v_cmp_lt_f32_e64 s[30:31], v14, v26
	s_and_b64 s[36:37], s[26:27], s[36:37]
	s_or_b64 s[30:31], s[30:31], s[36:37]
	v_cmp_eq_f32_e64 s[36:37], v15, v26
	v_cndmask_b32_e64 v27, 0, 1, s[30:31]
	v_cmp_lt_f32_e64 s[30:31], v15, v26
	s_and_b64 s[36:37], s[22:23], s[36:37]
	s_or_b64 s[30:31], s[30:31], s[36:37]
	v_cmp_eq_f32_e64 s[36:37], v12, v26
	v_cndmask_b32_e64 v28, 0, 1, s[30:31]
	v_cmp_lt_f32_e64 s[30:31], v12, v26
	s_and_b64 s[36:37], s[18:19], s[36:37]
	s_or_b64 s[30:31], s[30:31], s[36:37]
	v_cmp_eq_f32_e64 s[36:37], v13, v26
	v_cndmask_b32_e64 v29, 0, 1, s[30:31]
	v_cmp_lt_f32_e64 s[30:31], v13, v26
	s_and_b64 s[36:37], s[20:21], s[36:37]
	s_or_b64 s[30:31], s[30:31], s[36:37]
	v_cmp_eq_f32_e64 s[36:37], v10, v26
	v_cndmask_b32_e64 v30, 0, 1, s[30:31]
	v_cmp_lt_f32_e64 s[30:31], v10, v26
	s_and_b64 s[36:37], s[24:25], s[36:37]
	s_or_b64 s[30:31], s[30:31], s[36:37]
	v_cmp_eq_f32_e64 s[36:37], v11, v26
	v_cndmask_b32_e64 v31, 0, 1, s[30:31]
	v_cmp_lt_f32_e64 s[30:31], v11, v26
	s_and_b64 s[36:37], s[28:29], s[36:37]
	s_or_b64 s[30:31], s[30:31], s[36:37]
	v_cmp_eq_f32_e64 s[36:37], v16, v26
	v_cndmask_b32_e64 v38, 0, 1, s[30:31]
	v_cmp_lt_f32_e64 s[30:31], v16, v26
	s_and_b64 s[36:37], s[34:35], s[36:37]
	s_or_b64 s[30:31], s[30:31], s[36:37]
	v_cmp_eq_f32_e64 s[36:37], v9, v26
	v_cndmask_b32_e64 v39, 0, 1, s[30:31]
	v_cmp_lt_f32_e64 s[30:31], v9, v26
	s_and_b64 s[0:1], s[0:1], s[36:37]
	s_or_b64 s[0:1], s[30:31], s[0:1]
	s_waitcnt lgkmcnt(0)
	v_cmp_eq_f32_e64 s[36:37], v14, v40
	v_cmp_lt_i32_e64 s[30:31], 14, v32
	v_cndmask_b32_e64 v26, 0, 1, s[0:1]
	v_cmp_lt_f32_e64 s[0:1], v14, v40
	s_and_b64 s[36:37], s[30:31], s[36:37]
	s_or_b64 s[0:1], s[0:1], s[36:37]
	v_addc_co_u32_e64 v19, s[0:1], v19, v27, s[0:1]
	v_cmp_eq_f32_e64 s[36:37], v15, v40
	v_cmp_lt_f32_e64 s[0:1], v15, v40
	s_and_b64 s[36:37], s[26:27], s[36:37]
	s_or_b64 s[0:1], s[0:1], s[36:37]
	v_addc_co_u32_e64 v20, s[0:1], v20, v28, s[0:1]
	v_cmp_eq_f32_e64 s[36:37], v12, v40
	v_cmp_lt_f32_e64 s[0:1], v12, v40
	s_and_b64 s[36:37], s[22:23], s[36:37]
	s_or_b64 s[0:1], s[0:1], s[36:37]
	v_addc_co_u32_e64 v21, s[0:1], v21, v29, s[0:1]
	v_cmp_eq_f32_e64 s[36:37], v13, v40
	v_cmp_lt_f32_e64 s[0:1], v13, v40
	s_and_b64 s[36:37], s[18:19], s[36:37]
	s_or_b64 s[0:1], s[0:1], s[36:37]
	v_addc_co_u32_e64 v22, s[0:1], v22, v30, s[0:1]
	v_cmp_eq_f32_e64 s[36:37], v10, v40
	v_cmp_lt_f32_e64 s[0:1], v10, v40
	s_and_b64 s[36:37], s[20:21], s[36:37]
	s_or_b64 s[0:1], s[0:1], s[36:37]
	v_addc_co_u32_e64 v23, s[0:1], v23, v31, s[0:1]
	v_cmp_eq_f32_e64 s[36:37], v11, v40
	v_cmp_lt_f32_e64 s[0:1], v11, v40
	s_and_b64 s[36:37], s[24:25], s[36:37]
	s_or_b64 s[0:1], s[0:1], s[36:37]
	v_addc_co_u32_e64 v24, s[0:1], v24, v38, s[0:1]
	v_cmp_eq_f32_e64 s[36:37], v16, v40
	v_cmp_lt_f32_e64 s[0:1], v16, v40
	s_and_b64 s[36:37], s[28:29], s[36:37]
	s_or_b64 s[0:1], s[0:1], s[36:37]
	v_addc_co_u32_e64 v25, s[0:1], v25, v39, s[0:1]
	v_cmp_eq_f32_e64 s[36:37], v9, v40
	v_cmp_lt_f32_e64 s[0:1], v9, v40
	s_and_b64 s[34:35], s[34:35], s[36:37]
	s_or_b64 s[0:1], s[0:1], s[34:35]
	v_addc_co_u32_e64 v18, s[0:1], v18, v26, s[0:1]
	ds_bpermute_b32 v26, v17, v10 offset:128
	v_cmp_lt_i32_e64 s[34:35], 18, v32
	ds_bpermute_b32 v40, v17, v11 offset:128
	s_waitcnt lgkmcnt(1)
	v_cmp_eq_f32_e64 s[36:37], v14, v26
	v_cmp_lt_f32_e64 s[0:1], v14, v26
	s_and_b64 s[36:37], s[34:35], s[36:37]
	s_or_b64 s[0:1], s[0:1], s[36:37]
	v_cmp_eq_f32_e64 s[36:37], v15, v26
	v_cndmask_b32_e64 v27, 0, 1, s[0:1]
	v_cmp_lt_f32_e64 s[0:1], v15, v26
	s_and_b64 s[36:37], s[30:31], s[36:37]
	s_or_b64 s[0:1], s[0:1], s[36:37]
	v_cmp_eq_f32_e64 s[36:37], v12, v26
	v_cndmask_b32_e64 v28, 0, 1, s[0:1]
	v_cmp_lt_f32_e64 s[0:1], v12, v26
	s_and_b64 s[36:37], s[26:27], s[36:37]
	s_or_b64 s[0:1], s[0:1], s[36:37]
	v_cmp_eq_f32_e64 s[36:37], v13, v26
	v_cndmask_b32_e64 v29, 0, 1, s[0:1]
	v_cmp_lt_f32_e64 s[0:1], v13, v26
	s_and_b64 s[36:37], s[22:23], s[36:37]
	s_or_b64 s[0:1], s[0:1], s[36:37]
	v_cmp_eq_f32_e64 s[36:37], v10, v26
	v_cndmask_b32_e64 v30, 0, 1, s[0:1]
	v_cmp_lt_f32_e64 s[0:1], v10, v26
	s_and_b64 s[36:37], s[18:19], s[36:37]
	s_or_b64 s[0:1], s[0:1], s[36:37]
	v_cmp_eq_f32_e64 s[36:37], v11, v26
	v_cndmask_b32_e64 v31, 0, 1, s[0:1]
	v_cmp_lt_f32_e64 s[0:1], v11, v26
	s_and_b64 s[36:37], s[20:21], s[36:37]
	s_or_b64 s[0:1], s[0:1], s[36:37]
	v_cmp_eq_f32_e64 s[36:37], v16, v26
	v_cndmask_b32_e64 v38, 0, 1, s[0:1]
	v_cmp_lt_f32_e64 s[0:1], v16, v26
	s_and_b64 s[36:37], s[24:25], s[36:37]
	s_or_b64 s[0:1], s[0:1], s[36:37]
	v_cmp_eq_f32_e64 s[36:37], v9, v26
	v_cndmask_b32_e64 v39, 0, 1, s[0:1]
	v_cmp_lt_f32_e64 s[0:1], v9, v26
	s_and_b64 s[28:29], s[28:29], s[36:37]
	s_or_b64 s[0:1], s[0:1], s[28:29]
	v_cndmask_b32_e64 v26, 0, 1, s[0:1]
	s_waitcnt lgkmcnt(0)
	v_cmp_eq_f32_e64 s[36:37], v14, v40
	v_cmp_lt_i32_e64 s[0:1], 22, v32
	v_cmp_lt_f32_e64 s[28:29], v14, v40
	s_and_b64 s[36:37], s[0:1], s[36:37]
	s_or_b64 s[28:29], s[28:29], s[36:37]
	v_addc_co_u32_e64 v19, s[28:29], v19, v27, s[28:29]
	v_cmp_eq_f32_e64 s[36:37], v15, v40
	v_cmp_lt_f32_e64 s[28:29], v15, v40
	s_and_b64 s[36:37], s[34:35], s[36:37]
	s_or_b64 s[28:29], s[28:29], s[36:37]
	v_addc_co_u32_e64 v20, s[28:29], v20, v28, s[28:29]
	v_cmp_eq_f32_e64 s[36:37], v12, v40
	v_cmp_lt_f32_e64 s[28:29], v12, v40
	s_and_b64 s[36:37], s[30:31], s[36:37]
	s_or_b64 s[28:29], s[28:29], s[36:37]
	v_addc_co_u32_e64 v21, s[28:29], v21, v29, s[28:29]
	v_cmp_eq_f32_e64 s[36:37], v13, v40
	v_cmp_lt_f32_e64 s[28:29], v13, v40
	s_and_b64 s[36:37], s[26:27], s[36:37]
	s_or_b64 s[28:29], s[28:29], s[36:37]
	v_addc_co_u32_e64 v22, s[28:29], v22, v30, s[28:29]
	v_cmp_eq_f32_e64 s[36:37], v10, v40
	v_cmp_lt_f32_e64 s[28:29], v10, v40
	s_and_b64 s[36:37], s[22:23], s[36:37]
	s_or_b64 s[28:29], s[28:29], s[36:37]
	v_addc_co_u32_e64 v23, s[28:29], v23, v31, s[28:29]
	v_cmp_eq_f32_e64 s[36:37], v11, v40
	v_cmp_lt_f32_e64 s[28:29], v11, v40
	s_and_b64 s[36:37], s[18:19], s[36:37]
	s_or_b64 s[28:29], s[28:29], s[36:37]
	v_addc_co_u32_e64 v24, s[28:29], v24, v38, s[28:29]
	v_cmp_eq_f32_e64 s[36:37], v16, v40
	v_cmp_lt_f32_e64 s[28:29], v16, v40
	s_and_b64 s[36:37], s[20:21], s[36:37]
	s_or_b64 s[28:29], s[28:29], s[36:37]
	v_addc_co_u32_e64 v25, s[28:29], v25, v39, s[28:29]
	v_cmp_eq_f32_e64 s[36:37], v9, v40
	v_cmp_lt_f32_e64 s[28:29], v9, v40
	s_and_b64 s[24:25], s[24:25], s[36:37]
	s_or_b64 s[24:25], s[28:29], s[24:25]
	v_addc_co_u32_e64 v18, s[24:25], v18, v26, s[24:25]
	ds_bpermute_b32 v26, v17, v16 offset:128
	v_cmp_lt_i32_e64 s[36:37], 26, v32
	ds_bpermute_b32 v40, v17, v9 offset:128
	s_waitcnt lgkmcnt(1)
	v_cmp_eq_f32_e64 s[28:29], v14, v26
	v_cmp_lt_f32_e64 s[24:25], v14, v26
	s_and_b64 s[28:29], s[36:37], s[28:29]
	s_or_b64 s[24:25], s[24:25], s[28:29]
	v_cmp_eq_f32_e64 s[28:29], v15, v26
	v_cndmask_b32_e64 v27, 0, 1, s[24:25]
	v_cmp_lt_f32_e64 s[24:25], v15, v26
	s_and_b64 s[28:29], s[0:1], s[28:29]
	s_or_b64 s[24:25], s[24:25], s[28:29]
	v_cmp_eq_f32_e64 s[28:29], v12, v26
	v_cndmask_b32_e64 v28, 0, 1, s[24:25]
	v_cmp_lt_f32_e64 s[24:25], v12, v26
	s_and_b64 s[28:29], s[34:35], s[28:29]
	s_or_b64 s[24:25], s[24:25], s[28:29]
	v_cmp_eq_f32_e64 s[28:29], v13, v26
	v_cndmask_b32_e64 v29, 0, 1, s[24:25]
	v_cmp_lt_f32_e64 s[24:25], v13, v26
	s_and_b64 s[28:29], s[30:31], s[28:29]
	s_or_b64 s[24:25], s[24:25], s[28:29]
	v_cmp_eq_f32_e64 s[28:29], v10, v26
	v_cndmask_b32_e64 v30, 0, 1, s[24:25]
	v_cmp_lt_f32_e64 s[24:25], v10, v26
	s_and_b64 s[28:29], s[26:27], s[28:29]
	s_or_b64 s[24:25], s[24:25], s[28:29]
	v_cmp_eq_f32_e64 s[28:29], v11, v26
	v_cndmask_b32_e64 v31, 0, 1, s[24:25]
	v_cmp_lt_f32_e64 s[24:25], v11, v26
	s_and_b64 s[28:29], s[22:23], s[28:29]
	s_or_b64 s[24:25], s[24:25], s[28:29]
	v_cmp_eq_f32_e64 s[28:29], v16, v26
	v_cndmask_b32_e64 v38, 0, 1, s[24:25]
	v_cmp_lt_f32_e64 s[24:25], v16, v26
	s_and_b64 s[28:29], s[18:19], s[28:29]
	s_or_b64 s[24:25], s[24:25], s[28:29]
	v_cmp_eq_f32_e64 s[28:29], v9, v26
	v_cndmask_b32_e64 v39, 0, 1, s[24:25]
	v_cmp_lt_f32_e64 s[24:25], v9, v26
	s_and_b64 s[20:21], s[20:21], s[28:29]
	s_or_b64 s[20:21], s[24:25], s[20:21]
	s_waitcnt lgkmcnt(0)
	v_cmp_eq_f32_e64 s[24:25], v14, v40
	v_cmp_lt_i32_e64 s[28:29], 30, v32
	v_cndmask_b32_e64 v26, 0, 1, s[20:21]
	v_cmp_lt_f32_e64 s[20:21], v14, v40
	s_and_b64 s[24:25], s[28:29], s[24:25]
	s_or_b64 s[20:21], s[20:21], s[24:25]
	v_addc_co_u32_e64 v19, s[20:21], v19, v27, s[20:21]
	v_cmp_eq_f32_e64 s[24:25], v15, v40
	v_cmp_lt_f32_e64 s[20:21], v15, v40
	s_and_b64 s[24:25], s[36:37], s[24:25]
	s_or_b64 s[20:21], s[20:21], s[24:25]
	v_addc_co_u32_e64 v20, s[20:21], v20, v28, s[20:21]
	v_cmp_eq_f32_e64 s[24:25], v12, v40
	v_cmp_lt_f32_e64 s[20:21], v12, v40
	s_and_b64 s[0:1], s[0:1], s[24:25]
	s_or_b64 s[0:1], s[20:21], s[0:1]
	v_addc_co_u32_e64 v21, s[0:1], v21, v29, s[0:1]
	v_cmp_eq_f32_e64 s[20:21], v13, v40
	v_cmp_lt_f32_e64 s[0:1], v13, v40
	s_and_b64 s[20:21], s[34:35], s[20:21]
	s_or_b64 s[0:1], s[0:1], s[20:21]
	v_addc_co_u32_e64 v22, s[0:1], v22, v30, s[0:1]
	v_cmp_eq_f32_e64 s[20:21], v10, v40
	v_cmp_lt_f32_e64 s[0:1], v10, v40
	s_and_b64 s[20:21], s[30:31], s[20:21]
	s_or_b64 s[0:1], s[0:1], s[20:21]
	v_addc_co_u32_e64 v23, s[0:1], v23, v31, s[0:1]
	v_cmp_eq_f32_e64 s[20:21], v11, v40
	v_cmp_lt_f32_e64 s[0:1], v11, v40
	s_and_b64 s[20:21], s[26:27], s[20:21]
	s_or_b64 s[0:1], s[0:1], s[20:21]
	v_addc_co_u32_e64 v24, s[0:1], v24, v38, s[0:1]
	v_cmp_eq_f32_e64 s[20:21], v16, v40
	v_cmp_lt_f32_e64 s[0:1], v16, v40
	s_and_b64 s[20:21], s[22:23], s[20:21]
	s_or_b64 s[0:1], s[0:1], s[20:21]
	v_addc_co_u32_e64 v25, s[0:1], v25, v39, s[0:1]
	v_cmp_eq_f32_e64 s[20:21], v9, v40
	v_cmp_lt_f32_e64 s[0:1], v9, v40
	s_and_b64 s[18:19], s[18:19], s[20:21]
	s_or_b64 s[0:1], s[0:1], s[18:19]
	v_addc_co_u32_e64 v18, s[0:1], v18, v26, s[0:1]
	ds_bpermute_b32 v26, v17, v14 offset:192
	v_cmp_lt_i32_e64 s[18:19], 3, v32
	v_cmp_lt_i32_e64 s[24:25], -5, v32
	v_cmp_lt_i32_e64 s[28:29], -9, v32
	v_cmp_lt_i32_e64 s[34:35], -13, v32
	s_waitcnt lgkmcnt(0)
	v_cmp_eq_f32_e64 s[20:21], v14, v26
	v_cmp_lt_f32_e64 s[0:1], v14, v26
	s_and_b64 s[20:21], s[18:19], s[20:21]
	s_or_b64 s[0:1], s[0:1], s[20:21]
	v_cmp_eq_f32_e64 s[22:23], v15, v26
	v_cmp_lt_i32_e64 s[20:21], -1, v32
	v_cndmask_b32_e64 v27, 0, 1, s[0:1]
	v_cmp_lt_f32_e64 s[0:1], v15, v26
	s_and_b64 s[22:23], s[20:21], s[22:23]
	s_or_b64 s[0:1], s[0:1], s[22:23]
	v_cmp_eq_f32_e64 s[22:23], v12, v26
	v_cndmask_b32_e64 v28, 0, 1, s[0:1]
	v_cmp_lt_f32_e64 s[0:1], v12, v26
	s_and_b64 s[22:23], s[24:25], s[22:23]
	s_or_b64 s[0:1], s[0:1], s[22:23]
	v_cmp_eq_f32_e64 s[22:23], v13, v26
	v_cndmask_b32_e64 v29, 0, 1, s[0:1]
	v_cmp_lt_f32_e64 s[0:1], v13, v26
	s_and_b64 s[22:23], s[28:29], s[22:23]
	s_or_b64 s[0:1], s[0:1], s[22:23]
	v_cmp_eq_f32_e64 s[22:23], v10, v26
	v_cndmask_b32_e64 v30, 0, 1, s[0:1]
	v_cmp_lt_f32_e64 s[0:1], v10, v26
	s_and_b64 s[22:23], s[34:35], s[22:23]
	s_or_b64 s[0:1], s[0:1], s[22:23]
	v_cndmask_b32_e64 v31, 0, 1, s[0:1]
	s_movk_i32 s0, 0xffef
	v_cmp_eq_f32_e64 s[26:27], v11, v26
	v_cmp_lt_i32_e64 s[0:1], s0, v32
	v_cmp_lt_f32_e64 s[22:23], v11, v26
	s_and_b64 s[26:27], s[0:1], s[26:27]
	s_movk_i32 s30, 0xffeb
	s_or_b64 s[22:23], s[22:23], s[26:27]
	v_cmp_eq_f32_e64 s[26:27], v16, v26
	v_cmp_lt_i32_e64 s[30:31], s30, v32
	ds_bpermute_b32 v40, v17, v15 offset:192
	v_cndmask_b32_e64 v38, 0, 1, s[22:23]
	v_cmp_lt_f32_e64 s[22:23], v16, v26
	s_and_b64 s[26:27], s[30:31], s[26:27]
	s_movk_i32 s36, 0xffe7
	s_or_b64 s[22:23], s[22:23], s[26:27]
	v_cmp_eq_f32_e64 s[26:27], v9, v26
	v_cmp_lt_i32_e64 s[36:37], s36, v32
	v_cndmask_b32_e64 v39, 0, 1, s[22:23]
	v_cmp_lt_f32_e64 s[22:23], v9, v26
	s_and_b64 s[26:27], s[36:37], s[26:27]
	s_or_b64 s[22:23], s[22:23], s[26:27]
	v_cndmask_b32_e64 v26, 0, 1, s[22:23]
	s_waitcnt lgkmcnt(0)
	v_cmp_eq_f32_e64 s[36:37], v14, v40
	v_cmp_lt_i32_e64 s[22:23], 7, v32
	v_cmp_lt_f32_e64 s[26:27], v14, v40
	s_and_b64 s[36:37], s[22:23], s[36:37]
	s_or_b64 s[26:27], s[26:27], s[36:37]
	v_addc_co_u32_e64 v19, s[26:27], v19, v27, s[26:27]
	v_cmp_eq_f32_e64 s[36:37], v15, v40
	v_cmp_lt_f32_e64 s[26:27], v15, v40
	s_and_b64 s[36:37], s[18:19], s[36:37]
	s_or_b64 s[26:27], s[26:27], s[36:37]
	v_addc_co_u32_e64 v20, s[26:27], v20, v28, s[26:27]
	v_cmp_eq_f32_e64 s[36:37], v12, v40
	v_cmp_lt_f32_e64 s[26:27], v12, v40
	s_and_b64 s[36:37], s[20:21], s[36:37]
	s_or_b64 s[26:27], s[26:27], s[36:37]
	v_addc_co_u32_e64 v21, s[26:27], v21, v29, s[26:27]
	v_cmp_eq_f32_e64 s[36:37], v13, v40
	v_cmp_lt_f32_e64 s[26:27], v13, v40
	s_and_b64 s[36:37], s[24:25], s[36:37]
	s_or_b64 s[26:27], s[26:27], s[36:37]
	v_addc_co_u32_e64 v22, s[26:27], v22, v30, s[26:27]
	v_cmp_eq_f32_e64 s[36:37], v10, v40
	v_cmp_lt_f32_e64 s[26:27], v10, v40
	s_and_b64 s[36:37], s[28:29], s[36:37]
	s_or_b64 s[26:27], s[26:27], s[36:37]
	v_addc_co_u32_e64 v23, s[26:27], v23, v31, s[26:27]
	v_cmp_eq_f32_e64 s[36:37], v11, v40
	v_cmp_lt_f32_e64 s[26:27], v11, v40
	s_and_b64 s[36:37], s[34:35], s[36:37]
	s_or_b64 s[26:27], s[26:27], s[36:37]
	v_addc_co_u32_e64 v24, s[26:27], v24, v38, s[26:27]
	v_cmp_eq_f32_e64 s[36:37], v16, v40
	v_cmp_lt_f32_e64 s[26:27], v16, v40
	s_and_b64 s[36:37], s[0:1], s[36:37]
	s_or_b64 s[26:27], s[26:27], s[36:37]
	v_addc_co_u32_e64 v25, s[26:27], v25, v39, s[26:27]
	v_cmp_eq_f32_e64 s[36:37], v9, v40
	v_cmp_lt_f32_e64 s[26:27], v9, v40
	s_and_b64 s[30:31], s[30:31], s[36:37]
	s_or_b64 s[26:27], s[26:27], s[30:31]
	v_addc_co_u32_e64 v18, s[26:27], v18, v26, s[26:27]
	ds_bpermute_b32 v26, v17, v12 offset:192
	v_cmp_lt_i32_e64 s[26:27], 11, v32
	ds_bpermute_b32 v40, v17, v13 offset:192
	s_waitcnt lgkmcnt(1)
	v_cmp_eq_f32_e64 s[36:37], v14, v26
	v_cmp_lt_f32_e64 s[30:31], v14, v26
	s_and_b64 s[36:37], s[26:27], s[36:37]
	s_or_b64 s[30:31], s[30:31], s[36:37]
	v_cmp_eq_f32_e64 s[36:37], v15, v26
	v_cndmask_b32_e64 v27, 0, 1, s[30:31]
	v_cmp_lt_f32_e64 s[30:31], v15, v26
	s_and_b64 s[36:37], s[22:23], s[36:37]
	s_or_b64 s[30:31], s[30:31], s[36:37]
	v_cmp_eq_f32_e64 s[36:37], v12, v26
	v_cndmask_b32_e64 v28, 0, 1, s[30:31]
	v_cmp_lt_f32_e64 s[30:31], v12, v26
	s_and_b64 s[36:37], s[18:19], s[36:37]
	s_or_b64 s[30:31], s[30:31], s[36:37]
	v_cmp_eq_f32_e64 s[36:37], v13, v26
	v_cndmask_b32_e64 v29, 0, 1, s[30:31]
	v_cmp_lt_f32_e64 s[30:31], v13, v26
	s_and_b64 s[36:37], s[20:21], s[36:37]
	s_or_b64 s[30:31], s[30:31], s[36:37]
	v_cmp_eq_f32_e64 s[36:37], v10, v26
	v_cndmask_b32_e64 v30, 0, 1, s[30:31]
	v_cmp_lt_f32_e64 s[30:31], v10, v26
	s_and_b64 s[36:37], s[24:25], s[36:37]
	s_or_b64 s[30:31], s[30:31], s[36:37]
	v_cmp_eq_f32_e64 s[36:37], v11, v26
	v_cndmask_b32_e64 v31, 0, 1, s[30:31]
	v_cmp_lt_f32_e64 s[30:31], v11, v26
	s_and_b64 s[36:37], s[28:29], s[36:37]
	s_or_b64 s[30:31], s[30:31], s[36:37]
	v_cmp_eq_f32_e64 s[36:37], v16, v26
	v_cndmask_b32_e64 v38, 0, 1, s[30:31]
	v_cmp_lt_f32_e64 s[30:31], v16, v26
	s_and_b64 s[36:37], s[34:35], s[36:37]
	s_or_b64 s[30:31], s[30:31], s[36:37]
	v_cmp_eq_f32_e64 s[36:37], v9, v26
	v_cndmask_b32_e64 v39, 0, 1, s[30:31]
	v_cmp_lt_f32_e64 s[30:31], v9, v26
	s_and_b64 s[0:1], s[0:1], s[36:37]
	s_or_b64 s[0:1], s[30:31], s[0:1]
	s_waitcnt lgkmcnt(0)
	v_cmp_eq_f32_e64 s[36:37], v14, v40
	v_cmp_lt_i32_e64 s[30:31], 15, v32
	v_cndmask_b32_e64 v26, 0, 1, s[0:1]
	v_cmp_lt_f32_e64 s[0:1], v14, v40
	s_and_b64 s[36:37], s[30:31], s[36:37]
	s_or_b64 s[0:1], s[0:1], s[36:37]
	v_addc_co_u32_e64 v19, s[0:1], v19, v27, s[0:1]
	v_cmp_eq_f32_e64 s[36:37], v15, v40
	v_cmp_lt_f32_e64 s[0:1], v15, v40
	s_and_b64 s[36:37], s[26:27], s[36:37]
	s_or_b64 s[0:1], s[0:1], s[36:37]
	v_addc_co_u32_e64 v20, s[0:1], v20, v28, s[0:1]
	v_cmp_eq_f32_e64 s[36:37], v12, v40
	v_cmp_lt_f32_e64 s[0:1], v12, v40
	s_and_b64 s[36:37], s[22:23], s[36:37]
	s_or_b64 s[0:1], s[0:1], s[36:37]
	v_addc_co_u32_e64 v21, s[0:1], v21, v29, s[0:1]
	v_cmp_eq_f32_e64 s[36:37], v13, v40
	v_cmp_lt_f32_e64 s[0:1], v13, v40
	s_and_b64 s[36:37], s[18:19], s[36:37]
	s_or_b64 s[0:1], s[0:1], s[36:37]
	v_addc_co_u32_e64 v22, s[0:1], v22, v30, s[0:1]
	v_cmp_eq_f32_e64 s[36:37], v10, v40
	v_cmp_lt_f32_e64 s[0:1], v10, v40
	s_and_b64 s[36:37], s[20:21], s[36:37]
	s_or_b64 s[0:1], s[0:1], s[36:37]
	v_addc_co_u32_e64 v23, s[0:1], v23, v31, s[0:1]
	v_cmp_eq_f32_e64 s[36:37], v11, v40
	v_cmp_lt_f32_e64 s[0:1], v11, v40
	s_and_b64 s[36:37], s[24:25], s[36:37]
	s_or_b64 s[0:1], s[0:1], s[36:37]
	v_addc_co_u32_e64 v24, s[0:1], v24, v38, s[0:1]
	v_cmp_eq_f32_e64 s[36:37], v16, v40
	v_cmp_lt_f32_e64 s[0:1], v16, v40
	s_and_b64 s[36:37], s[28:29], s[36:37]
	s_or_b64 s[0:1], s[0:1], s[36:37]
	v_addc_co_u32_e64 v25, s[0:1], v25, v39, s[0:1]
	v_cmp_eq_f32_e64 s[36:37], v9, v40
	v_cmp_lt_f32_e64 s[0:1], v9, v40
	s_and_b64 s[34:35], s[34:35], s[36:37]
	s_or_b64 s[0:1], s[0:1], s[34:35]
	v_addc_co_u32_e64 v18, s[0:1], v18, v26, s[0:1]
	ds_bpermute_b32 v26, v17, v10 offset:192
	v_cmp_lt_i32_e64 s[34:35], 19, v32
	ds_bpermute_b32 v40, v17, v11 offset:192
	s_waitcnt lgkmcnt(1)
	v_cmp_eq_f32_e64 s[36:37], v14, v26
	v_cmp_lt_f32_e64 s[0:1], v14, v26
	s_and_b64 s[36:37], s[34:35], s[36:37]
	s_or_b64 s[0:1], s[0:1], s[36:37]
	v_cmp_eq_f32_e64 s[36:37], v15, v26
	v_cndmask_b32_e64 v27, 0, 1, s[0:1]
	v_cmp_lt_f32_e64 s[0:1], v15, v26
	s_and_b64 s[36:37], s[30:31], s[36:37]
	s_or_b64 s[0:1], s[0:1], s[36:37]
	v_cmp_eq_f32_e64 s[36:37], v12, v26
	v_cndmask_b32_e64 v28, 0, 1, s[0:1]
	v_cmp_lt_f32_e64 s[0:1], v12, v26
	s_and_b64 s[36:37], s[26:27], s[36:37]
	s_or_b64 s[0:1], s[0:1], s[36:37]
	v_cmp_eq_f32_e64 s[36:37], v13, v26
	v_cndmask_b32_e64 v29, 0, 1, s[0:1]
	v_cmp_lt_f32_e64 s[0:1], v13, v26
	s_and_b64 s[36:37], s[22:23], s[36:37]
	s_or_b64 s[0:1], s[0:1], s[36:37]
	v_cmp_eq_f32_e64 s[36:37], v10, v26
	v_cndmask_b32_e64 v30, 0, 1, s[0:1]
	v_cmp_lt_f32_e64 s[0:1], v10, v26
	s_and_b64 s[36:37], s[18:19], s[36:37]
	s_or_b64 s[0:1], s[0:1], s[36:37]
	v_cmp_eq_f32_e64 s[36:37], v11, v26
	v_cndmask_b32_e64 v31, 0, 1, s[0:1]
	v_cmp_lt_f32_e64 s[0:1], v11, v26
	s_and_b64 s[36:37], s[20:21], s[36:37]
	s_or_b64 s[0:1], s[0:1], s[36:37]
	v_cmp_eq_f32_e64 s[36:37], v16, v26
	v_cndmask_b32_e64 v38, 0, 1, s[0:1]
	v_cmp_lt_f32_e64 s[0:1], v16, v26
	s_and_b64 s[36:37], s[24:25], s[36:37]
	s_or_b64 s[0:1], s[0:1], s[36:37]
	v_cmp_eq_f32_e64 s[36:37], v9, v26
	v_cndmask_b32_e64 v39, 0, 1, s[0:1]
	v_cmp_lt_f32_e64 s[0:1], v9, v26
	s_and_b64 s[28:29], s[28:29], s[36:37]
	s_or_b64 s[0:1], s[0:1], s[28:29]
	v_cndmask_b32_e64 v26, 0, 1, s[0:1]
	s_waitcnt lgkmcnt(0)
	v_cmp_eq_f32_e64 s[36:37], v14, v40
	v_cmp_lt_i32_e64 s[0:1], 23, v32
	v_cmp_lt_f32_e64 s[28:29], v14, v40
	s_and_b64 s[36:37], s[0:1], s[36:37]
	s_or_b64 s[28:29], s[28:29], s[36:37]
	v_addc_co_u32_e64 v19, s[28:29], v19, v27, s[28:29]
	v_cmp_eq_f32_e64 s[36:37], v15, v40
	v_cmp_lt_f32_e64 s[28:29], v15, v40
	s_and_b64 s[36:37], s[34:35], s[36:37]
	s_or_b64 s[28:29], s[28:29], s[36:37]
	v_addc_co_u32_e64 v20, s[28:29], v20, v28, s[28:29]
	v_cmp_eq_f32_e64 s[36:37], v12, v40
	v_cmp_lt_f32_e64 s[28:29], v12, v40
	s_and_b64 s[36:37], s[30:31], s[36:37]
	s_or_b64 s[28:29], s[28:29], s[36:37]
	v_addc_co_u32_e64 v21, s[28:29], v21, v29, s[28:29]
	v_cmp_eq_f32_e64 s[36:37], v13, v40
	v_cmp_lt_f32_e64 s[28:29], v13, v40
	s_and_b64 s[36:37], s[26:27], s[36:37]
	s_or_b64 s[28:29], s[28:29], s[36:37]
	v_addc_co_u32_e64 v22, s[28:29], v22, v30, s[28:29]
	v_cmp_eq_f32_e64 s[36:37], v10, v40
	v_cmp_lt_f32_e64 s[28:29], v10, v40
	s_and_b64 s[36:37], s[22:23], s[36:37]
	s_or_b64 s[28:29], s[28:29], s[36:37]
	v_addc_co_u32_e64 v23, s[28:29], v23, v31, s[28:29]
	v_cmp_eq_f32_e64 s[36:37], v11, v40
	v_cmp_lt_f32_e64 s[28:29], v11, v40
	s_and_b64 s[36:37], s[18:19], s[36:37]
	s_or_b64 s[28:29], s[28:29], s[36:37]
	v_addc_co_u32_e64 v24, s[28:29], v24, v38, s[28:29]
	v_cmp_eq_f32_e64 s[36:37], v16, v40
	v_cmp_lt_f32_e64 s[28:29], v16, v40
	s_and_b64 s[36:37], s[20:21], s[36:37]
	s_or_b64 s[28:29], s[28:29], s[36:37]
	v_addc_co_u32_e64 v25, s[28:29], v25, v39, s[28:29]
	v_cmp_eq_f32_e64 s[36:37], v9, v40
	v_cmp_lt_f32_e64 s[28:29], v9, v40
	s_and_b64 s[24:25], s[24:25], s[36:37]
	s_or_b64 s[24:25], s[28:29], s[24:25]
	v_addc_co_u32_e64 v18, s[24:25], v18, v26, s[24:25]
	ds_bpermute_b32 v26, v17, v16 offset:192
	v_cmp_lt_i32_e64 s[36:37], 27, v32
	ds_bpermute_b32 v17, v17, v9 offset:192
	s_waitcnt lgkmcnt(1)
	v_cmp_eq_f32_e64 s[28:29], v14, v26
	v_cmp_lt_f32_e64 s[24:25], v14, v26
	s_and_b64 s[28:29], s[36:37], s[28:29]
	s_or_b64 s[24:25], s[24:25], s[28:29]
	v_cmp_eq_f32_e64 s[28:29], v15, v26
	v_cndmask_b32_e64 v27, 0, 1, s[24:25]
	v_cmp_lt_f32_e64 s[24:25], v15, v26
	s_and_b64 s[28:29], s[0:1], s[28:29]
	s_or_b64 s[24:25], s[24:25], s[28:29]
	v_cmp_eq_f32_e64 s[28:29], v12, v26
	v_cndmask_b32_e64 v28, 0, 1, s[24:25]
	v_cmp_lt_f32_e64 s[24:25], v12, v26
	s_and_b64 s[28:29], s[34:35], s[28:29]
	s_or_b64 s[24:25], s[24:25], s[28:29]
	v_cmp_eq_f32_e64 s[28:29], v13, v26
	v_cndmask_b32_e64 v29, 0, 1, s[24:25]
	v_cmp_lt_f32_e64 s[24:25], v13, v26
	s_and_b64 s[28:29], s[30:31], s[28:29]
	s_or_b64 s[24:25], s[24:25], s[28:29]
	v_cmp_eq_f32_e64 s[28:29], v10, v26
	v_cndmask_b32_e64 v30, 0, 1, s[24:25]
	v_cmp_lt_f32_e64 s[24:25], v10, v26
	s_and_b64 s[28:29], s[26:27], s[28:29]
	s_or_b64 s[24:25], s[24:25], s[28:29]
	v_cmp_eq_f32_e64 s[28:29], v11, v26
	v_cndmask_b32_e64 v31, 0, 1, s[24:25]
	v_cmp_lt_f32_e64 s[24:25], v11, v26
	s_and_b64 s[28:29], s[22:23], s[28:29]
	s_or_b64 s[24:25], s[24:25], s[28:29]
	v_cmp_eq_f32_e64 s[28:29], v16, v26
	v_cndmask_b32_e64 v38, 0, 1, s[24:25]
	v_cmp_lt_f32_e64 s[24:25], v16, v26
	s_and_b64 s[28:29], s[18:19], s[28:29]
	s_or_b64 s[24:25], s[24:25], s[28:29]
	v_cmp_eq_f32_e64 s[28:29], v9, v26
	v_cndmask_b32_e64 v39, 0, 1, s[24:25]
	v_cmp_lt_f32_e64 s[24:25], v9, v26
	s_and_b64 s[20:21], s[20:21], s[28:29]
	s_or_b64 s[20:21], s[24:25], s[20:21]
	s_waitcnt lgkmcnt(0)
	v_cmp_eq_f32_e64 s[24:25], v14, v17
	v_cmp_lt_i32_e64 s[28:29], 31, v32
	v_cndmask_b32_e64 v26, 0, 1, s[20:21]
	v_cmp_lt_f32_e64 s[20:21], v14, v17
	s_and_b64 s[24:25], s[28:29], s[24:25]
	s_or_b64 s[20:21], s[20:21], s[24:25]
	v_addc_co_u32_e64 v14, s[20:21], v19, v27, s[20:21]
	v_cmp_eq_f32_e64 s[24:25], v15, v17
	v_cmp_lt_f32_e64 s[20:21], v15, v17
	s_and_b64 s[24:25], s[36:37], s[24:25]
	s_or_b64 s[20:21], s[20:21], s[24:25]
	v_addc_co_u32_e64 v15, s[20:21], v20, v28, s[20:21]
	v_cmp_eq_f32_e64 s[24:25], v12, v17
	v_cmp_lt_f32_e64 s[20:21], v12, v17
	s_and_b64 s[0:1], s[0:1], s[24:25]
	s_or_b64 s[0:1], s[20:21], s[0:1]
	v_addc_co_u32_e64 v12, s[0:1], v21, v29, s[0:1]
	v_cmp_eq_f32_e64 s[20:21], v13, v17
	v_cmp_lt_f32_e64 s[0:1], v13, v17
	s_and_b64 s[20:21], s[34:35], s[20:21]
	s_or_b64 s[0:1], s[0:1], s[20:21]
	v_addc_co_u32_e64 v13, s[0:1], v22, v30, s[0:1]
	v_cmp_eq_f32_e64 s[20:21], v10, v17
	v_cmp_lt_f32_e64 s[0:1], v10, v17
	s_and_b64 s[20:21], s[30:31], s[20:21]
	s_or_b64 s[0:1], s[0:1], s[20:21]
	v_addc_co_u32_e64 v10, s[0:1], v23, v31, s[0:1]
	v_cmp_eq_f32_e64 s[20:21], v11, v17
	v_cmp_lt_f32_e64 s[0:1], v11, v17
	s_and_b64 s[20:21], s[26:27], s[20:21]
	s_or_b64 s[0:1], s[0:1], s[20:21]
	v_addc_co_u32_e64 v11, s[0:1], v24, v38, s[0:1]
	v_cmp_eq_f32_e64 s[20:21], v16, v17
	v_cmp_lt_f32_e64 s[0:1], v16, v17
	s_and_b64 s[20:21], s[22:23], s[20:21]
	s_or_b64 s[0:1], s[0:1], s[20:21]
	v_addc_co_u32_e64 v16, s[0:1], v25, v39, s[0:1]
	v_cmp_eq_f32_e64 s[20:21], v9, v17
	v_cmp_lt_f32_e64 s[0:1], v9, v17
	s_and_b64 s[18:19], s[18:19], s[20:21]
	s_or_b64 s[0:1], s[0:1], s[18:19]
	v_addc_co_u32_e64 v9, s[0:1], v18, v26, s[0:1]
	v_cmp_lt_u32_e64 s[0:1], 7, v14
	s_or_b64 s[0:1], vcc, s[0:1]
	v_lshlrev_b32_e64 v14, v32, 1
	v_cmp_lt_u32_e32 vcc, 7, v15
	v_cndmask_b32_e64 v14, v14, 0, s[0:1]
	s_or_b64 s[0:1], s[4:5], vcc
	v_cmp_lt_u32_e32 vcc, 7, v12
	v_cndmask_b32_e64 v2, v2, 0, s[0:1]
	s_or_b64 s[0:1], s[6:7], vcc
	v_cmp_lt_u32_e32 vcc, 7, v13
	v_cndmask_b32_e64 v3, v3, 0, s[0:1]
	s_or_b64 s[0:1], s[8:9], vcc
	v_or_b32_e32 v2, v2, v14
	v_cndmask_b32_e64 v4, v4, 0, s[0:1]
	v_cmp_lt_u32_e32 vcc, 7, v10
	v_or3_b32 v2, v2, v3, v4
	s_or_b64 s[0:1], s[10:11], vcc
	v_lshlrev_b32_e64 v3, v5, 1
	v_cmp_lt_u32_e32 vcc, 7, v11
	v_cndmask_b32_e64 v3, v3, 0, s[0:1]
	s_or_b64 s[0:1], s[12:13], vcc
	v_lshlrev_b32_e64 v4, v6, 1
	v_cndmask_b32_e64 v4, v4, 0, s[0:1]
	v_cmp_lt_u32_e32 vcc, 7, v16
	v_or3_b32 v2, v2, v3, v4
	s_or_b64 s[0:1], s[14:15], vcc
	v_lshlrev_b32_e64 v3, v7, 1
	v_cmp_lt_u32_e32 vcc, 7, v9
	v_cndmask_b32_e64 v3, v3, 0, s[0:1]
	s_or_b64 s[0:1], s[16:17], vcc
	v_lshlrev_b32_e64 v4, v8, 1
	v_cndmask_b32_e64 v4, v4, 0, s[0:1]
	v_or3_b32 v2, v2, v3, v4
	ds_bpermute_b32 v3, v193, v2
	v_cmp_lt_i32_e32 vcc, v214, v213
	s_waitcnt lgkmcnt(0)
	v_or_b32_e32 v2, v2, v3
	ds_bpermute_b32 v3, v194, v2
	s_waitcnt lgkmcnt(0)
	v_or_b32_e32 v195, v2, v3
	v_cndmask_b32_e32 v2, v211, v214, vcc
	v_lshlrev_b32_e32 v2, 2, v2
	ds_bpermute_b32 v2, v2, v195
	v_cmp_lt_i32_e32 vcc, v215, v213
	s_waitcnt lgkmcnt(0)
	v_or_b32_e32 v2, v195, v2
	v_cndmask_b32_e32 v3, v211, v215, vcc
	v_lshlrev_b32_e32 v3, 2, v3
	ds_bpermute_b32 v3, v3, v2
	v_cmp_lt_i32_e32 vcc, v216, v213
	s_waitcnt lgkmcnt(0)
	v_or_b32_e32 v2, v2, v3
	v_cndmask_b32_e32 v3, v211, v216, vcc
	v_lshlrev_b32_e32 v3, 2, v3
	ds_bpermute_b32 v3, v3, v2
	v_cmp_lt_i32_e32 vcc, v217, v213
	s_waitcnt lgkmcnt(0)
	v_or_b32_e32 v2, v2, v3
	v_cndmask_b32_e32 v3, v211, v217, vcc
	v_lshlrev_b32_e32 v3, 2, v3
	ds_bpermute_b32 v3, v3, v2
	s_waitcnt lgkmcnt(0)
	v_or_b32_e32 v40, v2, v3
	s_add_u32 s16, s86, 0x29200000
	v_lshl_add_u64 v[0:1], v[146:147], 1, v[0:1]
	s_mov_b64 s[0:1], 0x15200000
	s_addc_u32 s17, s87, 0
	v_lshl_add_u64 v[38:39], v[0:1], 0, s[0:1]
	s_lshl_b32 s82, s2, 9
	v_lshl_add_u64 v[28:29], v[38:39], 0, s[82:83]
	global_load_dwordx4 v[0:3], v[28:29], off
	global_load_dwordx4 v[4:7], v[28:29], off offset:64
	global_load_dwordx4 v[8:11], v[28:29], off offset:128
	global_load_dwordx4 v[12:15], v[28:29], off offset:192
	global_load_dwordx4 v[16:19], v[28:29], off offset:256
	global_load_dwordx4 v[20:23], v[28:29], off offset:320
	global_load_dwordx4 v[24:27], v[28:29], off offset:384
	s_nop 0
	global_load_dwordx4 v[28:31], v[28:29], off offset:448
	v_lshlrev_b64 v[32:33], 3, v[32:33]
	v_sub_co_u32_e32 v32, vcc, 0, v32
	v_mul_f32_e32 v196, 0x3fb8aa3b, v34
	v_readfirstlane_b32 s18, v40
	v_subb_co_u32_e32 v33, vcc, 0, v33, vcc
	v_mov_b32_e32 v34, 0x1ff
	s_ff1_i32_b32 s0, s18
	v_sub_co_u32_e32 v34, vcc, s81, v34
	s_ashr_i32 s95, s94, 31
	s_lshl_b32 s19, s0, 6
	v_readfirstlane_b32 s0, v34
	s_lshl_b64 s[6:7], s[94:95], 19
	s_lshl_b32 s4, s2, 6
	s_lshl_b64 s[8:9], s[84:85], 18
	s_sub_i32 s2, s81, 17
	s_add_i32 s20, s18, -1
	s_and_b32 s5, s0, 0xffffffe0
	v_lshl_add_u64 v[32:33], v[38:39], 0, v[32:33]
	s_and_b64 s[0:1], vcc, exec
	v_lshlrev_b32_e32 v34, 11, v190
	v_mul_f32_e32 v197, 0x3fb8aa3b, v35
	v_mul_f32_e32 v198, 0x3fb8aa3b, v36
	v_mul_f32_e32 v199, 0x3fb8aa3b, v37
	s_cselect_b32 s21, 0, s5
	v_add_u32_e32 v200, 0xfffffe01, v191
	v_lshl_add_u64 v[150:151], v[32:33], 0, s[82:83]
	s_mov_b64 s[10:11], 0
	s_lshl_b32 s22, s4, 1
	v_lshlrev_b32_e32 v152, 1, v34
	v_readlane_b32 s56, v252, 21
	v_readlane_b32 s57, v252, 22
	s_branch .LBB0_191

.LBB0_200:
	s_lshr_b32 s0, s82, 6
	s_lshl_b32 s0, 1, s0
	v_and_b32_e32 v112, s0, v195
	v_cmp_ne_u32_e32 vcc, 0, v112
	s_or_b64 s[14:15], s[10:11], vcc
	s_cmp_lt_i32 s23, 0
	s_cselect_b64 s[4:5], -1, 0
	s_and_b64 s[0:1], s[4:5], exec
	s_cselect_b32 s0, s82, s23
	v_add_u32_e32 v120, s0, v190
	v_ashrrev_i32_e32 v121, 31, v120
	v_lshlrev_b64 v[112:113], 8, v[120:121]
	v_add_u32_e32 v120, 16, v120
	v_ashrrev_i32_e32 v121, 31, v120
	v_lshl_add_u64 v[128:129], s[82:83], 1, v[170:171]
	v_lshlrev_b64 v[120:121], 8, v[120:121]
	v_add_co_u32_e32 v130, vcc, s3, v128
	v_lshl_add_u64 v[116:117], v[158:159], 0, v[112:113]
	v_lshl_add_u64 v[124:125], v[158:159], 0, v[120:121]
	v_addc_co_u32_e32 v131, vcc, 0, v129, vcc
	s_mov_b32 s0, 0x20000
	global_load_dwordx2 v[136:137], v[128:129], off
	global_load_dwordx2 v[138:139], v[128:129], off offset:32
	global_load_dwordx2 v[140:141], v[130:131], off
	global_load_dwordx2 v[142:143], v[130:131], off offset:32
	v_add_co_u32_e32 v130, vcc, s0, v128
	s_mov_b32 s0, 0x30000
	s_nop 0
	v_addc_co_u32_e32 v131, vcc, 0, v129, vcc
	global_load_dwordx2 v[132:133], v[130:131], off
	global_load_dwordx2 v[134:135], v[130:131], off offset:32
	v_add_co_u32_e32 v130, vcc, s0, v128
	v_add_u32_e32 v166, s82, v144
	s_nop 0
	v_addc_co_u32_e32 v131, vcc, 0, v129, vcc
	global_load_dwordx2 v[128:129], v[130:131], off
	s_nop 0
	global_load_dwordx2 v[130:131], v[130:131], off offset:32
	global_load_dwordx4 v[112:115], v[116:117], off
	s_nop 0
	global_load_dwordx4 v[116:119], v[116:117], off offset:64
	s_nop 0
	global_load_dwordx4 v[120:123], v[124:125], off
	s_nop 0
	global_load_dwordx4 v[124:127], v[124:125], off offset:64
	v_cmp_ge_i32_e32 vcc, v166, v160
	v_cmp_lt_i32_e64 s[0:1], v191, v166
	v_add_u32_e32 v167, 16, v166
	s_and_b64 vcc, s[14:15], vcc
	v_cndmask_b32_e64 v168, 0, v223, s[0:1]
	v_cndmask_b32_e32 v179, v223, v168, vcc
	v_cmp_ge_i32_e32 vcc, v167, v160
	v_cmp_gt_i32_e64 s[0:1], v167, v191
	s_and_b64 vcc, s[14:15], vcc
	v_add_u32_e32 v168, 18, v166
	v_cndmask_b32_e64 v167, 0, v223, s[0:1]
	v_cndmask_b32_e32 v181, v223, v167, vcc
	v_cmp_ge_i32_e32 vcc, v166, v153
	v_cmp_gt_i32_e64 s[0:1], v191, v166
	s_and_b64 s[0:1], s[0:1], vcc
	v_add_u32_e32 v167, 17, v166
	s_and_b64 s[0:1], s[14:15], s[0:1]
	v_cndmask_b32_e64 v183, v223, 0, s[0:1]
	v_cmp_ge_i32_e32 vcc, v167, v160
	v_cmp_gt_i32_e64 s[0:1], v167, v191
	s_and_b64 vcc, s[14:15], vcc
	s_waitcnt vmcnt(12)
	v_mfma_f32_16x16x32_bf16 v[228:231], v[108:111], v[0:3], 0
	v_cndmask_b32_e64 v167, 0, v223, s[0:1]
	v_cndmask_b32_e32 v185, v223, v167, vcc
	v_add_u32_e32 v167, 2, v166
	v_cmp_ge_i32_e32 vcc, v167, v160
	v_cmp_gt_i32_e64 s[0:1], v167, v191
	s_and_b64 vcc, s[14:15], vcc
	v_mfma_f32_16x16x32_bf16 v[232:235], v[100:103], v[0:3], 0
	v_cndmask_b32_e64 v167, 0, v223, s[0:1]
	v_cndmask_b32_e32 v187, v223, v167, vcc
	v_cmp_ge_i32_e32 vcc, v168, v160
	v_cmp_gt_i32_e64 s[0:1], v168, v191
	s_and_b64 vcc, s[14:15], vcc
	v_add_u32_e32 v168, 19, v166
	v_cndmask_b32_e64 v167, 0, v223, s[0:1]
	v_cndmask_b32_e32 v189, v223, v167, vcc
	v_add_u32_e32 v167, 3, v166
	v_sub_u32_e32 v166, v191, v166
	v_cvt_f32_i32_e32 v204, v166
	v_cmp_ge_i32_e32 vcc, v167, v160
	v_cmp_gt_i32_e64 s[0:1], v167, v191
	s_and_b64 vcc, s[14:15], vcc
	v_mfma_f32_16x16x32_bf16 v[228:231], v[104:107], v[4:7], v[228:231]
	v_cndmask_b32_e64 v167, 0, v223, s[0:1]
	v_cndmask_b32_e32 v202, v223, v167, vcc
	v_cmp_ge_i32_e32 vcc, v168, v160
	v_mfma_f32_16x16x32_bf16 v[232:235], v[96:99], v[4:7], v[232:235]
	v_cmp_gt_i32_e64 s[0:1], v168, v191
	s_and_b64 vcc, s[14:15], vcc
	v_mul_f32_e64 v166, -v196, v204
	v_cndmask_b32_e64 v167, 0, v223, s[0:1]
	v_cndmask_b32_e32 v203, v223, v167, vcc
	v_fma_f32 v167, 0, v196, v166
	v_fmamk_f32 v168, v196, 0x41800000, v166
	v_fma_f32 v174, -v196, v204, v196
	v_fmamk_f32 v176, v196, 0x41880000, v166
	v_fmac_f32_e32 v167, 0x3e38aa3b, v228
	v_fmac_f32_e32 v168, 0x3e38aa3b, v232
	v_fmac_f32_e32 v174, 0x3e38aa3b, v229
	v_fmac_f32_e32 v176, 0x3e38aa3b, v233
	v_add_f32_e32 v167, v179, v167
	v_add_f32_e32 v168, v181, v168
	v_add_f32_e32 v174, v183, v174
	v_add_f32_e32 v182, v185, v176
	v_max_f32_e32 v169, v167, v168
	v_max_f32_e32 v176, v174, v182
	v_max3_f32 v169, v169, s73, v176
	v_fma_f32 v176, 2.0, v196, v166
	v_fmamk_f32 v178, v196, 0x41900000, v166
	v_fmamk_f32 v180, v196, 0x40400000, v166
	v_fmac_f32_e32 v166, 0x41980000, v196
	v_fmac_f32_e32 v176, 0x3e38aa3b, v230
	v_fmac_f32_e32 v178, 0x3e38aa3b, v234
	v_fmac_f32_e32 v180, 0x3e38aa3b, v231
	v_fmac_f32_e32 v166, 0x3e38aa3b, v235
	v_add_f32_e32 v176, v187, v176
	v_add_f32_e32 v186, v189, v178
	v_add_f32_e32 v180, v202, v180
	v_add_f32_e32 v166, v203, v166
	v_max_f32_e32 v178, v176, v186
	v_max_f32_e32 v184, v180, v166
	v_max3_f32 v169, v169, v178, v184
	v_mov_b32_e32 v178, v169
	v_mfma_f32_16x16x32_bf16 v[232:235], v[100:103], v[8:11], 0
	v_fma_f32 v205, -v197, v204, v197
	v_permlane16_swap_b32_e32 v178, v169
	v_max_f32_e32 v169, v169, v178
	v_mov_b32_e32 v178, v169
	v_mfma_f32_16x16x32_bf16 v[232:235], v[96:99], v[12:15], v[232:235]
	s_nop 0
	v_permlane32_swap_b32_e32 v178, v169
	v_max3_f32 v201, v172, v169, v178
	v_sub_f32_e32 v167, v167, v201
	v_sub_f32_e32 v169, v172, v201
	v_exp_f32_e32 v172, v167
	v_sub_f32_e32 v167, v174, v201
	v_exp_f32_e32 v174, v167
	v_sub_f32_e32 v167, v176, v201
	v_exp_f32_e32 v176, v167
	v_sub_f32_e32 v167, v180, v201
	v_exp_f32_e32 v178, v167
	v_sub_f32_e32 v167, v168, v201
	v_exp_f32_e32 v180, v167
	v_sub_f32_e32 v167, v182, v201
	v_exp_f32_e32 v184, v167
	v_sub_f32_e32 v167, v186, v201
	v_sub_f32_e32 v166, v166, v201
	v_exp_f32_e32 v186, v167
	v_exp_f32_e32 v188, v166
	v_exp_f32_e32 v182, v169
	v_cvt_pk_bf16_f32 v228, v172, v174
	v_cvt_pk_bf16_f32 v229, v176, v178
	v_cvt_pk_bf16_f32 v230, v180, v184
	v_cvt_pk_bf16_f32 v231, v186, v188
	v_pk_mul_f32 v[94:95], v[94:95], v[182:183] op_sel_hi:[1,0]
	v_pk_mul_f32 v[92:93], v[92:93], v[182:183] op_sel_hi:[1,0]
	v_pk_mul_f32 v[90:91], v[90:91], v[182:183] op_sel_hi:[1,0]
	v_pk_mul_f32 v[88:89], v[88:89], v[182:183] op_sel_hi:[1,0]
	v_pk_mul_f32 v[86:87], v[86:87], v[182:183] op_sel_hi:[1,0]
	v_pk_mul_f32 v[84:85], v[84:85], v[182:183] op_sel_hi:[1,0]
	v_pk_mul_f32 v[82:83], v[82:83], v[182:183] op_sel_hi:[1,0]
	v_pk_mul_f32 v[80:81], v[80:81], v[182:183] op_sel_hi:[1,0]
	s_waitcnt vmcnt(4)
	v_mfma_f32_16x16x32_bf16 v[92:95], v[136:139], v[228:231], v[92:95]
	v_mul_f32_e64 v166, -v197, v204
	v_fma_f32 v167, 0, v197, v166
	v_fmamk_f32 v168, v197, 0x41800000, v166
	v_mfma_f32_16x16x32_bf16 v[88:91], v[140:143], v[228:231], v[88:91]
	v_fmac_f32_e32 v168, 0x3e38aa3b, v232
	v_add_f32_e32 v169, v181, v168
	v_mfma_f32_16x16x32_bf16 v[84:87], v[132:135], v[228:231], v[84:87]
	v_mfma_f32_16x16x32_bf16 v[80:83], v[128:131], v[228:231], v[80:83]
	v_mfma_f32_16x16x32_bf16 v[228:231], v[108:111], v[8:11], 0
	v_mfma_f32_16x16x32_bf16 v[228:231], v[104:107], v[12:15], v[228:231]
	s_nop 7
	v_fmac_f32_e32 v205, 0x3e38aa3b, v229
	v_add_f32_e32 v206, v183, v205
	v_fmamk_f32 v205, v197, 0x41880000, v166
	v_fmac_f32_e32 v167, 0x3e38aa3b, v228
	v_fmac_f32_e32 v205, 0x3e38aa3b, v233
	v_add_f32_e32 v167, v179, v167
	v_add_f32_e32 v207, v185, v205
	v_max_f32_e32 v168, v167, v169
	v_max_f32_e32 v205, v206, v207
	v_max3_f32 v168, v168, s73, v205
	v_fma_f32 v205, 2.0, v197, v166
	v_fmac_f32_e32 v205, 0x3e38aa3b, v230
	v_add_f32_e32 v228, v187, v205
	v_fmamk_f32 v205, v197, 0x41900000, v166
	v_fmamk_f32 v230, v197, 0x40400000, v166
	v_fmac_f32_e32 v166, 0x41980000, v197
	v_fmac_f32_e32 v205, 0x3e38aa3b, v234
	v_fmac_f32_e32 v230, 0x3e38aa3b, v231
	v_fmac_f32_e32 v166, 0x3e38aa3b, v235
	v_add_f32_e32 v229, v189, v205
	v_add_f32_e32 v230, v202, v230
	v_add_f32_e32 v231, v203, v166
	v_max_f32_e32 v205, v228, v229
	v_max_f32_e32 v166, v230, v231
	v_max3_f32 v166, v168, v205, v166
	v_mov_b32_e32 v168, v166
	s_nop 1
	v_permlane16_swap_b32_e32 v168, v166
	v_max_f32_e32 v166, v166, v168
	v_mov_b32_e32 v168, v166
	s_nop 1
	v_permlane32_swap_b32_e32 v168, v166
	v_max3_f32 v205, v177, v166, v168
	v_sub_f32_e32 v166, v167, v205
	v_sub_f32_e32 v167, v206, v205
	v_exp_f32_e32 v168, v167
	v_sub_f32_e32 v167, v228, v205
	v_exp_f32_e32 v236, v167
	v_sub_f32_e32 v167, v230, v205
	v_exp_f32_e32 v238, v167
	v_sub_f32_e32 v167, v169, v205
	v_exp_f32_e32 v240, v167
	v_sub_f32_e32 v167, v207, v205
	v_exp_f32_e32 v242, v167
	v_sub_f32_e32 v167, v229, v205
	v_sub_f32_e32 v177, v177, v205
	v_exp_f32_e32 v244, v167
	v_sub_f32_e32 v167, v231, v205
	v_exp_f32_e32 v166, v166
	v_exp_f32_e32 v246, v167
	v_exp_f32_e32 v248, v177
	v_cvt_pk_bf16_f32 v229, v236, v238
	v_cvt_pk_bf16_f32 v228, v166, v168
	v_cvt_pk_bf16_f32 v230, v240, v242
	v_cvt_pk_bf16_f32 v231, v244, v246
	v_pk_mul_f32 v[78:79], v[78:79], v[248:249] op_sel_hi:[1,0]
	v_pk_mul_f32 v[76:77], v[76:77], v[248:249] op_sel_hi:[1,0]
	v_pk_mul_f32 v[74:75], v[74:75], v[248:249] op_sel_hi:[1,0]
	v_pk_mul_f32 v[72:73], v[72:73], v[248:249] op_sel_hi:[1,0]
	v_pk_mul_f32 v[70:71], v[70:71], v[248:249] op_sel_hi:[1,0]
	v_pk_mul_f32 v[68:69], v[68:69], v[248:249] op_sel_hi:[1,0]
	v_pk_mul_f32 v[66:67], v[66:67], v[248:249] op_sel_hi:[1,0]
	v_pk_mul_f32 v[64:65], v[64:65], v[248:249] op_sel_hi:[1,0]
	v_mfma_f32_16x16x32_bf16 v[76:79], v[136:139], v[228:231], v[76:79]
	v_mfma_f32_16x16x32_bf16 v[72:75], v[140:143], v[228:231], v[72:75]
	v_mfma_f32_16x16x32_bf16 v[68:71], v[132:135], v[228:231], v[68:71]
	v_mfma_f32_16x16x32_bf16 v[64:67], v[128:131], v[228:231], v[64:67]
	v_mfma_f32_16x16x32_bf16 v[228:231], v[108:111], v[16:19], 0
	v_mul_f32_e64 v167, -v198, v204
	v_fma_f32 v169, 0, v198, v167
	v_fmamk_f32 v177, v198, 0x41800000, v167
	v_mfma_f32_16x16x32_bf16 v[232:235], v[100:103], v[16:19], 0
	v_fma_f32 v207, -v198, v204, v198
	v_mfma_f32_16x16x32_bf16 v[108:111], v[108:111], v[24:27], 0
	v_mfma_f32_16x16x32_bf16 v[100:103], v[100:103], v[24:27], 0
	v_mfma_f32_16x16x32_bf16 v[228:231], v[104:107], v[20:23], v[228:231]
	v_mfma_f32_16x16x32_bf16 v[232:235], v[96:99], v[20:23], v[232:235]
	v_mfma_f32_16x16x32_bf16 v[104:107], v[104:107], v[28:31], v[108:111]
	s_nop 5
	v_fmac_f32_e32 v169, 0x3e38aa3b, v228
	v_fmamk_f32 v228, v198, 0x41880000, v167
	v_fmac_f32_e32 v177, 0x3e38aa3b, v232
	v_mfma_f32_16x16x32_bf16 v[96:99], v[96:99], v[28:31], v[100:103]
	v_fmac_f32_e32 v207, 0x3e38aa3b, v229
	v_fmac_f32_e32 v228, 0x3e38aa3b, v233
	v_add_f32_e32 v169, v179, v169
	v_mul_f32_e64 v100, -v199, v204
	v_fma_f32 v101, 0, v199, v100
	v_fmac_f32_e32 v101, 0x3e38aa3b, v104
	v_fmamk_f32 v102, v199, 0x41800000, v100
	v_fma_f32 v103, -v199, v204, v199
	v_fmamk_f32 v104, v199, 0x41880000, v100
	v_add_f32_e32 v177, v181, v177
	v_add_f32_e32 v207, v183, v207
	v_add_f32_e32 v228, v185, v228
	v_fmac_f32_e32 v102, 0x3e38aa3b, v96
	v_fmac_f32_e32 v103, 0x3e38aa3b, v105
	v_fmac_f32_e32 v104, 0x3e38aa3b, v97
	v_max_f32_e32 v206, v169, v177
	v_max_f32_e32 v229, v207, v228
	v_add_f32_e32 v101, v179, v101
	v_add_f32_e32 v96, v181, v102
	v_add_f32_e32 v103, v183, v103
	v_add_f32_e32 v97, v185, v104
	v_max3_f32 v206, v206, s73, v229
	v_fma_f32 v229, 2.0, v198, v167
	v_max_f32_e32 v102, v101, v96
	v_max_f32_e32 v104, v103, v97
	v_fmac_f32_e32 v229, 0x3e38aa3b, v230
	v_fmamk_f32 v230, v198, 0x41900000, v167
	v_fmamk_f32 v233, v198, 0x40400000, v167
	v_fmac_f32_e32 v167, 0x41980000, v198
	v_max3_f32 v102, v102, s73, v104
	v_fma_f32 v104, 2.0, v199, v100
	v_fmac_f32_e32 v230, 0x3e38aa3b, v234
	v_fmac_f32_e32 v233, 0x3e38aa3b, v231
	v_fmac_f32_e32 v167, 0x3e38aa3b, v235
	v_fmac_f32_e32 v104, 0x3e38aa3b, v106
	v_fmamk_f32 v105, v199, 0x41900000, v100
	v_fmamk_f32 v106, v199, 0x40400000, v100
	v_fmac_f32_e32 v100, 0x41980000, v199
	v_add_f32_e32 v229, v187, v229
	v_add_f32_e32 v230, v189, v230
	v_add_f32_e32 v231, v202, v233
	v_add_f32_e32 v233, v203, v167
	v_fmac_f32_e32 v105, 0x3e38aa3b, v98
	v_fmac_f32_e32 v106, 0x3e38aa3b, v107
	v_fmac_f32_e32 v100, 0x3e38aa3b, v99
	v_max_f32_e32 v232, v229, v230
	v_max_f32_e32 v167, v231, v233
	v_add_f32_e32 v104, v187, v104
	v_add_f32_e32 v98, v189, v105
	v_add_f32_e32 v106, v202, v106
	v_add_f32_e32 v99, v203, v100
	v_max3_f32 v167, v206, v232, v167
	v_max_f32_e32 v105, v104, v98
	v_max_f32_e32 v100, v106, v99
	v_mov_b32_e32 v206, v167
	v_max3_f32 v100, v102, v105, v100
	v_mov_b32_e32 v102, v100
	s_nop 0
	v_permlane16_swap_b32_e32 v206, v167
	s_nop 0
	v_permlane16_swap_b32_e32 v102, v100
	v_max_f32_e32 v167, v167, v206
	v_max_f32_e32 v100, v100, v102
	v_mov_b32_e32 v206, v167
	v_mov_b32_e32 v102, v100
	s_nop 1
	v_permlane32_swap_b32_e32 v206, v167
	v_permlane32_swap_b32_e32 v102, v100
	v_max3_f32 v206, v175, v167, v206
	v_sub_f32_e32 v177, v177, v206
	v_max3_f32 v202, v173, v100, v102
	v_sub_f32_e32 v167, v169, v206
	v_exp_f32_e32 v241, v177
	v_sub_f32_e32 v177, v228, v206
	v_sub_f32_e32 v101, v101, v202
	v_sub_f32_e32 v175, v175, v206
	v_exp_f32_e32 v167, v167
	v_sub_f32_e32 v169, v207, v206
	v_exp_f32_e32 v243, v177
	v_sub_f32_e32 v177, v230, v206
	v_sub_f32_e32 v100, v173, v202
	v_exp_f32_e32 v173, v101
	v_sub_f32_e32 v101, v103, v202
	v_sub_f32_e32 v96, v96, v202
	v_exp_f32_e32 v169, v169
	v_sub_f32_e32 v207, v229, v206
	v_exp_f32_e32 v245, v177
	v_sub_f32_e32 v177, v233, v206
	v_exp_f32_e32 v249, v175
	v_exp_f32_e32 v175, v101
	v_sub_f32_e32 v101, v104, v202
	v_exp_f32_e32 v181, v96
	v_sub_f32_e32 v96, v97, v202
	v_exp_f32_e32 v237, v207
	v_sub_f32_e32 v207, v231, v206
	v_exp_f32_e32 v247, v177
	v_exp_f32_e32 v177, v101
	v_sub_f32_e32 v101, v106, v202
	v_exp_f32_e32 v185, v96
	v_sub_f32_e32 v96, v98, v202
	v_exp_f32_e32 v239, v207
	v_exp_f32_e32 v179, v101
	v_exp_f32_e32 v187, v96
	v_sub_f32_e32 v96, v99, v202
	v_pk_add_f32 v[228:229], v[166:167], 0 op_sel_hi:[1,0]
	v_exp_f32_e32 v189, v96
	v_pk_add_f32 v[96:97], v[172:173], 0 op_sel_hi:[1,0]
	v_pk_add_f32 v[228:229], v[168:169], v[228:229]
	v_pk_add_f32 v[96:97], v[174:175], v[96:97]
	v_pk_add_f32 v[228:229], v[236:237], v[228:229]
	v_pk_add_f32 v[96:97], v[176:177], v[96:97]
	v_pk_add_f32 v[228:229], v[238:239], v[228:229]
	v_exp_f32_e32 v183, v100
	v_pk_add_f32 v[96:97], v[178:179], v[96:97]
	v_pk_add_f32 v[228:229], v[240:241], v[228:229]
	v_pk_add_f32 v[96:97], v[180:181], v[96:97]
	v_pk_add_f32 v[228:229], v[242:243], v[228:229]
	v_pk_add_f32 v[96:97], v[184:185], v[96:97]
	v_pk_add_f32 v[228:229], v[244:245], v[228:229]
	v_pk_add_f32 v[96:97], v[186:187], v[96:97]
	v_pk_add_f32 v[228:229], v[246:247], v[228:229]
	v_mov_b32_e32 v166, v249
	v_pk_add_f32 v[96:97], v[188:189], v[96:97]
	v_mov_b32_e32 v100, v183
	v_pk_fma_f32 v[156:157], v[156:157], v[248:249], v[228:229]
	v_cvt_pk_bf16_f32 v228, v167, v169
	v_cvt_pk_bf16_f32 v229, v237, v239
	v_cvt_pk_bf16_f32 v230, v241, v243
	v_cvt_pk_bf16_f32 v231, v245, v247
	v_pk_mul_f32 v[62:63], v[62:63], v[166:167] op_sel_hi:[1,0]
	v_pk_mul_f32 v[60:61], v[60:61], v[166:167] op_sel_hi:[1,0]
	v_pk_mul_f32 v[58:59], v[58:59], v[166:167] op_sel_hi:[1,0]
	v_pk_mul_f32 v[56:57], v[56:57], v[166:167] op_sel_hi:[1,0]
	v_pk_mul_f32 v[54:55], v[54:55], v[166:167] op_sel_hi:[1,0]
	v_pk_mul_f32 v[52:53], v[52:53], v[166:167] op_sel_hi:[1,0]
	v_pk_mul_f32 v[50:51], v[50:51], v[166:167] op_sel_hi:[1,0]
	v_pk_mul_f32 v[48:49], v[48:49], v[166:167] op_sel_hi:[1,0]
	v_pk_fma_f32 v[154:155], v[154:155], v[182:183], v[96:97]
	v_cvt_pk_bf16_f32 v96, v173, v175
	v_cvt_pk_bf16_f32 v97, v177, v179
	v_cvt_pk_bf16_f32 v98, v181, v185
	v_cvt_pk_bf16_f32 v99, v187, v189
	v_pk_mul_f32 v[46:47], v[46:47], v[100:101] op_sel_hi:[1,0]
	v_pk_mul_f32 v[44:45], v[44:45], v[100:101] op_sel_hi:[1,0]
	v_pk_mul_f32 v[42:43], v[42:43], v[100:101] op_sel_hi:[1,0]
	v_pk_mul_f32 v[40:41], v[40:41], v[100:101] op_sel_hi:[1,0]
	v_pk_mul_f32 v[38:39], v[38:39], v[100:101] op_sel_hi:[1,0]
	v_pk_mul_f32 v[36:37], v[36:37], v[100:101] op_sel_hi:[1,0]
	v_pk_mul_f32 v[34:35], v[34:35], v[100:101] op_sel_hi:[1,0]
	v_pk_mul_f32 v[32:33], v[32:33], v[100:101] op_sel_hi:[1,0]
	v_mfma_f32_16x16x32_bf16 v[60:63], v[136:139], v[228:231], v[60:63]
	v_mfma_f32_16x16x32_bf16 v[56:59], v[140:143], v[228:231], v[56:59]
	v_mfma_f32_16x16x32_bf16 v[52:55], v[132:135], v[228:231], v[52:55]
	v_mfma_f32_16x16x32_bf16 v[48:51], v[128:131], v[228:231], v[48:51]
	v_mfma_f32_16x16x32_bf16 v[44:47], v[136:139], v[96:99], v[44:47]
	v_mfma_f32_16x16x32_bf16 v[40:43], v[140:143], v[96:99], v[40:43]
	v_mfma_f32_16x16x32_bf16 v[36:39], v[132:135], v[96:99], v[36:39]
	v_mfma_f32_16x16x32_bf16 v[32:35], v[128:131], v[96:99], v[32:35]
	s_waitcnt vmcnt(0)
	s_and_b64 vcc, exec, s[4:5]
	s_cbranch_vccnz .LBB0_203
	v_mov_b64_e32 v[108:109], v[112:113]
	v_mov_b64_e32 v[104:105], v[116:117]
	v_mov_b64_e32 v[100:101], v[120:121]
	v_mov_b64_e32 v[96:97], v[124:125]
	s_mov_b32 s82, s23
	s_mov_b32 s4, s24
	v_mov_b64_e32 v[110:111], v[114:115]
	v_mov_b64_e32 v[106:107], v[118:119]
	v_mov_b64_e32 v[102:103], v[122:123]
	v_mov_b64_e32 v[98:99], v[126:127]
	v_mov_b32_e32 v172, v201
	v_mov_b32_e32 v177, v205
	v_mov_b32_e32 v175, v206
	v_mov_b32_e32 v173, v202
	s_andn2_b64 vcc, exec, s[12:13]
	s_mov_b64 s[0:1], -1
	s_cbranch_vccz .LBB0_193
	s_branch .LBB0_198

.LBB0_562:
	s_and_b64 vcc, exec, s[0:1]
	s_cbranch_vccz .LBB0_569
	v_mov_b32_e32 v0, 16
	v_mov_b32_e32 v2, 0xe8
	v_add_u32_e32 v0, s91, v0
	ds_read_b64 v[0:1], v0
	v_readlane_b32 s0, v253, 11
	v_add_u32_e32 v2, s91, v2
	ds_read_b64 v[2:3], v2
	s_waitcnt lgkmcnt(0)
	v_readfirstlane_b32 s2, v1
	v_readfirstlane_b32 s6, v0
	v_mbcnt_lo_u32_b32 v0, -1, 0
	v_mbcnt_hi_u32_b32 v0, -1, v0
	v_readfirstlane_b32 s5, v3
	v_add_u32_e32 v1, s57, v0
	v_ashrrev_i32_e32 v1, 6, v1
	v_add_u32_e32 v52, s0, v1
	v_readfirstlane_b32 s4, v2
	v_cmp_gt_i32_e32 vcc, s3, v52
	s_and_saveexec_b64 s[0:1], vcc
	v_readlane_b32 s10, v252, 23
	s_cbranch_execz .LBB0_568
	v_readfirstlane_b32 s100, v52
	v_readlane_b32 s7, v252, 31
	s_nop 3
	s_lshl_b32 s8, s7, 12
	s_mov_b32 s7, s2
	s_add_u32 s6, s6, s8
	s_addc_u32 s7, s7, 0
	s_add_u32 s4, s4, 0x5200000
	s_addc_u32 s5, s5, 0
	v_readlane_b32 s8, v252, 25
	v_readlane_b32 s9, v252, 26
	s_nop 3
	v_lshlrev_b32_e32 v120, 4, v0
	v_lshlrev_b32_e32 v121, 3, v0
	v_lshlrev_b32_e32 v122, 2, v214
	v_lshlrev_b32_e32 v123, 2, v215
	v_lshlrev_b32_e32 v124, 2, v216
	v_lshlrev_b32_e32 v125, 2, v217
	v_lshlrev_b32_e32 v126, 2, v218
	v_lshlrev_b32_e32 v127, 2, v219
	s_lshr_b32 s2, s100, 6
	s_lshl_b32 s2, s2, 11
	s_and_b32 s101, s100, 63
	s_add_u32 s2, s2, s101
	s_lshl_b32 s101, s2, 12
	s_add_u32 s8, s8, s101
	s_addc_u32 s9, s9, 0
	s_lshl_b32 s101, s2, 11
	s_add_u32 s4, s4, s101
	s_addc_u32 s5, s5, 0
	global_load_dwordx4 v[0:3], v120, s[6:7] offset:0
	global_load_dwordx4 v[4:7], v120, s[6:7] offset:1024
	global_load_dwordx4 v[8:11], v120, s[6:7] offset:2048
	global_load_dwordx4 v[12:15], v120, s[6:7] offset:3072
	v_readlane_b32 s6, v252, 32
	v_readlane_b32 s7, v252, 33
	s_lshr_b32 s2, s100, 6
	s_mul_i32 s2, s2, 0x6000
	s_nop 3
	s_add_u32 s6, s6, s2
	s_addc_u32 s7, s7, 0
	s_add_u32 s6, s6, 0x1000
	s_addc_u32 s7, s7, 0
	global_load_dwordx4 v[16:19], v120, s[6:7] offset:0
	global_load_dwordx4 v[20:23], v120, s[6:7] offset:1024
	global_load_dwordx4 v[24:27], v120, s[6:7] offset:2048
	global_load_dwordx4 v[28:31], v120, s[6:7] offset:3072
	s_sub_u32 s6, s6, 0x1000
	s_subb_u32 s7, s7, 0
	global_load_dwordx4 v[32:35], v120, s[6:7] offset:0
	global_load_dwordx4 v[36:39], v120, s[6:7] offset:1024
	global_load_dwordx4 v[40:43], v120, s[6:7] offset:2048
	global_load_dwordx4 v[44:47], v120, s[6:7] offset:3072
	s_waitcnt vmcnt(0)
	v_add_f32_e32 v16, 1.0, v16
	v_add_f32_e32 v17, 1.0, v17
	v_add_f32_e32 v18, 1.0, v18
	v_add_f32_e32 v19, 1.0, v19
	v_add_f32_e32 v20, 1.0, v20
	v_add_f32_e32 v21, 1.0, v21
	v_add_f32_e32 v22, 1.0, v22
	v_add_f32_e32 v23, 1.0, v23
	v_add_f32_e32 v24, 1.0, v24
	v_add_f32_e32 v25, 1.0, v25
	v_add_f32_e32 v26, 1.0, v26
	v_add_f32_e32 v27, 1.0, v27
	v_add_f32_e32 v28, 1.0, v28
	v_add_f32_e32 v29, 1.0, v29
	v_add_f32_e32 v30, 1.0, v30
	v_add_f32_e32 v31, 1.0, v31
	s_movk_i32 s2, 3
	global_load_dwordx4 v[48:51], v120, s[8:9] offset:0
	global_load_dwordx4 v[52:55], v120, s[8:9] offset:1024
	global_load_dwordx4 v[56:59], v120, s[8:9] offset:2048
	global_load_dwordx4 v[60:63], v120, s[8:9] offset:3072
	s_add_u32 s8, s8, 0x40000
	s_addc_u32 s9, s9, 0
	global_load_dwordx4 v[64:67], v120, s[8:9] offset:0
	global_load_dwordx4 v[68:71], v120, s[8:9] offset:1024
	global_load_dwordx4 v[72:75], v120, s[8:9] offset:2048
	global_load_dwordx4 v[76:79], v120, s[8:9] offset:3072
	s_add_u32 s8, s8, 0x40000
	s_addc_u32 s9, s9, 0
	global_load_dwordx4 v[80:83], v120, s[8:9] offset:0
	global_load_dwordx4 v[84:87], v120, s[8:9] offset:1024
	global_load_dwordx4 v[88:91], v120, s[8:9] offset:2048
	global_load_dwordx4 v[92:95], v120, s[8:9] offset:3072
	s_add_u32 s8, s8, 0x40000
	s_addc_u32 s9, s9, 0
	global_load_dwordx4 v[96:99], v120, s[8:9] offset:0
	global_load_dwordx4 v[100:103], v120, s[8:9] offset:1024
	global_load_dwordx4 v[104:107], v120, s[8:9] offset:2048
	global_load_dwordx4 v[108:111], v120, s[8:9] offset:3072
	s_add_u32 s8, s8, 0x40000
	s_addc_u32 s9, s9, 0
	global_load_dwordx4 v[132:135], v120, s[8:9] offset:0
	global_load_dwordx4 v[136:139], v120, s[8:9] offset:1024
	global_load_dwordx4 v[140:143], v120, s[8:9] offset:2048
	global_load_dwordx4 v[144:147], v120, s[8:9] offset:3072
	s_add_u32 s8, s8, 0x40000
	s_addc_u32 s9, s9, 0
	global_load_dwordx4 v[166:169], v120, s[8:9] offset:0
	global_load_dwordx4 v[170:173], v120, s[8:9] offset:1024
	global_load_dwordx4 v[174:177], v120, s[8:9] offset:2048
	global_load_dwordx4 v[178:181], v120, s[8:9] offset:3072
	s_add_u32 s8, s8, 0x40000
	s_addc_u32 s9, s9, 0
	global_load_dwordx4 v[182:185], v120, s[8:9] offset:0
	global_load_dwordx4 v[186:189], v120, s[8:9] offset:1024
	global_load_dwordx4 v[190:193], v120, s[8:9] offset:2048
	global_load_dwordx4 v[194:197], v120, s[8:9] offset:3072
	s_add_u32 s8, s8, 0x40000
	s_addc_u32 s9, s9, 0
	global_load_dwordx4 v[228:231], v120, s[8:9] offset:0
	global_load_dwordx4 v[232:235], v120, s[8:9] offset:1024
	global_load_dwordx4 v[236:239], v120, s[8:9] offset:2048
	global_load_dwordx4 v[240:243], v120, s[8:9] offset:3072
	s_add_u32 s8, s8, 0x40000
	s_addc_u32 s9, s9, 0
	s_waitcnt vmcnt(28)
	v_mul_f32_e32 v112, v48, v48
	v_fmac_f32_e32 v112, v49, v49
	v_fmac_f32_e32 v112, v50, v50
	v_fmac_f32_e32 v112, v51, v51
	v_fmac_f32_e32 v112, v52, v52
	v_fmac_f32_e32 v112, v53, v53
	v_fmac_f32_e32 v112, v54, v54
	v_fmac_f32_e32 v112, v55, v55
	v_fmac_f32_e32 v112, v56, v56
	v_fmac_f32_e32 v112, v57, v57
	v_fmac_f32_e32 v112, v58, v58
	v_fmac_f32_e32 v112, v59, v59
	v_fmac_f32_e32 v112, v60, v60
	v_fmac_f32_e32 v112, v61, v61
	v_fmac_f32_e32 v112, v62, v62
	v_fmac_f32_e32 v112, v63, v63
	s_waitcnt vmcnt(24)
	v_mul_f32_e32 v113, v64, v64
	v_fmac_f32_e32 v113, v65, v65
	v_fmac_f32_e32 v113, v66, v66
	v_fmac_f32_e32 v113, v67, v67
	v_fmac_f32_e32 v113, v68, v68
	v_fmac_f32_e32 v113, v69, v69
	v_fmac_f32_e32 v113, v70, v70
	v_fmac_f32_e32 v113, v71, v71
	v_fmac_f32_e32 v113, v72, v72
	v_fmac_f32_e32 v113, v73, v73
	v_fmac_f32_e32 v113, v74, v74
	v_fmac_f32_e32 v113, v75, v75
	v_fmac_f32_e32 v113, v76, v76
	v_fmac_f32_e32 v113, v77, v77
	v_fmac_f32_e32 v113, v78, v78
	v_fmac_f32_e32 v113, v79, v79
	s_waitcnt vmcnt(20)
	v_mul_f32_e32 v114, v80, v80
	v_fmac_f32_e32 v114, v81, v81
	v_fmac_f32_e32 v114, v82, v82
	v_fmac_f32_e32 v114, v83, v83
	v_fmac_f32_e32 v114, v84, v84
	v_fmac_f32_e32 v114, v85, v85
	v_fmac_f32_e32 v114, v86, v86
	v_fmac_f32_e32 v114, v87, v87
	v_fmac_f32_e32 v114, v88, v88
	v_fmac_f32_e32 v114, v89, v89
	v_fmac_f32_e32 v114, v90, v90
	v_fmac_f32_e32 v114, v91, v91
	v_fmac_f32_e32 v114, v92, v92
	v_fmac_f32_e32 v114, v93, v93
	v_fmac_f32_e32 v114, v94, v94
	v_fmac_f32_e32 v114, v95, v95
	s_waitcnt vmcnt(16)
	v_mul_f32_e32 v115, v96, v96
	v_fmac_f32_e32 v115, v97, v97
	v_fmac_f32_e32 v115, v98, v98
	v_fmac_f32_e32 v115, v99, v99
	v_fmac_f32_e32 v115, v100, v100
	v_fmac_f32_e32 v115, v101, v101
	v_fmac_f32_e32 v115, v102, v102
	v_fmac_f32_e32 v115, v103, v103
	v_fmac_f32_e32 v115, v104, v104
	v_fmac_f32_e32 v115, v105, v105
	v_fmac_f32_e32 v115, v106, v106
	v_fmac_f32_e32 v115, v107, v107
	v_fmac_f32_e32 v115, v108, v108
	v_fmac_f32_e32 v115, v109, v109
	v_fmac_f32_e32 v115, v110, v110
	v_fmac_f32_e32 v115, v111, v111
	ds_bpermute_b32 v116, v122, v112
	ds_bpermute_b32 v117, v122, v113
	ds_bpermute_b32 v118, v122, v114
	ds_bpermute_b32 v119, v122, v115
	s_waitcnt lgkmcnt(0)
	v_add_f32_e32 v112, v112, v116
	v_add_f32_e32 v113, v113, v117
	v_add_f32_e32 v114, v114, v118
	v_add_f32_e32 v115, v115, v119
	ds_bpermute_b32 v116, v123, v112
	ds_bpermute_b32 v117, v123, v113
	ds_bpermute_b32 v118, v123, v114
	ds_bpermute_b32 v119, v123, v115
	s_waitcnt lgkmcnt(0)
	v_add_f32_e32 v112, v112, v116
	v_add_f32_e32 v113, v113, v117
	v_add_f32_e32 v114, v114, v118
	v_add_f32_e32 v115, v115, v119
	ds_bpermute_b32 v116, v124, v112
	ds_bpermute_b32 v117, v124, v113
	ds_bpermute_b32 v118, v124, v114
	ds_bpermute_b32 v119, v124, v115
	s_waitcnt lgkmcnt(0)
	v_add_f32_e32 v112, v112, v116
	v_add_f32_e32 v113, v113, v117
	v_add_f32_e32 v114, v114, v118
	v_add_f32_e32 v115, v115, v119
	ds_bpermute_b32 v116, v125, v112
	ds_bpermute_b32 v117, v125, v113
	ds_bpermute_b32 v118, v125, v114
	ds_bpermute_b32 v119, v125, v115
	s_waitcnt lgkmcnt(0)
	v_add_f32_e32 v112, v112, v116
	v_add_f32_e32 v113, v113, v117
	v_add_f32_e32 v114, v114, v118
	v_add_f32_e32 v115, v115, v119
	ds_bpermute_b32 v116, v126, v112
	ds_bpermute_b32 v117, v126, v113
	ds_bpermute_b32 v118, v126, v114
	ds_bpermute_b32 v119, v126, v115
	s_waitcnt lgkmcnt(0)
	v_add_f32_e32 v112, v112, v116
	v_add_f32_e32 v113, v113, v117
	v_add_f32_e32 v114, v114, v118
	v_add_f32_e32 v115, v115, v119
	ds_bpermute_b32 v116, v127, v112
	ds_bpermute_b32 v117, v127, v113
	ds_bpermute_b32 v118, v127, v114
	ds_bpermute_b32 v119, v127, v115
	s_waitcnt lgkmcnt(0)
	v_add_f32_e32 v112, v112, v116
	v_add_f32_e32 v113, v113, v117
	v_add_f32_e32 v114, v114, v118
	v_add_f32_e32 v115, v115, v119
	v_fmamk_f32 v112, v112, 0x3a800000, v208
	v_fmamk_f32 v113, v113, 0x3a800000, v208
	v_fmamk_f32 v114, v114, 0x3a800000, v208
	v_fmamk_f32 v115, v115, 0x3a800000, v208
	v_rsq_f32_e32 v112, v112
	v_rsq_f32_e32 v113, v113
	v_rsq_f32_e32 v114, v114
	v_rsq_f32_e32 v115, v115
	s_nop 1
	v_mul_f32_e32 v48, v48, v112
	v_mul_f32_e32 v49, v49, v112
	v_mul_f32_e32 v50, v50, v112
	v_mul_f32_e32 v51, v51, v112
	v_mul_f32_e32 v48, v0, v48
	v_mul_f32_e32 v49, v1, v49
	v_mul_f32_e32 v50, v2, v50
	v_mul_f32_e32 v51, v3, v51
	v_fma_f32 v48, v48, v16, v32
	v_fma_f32 v49, v49, v17, v33
	v_fma_f32 v50, v50, v18, v34
	v_fma_f32 v51, v51, v19, v35
	v_cvt_pk_bf16_f32 v128, v48, v49
	v_cvt_pk_bf16_f32 v129, v50, v51
	global_store_dwordx2 v121, v[128:129], s[4:5] offset:0
	v_mul_f32_e32 v52, v52, v112
	v_mul_f32_e32 v53, v53, v112
	v_mul_f32_e32 v54, v54, v112
	v_mul_f32_e32 v55, v55, v112
	v_mul_f32_e32 v52, v4, v52
	v_mul_f32_e32 v53, v5, v53
	v_mul_f32_e32 v54, v6, v54
	v_mul_f32_e32 v55, v7, v55
	v_fma_f32 v52, v52, v20, v36
	v_fma_f32 v53, v53, v21, v37
	v_fma_f32 v54, v54, v22, v38
	v_fma_f32 v55, v55, v23, v39
	v_cvt_pk_bf16_f32 v130, v52, v53
	v_cvt_pk_bf16_f32 v131, v54, v55
	global_store_dwordx2 v121, v[130:131], s[4:5] offset:512
	v_mul_f32_e32 v56, v56, v112
	v_mul_f32_e32 v57, v57, v112
	v_mul_f32_e32 v58, v58, v112
	v_mul_f32_e32 v59, v59, v112
	v_mul_f32_e32 v56, v8, v56
	v_mul_f32_e32 v57, v9, v57
	v_mul_f32_e32 v58, v10, v58
	v_mul_f32_e32 v59, v11, v59
	v_fma_f32 v56, v56, v24, v40
	v_fma_f32 v57, v57, v25, v41
	v_fma_f32 v58, v58, v26, v42
	v_fma_f32 v59, v59, v27, v43
	v_cvt_pk_bf16_f32 v128, v56, v57
	v_cvt_pk_bf16_f32 v129, v58, v59
	global_store_dwordx2 v121, v[128:129], s[4:5] offset:1024
	v_mul_f32_e32 v60, v60, v112
	v_mul_f32_e32 v61, v61, v112
	v_mul_f32_e32 v62, v62, v112
	v_mul_f32_e32 v63, v63, v112
	v_mul_f32_e32 v60, v12, v60
	v_mul_f32_e32 v61, v13, v61
	v_mul_f32_e32 v62, v14, v62
	v_mul_f32_e32 v63, v15, v63
	v_fma_f32 v60, v60, v28, v44
	v_fma_f32 v61, v61, v29, v45
	v_fma_f32 v62, v62, v30, v46
	v_fma_f32 v63, v63, v31, v47
	v_cvt_pk_bf16_f32 v130, v60, v61
	v_cvt_pk_bf16_f32 v131, v62, v63
	global_store_dwordx2 v121, v[130:131], s[4:5] offset:1536
	s_add_u32 s4, s4, 0x20000
	s_addc_u32 s5, s5, 0
	v_mul_f32_e32 v64, v64, v113
	v_mul_f32_e32 v65, v65, v113
	v_mul_f32_e32 v66, v66, v113
	v_mul_f32_e32 v67, v67, v113
	v_mul_f32_e32 v64, v0, v64
	v_mul_f32_e32 v65, v1, v65
	v_mul_f32_e32 v66, v2, v66
	v_mul_f32_e32 v67, v3, v67
	v_fma_f32 v64, v64, v16, v32
	v_fma_f32 v65, v65, v17, v33
	v_fma_f32 v66, v66, v18, v34
	v_fma_f32 v67, v67, v19, v35
	v_cvt_pk_bf16_f32 v128, v64, v65
	v_cvt_pk_bf16_f32 v129, v66, v67
	global_store_dwordx2 v121, v[128:129], s[4:5] offset:0
	v_mul_f32_e32 v68, v68, v113
	v_mul_f32_e32 v69, v69, v113
	v_mul_f32_e32 v70, v70, v113
	v_mul_f32_e32 v71, v71, v113
	v_mul_f32_e32 v68, v4, v68
	v_mul_f32_e32 v69, v5, v69
	v_mul_f32_e32 v70, v6, v70
	v_mul_f32_e32 v71, v7, v71
	v_fma_f32 v68, v68, v20, v36
	v_fma_f32 v69, v69, v21, v37
	v_fma_f32 v70, v70, v22, v38
	v_fma_f32 v71, v71, v23, v39
	v_cvt_pk_bf16_f32 v130, v68, v69
	v_cvt_pk_bf16_f32 v131, v70, v71
	global_store_dwordx2 v121, v[130:131], s[4:5] offset:512
	v_mul_f32_e32 v72, v72, v113
	v_mul_f32_e32 v73, v73, v113
	v_mul_f32_e32 v74, v74, v113
	v_mul_f32_e32 v75, v75, v113
	v_mul_f32_e32 v72, v8, v72
	v_mul_f32_e32 v73, v9, v73
	v_mul_f32_e32 v74, v10, v74
	v_mul_f32_e32 v75, v11, v75
	v_fma_f32 v72, v72, v24, v40
	v_fma_f32 v73, v73, v25, v41
	v_fma_f32 v74, v74, v26, v42
	v_fma_f32 v75, v75, v27, v43
	v_cvt_pk_bf16_f32 v128, v72, v73
	v_cvt_pk_bf16_f32 v129, v74, v75
	global_store_dwordx2 v121, v[128:129], s[4:5] offset:1024
	v_mul_f32_e32 v76, v76, v113
	v_mul_f32_e32 v77, v77, v113
	v_mul_f32_e32 v78, v78, v113
	v_mul_f32_e32 v79, v79, v113
	v_mul_f32_e32 v76, v12, v76
	v_mul_f32_e32 v77, v13, v77
	v_mul_f32_e32 v78, v14, v78
	v_mul_f32_e32 v79, v15, v79
	v_fma_f32 v76, v76, v28, v44
	v_fma_f32 v77, v77, v29, v45
	v_fma_f32 v78, v78, v30, v46
	v_fma_f32 v79, v79, v31, v47
	v_cvt_pk_bf16_f32 v130, v76, v77
	v_cvt_pk_bf16_f32 v131, v78, v79
	global_store_dwordx2 v121, v[130:131], s[4:5] offset:1536
	s_add_u32 s4, s4, 0x20000
	s_addc_u32 s5, s5, 0
	v_mul_f32_e32 v80, v80, v114
	v_mul_f32_e32 v81, v81, v114
	v_mul_f32_e32 v82, v82, v114
	v_mul_f32_e32 v83, v83, v114
	v_mul_f32_e32 v80, v0, v80
	v_mul_f32_e32 v81, v1, v81
	v_mul_f32_e32 v82, v2, v82
	v_mul_f32_e32 v83, v3, v83
	v_fma_f32 v80, v80, v16, v32
	v_fma_f32 v81, v81, v17, v33
	v_fma_f32 v82, v82, v18, v34
	v_fma_f32 v83, v83, v19, v35
	v_cvt_pk_bf16_f32 v128, v80, v81
	v_cvt_pk_bf16_f32 v129, v82, v83
	global_store_dwordx2 v121, v[128:129], s[4:5] offset:0
	v_mul_f32_e32 v84, v84, v114
	v_mul_f32_e32 v85, v85, v114
	v_mul_f32_e32 v86, v86, v114
	v_mul_f32_e32 v87, v87, v114
	v_mul_f32_e32 v84, v4, v84
	v_mul_f32_e32 v85, v5, v85
	v_mul_f32_e32 v86, v6, v86
	v_mul_f32_e32 v87, v7, v87
	v_fma_f32 v84, v84, v20, v36
	v_fma_f32 v85, v85, v21, v37
	v_fma_f32 v86, v86, v22, v38
	v_fma_f32 v87, v87, v23, v39
	v_cvt_pk_bf16_f32 v130, v84, v85
	v_cvt_pk_bf16_f32 v131, v86, v87
	global_store_dwordx2 v121, v[130:131], s[4:5] offset:512
	v_mul_f32_e32 v88, v88, v114
	v_mul_f32_e32 v89, v89, v114
	v_mul_f32_e32 v90, v90, v114
	v_mul_f32_e32 v91, v91, v114
	v_mul_f32_e32 v88, v8, v88
	v_mul_f32_e32 v89, v9, v89
	v_mul_f32_e32 v90, v10, v90
	v_mul_f32_e32 v91, v11, v91
	v_fma_f32 v88, v88, v24, v40
	v_fma_f32 v89, v89, v25, v41
	v_fma_f32 v90, v90, v26, v42
	v_fma_f32 v91, v91, v27, v43
	v_cvt_pk_bf16_f32 v128, v88, v89
	v_cvt_pk_bf16_f32 v129, v90, v91
	global_store_dwordx2 v121, v[128:129], s[4:5] offset:1024
	v_mul_f32_e32 v92, v92, v114
	v_mul_f32_e32 v93, v93, v114
	v_mul_f32_e32 v94, v94, v114
	v_mul_f32_e32 v95, v95, v114
	v_mul_f32_e32 v92, v12, v92
	v_mul_f32_e32 v93, v13, v93
	v_mul_f32_e32 v94, v14, v94
	v_mul_f32_e32 v95, v15, v95
	v_fma_f32 v92, v92, v28, v44
	v_fma_f32 v93, v93, v29, v45
	v_fma_f32 v94, v94, v30, v46
	v_fma_f32 v95, v95, v31, v47
	v_cvt_pk_bf16_f32 v130, v92, v93
	v_cvt_pk_bf16_f32 v131, v94, v95
	global_store_dwordx2 v121, v[130:131], s[4:5] offset:1536
	s_add_u32 s4, s4, 0x20000
	s_addc_u32 s5, s5, 0
	v_mul_f32_e32 v96, v96, v115
	v_mul_f32_e32 v97, v97, v115
	v_mul_f32_e32 v98, v98, v115
	v_mul_f32_e32 v99, v99, v115
	v_mul_f32_e32 v96, v0, v96
	v_mul_f32_e32 v97, v1, v97
	v_mul_f32_e32 v98, v2, v98
	v_mul_f32_e32 v99, v3, v99
	v_fma_f32 v96, v96, v16, v32
	v_fma_f32 v97, v97, v17, v33
	v_fma_f32 v98, v98, v18, v34
	v_fma_f32 v99, v99, v19, v35
	v_cvt_pk_bf16_f32 v128, v96, v97
	v_cvt_pk_bf16_f32 v129, v98, v99
	global_store_dwordx2 v121, v[128:129], s[4:5] offset:0
	v_mul_f32_e32 v100, v100, v115
	v_mul_f32_e32 v101, v101, v115
	v_mul_f32_e32 v102, v102, v115
	v_mul_f32_e32 v103, v103, v115
	v_mul_f32_e32 v100, v4, v100
	v_mul_f32_e32 v101, v5, v101
	v_mul_f32_e32 v102, v6, v102
	v_mul_f32_e32 v103, v7, v103
	v_fma_f32 v100, v100, v20, v36
	v_fma_f32 v101, v101, v21, v37
	v_fma_f32 v102, v102, v22, v38
	v_fma_f32 v103, v103, v23, v39
	v_cvt_pk_bf16_f32 v130, v100, v101
	v_cvt_pk_bf16_f32 v131, v102, v103
	global_store_dwordx2 v121, v[130:131], s[4:5] offset:512
	v_mul_f32_e32 v104, v104, v115
	v_mul_f32_e32 v105, v105, v115
	v_mul_f32_e32 v106, v106, v115
	v_mul_f32_e32 v107, v107, v115
	v_mul_f32_e32 v104, v8, v104
	v_mul_f32_e32 v105, v9, v105
	v_mul_f32_e32 v106, v10, v106
	v_mul_f32_e32 v107, v11, v107
	v_fma_f32 v104, v104, v24, v40
	v_fma_f32 v105, v105, v25, v41
	v_fma_f32 v106, v106, v26, v42
	v_fma_f32 v107, v107, v27, v43
	v_cvt_pk_bf16_f32 v128, v104, v105
	v_cvt_pk_bf16_f32 v129, v106, v107
	global_store_dwordx2 v121, v[128:129], s[4:5] offset:1024
	v_mul_f32_e32 v108, v108, v115
	v_mul_f32_e32 v109, v109, v115
	v_mul_f32_e32 v110, v110, v115
	v_mul_f32_e32 v111, v111, v115
	v_mul_f32_e32 v108, v12, v108
	v_mul_f32_e32 v109, v13, v109
	v_mul_f32_e32 v110, v14, v110
	v_mul_f32_e32 v111, v15, v111
	v_fma_f32 v108, v108, v28, v44
	v_fma_f32 v109, v109, v29, v45
	v_fma_f32 v110, v110, v30, v46
	v_fma_f32 v111, v111, v31, v47
	v_cvt_pk_bf16_f32 v130, v108, v109
	v_cvt_pk_bf16_f32 v131, v110, v111
	global_store_dwordx2 v121, v[130:131], s[4:5] offset:1536
	s_add_u32 s4, s4, 0x20000
	s_addc_u32 s5, s5, 0
.Lrms_sub0_loop:
	global_load_dwordx4 v[48:51], v120, s[8:9] offset:0
	global_load_dwordx4 v[52:55], v120, s[8:9] offset:1024
	global_load_dwordx4 v[56:59], v120, s[8:9] offset:2048
	global_load_dwordx4 v[60:63], v120, s[8:9] offset:3072
	s_add_u32 s8, s8, 0x40000
	s_addc_u32 s9, s9, 0
	global_load_dwordx4 v[64:67], v120, s[8:9] offset:0
	global_load_dwordx4 v[68:71], v120, s[8:9] offset:1024
	global_load_dwordx4 v[72:75], v120, s[8:9] offset:2048
	global_load_dwordx4 v[76:79], v120, s[8:9] offset:3072
	s_add_u32 s8, s8, 0x40000
	s_addc_u32 s9, s9, 0
	global_load_dwordx4 v[80:83], v120, s[8:9] offset:0
	global_load_dwordx4 v[84:87], v120, s[8:9] offset:1024
	global_load_dwordx4 v[88:91], v120, s[8:9] offset:2048
	global_load_dwordx4 v[92:95], v120, s[8:9] offset:3072
	s_add_u32 s8, s8, 0x40000
	s_addc_u32 s9, s9, 0
	global_load_dwordx4 v[96:99], v120, s[8:9] offset:0
	global_load_dwordx4 v[100:103], v120, s[8:9] offset:1024
	global_load_dwordx4 v[104:107], v120, s[8:9] offset:2048
	global_load_dwordx4 v[108:111], v120, s[8:9] offset:3072
	s_add_u32 s8, s8, 0x40000
	s_addc_u32 s9, s9, 0
	s_waitcnt vmcnt(44)
	v_mul_f32_e32 v112, v132, v132
	v_fmac_f32_e32 v112, v133, v133
	v_fmac_f32_e32 v112, v134, v134
	v_fmac_f32_e32 v112, v135, v135
	v_fmac_f32_e32 v112, v136, v136
	v_fmac_f32_e32 v112, v137, v137
	v_fmac_f32_e32 v112, v138, v138
	v_fmac_f32_e32 v112, v139, v139
	v_fmac_f32_e32 v112, v140, v140
	v_fmac_f32_e32 v112, v141, v141
	v_fmac_f32_e32 v112, v142, v142
	v_fmac_f32_e32 v112, v143, v143
	v_fmac_f32_e32 v112, v144, v144
	v_fmac_f32_e32 v112, v145, v145
	v_fmac_f32_e32 v112, v146, v146
	v_fmac_f32_e32 v112, v147, v147
	s_waitcnt vmcnt(40)
	v_mul_f32_e32 v113, v166, v166
	v_fmac_f32_e32 v113, v167, v167
	v_fmac_f32_e32 v113, v168, v168
	v_fmac_f32_e32 v113, v169, v169
	v_fmac_f32_e32 v113, v170, v170
	v_fmac_f32_e32 v113, v171, v171
	v_fmac_f32_e32 v113, v172, v172
	v_fmac_f32_e32 v113, v173, v173
	v_fmac_f32_e32 v113, v174, v174
	v_fmac_f32_e32 v113, v175, v175
	v_fmac_f32_e32 v113, v176, v176
	v_fmac_f32_e32 v113, v177, v177
	v_fmac_f32_e32 v113, v178, v178
	v_fmac_f32_e32 v113, v179, v179
	v_fmac_f32_e32 v113, v180, v180
	v_fmac_f32_e32 v113, v181, v181
	s_waitcnt vmcnt(36)
	v_mul_f32_e32 v114, v182, v182
	v_fmac_f32_e32 v114, v183, v183
	v_fmac_f32_e32 v114, v184, v184
	v_fmac_f32_e32 v114, v185, v185
	v_fmac_f32_e32 v114, v186, v186
	v_fmac_f32_e32 v114, v187, v187
	v_fmac_f32_e32 v114, v188, v188
	v_fmac_f32_e32 v114, v189, v189
	v_fmac_f32_e32 v114, v190, v190
	v_fmac_f32_e32 v114, v191, v191
	v_fmac_f32_e32 v114, v192, v192
	v_fmac_f32_e32 v114, v193, v193
	v_fmac_f32_e32 v114, v194, v194
	v_fmac_f32_e32 v114, v195, v195
	v_fmac_f32_e32 v114, v196, v196
	v_fmac_f32_e32 v114, v197, v197
	s_waitcnt vmcnt(32)
	v_mul_f32_e32 v115, v228, v228
	v_fmac_f32_e32 v115, v229, v229
	v_fmac_f32_e32 v115, v230, v230
	v_fmac_f32_e32 v115, v231, v231
	v_fmac_f32_e32 v115, v232, v232
	v_fmac_f32_e32 v115, v233, v233
	v_fmac_f32_e32 v115, v234, v234
	v_fmac_f32_e32 v115, v235, v235
	v_fmac_f32_e32 v115, v236, v236
	v_fmac_f32_e32 v115, v237, v237
	v_fmac_f32_e32 v115, v238, v238
	v_fmac_f32_e32 v115, v239, v239
	v_fmac_f32_e32 v115, v240, v240
	v_fmac_f32_e32 v115, v241, v241
	v_fmac_f32_e32 v115, v242, v242
	v_fmac_f32_e32 v115, v243, v243
	ds_bpermute_b32 v116, v122, v112
	ds_bpermute_b32 v117, v122, v113
	ds_bpermute_b32 v118, v122, v114
	ds_bpermute_b32 v119, v122, v115
	s_waitcnt lgkmcnt(0)
	v_add_f32_e32 v112, v112, v116
	v_add_f32_e32 v113, v113, v117
	v_add_f32_e32 v114, v114, v118
	v_add_f32_e32 v115, v115, v119
	ds_bpermute_b32 v116, v123, v112
	ds_bpermute_b32 v117, v123, v113
	ds_bpermute_b32 v118, v123, v114
	ds_bpermute_b32 v119, v123, v115
	s_waitcnt lgkmcnt(0)
	v_add_f32_e32 v112, v112, v116
	v_add_f32_e32 v113, v113, v117
	v_add_f32_e32 v114, v114, v118
	v_add_f32_e32 v115, v115, v119
	ds_bpermute_b32 v116, v124, v112
	ds_bpermute_b32 v117, v124, v113
	ds_bpermute_b32 v118, v124, v114
	ds_bpermute_b32 v119, v124, v115
	s_waitcnt lgkmcnt(0)
	v_add_f32_e32 v112, v112, v116
	v_add_f32_e32 v113, v113, v117
	v_add_f32_e32 v114, v114, v118
	v_add_f32_e32 v115, v115, v119
	ds_bpermute_b32 v116, v125, v112
	ds_bpermute_b32 v117, v125, v113
	ds_bpermute_b32 v118, v125, v114
	ds_bpermute_b32 v119, v125, v115
	s_waitcnt lgkmcnt(0)
	v_add_f32_e32 v112, v112, v116
	v_add_f32_e32 v113, v113, v117
	v_add_f32_e32 v114, v114, v118
	v_add_f32_e32 v115, v115, v119
	ds_bpermute_b32 v116, v126, v112
	ds_bpermute_b32 v117, v126, v113
	ds_bpermute_b32 v118, v126, v114
	ds_bpermute_b32 v119, v126, v115
	s_waitcnt lgkmcnt(0)
	v_add_f32_e32 v112, v112, v116
	v_add_f32_e32 v113, v113, v117
	v_add_f32_e32 v114, v114, v118
	v_add_f32_e32 v115, v115, v119
	ds_bpermute_b32 v116, v127, v112
	ds_bpermute_b32 v117, v127, v113
	ds_bpermute_b32 v118, v127, v114
	ds_bpermute_b32 v119, v127, v115
	s_waitcnt lgkmcnt(0)
	v_add_f32_e32 v112, v112, v116
	v_add_f32_e32 v113, v113, v117
	v_add_f32_e32 v114, v114, v118
	v_add_f32_e32 v115, v115, v119
	v_fmamk_f32 v112, v112, 0x3a800000, v208
	v_fmamk_f32 v113, v113, 0x3a800000, v208
	v_fmamk_f32 v114, v114, 0x3a800000, v208
	v_fmamk_f32 v115, v115, 0x3a800000, v208
	v_rsq_f32_e32 v112, v112
	v_rsq_f32_e32 v113, v113
	v_rsq_f32_e32 v114, v114
	v_rsq_f32_e32 v115, v115
	s_nop 1
	v_mul_f32_e32 v132, v132, v112
	v_mul_f32_e32 v133, v133, v112
	v_mul_f32_e32 v134, v134, v112
	v_mul_f32_e32 v135, v135, v112
	v_mul_f32_e32 v132, v0, v132
	v_mul_f32_e32 v133, v1, v133
	v_mul_f32_e32 v134, v2, v134
	v_mul_f32_e32 v135, v3, v135
	v_fma_f32 v132, v132, v16, v32
	v_fma_f32 v133, v133, v17, v33
	v_fma_f32 v134, v134, v18, v34
	v_fma_f32 v135, v135, v19, v35
	v_cvt_pk_bf16_f32 v128, v132, v133
	v_cvt_pk_bf16_f32 v129, v134, v135
	global_store_dwordx2 v121, v[128:129], s[4:5] offset:0
	v_mul_f32_e32 v136, v136, v112
	v_mul_f32_e32 v137, v137, v112
	v_mul_f32_e32 v138, v138, v112
	v_mul_f32_e32 v139, v139, v112
	v_mul_f32_e32 v136, v4, v136
	v_mul_f32_e32 v137, v5, v137
	v_mul_f32_e32 v138, v6, v138
	v_mul_f32_e32 v139, v7, v139
	v_fma_f32 v136, v136, v20, v36
	v_fma_f32 v137, v137, v21, v37
	v_fma_f32 v138, v138, v22, v38
	v_fma_f32 v139, v139, v23, v39
	v_cvt_pk_bf16_f32 v130, v136, v137
	v_cvt_pk_bf16_f32 v131, v138, v139
	global_store_dwordx2 v121, v[130:131], s[4:5] offset:512
	v_mul_f32_e32 v140, v140, v112
	v_mul_f32_e32 v141, v141, v112
	v_mul_f32_e32 v142, v142, v112
	v_mul_f32_e32 v143, v143, v112
	v_mul_f32_e32 v140, v8, v140
	v_mul_f32_e32 v141, v9, v141
	v_mul_f32_e32 v142, v10, v142
	v_mul_f32_e32 v143, v11, v143
	v_fma_f32 v140, v140, v24, v40
	v_fma_f32 v141, v141, v25, v41
	v_fma_f32 v142, v142, v26, v42
	v_fma_f32 v143, v143, v27, v43
	v_cvt_pk_bf16_f32 v128, v140, v141
	v_cvt_pk_bf16_f32 v129, v142, v143
	global_store_dwordx2 v121, v[128:129], s[4:5] offset:1024
	v_mul_f32_e32 v144, v144, v112
	v_mul_f32_e32 v145, v145, v112
	v_mul_f32_e32 v146, v146, v112
	v_mul_f32_e32 v147, v147, v112
	v_mul_f32_e32 v144, v12, v144
	v_mul_f32_e32 v145, v13, v145
	v_mul_f32_e32 v146, v14, v146
	v_mul_f32_e32 v147, v15, v147
	v_fma_f32 v144, v144, v28, v44
	v_fma_f32 v145, v145, v29, v45
	v_fma_f32 v146, v146, v30, v46
	v_fma_f32 v147, v147, v31, v47
	v_cvt_pk_bf16_f32 v130, v144, v145
	v_cvt_pk_bf16_f32 v131, v146, v147
	global_store_dwordx2 v121, v[130:131], s[4:5] offset:1536
	s_add_u32 s4, s4, 0x20000
	s_addc_u32 s5, s5, 0
	v_mul_f32_e32 v166, v166, v113
	v_mul_f32_e32 v167, v167, v113
	v_mul_f32_e32 v168, v168, v113
	v_mul_f32_e32 v169, v169, v113
	v_mul_f32_e32 v166, v0, v166
	v_mul_f32_e32 v167, v1, v167
	v_mul_f32_e32 v168, v2, v168
	v_mul_f32_e32 v169, v3, v169
	v_fma_f32 v166, v166, v16, v32
	v_fma_f32 v167, v167, v17, v33
	v_fma_f32 v168, v168, v18, v34
	v_fma_f32 v169, v169, v19, v35
	v_cvt_pk_bf16_f32 v128, v166, v167
	v_cvt_pk_bf16_f32 v129, v168, v169
	global_store_dwordx2 v121, v[128:129], s[4:5] offset:0
	v_mul_f32_e32 v170, v170, v113
	v_mul_f32_e32 v171, v171, v113
	v_mul_f32_e32 v172, v172, v113
	v_mul_f32_e32 v173, v173, v113
	v_mul_f32_e32 v170, v4, v170
	v_mul_f32_e32 v171, v5, v171
	v_mul_f32_e32 v172, v6, v172
	v_mul_f32_e32 v173, v7, v173
	v_fma_f32 v170, v170, v20, v36
	v_fma_f32 v171, v171, v21, v37
	v_fma_f32 v172, v172, v22, v38
	v_fma_f32 v173, v173, v23, v39
	v_cvt_pk_bf16_f32 v130, v170, v171
	v_cvt_pk_bf16_f32 v131, v172, v173
	global_store_dwordx2 v121, v[130:131], s[4:5] offset:512
	v_mul_f32_e32 v174, v174, v113
	v_mul_f32_e32 v175, v175, v113
	v_mul_f32_e32 v176, v176, v113
	v_mul_f32_e32 v177, v177, v113
	v_mul_f32_e32 v174, v8, v174
	v_mul_f32_e32 v175, v9, v175
	v_mul_f32_e32 v176, v10, v176
	v_mul_f32_e32 v177, v11, v177
	v_fma_f32 v174, v174, v24, v40
	v_fma_f32 v175, v175, v25, v41
	v_fma_f32 v176, v176, v26, v42
	v_fma_f32 v177, v177, v27, v43
	v_cvt_pk_bf16_f32 v128, v174, v175
	v_cvt_pk_bf16_f32 v129, v176, v177
	global_store_dwordx2 v121, v[128:129], s[4:5] offset:1024
	v_mul_f32_e32 v178, v178, v113
	v_mul_f32_e32 v179, v179, v113
	v_mul_f32_e32 v180, v180, v113
	v_mul_f32_e32 v181, v181, v113
	v_mul_f32_e32 v178, v12, v178
	v_mul_f32_e32 v179, v13, v179
	v_mul_f32_e32 v180, v14, v180
	v_mul_f32_e32 v181, v15, v181
	v_fma_f32 v178, v178, v28, v44
	v_fma_f32 v179, v179, v29, v45
	v_fma_f32 v180, v180, v30, v46
	v_fma_f32 v181, v181, v31, v47
	v_cvt_pk_bf16_f32 v130, v178, v179
	v_cvt_pk_bf16_f32 v131, v180, v181
	global_store_dwordx2 v121, v[130:131], s[4:5] offset:1536
	s_add_u32 s4, s4, 0x20000
	s_addc_u32 s5, s5, 0
	v_mul_f32_e32 v182, v182, v114
	v_mul_f32_e32 v183, v183, v114
	v_mul_f32_e32 v184, v184, v114
	v_mul_f32_e32 v185, v185, v114
	v_mul_f32_e32 v182, v0, v182
	v_mul_f32_e32 v183, v1, v183
	v_mul_f32_e32 v184, v2, v184
	v_mul_f32_e32 v185, v3, v185
	v_fma_f32 v182, v182, v16, v32
	v_fma_f32 v183, v183, v17, v33
	v_fma_f32 v184, v184, v18, v34
	v_fma_f32 v185, v185, v19, v35
	v_cvt_pk_bf16_f32 v128, v182, v183
	v_cvt_pk_bf16_f32 v129, v184, v185
	global_store_dwordx2 v121, v[128:129], s[4:5] offset:0
	v_mul_f32_e32 v186, v186, v114
	v_mul_f32_e32 v187, v187, v114
	v_mul_f32_e32 v188, v188, v114
	v_mul_f32_e32 v189, v189, v114
	v_mul_f32_e32 v186, v4, v186
	v_mul_f32_e32 v187, v5, v187
	v_mul_f32_e32 v188, v6, v188
	v_mul_f32_e32 v189, v7, v189
	v_fma_f32 v186, v186, v20, v36
	v_fma_f32 v187, v187, v21, v37
	v_fma_f32 v188, v188, v22, v38
	v_fma_f32 v189, v189, v23, v39
	v_cvt_pk_bf16_f32 v130, v186, v187
	v_cvt_pk_bf16_f32 v131, v188, v189
	global_store_dwordx2 v121, v[130:131], s[4:5] offset:512
	v_mul_f32_e32 v190, v190, v114
	v_mul_f32_e32 v191, v191, v114
	v_mul_f32_e32 v192, v192, v114
	v_mul_f32_e32 v193, v193, v114
	v_mul_f32_e32 v190, v8, v190
	v_mul_f32_e32 v191, v9, v191
	v_mul_f32_e32 v192, v10, v192
	v_mul_f32_e32 v193, v11, v193
	v_fma_f32 v190, v190, v24, v40
	v_fma_f32 v191, v191, v25, v41
	v_fma_f32 v192, v192, v26, v42
	v_fma_f32 v193, v193, v27, v43
	v_cvt_pk_bf16_f32 v128, v190, v191
	v_cvt_pk_bf16_f32 v129, v192, v193
	global_store_dwordx2 v121, v[128:129], s[4:5] offset:1024
	v_mul_f32_e32 v194, v194, v114
	v_mul_f32_e32 v195, v195, v114
	v_mul_f32_e32 v196, v196, v114
	v_mul_f32_e32 v197, v197, v114
	v_mul_f32_e32 v194, v12, v194
	v_mul_f32_e32 v195, v13, v195
	v_mul_f32_e32 v196, v14, v196
	v_mul_f32_e32 v197, v15, v197
	v_fma_f32 v194, v194, v28, v44
	v_fma_f32 v195, v195, v29, v45
	v_fma_f32 v196, v196, v30, v46
	v_fma_f32 v197, v197, v31, v47
	v_cvt_pk_bf16_f32 v130, v194, v195
	v_cvt_pk_bf16_f32 v131, v196, v197
	global_store_dwordx2 v121, v[130:131], s[4:5] offset:1536
	s_add_u32 s4, s4, 0x20000
	s_addc_u32 s5, s5, 0
	v_mul_f32_e32 v228, v228, v115
	v_mul_f32_e32 v229, v229, v115
	v_mul_f32_e32 v230, v230, v115
	v_mul_f32_e32 v231, v231, v115
	v_mul_f32_e32 v228, v0, v228
	v_mul_f32_e32 v229, v1, v229
	v_mul_f32_e32 v230, v2, v230
	v_mul_f32_e32 v231, v3, v231
	v_fma_f32 v228, v228, v16, v32
	v_fma_f32 v229, v229, v17, v33
	v_fma_f32 v230, v230, v18, v34
	v_fma_f32 v231, v231, v19, v35
	v_cvt_pk_bf16_f32 v128, v228, v229
	v_cvt_pk_bf16_f32 v129, v230, v231
	global_store_dwordx2 v121, v[128:129], s[4:5] offset:0
	v_mul_f32_e32 v232, v232, v115
	v_mul_f32_e32 v233, v233, v115
	v_mul_f32_e32 v234, v234, v115
	v_mul_f32_e32 v235, v235, v115
	v_mul_f32_e32 v232, v4, v232
	v_mul_f32_e32 v233, v5, v233
	v_mul_f32_e32 v234, v6, v234
	v_mul_f32_e32 v235, v7, v235
	v_fma_f32 v232, v232, v20, v36
	v_fma_f32 v233, v233, v21, v37
	v_fma_f32 v234, v234, v22, v38
	v_fma_f32 v235, v235, v23, v39
	v_cvt_pk_bf16_f32 v130, v232, v233
	v_cvt_pk_bf16_f32 v131, v234, v235
	global_store_dwordx2 v121, v[130:131], s[4:5] offset:512
	v_mul_f32_e32 v236, v236, v115
	v_mul_f32_e32 v237, v237, v115
	v_mul_f32_e32 v238, v238, v115
	v_mul_f32_e32 v239, v239, v115
	v_mul_f32_e32 v236, v8, v236
	v_mul_f32_e32 v237, v9, v237
	v_mul_f32_e32 v238, v10, v238
	v_mul_f32_e32 v239, v11, v239
	v_fma_f32 v236, v236, v24, v40
	v_fma_f32 v237, v237, v25, v41
	v_fma_f32 v238, v238, v26, v42
	v_fma_f32 v239, v239, v27, v43
	v_cvt_pk_bf16_f32 v128, v236, v237
	v_cvt_pk_bf16_f32 v129, v238, v239
	global_store_dwordx2 v121, v[128:129], s[4:5] offset:1024
	v_mul_f32_e32 v240, v240, v115
	v_mul_f32_e32 v241, v241, v115
	v_mul_f32_e32 v242, v242, v115
	v_mul_f32_e32 v243, v243, v115
	v_mul_f32_e32 v240, v12, v240
	v_mul_f32_e32 v241, v13, v241
	v_mul_f32_e32 v242, v14, v242
	v_mul_f32_e32 v243, v15, v243
	v_fma_f32 v240, v240, v28, v44
	v_fma_f32 v241, v241, v29, v45
	v_fma_f32 v242, v242, v30, v46
	v_fma_f32 v243, v243, v31, v47
	v_cvt_pk_bf16_f32 v130, v240, v241
	v_cvt_pk_bf16_f32 v131, v242, v243
	global_store_dwordx2 v121, v[130:131], s[4:5] offset:1536
	s_add_u32 s4, s4, 0x20000
	s_addc_u32 s5, s5, 0
	global_load_dwordx4 v[132:135], v120, s[8:9] offset:0
	global_load_dwordx4 v[136:139], v120, s[8:9] offset:1024
	global_load_dwordx4 v[140:143], v120, s[8:9] offset:2048
	global_load_dwordx4 v[144:147], v120, s[8:9] offset:3072
	s_add_u32 s8, s8, 0x40000
	s_addc_u32 s9, s9, 0
	global_load_dwordx4 v[166:169], v120, s[8:9] offset:0
	global_load_dwordx4 v[170:173], v120, s[8:9] offset:1024
	global_load_dwordx4 v[174:177], v120, s[8:9] offset:2048
	global_load_dwordx4 v[178:181], v120, s[8:9] offset:3072
	s_add_u32 s8, s8, 0x40000
	s_addc_u32 s9, s9, 0
	global_load_dwordx4 v[182:185], v120, s[8:9] offset:0
	global_load_dwordx4 v[186:189], v120, s[8:9] offset:1024
	global_load_dwordx4 v[190:193], v120, s[8:9] offset:2048
	global_load_dwordx4 v[194:197], v120, s[8:9] offset:3072
	s_add_u32 s8, s8, 0x40000
	s_addc_u32 s9, s9, 0
	global_load_dwordx4 v[228:231], v120, s[8:9] offset:0
	global_load_dwordx4 v[232:235], v120, s[8:9] offset:1024
	global_load_dwordx4 v[236:239], v120, s[8:9] offset:2048
	global_load_dwordx4 v[240:243], v120, s[8:9] offset:3072
	s_add_u32 s8, s8, 0x40000
	s_addc_u32 s9, s9, 0
	s_waitcnt vmcnt(44)
	v_mul_f32_e32 v112, v48, v48
	v_fmac_f32_e32 v112, v49, v49
	v_fmac_f32_e32 v112, v50, v50
	v_fmac_f32_e32 v112, v51, v51
	v_fmac_f32_e32 v112, v52, v52
	v_fmac_f32_e32 v112, v53, v53
	v_fmac_f32_e32 v112, v54, v54
	v_fmac_f32_e32 v112, v55, v55
	v_fmac_f32_e32 v112, v56, v56
	v_fmac_f32_e32 v112, v57, v57
	v_fmac_f32_e32 v112, v58, v58
	v_fmac_f32_e32 v112, v59, v59
	v_fmac_f32_e32 v112, v60, v60
	v_fmac_f32_e32 v112, v61, v61
	v_fmac_f32_e32 v112, v62, v62
	v_fmac_f32_e32 v112, v63, v63
	s_waitcnt vmcnt(40)
	v_mul_f32_e32 v113, v64, v64
	v_fmac_f32_e32 v113, v65, v65
	v_fmac_f32_e32 v113, v66, v66
	v_fmac_f32_e32 v113, v67, v67
	v_fmac_f32_e32 v113, v68, v68
	v_fmac_f32_e32 v113, v69, v69
	v_fmac_f32_e32 v113, v70, v70
	v_fmac_f32_e32 v113, v71, v71
	v_fmac_f32_e32 v113, v72, v72
	v_fmac_f32_e32 v113, v73, v73
	v_fmac_f32_e32 v113, v74, v74
	v_fmac_f32_e32 v113, v75, v75
	v_fmac_f32_e32 v113, v76, v76
	v_fmac_f32_e32 v113, v77, v77
	v_fmac_f32_e32 v113, v78, v78
	v_fmac_f32_e32 v113, v79, v79
	s_waitcnt vmcnt(36)
	v_mul_f32_e32 v114, v80, v80
	v_fmac_f32_e32 v114, v81, v81
	v_fmac_f32_e32 v114, v82, v82
	v_fmac_f32_e32 v114, v83, v83
	v_fmac_f32_e32 v114, v84, v84
	v_fmac_f32_e32 v114, v85, v85
	v_fmac_f32_e32 v114, v86, v86
	v_fmac_f32_e32 v114, v87, v87
	v_fmac_f32_e32 v114, v88, v88
	v_fmac_f32_e32 v114, v89, v89
	v_fmac_f32_e32 v114, v90, v90
	v_fmac_f32_e32 v114, v91, v91
	v_fmac_f32_e32 v114, v92, v92
	v_fmac_f32_e32 v114, v93, v93
	v_fmac_f32_e32 v114, v94, v94
	v_fmac_f32_e32 v114, v95, v95
	s_waitcnt vmcnt(32)
	v_mul_f32_e32 v115, v96, v96
	v_fmac_f32_e32 v115, v97, v97
	v_fmac_f32_e32 v115, v98, v98
	v_fmac_f32_e32 v115, v99, v99
	v_fmac_f32_e32 v115, v100, v100
	v_fmac_f32_e32 v115, v101, v101
	v_fmac_f32_e32 v115, v102, v102
	v_fmac_f32_e32 v115, v103, v103
	v_fmac_f32_e32 v115, v104, v104
	v_fmac_f32_e32 v115, v105, v105
	v_fmac_f32_e32 v115, v106, v106
	v_fmac_f32_e32 v115, v107, v107
	v_fmac_f32_e32 v115, v108, v108
	v_fmac_f32_e32 v115, v109, v109
	v_fmac_f32_e32 v115, v110, v110
	v_fmac_f32_e32 v115, v111, v111
	ds_bpermute_b32 v116, v122, v112
	ds_bpermute_b32 v117, v122, v113
	ds_bpermute_b32 v118, v122, v114
	ds_bpermute_b32 v119, v122, v115
	s_waitcnt lgkmcnt(0)
	v_add_f32_e32 v112, v112, v116
	v_add_f32_e32 v113, v113, v117
	v_add_f32_e32 v114, v114, v118
	v_add_f32_e32 v115, v115, v119
	ds_bpermute_b32 v116, v123, v112
	ds_bpermute_b32 v117, v123, v113
	ds_bpermute_b32 v118, v123, v114
	ds_bpermute_b32 v119, v123, v115
	s_waitcnt lgkmcnt(0)
	v_add_f32_e32 v112, v112, v116
	v_add_f32_e32 v113, v113, v117
	v_add_f32_e32 v114, v114, v118
	v_add_f32_e32 v115, v115, v119
	ds_bpermute_b32 v116, v124, v112
	ds_bpermute_b32 v117, v124, v113
	ds_bpermute_b32 v118, v124, v114
	ds_bpermute_b32 v119, v124, v115
	s_waitcnt lgkmcnt(0)
	v_add_f32_e32 v112, v112, v116
	v_add_f32_e32 v113, v113, v117
	v_add_f32_e32 v114, v114, v118
	v_add_f32_e32 v115, v115, v119
	ds_bpermute_b32 v116, v125, v112
	ds_bpermute_b32 v117, v125, v113
	ds_bpermute_b32 v118, v125, v114
	ds_bpermute_b32 v119, v125, v115
	s_waitcnt lgkmcnt(0)
	v_add_f32_e32 v112, v112, v116
	v_add_f32_e32 v113, v113, v117
	v_add_f32_e32 v114, v114, v118
	v_add_f32_e32 v115, v115, v119
	ds_bpermute_b32 v116, v126, v112
	ds_bpermute_b32 v117, v126, v113
	ds_bpermute_b32 v118, v126, v114
	ds_bpermute_b32 v119, v126, v115
	s_waitcnt lgkmcnt(0)
	v_add_f32_e32 v112, v112, v116
	v_add_f32_e32 v113, v113, v117
	v_add_f32_e32 v114, v114, v118
	v_add_f32_e32 v115, v115, v119
	ds_bpermute_b32 v116, v127, v112
	ds_bpermute_b32 v117, v127, v113
	ds_bpermute_b32 v118, v127, v114
	ds_bpermute_b32 v119, v127, v115
	s_waitcnt lgkmcnt(0)
	v_add_f32_e32 v112, v112, v116
	v_add_f32_e32 v113, v113, v117
	v_add_f32_e32 v114, v114, v118
	v_add_f32_e32 v115, v115, v119
	v_fmamk_f32 v112, v112, 0x3a800000, v208
	v_fmamk_f32 v113, v113, 0x3a800000, v208
	v_fmamk_f32 v114, v114, 0x3a800000, v208
	v_fmamk_f32 v115, v115, 0x3a800000, v208
	v_rsq_f32_e32 v112, v112
	v_rsq_f32_e32 v113, v113
	v_rsq_f32_e32 v114, v114
	v_rsq_f32_e32 v115, v115
	s_nop 1
	v_mul_f32_e32 v48, v48, v112
	v_mul_f32_e32 v49, v49, v112
	v_mul_f32_e32 v50, v50, v112
	v_mul_f32_e32 v51, v51, v112
	v_mul_f32_e32 v48, v0, v48
	v_mul_f32_e32 v49, v1, v49
	v_mul_f32_e32 v50, v2, v50
	v_mul_f32_e32 v51, v3, v51
	v_fma_f32 v48, v48, v16, v32
	v_fma_f32 v49, v49, v17, v33
	v_fma_f32 v50, v50, v18, v34
	v_fma_f32 v51, v51, v19, v35
	v_cvt_pk_bf16_f32 v128, v48, v49
	v_cvt_pk_bf16_f32 v129, v50, v51
	global_store_dwordx2 v121, v[128:129], s[4:5] offset:0
	v_mul_f32_e32 v52, v52, v112
	v_mul_f32_e32 v53, v53, v112
	v_mul_f32_e32 v54, v54, v112
	v_mul_f32_e32 v55, v55, v112
	v_mul_f32_e32 v52, v4, v52
	v_mul_f32_e32 v53, v5, v53
	v_mul_f32_e32 v54, v6, v54
	v_mul_f32_e32 v55, v7, v55
	v_fma_f32 v52, v52, v20, v36
	v_fma_f32 v53, v53, v21, v37
	v_fma_f32 v54, v54, v22, v38
	v_fma_f32 v55, v55, v23, v39
	v_cvt_pk_bf16_f32 v130, v52, v53
	v_cvt_pk_bf16_f32 v131, v54, v55
	global_store_dwordx2 v121, v[130:131], s[4:5] offset:512
	v_mul_f32_e32 v56, v56, v112
	v_mul_f32_e32 v57, v57, v112
	v_mul_f32_e32 v58, v58, v112
	v_mul_f32_e32 v59, v59, v112
	v_mul_f32_e32 v56, v8, v56
	v_mul_f32_e32 v57, v9, v57
	v_mul_f32_e32 v58, v10, v58
	v_mul_f32_e32 v59, v11, v59
	v_fma_f32 v56, v56, v24, v40
	v_fma_f32 v57, v57, v25, v41
	v_fma_f32 v58, v58, v26, v42
	v_fma_f32 v59, v59, v27, v43
	v_cvt_pk_bf16_f32 v128, v56, v57
	v_cvt_pk_bf16_f32 v129, v58, v59
	global_store_dwordx2 v121, v[128:129], s[4:5] offset:1024
	v_mul_f32_e32 v60, v60, v112
	v_mul_f32_e32 v61, v61, v112
	v_mul_f32_e32 v62, v62, v112
	v_mul_f32_e32 v63, v63, v112
	v_mul_f32_e32 v60, v12, v60
	v_mul_f32_e32 v61, v13, v61
	v_mul_f32_e32 v62, v14, v62
	v_mul_f32_e32 v63, v15, v63
	v_fma_f32 v60, v60, v28, v44
	v_fma_f32 v61, v61, v29, v45
	v_fma_f32 v62, v62, v30, v46
	v_fma_f32 v63, v63, v31, v47
	v_cvt_pk_bf16_f32 v130, v60, v61
	v_cvt_pk_bf16_f32 v131, v62, v63
	global_store_dwordx2 v121, v[130:131], s[4:5] offset:1536
	s_add_u32 s4, s4, 0x20000
	s_addc_u32 s5, s5, 0
	v_mul_f32_e32 v64, v64, v113
	v_mul_f32_e32 v65, v65, v113
	v_mul_f32_e32 v66, v66, v113
	v_mul_f32_e32 v67, v67, v113
	v_mul_f32_e32 v64, v0, v64
	v_mul_f32_e32 v65, v1, v65
	v_mul_f32_e32 v66, v2, v66
	v_mul_f32_e32 v67, v3, v67
	v_fma_f32 v64, v64, v16, v32
	v_fma_f32 v65, v65, v17, v33
	v_fma_f32 v66, v66, v18, v34
	v_fma_f32 v67, v67, v19, v35
	v_cvt_pk_bf16_f32 v128, v64, v65
	v_cvt_pk_bf16_f32 v129, v66, v67
	global_store_dwordx2 v121, v[128:129], s[4:5] offset:0
	v_mul_f32_e32 v68, v68, v113
	v_mul_f32_e32 v69, v69, v113
	v_mul_f32_e32 v70, v70, v113
	v_mul_f32_e32 v71, v71, v113
	v_mul_f32_e32 v68, v4, v68
	v_mul_f32_e32 v69, v5, v69
	v_mul_f32_e32 v70, v6, v70
	v_mul_f32_e32 v71, v7, v71
	v_fma_f32 v68, v68, v20, v36
	v_fma_f32 v69, v69, v21, v37
	v_fma_f32 v70, v70, v22, v38
	v_fma_f32 v71, v71, v23, v39
	v_cvt_pk_bf16_f32 v130, v68, v69
	v_cvt_pk_bf16_f32 v131, v70, v71
	global_store_dwordx2 v121, v[130:131], s[4:5] offset:512
	v_mul_f32_e32 v72, v72, v113
	v_mul_f32_e32 v73, v73, v113
	v_mul_f32_e32 v74, v74, v113
	v_mul_f32_e32 v75, v75, v113
	v_mul_f32_e32 v72, v8, v72
	v_mul_f32_e32 v73, v9, v73
	v_mul_f32_e32 v74, v10, v74
	v_mul_f32_e32 v75, v11, v75
	v_fma_f32 v72, v72, v24, v40
	v_fma_f32 v73, v73, v25, v41
	v_fma_f32 v74, v74, v26, v42
	v_fma_f32 v75, v75, v27, v43
	v_cvt_pk_bf16_f32 v128, v72, v73
	v_cvt_pk_bf16_f32 v129, v74, v75
	global_store_dwordx2 v121, v[128:129], s[4:5] offset:1024
	v_mul_f32_e32 v76, v76, v113
	v_mul_f32_e32 v77, v77, v113
	v_mul_f32_e32 v78, v78, v113
	v_mul_f32_e32 v79, v79, v113
	v_mul_f32_e32 v76, v12, v76
	v_mul_f32_e32 v77, v13, v77
	v_mul_f32_e32 v78, v14, v78
	v_mul_f32_e32 v79, v15, v79
	v_fma_f32 v76, v76, v28, v44
	v_fma_f32 v77, v77, v29, v45
	v_fma_f32 v78, v78, v30, v46
	v_fma_f32 v79, v79, v31, v47
	v_cvt_pk_bf16_f32 v130, v76, v77
	v_cvt_pk_bf16_f32 v131, v78, v79
	global_store_dwordx2 v121, v[130:131], s[4:5] offset:1536
	s_add_u32 s4, s4, 0x20000
	s_addc_u32 s5, s5, 0
	v_mul_f32_e32 v80, v80, v114
	v_mul_f32_e32 v81, v81, v114
	v_mul_f32_e32 v82, v82, v114
	v_mul_f32_e32 v83, v83, v114
	v_mul_f32_e32 v80, v0, v80
	v_mul_f32_e32 v81, v1, v81
	v_mul_f32_e32 v82, v2, v82
	v_mul_f32_e32 v83, v3, v83
	v_fma_f32 v80, v80, v16, v32
	v_fma_f32 v81, v81, v17, v33
	v_fma_f32 v82, v82, v18, v34
	v_fma_f32 v83, v83, v19, v35
	v_cvt_pk_bf16_f32 v128, v80, v81
	v_cvt_pk_bf16_f32 v129, v82, v83
	global_store_dwordx2 v121, v[128:129], s[4:5] offset:0
	v_mul_f32_e32 v84, v84, v114
	v_mul_f32_e32 v85, v85, v114
	v_mul_f32_e32 v86, v86, v114
	v_mul_f32_e32 v87, v87, v114
	v_mul_f32_e32 v84, v4, v84
	v_mul_f32_e32 v85, v5, v85
	v_mul_f32_e32 v86, v6, v86
	v_mul_f32_e32 v87, v7, v87
	v_fma_f32 v84, v84, v20, v36
	v_fma_f32 v85, v85, v21, v37
	v_fma_f32 v86, v86, v22, v38
	v_fma_f32 v87, v87, v23, v39
	v_cvt_pk_bf16_f32 v130, v84, v85
	v_cvt_pk_bf16_f32 v131, v86, v87
	global_store_dwordx2 v121, v[130:131], s[4:5] offset:512
	v_mul_f32_e32 v88, v88, v114
	v_mul_f32_e32 v89, v89, v114
	v_mul_f32_e32 v90, v90, v114
	v_mul_f32_e32 v91, v91, v114
	v_mul_f32_e32 v88, v8, v88
	v_mul_f32_e32 v89, v9, v89
	v_mul_f32_e32 v90, v10, v90
	v_mul_f32_e32 v91, v11, v91
	v_fma_f32 v88, v88, v24, v40
	v_fma_f32 v89, v89, v25, v41
	v_fma_f32 v90, v90, v26, v42
	v_fma_f32 v91, v91, v27, v43
	v_cvt_pk_bf16_f32 v128, v88, v89
	v_cvt_pk_bf16_f32 v129, v90, v91
	global_store_dwordx2 v121, v[128:129], s[4:5] offset:1024
	v_mul_f32_e32 v92, v92, v114
	v_mul_f32_e32 v93, v93, v114
	v_mul_f32_e32 v94, v94, v114
	v_mul_f32_e32 v95, v95, v114
	v_mul_f32_e32 v92, v12, v92
	v_mul_f32_e32 v93, v13, v93
	v_mul_f32_e32 v94, v14, v94
	v_mul_f32_e32 v95, v15, v95
	v_fma_f32 v92, v92, v28, v44
	v_fma_f32 v93, v93, v29, v45
	v_fma_f32 v94, v94, v30, v46
	v_fma_f32 v95, v95, v31, v47
	v_cvt_pk_bf16_f32 v130, v92, v93
	v_cvt_pk_bf16_f32 v131, v94, v95
	global_store_dwordx2 v121, v[130:131], s[4:5] offset:1536
	s_add_u32 s4, s4, 0x20000
	s_addc_u32 s5, s5, 0
	v_mul_f32_e32 v96, v96, v115
	v_mul_f32_e32 v97, v97, v115
	v_mul_f32_e32 v98, v98, v115
	v_mul_f32_e32 v99, v99, v115
	v_mul_f32_e32 v96, v0, v96
	v_mul_f32_e32 v97, v1, v97
	v_mul_f32_e32 v98, v2, v98
	v_mul_f32_e32 v99, v3, v99
	v_fma_f32 v96, v96, v16, v32
	v_fma_f32 v97, v97, v17, v33
	v_fma_f32 v98, v98, v18, v34
	v_fma_f32 v99, v99, v19, v35
	v_cvt_pk_bf16_f32 v128, v96, v97
	v_cvt_pk_bf16_f32 v129, v98, v99
	global_store_dwordx2 v121, v[128:129], s[4:5] offset:0
	v_mul_f32_e32 v100, v100, v115
	v_mul_f32_e32 v101, v101, v115
	v_mul_f32_e32 v102, v102, v115
	v_mul_f32_e32 v103, v103, v115
	v_mul_f32_e32 v100, v4, v100
	v_mul_f32_e32 v101, v5, v101
	v_mul_f32_e32 v102, v6, v102
	v_mul_f32_e32 v103, v7, v103
	v_fma_f32 v100, v100, v20, v36
	v_fma_f32 v101, v101, v21, v37
	v_fma_f32 v102, v102, v22, v38
	v_fma_f32 v103, v103, v23, v39
	v_cvt_pk_bf16_f32 v130, v100, v101
	v_cvt_pk_bf16_f32 v131, v102, v103
	global_store_dwordx2 v121, v[130:131], s[4:5] offset:512
	v_mul_f32_e32 v104, v104, v115
	v_mul_f32_e32 v105, v105, v115
	v_mul_f32_e32 v106, v106, v115
	v_mul_f32_e32 v107, v107, v115
	v_mul_f32_e32 v104, v8, v104
	v_mul_f32_e32 v105, v9, v105
	v_mul_f32_e32 v106, v10, v106
	v_mul_f32_e32 v107, v11, v107
	v_fma_f32 v104, v104, v24, v40
	v_fma_f32 v105, v105, v25, v41
	v_fma_f32 v106, v106, v26, v42
	v_fma_f32 v107, v107, v27, v43
	v_cvt_pk_bf16_f32 v128, v104, v105
	v_cvt_pk_bf16_f32 v129, v106, v107
	global_store_dwordx2 v121, v[128:129], s[4:5] offset:1024
	v_mul_f32_e32 v108, v108, v115
	v_mul_f32_e32 v109, v109, v115
	v_mul_f32_e32 v110, v110, v115
	v_mul_f32_e32 v111, v111, v115
	v_mul_f32_e32 v108, v12, v108
	v_mul_f32_e32 v109, v13, v109
	v_mul_f32_e32 v110, v14, v110
	v_mul_f32_e32 v111, v15, v111
	v_fma_f32 v108, v108, v28, v44
	v_fma_f32 v109, v109, v29, v45
	v_fma_f32 v110, v110, v30, v46
	v_fma_f32 v111, v111, v31, v47
	v_cvt_pk_bf16_f32 v130, v108, v109
	v_cvt_pk_bf16_f32 v131, v110, v111
	global_store_dwordx2 v121, v[130:131], s[4:5] offset:1536
	s_add_u32 s4, s4, 0x20000
	s_addc_u32 s5, s5, 0
	s_sub_u32 s2, s2, 1
	s_cmp_lg_u32 s2, 0
	s_cbranch_scc1 .Lrms_sub0_loop
	s_waitcnt vmcnt(28)
	v_mul_f32_e32 v112, v132, v132
	v_fmac_f32_e32 v112, v133, v133
	v_fmac_f32_e32 v112, v134, v134
	v_fmac_f32_e32 v112, v135, v135
	v_fmac_f32_e32 v112, v136, v136
	v_fmac_f32_e32 v112, v137, v137
	v_fmac_f32_e32 v112, v138, v138
	v_fmac_f32_e32 v112, v139, v139
	v_fmac_f32_e32 v112, v140, v140
	v_fmac_f32_e32 v112, v141, v141
	v_fmac_f32_e32 v112, v142, v142
	v_fmac_f32_e32 v112, v143, v143
	v_fmac_f32_e32 v112, v144, v144
	v_fmac_f32_e32 v112, v145, v145
	v_fmac_f32_e32 v112, v146, v146
	v_fmac_f32_e32 v112, v147, v147
	s_waitcnt vmcnt(24)
	v_mul_f32_e32 v113, v166, v166
	v_fmac_f32_e32 v113, v167, v167
	v_fmac_f32_e32 v113, v168, v168
	v_fmac_f32_e32 v113, v169, v169
	v_fmac_f32_e32 v113, v170, v170
	v_fmac_f32_e32 v113, v171, v171
	v_fmac_f32_e32 v113, v172, v172
	v_fmac_f32_e32 v113, v173, v173
	v_fmac_f32_e32 v113, v174, v174
	v_fmac_f32_e32 v113, v175, v175
	v_fmac_f32_e32 v113, v176, v176
	v_fmac_f32_e32 v113, v177, v177
	v_fmac_f32_e32 v113, v178, v178
	v_fmac_f32_e32 v113, v179, v179
	v_fmac_f32_e32 v113, v180, v180
	v_fmac_f32_e32 v113, v181, v181
	s_waitcnt vmcnt(20)
	v_mul_f32_e32 v114, v182, v182
	v_fmac_f32_e32 v114, v183, v183
	v_fmac_f32_e32 v114, v184, v184
	v_fmac_f32_e32 v114, v185, v185
	v_fmac_f32_e32 v114, v186, v186
	v_fmac_f32_e32 v114, v187, v187
	v_fmac_f32_e32 v114, v188, v188
	v_fmac_f32_e32 v114, v189, v189
	v_fmac_f32_e32 v114, v190, v190
	v_fmac_f32_e32 v114, v191, v191
	v_fmac_f32_e32 v114, v192, v192
	v_fmac_f32_e32 v114, v193, v193
	v_fmac_f32_e32 v114, v194, v194
	v_fmac_f32_e32 v114, v195, v195
	v_fmac_f32_e32 v114, v196, v196
	v_fmac_f32_e32 v114, v197, v197
	s_waitcnt vmcnt(16)
	v_mul_f32_e32 v115, v228, v228
	v_fmac_f32_e32 v115, v229, v229
	v_fmac_f32_e32 v115, v230, v230
	v_fmac_f32_e32 v115, v231, v231
	v_fmac_f32_e32 v115, v232, v232
	v_fmac_f32_e32 v115, v233, v233
	v_fmac_f32_e32 v115, v234, v234
	v_fmac_f32_e32 v115, v235, v235
	v_fmac_f32_e32 v115, v236, v236
	v_fmac_f32_e32 v115, v237, v237
	v_fmac_f32_e32 v115, v238, v238
	v_fmac_f32_e32 v115, v239, v239
	v_fmac_f32_e32 v115, v240, v240
	v_fmac_f32_e32 v115, v241, v241
	v_fmac_f32_e32 v115, v242, v242
	v_fmac_f32_e32 v115, v243, v243
	ds_bpermute_b32 v116, v122, v112
	ds_bpermute_b32 v117, v122, v113
	ds_bpermute_b32 v118, v122, v114
	ds_bpermute_b32 v119, v122, v115
	s_waitcnt lgkmcnt(0)
	v_add_f32_e32 v112, v112, v116
	v_add_f32_e32 v113, v113, v117
	v_add_f32_e32 v114, v114, v118
	v_add_f32_e32 v115, v115, v119
	ds_bpermute_b32 v116, v123, v112
	ds_bpermute_b32 v117, v123, v113
	ds_bpermute_b32 v118, v123, v114
	ds_bpermute_b32 v119, v123, v115
	s_waitcnt lgkmcnt(0)
	v_add_f32_e32 v112, v112, v116
	v_add_f32_e32 v113, v113, v117
	v_add_f32_e32 v114, v114, v118
	v_add_f32_e32 v115, v115, v119
	ds_bpermute_b32 v116, v124, v112
	ds_bpermute_b32 v117, v124, v113
	ds_bpermute_b32 v118, v124, v114
	ds_bpermute_b32 v119, v124, v115
	s_waitcnt lgkmcnt(0)
	v_add_f32_e32 v112, v112, v116
	v_add_f32_e32 v113, v113, v117
	v_add_f32_e32 v114, v114, v118
	v_add_f32_e32 v115, v115, v119
	ds_bpermute_b32 v116, v125, v112
	ds_bpermute_b32 v117, v125, v113
	ds_bpermute_b32 v118, v125, v114
	ds_bpermute_b32 v119, v125, v115
	s_waitcnt lgkmcnt(0)
	v_add_f32_e32 v112, v112, v116
	v_add_f32_e32 v113, v113, v117
	v_add_f32_e32 v114, v114, v118
	v_add_f32_e32 v115, v115, v119
	ds_bpermute_b32 v116, v126, v112
	ds_bpermute_b32 v117, v126, v113
	ds_bpermute_b32 v118, v126, v114
	ds_bpermute_b32 v119, v126, v115
	s_waitcnt lgkmcnt(0)
	v_add_f32_e32 v112, v112, v116
	v_add_f32_e32 v113, v113, v117
	v_add_f32_e32 v114, v114, v118
	v_add_f32_e32 v115, v115, v119
	ds_bpermute_b32 v116, v127, v112
	ds_bpermute_b32 v117, v127, v113
	ds_bpermute_b32 v118, v127, v114
	ds_bpermute_b32 v119, v127, v115
	s_waitcnt lgkmcnt(0)
	v_add_f32_e32 v112, v112, v116
	v_add_f32_e32 v113, v113, v117
	v_add_f32_e32 v114, v114, v118
	v_add_f32_e32 v115, v115, v119
	v_fmamk_f32 v112, v112, 0x3a800000, v208
	v_fmamk_f32 v113, v113, 0x3a800000, v208
	v_fmamk_f32 v114, v114, 0x3a800000, v208
	v_fmamk_f32 v115, v115, 0x3a800000, v208
	v_rsq_f32_e32 v112, v112
	v_rsq_f32_e32 v113, v113
	v_rsq_f32_e32 v114, v114
	v_rsq_f32_e32 v115, v115
	s_nop 1
	v_mul_f32_e32 v132, v132, v112
	v_mul_f32_e32 v133, v133, v112
	v_mul_f32_e32 v134, v134, v112
	v_mul_f32_e32 v135, v135, v112
	v_mul_f32_e32 v132, v0, v132
	v_mul_f32_e32 v133, v1, v133
	v_mul_f32_e32 v134, v2, v134
	v_mul_f32_e32 v135, v3, v135
	v_fma_f32 v132, v132, v16, v32
	v_fma_f32 v133, v133, v17, v33
	v_fma_f32 v134, v134, v18, v34
	v_fma_f32 v135, v135, v19, v35
	v_cvt_pk_bf16_f32 v128, v132, v133
	v_cvt_pk_bf16_f32 v129, v134, v135
	global_store_dwordx2 v121, v[128:129], s[4:5] offset:0
	v_mul_f32_e32 v136, v136, v112
	v_mul_f32_e32 v137, v137, v112
	v_mul_f32_e32 v138, v138, v112
	v_mul_f32_e32 v139, v139, v112
	v_mul_f32_e32 v136, v4, v136
	v_mul_f32_e32 v137, v5, v137
	v_mul_f32_e32 v138, v6, v138
	v_mul_f32_e32 v139, v7, v139
	v_fma_f32 v136, v136, v20, v36
	v_fma_f32 v137, v137, v21, v37
	v_fma_f32 v138, v138, v22, v38
	v_fma_f32 v139, v139, v23, v39
	v_cvt_pk_bf16_f32 v130, v136, v137
	v_cvt_pk_bf16_f32 v131, v138, v139
	global_store_dwordx2 v121, v[130:131], s[4:5] offset:512
	v_mul_f32_e32 v140, v140, v112
	v_mul_f32_e32 v141, v141, v112
	v_mul_f32_e32 v142, v142, v112
	v_mul_f32_e32 v143, v143, v112
	v_mul_f32_e32 v140, v8, v140
	v_mul_f32_e32 v141, v9, v141
	v_mul_f32_e32 v142, v10, v142
	v_mul_f32_e32 v143, v11, v143
	v_fma_f32 v140, v140, v24, v40
	v_fma_f32 v141, v141, v25, v41
	v_fma_f32 v142, v142, v26, v42
	v_fma_f32 v143, v143, v27, v43
	v_cvt_pk_bf16_f32 v128, v140, v141
	v_cvt_pk_bf16_f32 v129, v142, v143
	global_store_dwordx2 v121, v[128:129], s[4:5] offset:1024
	v_mul_f32_e32 v144, v144, v112
	v_mul_f32_e32 v145, v145, v112
	v_mul_f32_e32 v146, v146, v112
	v_mul_f32_e32 v147, v147, v112
	v_mul_f32_e32 v144, v12, v144
	v_mul_f32_e32 v145, v13, v145
	v_mul_f32_e32 v146, v14, v146
	v_mul_f32_e32 v147, v15, v147
	v_fma_f32 v144, v144, v28, v44
	v_fma_f32 v145, v145, v29, v45
	v_fma_f32 v146, v146, v30, v46
	v_fma_f32 v147, v147, v31, v47
	v_cvt_pk_bf16_f32 v130, v144, v145
	v_cvt_pk_bf16_f32 v131, v146, v147
	global_store_dwordx2 v121, v[130:131], s[4:5] offset:1536
	s_add_u32 s4, s4, 0x20000
	s_addc_u32 s5, s5, 0
	v_mul_f32_e32 v166, v166, v113
	v_mul_f32_e32 v167, v167, v113
	v_mul_f32_e32 v168, v168, v113
	v_mul_f32_e32 v169, v169, v113
	v_mul_f32_e32 v166, v0, v166
	v_mul_f32_e32 v167, v1, v167
	v_mul_f32_e32 v168, v2, v168
	v_mul_f32_e32 v169, v3, v169
	v_fma_f32 v166, v166, v16, v32
	v_fma_f32 v167, v167, v17, v33
	v_fma_f32 v168, v168, v18, v34
	v_fma_f32 v169, v169, v19, v35
	v_cvt_pk_bf16_f32 v128, v166, v167
	v_cvt_pk_bf16_f32 v129, v168, v169
	global_store_dwordx2 v121, v[128:129], s[4:5] offset:0
	v_mul_f32_e32 v170, v170, v113
	v_mul_f32_e32 v171, v171, v113
	v_mul_f32_e32 v172, v172, v113
	v_mul_f32_e32 v173, v173, v113
	v_mul_f32_e32 v170, v4, v170
	v_mul_f32_e32 v171, v5, v171
	v_mul_f32_e32 v172, v6, v172
	v_mul_f32_e32 v173, v7, v173
	v_fma_f32 v170, v170, v20, v36
	v_fma_f32 v171, v171, v21, v37
	v_fma_f32 v172, v172, v22, v38
	v_fma_f32 v173, v173, v23, v39
	v_cvt_pk_bf16_f32 v130, v170, v171
	v_cvt_pk_bf16_f32 v131, v172, v173
	global_store_dwordx2 v121, v[130:131], s[4:5] offset:512
	v_mul_f32_e32 v174, v174, v113
	v_mul_f32_e32 v175, v175, v113
	v_mul_f32_e32 v176, v176, v113
	v_mul_f32_e32 v177, v177, v113
	v_mul_f32_e32 v174, v8, v174
	v_mul_f32_e32 v175, v9, v175
	v_mul_f32_e32 v176, v10, v176
	v_mul_f32_e32 v177, v11, v177
	v_fma_f32 v174, v174, v24, v40
	v_fma_f32 v175, v175, v25, v41
	v_fma_f32 v176, v176, v26, v42
	v_fma_f32 v177, v177, v27, v43
	v_cvt_pk_bf16_f32 v128, v174, v175
	v_cvt_pk_bf16_f32 v129, v176, v177
	global_store_dwordx2 v121, v[128:129], s[4:5] offset:1024
	v_mul_f32_e32 v178, v178, v113
	v_mul_f32_e32 v179, v179, v113
	v_mul_f32_e32 v180, v180, v113
	v_mul_f32_e32 v181, v181, v113
	v_mul_f32_e32 v178, v12, v178
	v_mul_f32_e32 v179, v13, v179
	v_mul_f32_e32 v180, v14, v180
	v_mul_f32_e32 v181, v15, v181
	v_fma_f32 v178, v178, v28, v44
	v_fma_f32 v179, v179, v29, v45
	v_fma_f32 v180, v180, v30, v46
	v_fma_f32 v181, v181, v31, v47
	v_cvt_pk_bf16_f32 v130, v178, v179
	v_cvt_pk_bf16_f32 v131, v180, v181
	global_store_dwordx2 v121, v[130:131], s[4:5] offset:1536
	s_add_u32 s4, s4, 0x20000
	s_addc_u32 s5, s5, 0
	v_mul_f32_e32 v182, v182, v114
	v_mul_f32_e32 v183, v183, v114
	v_mul_f32_e32 v184, v184, v114
	v_mul_f32_e32 v185, v185, v114
	v_mul_f32_e32 v182, v0, v182
	v_mul_f32_e32 v183, v1, v183
	v_mul_f32_e32 v184, v2, v184
	v_mul_f32_e32 v185, v3, v185
	v_fma_f32 v182, v182, v16, v32
	v_fma_f32 v183, v183, v17, v33
	v_fma_f32 v184, v184, v18, v34
	v_fma_f32 v185, v185, v19, v35
	v_cvt_pk_bf16_f32 v128, v182, v183
	v_cvt_pk_bf16_f32 v129, v184, v185
	global_store_dwordx2 v121, v[128:129], s[4:5] offset:0
	v_mul_f32_e32 v186, v186, v114
	v_mul_f32_e32 v187, v187, v114
	v_mul_f32_e32 v188, v188, v114
	v_mul_f32_e32 v189, v189, v114
	v_mul_f32_e32 v186, v4, v186
	v_mul_f32_e32 v187, v5, v187
	v_mul_f32_e32 v188, v6, v188
	v_mul_f32_e32 v189, v7, v189
	v_fma_f32 v186, v186, v20, v36
	v_fma_f32 v187, v187, v21, v37
	v_fma_f32 v188, v188, v22, v38
	v_fma_f32 v189, v189, v23, v39
	v_cvt_pk_bf16_f32 v130, v186, v187
	v_cvt_pk_bf16_f32 v131, v188, v189
	global_store_dwordx2 v121, v[130:131], s[4:5] offset:512
	v_mul_f32_e32 v190, v190, v114
	v_mul_f32_e32 v191, v191, v114
	v_mul_f32_e32 v192, v192, v114
	v_mul_f32_e32 v193, v193, v114
	v_mul_f32_e32 v190, v8, v190
	v_mul_f32_e32 v191, v9, v191
	v_mul_f32_e32 v192, v10, v192
	v_mul_f32_e32 v193, v11, v193
	v_fma_f32 v190, v190, v24, v40
	v_fma_f32 v191, v191, v25, v41
	v_fma_f32 v192, v192, v26, v42
	v_fma_f32 v193, v193, v27, v43
	v_cvt_pk_bf16_f32 v128, v190, v191
	v_cvt_pk_bf16_f32 v129, v192, v193
	global_store_dwordx2 v121, v[128:129], s[4:5] offset:1024
	v_mul_f32_e32 v194, v194, v114
	v_mul_f32_e32 v195, v195, v114
	v_mul_f32_e32 v196, v196, v114
	v_mul_f32_e32 v197, v197, v114
	v_mul_f32_e32 v194, v12, v194
	v_mul_f32_e32 v195, v13, v195
	v_mul_f32_e32 v196, v14, v196
	v_mul_f32_e32 v197, v15, v197
	v_fma_f32 v194, v194, v28, v44
	v_fma_f32 v195, v195, v29, v45
	v_fma_f32 v196, v196, v30, v46
	v_fma_f32 v197, v197, v31, v47
	v_cvt_pk_bf16_f32 v130, v194, v195
	v_cvt_pk_bf16_f32 v131, v196, v197
	global_store_dwordx2 v121, v[130:131], s[4:5] offset:1536
	s_add_u32 s4, s4, 0x20000
	s_addc_u32 s5, s5, 0
	v_mul_f32_e32 v228, v228, v115
	v_mul_f32_e32 v229, v229, v115
	v_mul_f32_e32 v230, v230, v115
	v_mul_f32_e32 v231, v231, v115
	v_mul_f32_e32 v228, v0, v228
	v_mul_f32_e32 v229, v1, v229
	v_mul_f32_e32 v230, v2, v230
	v_mul_f32_e32 v231, v3, v231
	v_fma_f32 v228, v228, v16, v32
	v_fma_f32 v229, v229, v17, v33
	v_fma_f32 v230, v230, v18, v34
	v_fma_f32 v231, v231, v19, v35
	v_cvt_pk_bf16_f32 v128, v228, v229
	v_cvt_pk_bf16_f32 v129, v230, v231
	global_store_dwordx2 v121, v[128:129], s[4:5] offset:0
	v_mul_f32_e32 v232, v232, v115
	v_mul_f32_e32 v233, v233, v115
	v_mul_f32_e32 v234, v234, v115
	v_mul_f32_e32 v235, v235, v115
	v_mul_f32_e32 v232, v4, v232
	v_mul_f32_e32 v233, v5, v233
	v_mul_f32_e32 v234, v6, v234
	v_mul_f32_e32 v235, v7, v235
	v_fma_f32 v232, v232, v20, v36
	v_fma_f32 v233, v233, v21, v37
	v_fma_f32 v234, v234, v22, v38
	v_fma_f32 v235, v235, v23, v39
	v_cvt_pk_bf16_f32 v130, v232, v233
	v_cvt_pk_bf16_f32 v131, v234, v235
	global_store_dwordx2 v121, v[130:131], s[4:5] offset:512
	v_mul_f32_e32 v236, v236, v115
	v_mul_f32_e32 v237, v237, v115
	v_mul_f32_e32 v238, v238, v115
	v_mul_f32_e32 v239, v239, v115
	v_mul_f32_e32 v236, v8, v236
	v_mul_f32_e32 v237, v9, v237
	v_mul_f32_e32 v238, v10, v238
	v_mul_f32_e32 v239, v11, v239
	v_fma_f32 v236, v236, v24, v40
	v_fma_f32 v237, v237, v25, v41
	v_fma_f32 v238, v238, v26, v42
	v_fma_f32 v239, v239, v27, v43
	v_cvt_pk_bf16_f32 v128, v236, v237
	v_cvt_pk_bf16_f32 v129, v238, v239
	global_store_dwordx2 v121, v[128:129], s[4:5] offset:1024
	v_mul_f32_e32 v240, v240, v115
	v_mul_f32_e32 v241, v241, v115
	v_mul_f32_e32 v242, v242, v115
	v_mul_f32_e32 v243, v243, v115
	v_mul_f32_e32 v240, v12, v240
	v_mul_f32_e32 v241, v13, v241
	v_mul_f32_e32 v242, v14, v242
	v_mul_f32_e32 v243, v15, v243
	v_fma_f32 v240, v240, v28, v44
	v_fma_f32 v241, v241, v29, v45
	v_fma_f32 v242, v242, v30, v46
	v_fma_f32 v243, v243, v31, v47
	v_cvt_pk_bf16_f32 v130, v240, v241
	v_cvt_pk_bf16_f32 v131, v242, v243
	global_store_dwordx2 v121, v[130:131], s[4:5] offset:1536
	s_add_u32 s4, s4, 0x20000
	s_addc_u32 s5, s5, 0

.LBB0_580:
	s_mul_hi_i32 s0, s14, 0x2aaaaaab
	s_lshr_b32 s1, s0, 31
	s_ashr_i32 s0, s0, 3
	s_add_i32 s0, s0, s1
	s_mul_i32 s1, s0, 48
	v_mov_b32_e32 v4, 8
	s_sub_i32 s16, s14, s1
	s_waitcnt lgkmcnt(0)
	s_barrier
	s_mul_i32 s1, s16, 43
	v_add_u32_e32 v4, s91, v4
	s_sext_i32_i16 s12, s1
	ds_read_b64 v[4:5], v4
	s_ashr_i32 s17, s12, 9
	s_bfe_u32 s1, s1, 0x1000f
	s_add_i32 s17, s17, s1
	s_sext_i32_i16 s15, s17
	v_lshl_or_b32 v8, s15, 13, v19
	s_waitcnt lgkmcnt(0)
	v_readfirstlane_b32 s1, v5
	v_readfirstlane_b32 s12, v4
	v_add_u32_e32 v6, v8, v21
	v_mov_b32_e32 v5, s1
	v_mov_b32_e32 v4, s12
	v_ashrrev_i32_e32 v7, 31, v6
	v_lshl_add_u64 v[4:5], v[6:7], 2, v[4:5]
	global_load_dword v4, v[4:5], off
	v_mov_b32_e32 v6, 8
	v_mov_b32_e32 v12, 32
	s_mul_i32 s17, s17, 12
	s_sub_i32 s16, s16, s17
	s_sext_i32_i8 s16, s16
	s_mul_i32 s20, s0, 0x1800000
	s_mul_hi_i32 s19, s0, 0x1800000
	s_mov_b32 s18, 0
	s_waitcnt vmcnt(0) lgkmcnt(0)
	v_mul_f32_e32 v5, 0xbfb8aa3b, v4
	v_exp_f32_e32 v5, v5
	s_nop 0
	v_add_f32_e32 v5, 1.0, v5
	v_rcp_f32_e32 v5, v5
	s_nop 0
	v_mul_f32_e32 v4, v4, v5
	ds_write_b32 v18, v4
	s_nop 0
	v_add_u32_e32 v4, s91, v6
	ds_read_b64 v[4:5], v4
	v_add_u32_e32 v6, v8, v22
	v_ashrrev_i32_e32 v7, 31, v6
	s_waitcnt lgkmcnt(0)
	v_readfirstlane_b32 s1, v5
	v_readfirstlane_b32 s12, v4
	s_nop 0
	v_mov_b32_e32 v5, s1
	v_mov_b32_e32 v4, s12
	v_lshl_add_u64 v[4:5], v[6:7], 2, v[4:5]
	global_load_dword v4, v[4:5], off
	v_mov_b32_e32 v6, 8
	s_waitcnt vmcnt(0) lgkmcnt(0)
	v_mul_f32_e32 v5, 0xbfb8aa3b, v4
	v_exp_f32_e32 v5, v5
	s_nop 0
	v_add_f32_e32 v5, 1.0, v5
	v_rcp_f32_e32 v5, v5
	s_nop 0
	v_mul_f32_e32 v4, v4, v5
	ds_write_b32 v18, v4 offset:2048
	s_nop 0
	v_add_u32_e32 v4, s91, v6
	ds_read_b64 v[4:5], v4
	v_add_u32_e32 v6, v8, v23
	v_ashrrev_i32_e32 v7, 31, v6
	s_waitcnt lgkmcnt(0)
	v_readfirstlane_b32 s1, v5
	v_readfirstlane_b32 s12, v4
	s_nop 0
	v_mov_b32_e32 v5, s1
	v_mov_b32_e32 v4, s12
	v_lshl_add_u64 v[4:5], v[6:7], 2, v[4:5]
	global_load_dword v4, v[4:5], off
	v_mov_b32_e32 v6, 8
	s_waitcnt vmcnt(0) lgkmcnt(0)
	v_mul_f32_e32 v5, 0xbfb8aa3b, v4
	v_exp_f32_e32 v5, v5
	s_nop 0
	v_add_f32_e32 v5, 1.0, v5
	v_rcp_f32_e32 v5, v5
	s_nop 0
	v_mul_f32_e32 v4, v4, v5
	ds_write_b32 v18, v4 offset:4096
	s_nop 0
	v_add_u32_e32 v4, s91, v6
	ds_read_b64 v[4:5], v4
	v_add_u32_e32 v6, v8, v24
	v_ashrrev_i32_e32 v7, 31, v6
	s_waitcnt lgkmcnt(0)
	v_readfirstlane_b32 s1, v5
	v_readfirstlane_b32 s12, v4
	s_nop 0
	v_mov_b32_e32 v5, s1
	v_mov_b32_e32 v4, s12
	v_lshl_add_u64 v[4:5], v[6:7], 2, v[4:5]
	global_load_dword v4, v[4:5], off
	v_mov_b32_e32 v6, 8
	s_waitcnt vmcnt(0) lgkmcnt(0)
	v_mul_f32_e32 v5, 0xbfb8aa3b, v4
	v_exp_f32_e32 v5, v5
	s_nop 0
	v_add_f32_e32 v5, 1.0, v5
	v_rcp_f32_e32 v5, v5
	s_nop 0
	v_mul_f32_e32 v4, v4, v5
	ds_write_b32 v18, v4 offset:6144
	s_nop 0
	v_add_u32_e32 v4, s91, v6
	ds_read_b64 v[4:5], v4
	v_add_u32_e32 v6, v8, v25
	v_ashrrev_i32_e32 v7, 31, v6
	s_waitcnt lgkmcnt(0)
	v_readfirstlane_b32 s1, v5
	v_readfirstlane_b32 s12, v4
	s_nop 0
	v_mov_b32_e32 v5, s1
	v_mov_b32_e32 v4, s12
	v_lshl_add_u64 v[4:5], v[6:7], 2, v[4:5]
	global_load_dword v4, v[4:5], off
	v_mov_b32_e32 v6, 8
	s_waitcnt vmcnt(0) lgkmcnt(0)
	v_mul_f32_e32 v5, 0xbfb8aa3b, v4
	v_exp_f32_e32 v5, v5
	s_nop 0
	v_add_f32_e32 v5, 1.0, v5
	v_rcp_f32_e32 v5, v5
	s_nop 0
	v_mul_f32_e32 v4, v4, v5
	ds_write_b32 v18, v4 offset:8192
	s_nop 0
	v_add_u32_e32 v4, s91, v6
	ds_read_b64 v[4:5], v4
	v_add_u32_e32 v6, v8, v26
	v_ashrrev_i32_e32 v7, 31, v6
	s_waitcnt lgkmcnt(0)
	v_readfirstlane_b32 s1, v5
	v_readfirstlane_b32 s12, v4
	s_nop 0
	v_mov_b32_e32 v5, s1
	v_mov_b32_e32 v4, s12
	v_lshl_add_u64 v[4:5], v[6:7], 2, v[4:5]
	global_load_dword v4, v[4:5], off
	v_mov_b32_e32 v6, 8
	s_waitcnt vmcnt(0) lgkmcnt(0)
	v_mul_f32_e32 v5, 0xbfb8aa3b, v4
	v_exp_f32_e32 v5, v5
	s_nop 0
	v_add_f32_e32 v5, 1.0, v5
	v_rcp_f32_e32 v5, v5
	s_nop 0
	v_mul_f32_e32 v4, v4, v5
	ds_write_b32 v18, v4 offset:10240
	s_nop 0
	v_add_u32_e32 v4, s91, v6
	ds_read_b64 v[4:5], v4
	v_add_u32_e32 v6, v8, v27
	v_ashrrev_i32_e32 v7, 31, v6
	s_waitcnt lgkmcnt(0)
	v_readfirstlane_b32 s1, v5
	v_readfirstlane_b32 s12, v4
	s_nop 0
	v_mov_b32_e32 v5, s1
	v_mov_b32_e32 v4, s12
	v_lshl_add_u64 v[4:5], v[6:7], 2, v[4:5]
	global_load_dword v4, v[4:5], off
	v_mov_b32_e32 v6, 8
	s_waitcnt vmcnt(0) lgkmcnt(0)
	v_mul_f32_e32 v5, 0xbfb8aa3b, v4
	v_exp_f32_e32 v5, v5
	s_nop 0
	v_add_f32_e32 v5, 1.0, v5
	v_rcp_f32_e32 v5, v5
	s_nop 0
	v_mul_f32_e32 v4, v4, v5
	ds_write_b32 v18, v4 offset:12288
	s_nop 0
	v_add_u32_e32 v4, s91, v6
	ds_read_b64 v[4:5], v4
	v_add_u32_e32 v6, v8, v28
	v_ashrrev_i32_e32 v7, 31, v6
	s_waitcnt lgkmcnt(0)
	v_readfirstlane_b32 s1, v5
	v_readfirstlane_b32 s12, v4
	s_nop 0
	v_mov_b32_e32 v5, s1
	v_mov_b32_e32 v4, s12
	v_lshl_add_u64 v[4:5], v[6:7], 2, v[4:5]
	global_load_dword v4, v[4:5], off
	v_mov_b32_e32 v6, 8
	s_waitcnt vmcnt(0) lgkmcnt(0)
	v_mul_f32_e32 v5, 0xbfb8aa3b, v4
	v_exp_f32_e32 v5, v5
	s_nop 0
	v_add_f32_e32 v5, 1.0, v5
	v_rcp_f32_e32 v5, v5
	s_nop 0
	v_mul_f32_e32 v4, v4, v5
	ds_write_b32 v18, v4 offset:14336
	s_nop 0
	v_add_u32_e32 v4, s91, v6
	ds_read_b64 v[4:5], v4
	v_add_u32_e32 v6, v8, v29
	v_ashrrev_i32_e32 v7, 31, v6
	s_waitcnt lgkmcnt(0)
	v_readfirstlane_b32 s1, v5
	v_readfirstlane_b32 s12, v4
	s_nop 0
	v_mov_b32_e32 v5, s1
	v_mov_b32_e32 v4, s12
	v_lshl_add_u64 v[4:5], v[6:7], 2, v[4:5]
	global_load_dword v4, v[4:5], off
	v_mov_b32_e32 v6, 8
	s_waitcnt vmcnt(0) lgkmcnt(0)
	v_mul_f32_e32 v5, 0xbfb8aa3b, v4
	v_exp_f32_e32 v5, v5
	s_nop 0
	v_add_f32_e32 v5, 1.0, v5
	v_rcp_f32_e32 v5, v5
	s_nop 0
	v_mul_f32_e32 v4, v4, v5
	ds_write_b32 v18, v4 offset:16384
	s_nop 0
	v_add_u32_e32 v4, s91, v6
	ds_read_b64 v[4:5], v4
	v_add_u32_e32 v6, v8, v30
	v_ashrrev_i32_e32 v7, 31, v6
	s_waitcnt lgkmcnt(0)
	v_readfirstlane_b32 s1, v5
	v_readfirstlane_b32 s12, v4
	s_nop 0
	v_mov_b32_e32 v5, s1
	v_mov_b32_e32 v4, s12
	v_lshl_add_u64 v[4:5], v[6:7], 2, v[4:5]
	global_load_dword v4, v[4:5], off
	v_mov_b32_e32 v6, 8
	s_waitcnt vmcnt(0) lgkmcnt(0)
	v_mul_f32_e32 v5, 0xbfb8aa3b, v4
	v_exp_f32_e32 v5, v5
	s_nop 0
	v_add_f32_e32 v5, 1.0, v5
	v_rcp_f32_e32 v5, v5
	s_nop 0
	v_mul_f32_e32 v4, v4, v5
	ds_write_b32 v18, v4 offset:18432
	s_nop 0
	v_add_u32_e32 v4, s91, v6
	ds_read_b64 v[4:5], v4
	v_add_u32_e32 v6, v8, v31
	v_ashrrev_i32_e32 v7, 31, v6
	s_waitcnt lgkmcnt(0)
	v_readfirstlane_b32 s1, v5
	v_readfirstlane_b32 s12, v4
	s_nop 0
	v_mov_b32_e32 v5, s1
	v_mov_b32_e32 v4, s12
	v_lshl_add_u64 v[4:5], v[6:7], 2, v[4:5]
	global_load_dword v4, v[4:5], off
	v_mov_b32_e32 v6, 8
	s_waitcnt vmcnt(0) lgkmcnt(0)
	v_mul_f32_e32 v5, 0xbfb8aa3b, v4
	v_exp_f32_e32 v5, v5
	s_nop 0
	v_add_f32_e32 v5, 1.0, v5
	v_rcp_f32_e32 v5, v5
	s_nop 0
	v_mul_f32_e32 v4, v4, v5
	ds_write_b32 v18, v4 offset:20480
	s_nop 0
	v_add_u32_e32 v4, s91, v6
	ds_read_b64 v[4:5], v4
	v_add_u32_e32 v6, v8, v32
	v_ashrrev_i32_e32 v7, 31, v6
	s_waitcnt lgkmcnt(0)
	v_readfirstlane_b32 s1, v5
	v_readfirstlane_b32 s12, v4
	s_nop 0
	v_mov_b32_e32 v5, s1
	v_mov_b32_e32 v4, s12
	v_lshl_add_u64 v[4:5], v[6:7], 2, v[4:5]
	global_load_dword v4, v[4:5], off
	v_mov_b32_e32 v6, 8
	s_waitcnt vmcnt(0) lgkmcnt(0)
	v_mul_f32_e32 v5, 0xbfb8aa3b, v4
	v_exp_f32_e32 v5, v5
	s_nop 0
	v_add_f32_e32 v5, 1.0, v5
	v_rcp_f32_e32 v5, v5
	s_nop 0
	v_mul_f32_e32 v4, v4, v5
	ds_write_b32 v18, v4 offset:22528
	s_nop 0
	v_add_u32_e32 v4, s91, v6
	ds_read_b64 v[4:5], v4
	v_add_u32_e32 v6, v8, v33
	v_ashrrev_i32_e32 v7, 31, v6
	s_waitcnt lgkmcnt(0)
	v_readfirstlane_b32 s1, v5
	v_readfirstlane_b32 s12, v4
	s_nop 0
	v_mov_b32_e32 v5, s1
	v_mov_b32_e32 v4, s12
	v_lshl_add_u64 v[4:5], v[6:7], 2, v[4:5]
	global_load_dword v4, v[4:5], off
	v_mov_b32_e32 v6, 8
	s_waitcnt vmcnt(0) lgkmcnt(0)
	v_mul_f32_e32 v5, 0xbfb8aa3b, v4
	v_exp_f32_e32 v5, v5
	s_nop 0
	v_add_f32_e32 v5, 1.0, v5
	v_rcp_f32_e32 v5, v5
	s_nop 0
	v_mul_f32_e32 v4, v4, v5
	ds_write_b32 v18, v4 offset:24576
	s_nop 0
	v_add_u32_e32 v4, s91, v6
	ds_read_b64 v[4:5], v4
	v_add_u32_e32 v6, v8, v34
	v_ashrrev_i32_e32 v7, 31, v6
	s_waitcnt lgkmcnt(0)
	v_readfirstlane_b32 s1, v5
	v_readfirstlane_b32 s12, v4
	s_nop 0
	v_mov_b32_e32 v5, s1
	v_mov_b32_e32 v4, s12
	v_lshl_add_u64 v[4:5], v[6:7], 2, v[4:5]
	global_load_dword v4, v[4:5], off
	v_mov_b32_e32 v6, 8
	s_waitcnt vmcnt(0) lgkmcnt(0)
	v_mul_f32_e32 v5, 0xbfb8aa3b, v4
	v_exp_f32_e32 v5, v5
	s_nop 0
	v_add_f32_e32 v5, 1.0, v5
	v_rcp_f32_e32 v5, v5
	s_nop 0
	v_mul_f32_e32 v4, v4, v5
	ds_write_b32 v18, v4 offset:26624
	s_nop 0
	v_add_u32_e32 v4, s91, v6
	ds_read_b64 v[4:5], v4
	v_add_u32_e32 v6, v8, v35
	v_ashrrev_i32_e32 v7, 31, v6
	s_waitcnt lgkmcnt(0)
	v_readfirstlane_b32 s1, v5
	v_readfirstlane_b32 s12, v4
	s_nop 0
	v_mov_b32_e32 v5, s1
	v_mov_b32_e32 v4, s12
	v_lshl_add_u64 v[4:5], v[6:7], 2, v[4:5]
	global_load_dword v4, v[4:5], off
	v_mov_b32_e32 v6, 8
	s_waitcnt vmcnt(0) lgkmcnt(0)
	v_mul_f32_e32 v5, 0xbfb8aa3b, v4
	v_exp_f32_e32 v5, v5
	s_nop 0
	v_add_f32_e32 v5, 1.0, v5
	v_rcp_f32_e32 v5, v5
	s_nop 0
	v_mul_f32_e32 v4, v4, v5
	ds_write_b32 v18, v4 offset:28672
	s_nop 0
	v_add_u32_e32 v4, s91, v6
	ds_read_b64 v[4:5], v4
	v_add_u32_e32 v6, v8, v36
	v_ashrrev_i32_e32 v7, 31, v6
	s_waitcnt lgkmcnt(0)
	v_readfirstlane_b32 s1, v5
	v_readfirstlane_b32 s12, v4
	s_nop 0
	v_mov_b32_e32 v5, s1
	s_ashr_i32 s1, s0, 31
	v_mov_b32_e32 v4, s12
	v_lshl_add_u64 v[4:5], v[6:7], 2, v[4:5]
	global_load_dword v11, v[4:5], off
	v_mov_b32_e32 v4, 0
	s_mov_b64 s[12:13], 0
	v_mov_b32_e32 v5, v4
	v_mov_b32_e32 v8, v4
	v_mov_b32_e32 v9, v4
	v_mov_b32_e32 v6, v4
	v_mov_b32_e32 v10, v4
	s_waitcnt vmcnt(0) lgkmcnt(0)
	v_mul_f32_e32 v7, 0xbfb8aa3b, v11
	v_exp_f32_e32 v13, v7
	v_mov_b32_e32 v7, v4
	v_add_f32_e32 v13, 1.0, v13
	v_rcp_f32_e32 v13, v13
	s_nop 0
	v_mul_f32_e32 v11, v11, v13
	ds_write_b32 v18, v11 offset:30720
	s_waitcnt lgkmcnt(0)
	s_barrier
	s_nop 0
	v_add_u32_e32 v11, s91, v12
	ds_read_b64 v[14:15], v11
	v_lshl_add_u32 v12, s16, 9, v17
	v_ashrrev_i32_e32 v13, 31, v12
	v_mov_b32_e32 v11, v4
	s_waitcnt lgkmcnt(0)
	v_readfirstlane_b32 s16, v14
	v_readfirstlane_b32 s17, v15
	s_add_u32 s16, s16, s20
	s_addc_u32 s17, s17, s19
	v_lshl_add_u64 v[14:15], v[12:13], 2, s[16:17]
	v_lshlrev_b32_e32 v136, 2, v12
	s_mov_b32 s100, s16
	s_mov_b32 s101, s17
	v_mov_b32_e32 v137, s18
.LBB0_581:
	global_load_dword v70, v136, s[100:101]
	s_add_u32 s100, s100, 0x6000
	s_addc_u32 s101, s101, 0
	global_load_dword v72, v136, s[100:101]
	s_add_u32 s100, s100, 0x6000
	s_addc_u32 s101, s101, 0
	global_load_dword v74, v136, s[100:101]
	s_add_u32 s100, s100, 0x6000
	s_addc_u32 s101, s101, 0
	global_load_dword v76, v136, s[100:101]
	s_add_u32 s100, s100, 0x6000
	s_addc_u32 s101, s101, 0
	global_load_dword v78, v136, s[100:101]
	s_add_u32 s100, s100, 0x6000
	s_addc_u32 s101, s101, 0
	global_load_dword v80, v136, s[100:101]
	s_add_u32 s100, s100, 0x6000
	s_addc_u32 s101, s101, 0
	global_load_dword v82, v136, s[100:101]
	s_add_u32 s100, s100, 0x6000
	s_addc_u32 s101, s101, 0
	global_load_dword v84, v136, s[100:101]
	s_add_u32 s100, s100, 0x6000
	s_addc_u32 s101, s101, 0
	global_load_dword v86, v136, s[100:101]
	s_add_u32 s100, s100, 0x6000
	s_addc_u32 s101, s101, 0
	global_load_dword v88, v136, s[100:101]
	s_add_u32 s100, s100, 0x6000
	s_addc_u32 s101, s101, 0
	global_load_dword v90, v136, s[100:101]
	s_add_u32 s100, s100, 0x6000
	s_addc_u32 s101, s101, 0
	global_load_dword v92, v136, s[100:101]
	s_add_u32 s100, s100, 0x6000
	s_addc_u32 s101, s101, 0
	global_load_dword v94, v136, s[100:101]
	s_add_u32 s100, s100, 0x6000
	s_addc_u32 s101, s101, 0
	global_load_dword v96, v136, s[100:101]
	s_add_u32 s100, s100, 0x6000
	s_addc_u32 s101, s101, 0
	global_load_dword v98, v136, s[100:101]
	s_add_u32 s100, s100, 0x6000
	s_addc_u32 s101, s101, 0
	global_load_dword v100, v136, s[100:101]
	s_add_u32 s100, s100, 0x6000
	s_addc_u32 s101, s101, 0
	global_load_dword v102, v136, s[100:101]
	s_add_u32 s100, s100, 0x6000
	s_addc_u32 s101, s101, 0
	global_load_dword v104, v136, s[100:101]
	s_add_u32 s100, s100, 0x6000
	s_addc_u32 s101, s101, 0
	global_load_dword v106, v136, s[100:101]
	s_add_u32 s100, s100, 0x6000
	s_addc_u32 s101, s101, 0
	global_load_dword v108, v136, s[100:101]
	s_add_u32 s100, s100, 0x6000
	s_addc_u32 s101, s101, 0
	global_load_dword v110, v136, s[100:101]
	s_add_u32 s100, s100, 0x6000
	s_addc_u32 s101, s101, 0
	global_load_dword v112, v136, s[100:101]
	s_add_u32 s100, s100, 0x6000
	s_addc_u32 s101, s101, 0
	global_load_dword v114, v136, s[100:101]
	s_add_u32 s100, s100, 0x6000
	s_addc_u32 s101, s101, 0
	global_load_dword v116, v136, s[100:101]
	s_add_u32 s100, s100, 0x6000
	s_addc_u32 s101, s101, 0
	global_load_dword v118, v136, s[100:101]
	s_add_u32 s100, s100, 0x6000
	s_addc_u32 s101, s101, 0
	global_load_dword v120, v136, s[100:101]
	s_add_u32 s100, s100, 0x6000
	s_addc_u32 s101, s101, 0
	global_load_dword v122, v136, s[100:101]
	s_add_u32 s100, s100, 0x6000
	s_addc_u32 s101, s101, 0
	global_load_dword v124, v136, s[100:101]
	s_add_u32 s100, s100, 0x6000
	s_addc_u32 s101, s101, 0
	global_load_dword v126, v136, s[100:101]
	s_add_u32 s100, s100, 0x6000
	s_addc_u32 s101, s101, 0
	global_load_dword v128, v136, s[100:101]
	s_add_u32 s100, s100, 0x6000
	s_addc_u32 s101, s101, 0
	global_load_dword v130, v136, s[100:101]
	s_add_u32 s100, s100, 0x6000
	s_addc_u32 s101, s101, 0
	global_load_dword v132, v136, s[100:101]
	s_add_u32 s100, s100, 0x6000
	s_addc_u32 s101, s101, 0
	ds_read_b128 v[38:41], v137 offset:0
	ds_read_b128 v[42:45], v137 offset:16
	ds_read_b128 v[46:49], v137 offset:32
	ds_read_b128 v[50:53], v137 offset:48
	ds_read_b128 v[54:57], v137 offset:64
	ds_read_b128 v[58:61], v137 offset:80
	ds_read_b128 v[62:65], v137 offset:96
	ds_read_b128 v[66:69], v137 offset:112
	s_waitcnt vmcnt(28) lgkmcnt(0)
	v_pk_fma_f32 v[8:9], v[70:71], v[38:39], v[8:9] op_sel_hi:[0,1,1]
	v_pk_fma_f32 v[6:7], v[70:71], v[40:41], v[6:7] op_sel_hi:[0,1,1]
	v_pk_fma_f32 v[10:11], v[70:71], v[42:43], v[10:11] op_sel_hi:[0,1,1]
	v_pk_fma_f32 v[4:5], v[70:71], v[44:45], v[4:5] op_sel_hi:[0,1,1]
	v_pk_fma_f32 v[8:9], v[72:73], v[46:47], v[8:9] op_sel_hi:[0,1,1]
	v_pk_fma_f32 v[6:7], v[72:73], v[48:49], v[6:7] op_sel_hi:[0,1,1]
	v_pk_fma_f32 v[10:11], v[72:73], v[50:51], v[10:11] op_sel_hi:[0,1,1]
	v_pk_fma_f32 v[4:5], v[72:73], v[52:53], v[4:5] op_sel_hi:[0,1,1]
	v_pk_fma_f32 v[8:9], v[74:75], v[54:55], v[8:9] op_sel_hi:[0,1,1]
	v_pk_fma_f32 v[6:7], v[74:75], v[56:57], v[6:7] op_sel_hi:[0,1,1]
	v_pk_fma_f32 v[10:11], v[74:75], v[58:59], v[10:11] op_sel_hi:[0,1,1]
	v_pk_fma_f32 v[4:5], v[74:75], v[60:61], v[4:5] op_sel_hi:[0,1,1]
	v_pk_fma_f32 v[8:9], v[76:77], v[62:63], v[8:9] op_sel_hi:[0,1,1]
	v_pk_fma_f32 v[6:7], v[76:77], v[64:65], v[6:7] op_sel_hi:[0,1,1]
	v_pk_fma_f32 v[10:11], v[76:77], v[66:67], v[10:11] op_sel_hi:[0,1,1]
	v_pk_fma_f32 v[4:5], v[76:77], v[68:69], v[4:5] op_sel_hi:[0,1,1]
	ds_read_b128 v[38:41], v137 offset:128
	ds_read_b128 v[42:45], v137 offset:144
	ds_read_b128 v[46:49], v137 offset:160
	ds_read_b128 v[50:53], v137 offset:176
	ds_read_b128 v[54:57], v137 offset:192
	ds_read_b128 v[58:61], v137 offset:208
	ds_read_b128 v[62:65], v137 offset:224
	ds_read_b128 v[66:69], v137 offset:240
	s_waitcnt vmcnt(24) lgkmcnt(0)
	v_pk_fma_f32 v[8:9], v[78:79], v[38:39], v[8:9] op_sel_hi:[0,1,1]
	v_pk_fma_f32 v[6:7], v[78:79], v[40:41], v[6:7] op_sel_hi:[0,1,1]
	v_pk_fma_f32 v[10:11], v[78:79], v[42:43], v[10:11] op_sel_hi:[0,1,1]
	v_pk_fma_f32 v[4:5], v[78:79], v[44:45], v[4:5] op_sel_hi:[0,1,1]
	v_pk_fma_f32 v[8:9], v[80:81], v[46:47], v[8:9] op_sel_hi:[0,1,1]
	v_pk_fma_f32 v[6:7], v[80:81], v[48:49], v[6:7] op_sel_hi:[0,1,1]
	v_pk_fma_f32 v[10:11], v[80:81], v[50:51], v[10:11] op_sel_hi:[0,1,1]
	v_pk_fma_f32 v[4:5], v[80:81], v[52:53], v[4:5] op_sel_hi:[0,1,1]
	v_pk_fma_f32 v[8:9], v[82:83], v[54:55], v[8:9] op_sel_hi:[0,1,1]
	v_pk_fma_f32 v[6:7], v[82:83], v[56:57], v[6:7] op_sel_hi:[0,1,1]
	v_pk_fma_f32 v[10:11], v[82:83], v[58:59], v[10:11] op_sel_hi:[0,1,1]
	v_pk_fma_f32 v[4:5], v[82:83], v[60:61], v[4:5] op_sel_hi:[0,1,1]
	v_pk_fma_f32 v[8:9], v[84:85], v[62:63], v[8:9] op_sel_hi:[0,1,1]
	v_pk_fma_f32 v[6:7], v[84:85], v[64:65], v[6:7] op_sel_hi:[0,1,1]
	v_pk_fma_f32 v[10:11], v[84:85], v[66:67], v[10:11] op_sel_hi:[0,1,1]
	v_pk_fma_f32 v[4:5], v[84:85], v[68:69], v[4:5] op_sel_hi:[0,1,1]
	ds_read_b128 v[38:41], v137 offset:256
	ds_read_b128 v[42:45], v137 offset:272
	ds_read_b128 v[46:49], v137 offset:288
	ds_read_b128 v[50:53], v137 offset:304
	ds_read_b128 v[54:57], v137 offset:320
	ds_read_b128 v[58:61], v137 offset:336
	ds_read_b128 v[62:65], v137 offset:352
	ds_read_b128 v[66:69], v137 offset:368
	s_waitcnt vmcnt(20) lgkmcnt(0)
	v_pk_fma_f32 v[8:9], v[86:87], v[38:39], v[8:9] op_sel_hi:[0,1,1]
	v_pk_fma_f32 v[6:7], v[86:87], v[40:41], v[6:7] op_sel_hi:[0,1,1]
	v_pk_fma_f32 v[10:11], v[86:87], v[42:43], v[10:11] op_sel_hi:[0,1,1]
	v_pk_fma_f32 v[4:5], v[86:87], v[44:45], v[4:5] op_sel_hi:[0,1,1]
	v_pk_fma_f32 v[8:9], v[88:89], v[46:47], v[8:9] op_sel_hi:[0,1,1]
	v_pk_fma_f32 v[6:7], v[88:89], v[48:49], v[6:7] op_sel_hi:[0,1,1]
	v_pk_fma_f32 v[10:11], v[88:89], v[50:51], v[10:11] op_sel_hi:[0,1,1]
	v_pk_fma_f32 v[4:5], v[88:89], v[52:53], v[4:5] op_sel_hi:[0,1,1]
	v_pk_fma_f32 v[8:9], v[90:91], v[54:55], v[8:9] op_sel_hi:[0,1,1]
	v_pk_fma_f32 v[6:7], v[90:91], v[56:57], v[6:7] op_sel_hi:[0,1,1]
	v_pk_fma_f32 v[10:11], v[90:91], v[58:59], v[10:11] op_sel_hi:[0,1,1]
	v_pk_fma_f32 v[4:5], v[90:91], v[60:61], v[4:5] op_sel_hi:[0,1,1]
	v_pk_fma_f32 v[8:9], v[92:93], v[62:63], v[8:9] op_sel_hi:[0,1,1]
	v_pk_fma_f32 v[6:7], v[92:93], v[64:65], v[6:7] op_sel_hi:[0,1,1]
	v_pk_fma_f32 v[10:11], v[92:93], v[66:67], v[10:11] op_sel_hi:[0,1,1]
	v_pk_fma_f32 v[4:5], v[92:93], v[68:69], v[4:5] op_sel_hi:[0,1,1]
	ds_read_b128 v[38:41], v137 offset:384
	ds_read_b128 v[42:45], v137 offset:400
	ds_read_b128 v[46:49], v137 offset:416
	ds_read_b128 v[50:53], v137 offset:432
	ds_read_b128 v[54:57], v137 offset:448
	ds_read_b128 v[58:61], v137 offset:464
	ds_read_b128 v[62:65], v137 offset:480
	ds_read_b128 v[66:69], v137 offset:496
	s_waitcnt vmcnt(16) lgkmcnt(0)
	v_pk_fma_f32 v[8:9], v[94:95], v[38:39], v[8:9] op_sel_hi:[0,1,1]
	v_pk_fma_f32 v[6:7], v[94:95], v[40:41], v[6:7] op_sel_hi:[0,1,1]
	v_pk_fma_f32 v[10:11], v[94:95], v[42:43], v[10:11] op_sel_hi:[0,1,1]
	v_pk_fma_f32 v[4:5], v[94:95], v[44:45], v[4:5] op_sel_hi:[0,1,1]
	v_pk_fma_f32 v[8:9], v[96:97], v[46:47], v[8:9] op_sel_hi:[0,1,1]
	v_pk_fma_f32 v[6:7], v[96:97], v[48:49], v[6:7] op_sel_hi:[0,1,1]
	v_pk_fma_f32 v[10:11], v[96:97], v[50:51], v[10:11] op_sel_hi:[0,1,1]
	v_pk_fma_f32 v[4:5], v[96:97], v[52:53], v[4:5] op_sel_hi:[0,1,1]
	v_pk_fma_f32 v[8:9], v[98:99], v[54:55], v[8:9] op_sel_hi:[0,1,1]
	v_pk_fma_f32 v[6:7], v[98:99], v[56:57], v[6:7] op_sel_hi:[0,1,1]
	v_pk_fma_f32 v[10:11], v[98:99], v[58:59], v[10:11] op_sel_hi:[0,1,1]
	v_pk_fma_f32 v[4:5], v[98:99], v[60:61], v[4:5] op_sel_hi:[0,1,1]
	v_pk_fma_f32 v[8:9], v[100:101], v[62:63], v[8:9] op_sel_hi:[0,1,1]
	v_pk_fma_f32 v[6:7], v[100:101], v[64:65], v[6:7] op_sel_hi:[0,1,1]
	v_pk_fma_f32 v[10:11], v[100:101], v[66:67], v[10:11] op_sel_hi:[0,1,1]
	v_pk_fma_f32 v[4:5], v[100:101], v[68:69], v[4:5] op_sel_hi:[0,1,1]
	ds_read_b128 v[38:41], v137 offset:512
	ds_read_b128 v[42:45], v137 offset:528
	ds_read_b128 v[46:49], v137 offset:544
	ds_read_b128 v[50:53], v137 offset:560
	ds_read_b128 v[54:57], v137 offset:576
	ds_read_b128 v[58:61], v137 offset:592
	ds_read_b128 v[62:65], v137 offset:608
	ds_read_b128 v[66:69], v137 offset:624
	s_waitcnt vmcnt(12) lgkmcnt(0)
	v_pk_fma_f32 v[8:9], v[102:103], v[38:39], v[8:9] op_sel_hi:[0,1,1]
	v_pk_fma_f32 v[6:7], v[102:103], v[40:41], v[6:7] op_sel_hi:[0,1,1]
	v_pk_fma_f32 v[10:11], v[102:103], v[42:43], v[10:11] op_sel_hi:[0,1,1]
	v_pk_fma_f32 v[4:5], v[102:103], v[44:45], v[4:5] op_sel_hi:[0,1,1]
	v_pk_fma_f32 v[8:9], v[104:105], v[46:47], v[8:9] op_sel_hi:[0,1,1]
	v_pk_fma_f32 v[6:7], v[104:105], v[48:49], v[6:7] op_sel_hi:[0,1,1]
	v_pk_fma_f32 v[10:11], v[104:105], v[50:51], v[10:11] op_sel_hi:[0,1,1]
	v_pk_fma_f32 v[4:5], v[104:105], v[52:53], v[4:5] op_sel_hi:[0,1,1]
	v_pk_fma_f32 v[8:9], v[106:107], v[54:55], v[8:9] op_sel_hi:[0,1,1]
	v_pk_fma_f32 v[6:7], v[106:107], v[56:57], v[6:7] op_sel_hi:[0,1,1]
	v_pk_fma_f32 v[10:11], v[106:107], v[58:59], v[10:11] op_sel_hi:[0,1,1]
	v_pk_fma_f32 v[4:5], v[106:107], v[60:61], v[4:5] op_sel_hi:[0,1,1]
	v_pk_fma_f32 v[8:9], v[108:109], v[62:63], v[8:9] op_sel_hi:[0,1,1]
	v_pk_fma_f32 v[6:7], v[108:109], v[64:65], v[6:7] op_sel_hi:[0,1,1]
	v_pk_fma_f32 v[10:11], v[108:109], v[66:67], v[10:11] op_sel_hi:[0,1,1]
	v_pk_fma_f32 v[4:5], v[108:109], v[68:69], v[4:5] op_sel_hi:[0,1,1]
	ds_read_b128 v[38:41], v137 offset:640
	ds_read_b128 v[42:45], v137 offset:656
	ds_read_b128 v[46:49], v137 offset:672
	ds_read_b128 v[50:53], v137 offset:688
	ds_read_b128 v[54:57], v137 offset:704
	ds_read_b128 v[58:61], v137 offset:720
	ds_read_b128 v[62:65], v137 offset:736
	ds_read_b128 v[66:69], v137 offset:752
	s_waitcnt vmcnt(8) lgkmcnt(0)
	v_pk_fma_f32 v[8:9], v[110:111], v[38:39], v[8:9] op_sel_hi:[0,1,1]
	v_pk_fma_f32 v[6:7], v[110:111], v[40:41], v[6:7] op_sel_hi:[0,1,1]
	v_pk_fma_f32 v[10:11], v[110:111], v[42:43], v[10:11] op_sel_hi:[0,1,1]
	v_pk_fma_f32 v[4:5], v[110:111], v[44:45], v[4:5] op_sel_hi:[0,1,1]
	v_pk_fma_f32 v[8:9], v[112:113], v[46:47], v[8:9] op_sel_hi:[0,1,1]
	v_pk_fma_f32 v[6:7], v[112:113], v[48:49], v[6:7] op_sel_hi:[0,1,1]
	v_pk_fma_f32 v[10:11], v[112:113], v[50:51], v[10:11] op_sel_hi:[0,1,1]
	v_pk_fma_f32 v[4:5], v[112:113], v[52:53], v[4:5] op_sel_hi:[0,1,1]
	v_pk_fma_f32 v[8:9], v[114:115], v[54:55], v[8:9] op_sel_hi:[0,1,1]
	v_pk_fma_f32 v[6:7], v[114:115], v[56:57], v[6:7] op_sel_hi:[0,1,1]
	v_pk_fma_f32 v[10:11], v[114:115], v[58:59], v[10:11] op_sel_hi:[0,1,1]
	v_pk_fma_f32 v[4:5], v[114:115], v[60:61], v[4:5] op_sel_hi:[0,1,1]
	v_pk_fma_f32 v[8:9], v[116:117], v[62:63], v[8:9] op_sel_hi:[0,1,1]
	v_pk_fma_f32 v[6:7], v[116:117], v[64:65], v[6:7] op_sel_hi:[0,1,1]
	v_pk_fma_f32 v[10:11], v[116:117], v[66:67], v[10:11] op_sel_hi:[0,1,1]
	v_pk_fma_f32 v[4:5], v[116:117], v[68:69], v[4:5] op_sel_hi:[0,1,1]
	ds_read_b128 v[38:41], v137 offset:768
	ds_read_b128 v[42:45], v137 offset:784
	ds_read_b128 v[46:49], v137 offset:800
	ds_read_b128 v[50:53], v137 offset:816
	ds_read_b128 v[54:57], v137 offset:832
	ds_read_b128 v[58:61], v137 offset:848
	ds_read_b128 v[62:65], v137 offset:864
	ds_read_b128 v[66:69], v137 offset:880
	s_waitcnt vmcnt(4) lgkmcnt(0)
	v_pk_fma_f32 v[8:9], v[118:119], v[38:39], v[8:9] op_sel_hi:[0,1,1]
	v_pk_fma_f32 v[6:7], v[118:119], v[40:41], v[6:7] op_sel_hi:[0,1,1]
	v_pk_fma_f32 v[10:11], v[118:119], v[42:43], v[10:11] op_sel_hi:[0,1,1]
	v_pk_fma_f32 v[4:5], v[118:119], v[44:45], v[4:5] op_sel_hi:[0,1,1]
	v_pk_fma_f32 v[8:9], v[120:121], v[46:47], v[8:9] op_sel_hi:[0,1,1]
	v_pk_fma_f32 v[6:7], v[120:121], v[48:49], v[6:7] op_sel_hi:[0,1,1]
	v_pk_fma_f32 v[10:11], v[120:121], v[50:51], v[10:11] op_sel_hi:[0,1,1]
	v_pk_fma_f32 v[4:5], v[120:121], v[52:53], v[4:5] op_sel_hi:[0,1,1]
	v_pk_fma_f32 v[8:9], v[122:123], v[54:55], v[8:9] op_sel_hi:[0,1,1]
	v_pk_fma_f32 v[6:7], v[122:123], v[56:57], v[6:7] op_sel_hi:[0,1,1]
	v_pk_fma_f32 v[10:11], v[122:123], v[58:59], v[10:11] op_sel_hi:[0,1,1]
	v_pk_fma_f32 v[4:5], v[122:123], v[60:61], v[4:5] op_sel_hi:[0,1,1]
	v_pk_fma_f32 v[8:9], v[124:125], v[62:63], v[8:9] op_sel_hi:[0,1,1]
	v_pk_fma_f32 v[6:7], v[124:125], v[64:65], v[6:7] op_sel_hi:[0,1,1]
	v_pk_fma_f32 v[10:11], v[124:125], v[66:67], v[10:11] op_sel_hi:[0,1,1]
	v_pk_fma_f32 v[4:5], v[124:125], v[68:69], v[4:5] op_sel_hi:[0,1,1]
	ds_read_b128 v[38:41], v137 offset:896
	ds_read_b128 v[42:45], v137 offset:912
	ds_read_b128 v[46:49], v137 offset:928
	ds_read_b128 v[50:53], v137 offset:944
	ds_read_b128 v[54:57], v137 offset:960
	ds_read_b128 v[58:61], v137 offset:976
	ds_read_b128 v[62:65], v137 offset:992
	ds_read_b128 v[66:69], v137 offset:1008
	s_waitcnt vmcnt(0) lgkmcnt(0)
	v_pk_fma_f32 v[8:9], v[126:127], v[38:39], v[8:9] op_sel_hi:[0,1,1]
	v_pk_fma_f32 v[6:7], v[126:127], v[40:41], v[6:7] op_sel_hi:[0,1,1]
	v_pk_fma_f32 v[10:11], v[126:127], v[42:43], v[10:11] op_sel_hi:[0,1,1]
	v_pk_fma_f32 v[4:5], v[126:127], v[44:45], v[4:5] op_sel_hi:[0,1,1]
	v_pk_fma_f32 v[8:9], v[128:129], v[46:47], v[8:9] op_sel_hi:[0,1,1]
	v_pk_fma_f32 v[6:7], v[128:129], v[48:49], v[6:7] op_sel_hi:[0,1,1]
	v_pk_fma_f32 v[10:11], v[128:129], v[50:51], v[10:11] op_sel_hi:[0,1,1]
	v_pk_fma_f32 v[4:5], v[128:129], v[52:53], v[4:5] op_sel_hi:[0,1,1]
	v_pk_fma_f32 v[8:9], v[130:131], v[54:55], v[8:9] op_sel_hi:[0,1,1]
	v_pk_fma_f32 v[6:7], v[130:131], v[56:57], v[6:7] op_sel_hi:[0,1,1]
	v_pk_fma_f32 v[10:11], v[130:131], v[58:59], v[10:11] op_sel_hi:[0,1,1]
	v_pk_fma_f32 v[4:5], v[130:131], v[60:61], v[4:5] op_sel_hi:[0,1,1]
	v_pk_fma_f32 v[8:9], v[132:133], v[62:63], v[8:9] op_sel_hi:[0,1,1]
	v_pk_fma_f32 v[6:7], v[132:133], v[64:65], v[6:7] op_sel_hi:[0,1,1]
	v_pk_fma_f32 v[10:11], v[132:133], v[66:67], v[10:11] op_sel_hi:[0,1,1]
	v_pk_fma_f32 v[4:5], v[132:133], v[68:69], v[4:5] op_sel_hi:[0,1,1]
	v_add_u32_e32 v137, 0x400, v137
	s_addk_i32 s18, 0x400
	s_add_u32 s12, s12, 0xc0000
	s_addc_u32 s13, s13, 0
	s_cmp_eq_u32 s12, 0x1800000
	s_cbranch_scc0 .LBB0_581
	v_mov_b32_e32 v14, 40
	s_mul_i32 s12, s0, 0x1800
	v_add_u32_e32 v14, 0, v14
	v_add_u32_e32 v14, 0x20400, v14
	ds_read_b64 v[14:15], v14
	v_add_u32_e32 v38, s12, v12
	v_ashrrev_i32_e32 v39, 31, v38
	s_lshl_b64 s[0:1], s[0:1], 5
	v_lshl_add_u64 v[12:13], v[12:13], 2, s[6:7]
	s_waitcnt lgkmcnt(0)
	v_readfirstlane_b32 s12, v15
	v_readfirstlane_b32 s13, v14
	s_nop 0
	v_mov_b32_e32 v15, s12
	v_mov_b32_e32 v14, s13
	v_lshl_add_u64 v[14:15], v[38:39], 2, v[14:15]
	global_load_dword v50, v[14:15], off
	s_lshl_b32 s12, s15, 3
	s_ashr_i32 s13, s12, 31
	s_add_u32 s0, s0, s12
	s_addc_u32 s12, s1, s13
	v_mad_u64_u32 v[12:13], s[0:1], s0, v227, v[12:13]
	s_mulk_i32 s12, 0x6000
	v_add_co_u32_e32 v14, vcc, s89, v12
	v_add_u32_e32 v13, s12, v13
	s_mov_b64 s[0:1], vcc
	v_add_co_u32_e32 v38, vcc, s80, v12
	v_addc_co_u32_e64 v15, s[0:1], 0, v13, s[0:1]
	s_nop 0
	v_addc_co_u32_e32 v39, vcc, 0, v13, vcc
	v_add_co_u32_e32 v40, vcc, s88, v12
	s_mov_b32 s0, 0x18000
	s_nop 0
	v_addc_co_u32_e32 v41, vcc, 0, v13, vcc
	v_add_co_u32_e32 v42, vcc, s0, v12
	s_waitcnt vmcnt(0) lgkmcnt(0)
	v_add_f32_e32 v8, v8, v50
	v_addc_co_u32_e32 v43, vcc, 0, v13, vcc
	v_add_co_u32_e32 v44, vcc, 0x1e000, v12
	v_add_f32_e32 v9, v9, v50
	s_nop 0
	v_addc_co_u32_e32 v45, vcc, 0, v13, vcc
	v_add_co_u32_e32 v46, vcc, 0x24000, v12
	v_add_f32_e32 v6, v6, v50
	s_nop 0
	v_addc_co_u32_e32 v47, vcc, 0, v13, vcc
	v_add_co_u32_e32 v48, vcc, 0x2a000, v12
	v_add_f32_e32 v7, v7, v50
	s_nop 0
	v_addc_co_u32_e32 v49, vcc, 0, v13, vcc
	v_add_f32_e32 v10, v10, v50
	v_add_f32_e32 v11, v11, v50
	v_add_f32_e32 v4, v4, v50
	v_add_f32_e32 v5, v5, v50
	global_store_dword v[12:13], v8, off
	global_store_dword v[14:15], v9, off
	global_store_dword v[38:39], v6, off
	global_store_dword v[40:41], v7, off
	global_store_dword v[42:43], v10, off
	global_store_dword v[44:45], v11, off
	global_store_dword v[46:47], v4, off
	global_store_dword v[48:49], v5, off
	s_branch .LBB0_572

	.amdhsa_kernel _Z8mega_fwdILi1023EEv2KP
		.amdhsa_group_segment_fixed_size 0
		.amdhsa_private_segment_fixed_size 0
		.amdhsa_kernarg_size 504
		.amdhsa_user_sgpr_count 2
		.amdhsa_user_sgpr_dispatch_ptr 0
		.amdhsa_user_sgpr_queue_ptr 0
		.amdhsa_user_sgpr_kernarg_segment_ptr 1
		.amdhsa_user_sgpr_dispatch_id 0
		.amdhsa_user_sgpr_kernarg_preload_length 0
		.amdhsa_user_sgpr_kernarg_preload_offset 0
		.amdhsa_user_sgpr_private_segment_size 0
		.amdhsa_uses_dynamic_stack 0
		.amdhsa_enable_private_segment 0
		.amdhsa_system_sgpr_workgroup_id_x 1
		.amdhsa_system_sgpr_workgroup_id_y 0
		.amdhsa_system_sgpr_workgroup_id_z 0
		.amdhsa_system_sgpr_workgroup_info 0
		.amdhsa_system_vgpr_workitem_id 2
		.amdhsa_next_free_vgpr 256
		.amdhsa_next_free_sgpr 102
		.amdhsa_accum_offset 256
		.amdhsa_reserve_vcc 1
		.amdhsa_float_round_mode_32 0
		.amdhsa_float_round_mode_16_64 0
		.amdhsa_float_denorm_mode_32 3
		.amdhsa_float_denorm_mode_16_64 3
		.amdhsa_dx10_clamp 1
		.amdhsa_ieee_mode 1
		.amdhsa_fp16_overflow 0
		.amdhsa_tg_split 0
		.amdhsa_exception_fp_ieee_invalid_op 0
		.amdhsa_exception_fp_denorm_src 0
		.amdhsa_exception_fp_ieee_div_zero 0
		.amdhsa_exception_fp_ieee_overflow 0
		.amdhsa_exception_fp_ieee_underflow 0
		.amdhsa_exception_fp_ieee_inexact 0
		.amdhsa_exception_int_div_zero 0
	.end_amdhsa_kernel

amdhsa.kernels:
  - .agpr_count:     0
    .args:
      - .offset:         0
        .size:           248
        .value_kind:     by_value
      - .offset:         248
        .size:           4
        .value_kind:     hidden_block_count_x
      - .offset:         252
        .size:           4
        .value_kind:     hidden_block_count_y
      - .offset:         256
        .size:           4
        .value_kind:     hidden_block_count_z
      - .offset:         260
        .size:           2
        .value_kind:     hidden_group_size_x
      - .offset:         262
        .size:           2
        .value_kind:     hidden_group_size_y
      - .offset:         264
        .size:           2
        .value_kind:     hidden_group_size_z
      - .offset:         266
        .size:           2
        .value_kind:     hidden_remainder_x
      - .offset:         268
        .size:           2
        .value_kind:     hidden_remainder_y
      - .offset:         270
        .size:           2
        .value_kind:     hidden_remainder_z
      - .offset:         288
        .size:           8
        .value_kind:     hidden_global_offset_x
      - .offset:         296
        .size:           8
        .value_kind:     hidden_global_offset_y
      - .offset:         304
        .size:           8
        .value_kind:     hidden_global_offset_z
      - .offset:         312
        .size:           2
        .value_kind:     hidden_grid_dims
      - .offset:         336
        .size:           8
        .value_kind:     hidden_multigrid_sync_arg
      - .offset:         368
        .size:           4
        .value_kind:     hidden_dynamic_lds_size
    .group_segment_fixed_size: 0
    .kernarg_segment_align: 8
    .kernarg_segment_size: 504
    .language:       OpenCL C
    .language_version:
      - 2
      - 0
    .max_flat_workgroup_size: 512
    .name:           _Z8mega_fwdILi1023EEv2KP
    .private_segment_fixed_size: 0
    .sgpr_count:     108
    .sgpr_spill_count: 176
    .symbol:         _Z8mega_fwdILi1023EEv2KP.kd
    .uniform_work_group_size: 1
    .uses_dynamic_stack: false
    .vgpr_count:     256
    .vgpr_spill_count: 0
    .wavefront_size: 64
